# 42 compiler-duplicated s_waitcnt lgkmcnt(0) (identical wait directly after the template's own) removed from the GEMM MFMA segments; s_setprio flips removed
# speedup vs baseline: 1.0059x; 1.0059x over previous
; #define PG8_STAGE(bufoff, gbase, voff) do { _Pragma("unroll") for (int _i = 0; _i < 2; ++_i) \
;         __builtin_amdgcn_global_load_lds((const unsigned*)((const char*)(gbase) + (voff)[_i]), (LAS unsigned*)(lds + (bufoff) + ldsw + _i * 8192), 16, 0, 0); } while (0)
; #define PG8_LDA(dst, b, h) do { _Pragma("unroll") for (int m = 0; m < 4; ++m) _Pragma("unroll") for (int k = 0; k < 2; ++k) dst[m][k] = *(const LAS bf16x8*)(lds + PG8_SA(b, h) + aoff + m * 2048 + k * 1024); } while (0)
; #define PG8_LDB(dst, b, h) do { _Pragma("unroll") for (int n = 0; n < 2; ++n) _Pragma("unroll") for (int k = 0; k < 2; ++k) dst[n][k] = *(const LAS bf16x8*)(lds + PG8_SB(b, h) + boff + n * 2048 + k * 1024); } while (0)
; #define PG8_MMA(ai, bj, At, Bt) do { __builtin_amdgcn_s_setprio(1); _Pragma("unroll") for (int m = 0; m < 4; ++m) _Pragma("unroll") for (int n = 0; n < 2; ++n) _Pragma("unroll") for (int k = 0; k < 2; ++k) \
;         acc[ai][bj][m][n] = __builtin_amdgcn_mfma_f32_16x16x32_bf16(Bt[n][k], At[m][k], acc[ai][bj][m][n], 0, 0, 0); __builtin_amdgcn_s_setprio(0); } while (0)
; #define PG8_WAIT_V(n) asm volatile("s_waitcnt vmcnt(" #n ")" ::: "memory")
; #define PG8_WAIT_L(n) asm volatile("s_waitcnt lgkmcnt(" #n ")" ::: "memory")
; #define PG8_BAR __builtin_amdgcn_s_barrier()
; #define PG8_SCHED __builtin_amdgcn_sched_barrier(0)
; template <class Epi, class Sched>
; __device__ __forceinline__ void gemm_phase(LAS unsigned char* lds, const Gemm g, const Sched& S, const Epi& E) {
;     ...
;             PG8_LDB(B0, 0, 0); PG8_SCHED; PG8_LDA(At, 0, 0); PG8_STAGE(PG8_SA(1, 1), a1 + hstepA, voffA);
;             PG8_WAIT_L(8); PG8_BAR; PG8_WAIT_L(0); PG8_MMA(0, 0, At, B0); PG8_BAR; PG8_SCHED;
;             PG8_LDB(B1, 0, 1); PG8_STAGE(PG8_SB(0, 0), b2, voffB);
;             PG8_BAR; PG8_WAIT_L(0); PG8_MMA(0, 1, At, B1); PG8_BAR;
;             PG8_LDA(At, 0, 1); PG8_STAGE(PG8_SA(0, 0), a2, voffA);
;             PG8_BAR; PG8_WAIT_L(0); PG8_MMA(1, 0, At, B0); PG8_BAR; PG8_SCHED;
;             PG8_STAGE(PG8_SB(0, 1), b2 + hstepB, voffB);
;             PG8_WAIT_V(6); PG8_BAR; PG8_MMA(1, 1, At, B1); PG8_BAR;
;             PG8_LDB(B0, 1, 0); PG8_SCHED; PG8_LDA(At, 1, 0); PG8_STAGE(PG8_SA(0, 1), a2 + hstepA, voffA);
;             PG8_WAIT_L(8); PG8_BAR; PG8_WAIT_L(0); PG8_MMA(0, 0, At, B0); PG8_BAR; PG8_SCHED;
.LBB0_197:
	s_add_u32 s54, s52, 0xfff80080
	s_addc_u32 s55, s53, -1
	s_add_i32 s67, 0, 0x10000
	v_add_u32_e32 v146, s67, v139
	ds_read_b128 v[170:173], v146
	ds_read_b128 v[174:177], v146 offset:1024
	ds_read_b128 v[178:181], v146 offset:2048
	ds_read_b128 v[182:185], v146 offset:3072
	s_cmp_eq_u32 s66, 28
	s_cselect_b32 s57, s37, s55
	s_cselect_b32 s56, s51, s54
	s_cselect_b32 s55, s1, vcc_hi
	s_cselect_b32 s54, s93, vcc_lo
	v_lshl_add_u64 v[146:147], s[52:53], 0, v[142:143]
	s_add_i32 m0, s26, 0xc000
	ds_read_b128 v[186:189], v150
	ds_read_b128 v[190:193], v150 offset:1024
	ds_read_b128 v[194:197], v150 offset:2048
	ds_read_b128 v[210:213], v150 offset:3072
	ds_read_b128 v[214:217], v150 offset:4096
	ds_read_b128 v[218:221], v150 offset:5120
	ds_read_b128 v[222:225], v150 offset:6144
	ds_read_b128 v[226:229], v150 offset:7168
	global_load_lds_dwordx4 v[146:147], off
	v_lshl_add_u64 v[146:147], s[52:53], 0, v[144:145]
	s_add_i32 m0, s26, 0xe000
	s_nop 0
	global_load_lds_dwordx4 v[146:147], off
	s_waitcnt lgkmcnt(8)
	s_barrier
	s_waitcnt lgkmcnt(0)
	v_mfma_f32_16x16x32_bf16 v[126:129], v[170:173], v[186:189], v[126:129]
	v_mfma_f32_16x16x32_bf16 v[122:125], v[178:181], v[186:189], v[122:125]
	v_mfma_f32_16x16x32_bf16 v[110:113], v[170:173], v[194:197], v[110:113]
	v_mfma_f32_16x16x32_bf16 v[106:109], v[178:181], v[194:197], v[106:109]
	v_mfma_f32_16x16x32_bf16 v[94:97], v[170:173], v[214:217], v[94:97]
	v_mfma_f32_16x16x32_bf16 v[90:93], v[178:181], v[214:217], v[90:93]
	v_mfma_f32_16x16x32_bf16 v[78:81], v[170:173], v[222:225], v[78:81]
	v_mfma_f32_16x16x32_bf16 v[74:77], v[178:181], v[222:225], v[74:77]
	v_mfma_f32_16x16x32_bf16 v[126:129], v[174:177], v[190:193], v[126:129]
	v_mfma_f32_16x16x32_bf16 v[122:125], v[182:185], v[190:193], v[122:125]
	v_mfma_f32_16x16x32_bf16 v[110:113], v[174:177], v[210:213], v[110:113]
	v_mfma_f32_16x16x32_bf16 v[106:109], v[182:185], v[210:213], v[106:109]
	v_mfma_f32_16x16x32_bf16 v[94:97], v[174:177], v[218:221], v[94:97]
	v_mfma_f32_16x16x32_bf16 v[90:93], v[182:185], v[218:221], v[90:93]
	v_mfma_f32_16x16x32_bf16 v[78:81], v[174:177], v[226:229], v[78:81]
	v_mfma_f32_16x16x32_bf16 v[74:77], v[182:185], v[226:229], v[74:77]
	s_barrier
	s_add_i32 s23, 0, 0x14000
	v_add_u32_e32 v146, s23, v139
	s_add_i32 s67, s67, s25
	ds_read_b128 v[230:233], v146
	ds_read_b128 v[234:237], v146 offset:1024
	ds_read_b128 v[238:241], v146 offset:2048
	ds_read_b128 v[242:245], v146 offset:3072
	v_lshl_add_u64 v[146:147], s[54:55], 0, v[132:133]
	s_mov_b32 m0, s67
	v_lshl_add_u64 v[152:153], s[54:55], 0, v[136:137]
	global_load_lds_dwordx4 v[146:147], off
	s_add_i32 m0, s67, 0x2000
	s_nop 0
	global_load_lds_dwordx4 v[152:153], off
	s_barrier
	s_waitcnt lgkmcnt(0)
	v_mfma_f32_16x16x32_bf16 v[118:121], v[230:233], v[186:189], v[118:121]
	v_mfma_f32_16x16x32_bf16 v[114:117], v[238:241], v[186:189], v[114:117]
	v_mfma_f32_16x16x32_bf16 v[102:105], v[230:233], v[194:197], v[102:105]
	v_mfma_f32_16x16x32_bf16 v[98:101], v[238:241], v[194:197], v[98:101]
	v_mfma_f32_16x16x32_bf16 v[86:89], v[230:233], v[214:217], v[86:89]
	v_mfma_f32_16x16x32_bf16 v[82:85], v[238:241], v[214:217], v[82:85]
	v_mfma_f32_16x16x32_bf16 v[70:73], v[230:233], v[222:225], v[70:73]
	v_mfma_f32_16x16x32_bf16 v[66:69], v[238:241], v[222:225], v[66:69]
	v_mfma_f32_16x16x32_bf16 v[118:121], v[234:237], v[190:193], v[118:121]
	v_mfma_f32_16x16x32_bf16 v[114:117], v[242:245], v[190:193], v[114:117]
	v_mfma_f32_16x16x32_bf16 v[102:105], v[234:237], v[210:213], v[102:105]
	v_mfma_f32_16x16x32_bf16 v[98:101], v[242:245], v[210:213], v[98:101]
	v_mfma_f32_16x16x32_bf16 v[86:89], v[234:237], v[218:221], v[86:89]
	v_mfma_f32_16x16x32_bf16 v[82:85], v[242:245], v[218:221], v[82:85]
	v_mfma_f32_16x16x32_bf16 v[70:73], v[234:237], v[226:229], v[70:73]
	v_mfma_f32_16x16x32_bf16 v[66:69], v[242:245], v[226:229], v[66:69]
	s_mov_b32 m0, s26
	v_lshl_add_u64 v[198:199], s[56:57], 0, v[130:131]
	s_barrier
	ds_read_b128 v[186:189], v150 offset:16384
	ds_read_b128 v[190:193], v150 offset:17408
	ds_read_b128 v[194:197], v150 offset:18432
	ds_read_b128 v[210:213], v150 offset:19456
	ds_read_b128 v[214:217], v150 offset:20480
	ds_read_b128 v[218:221], v150 offset:21504
	ds_read_b128 v[222:225], v150 offset:22528
	ds_read_b128 v[226:229], v150 offset:23552
	global_load_lds_dwordx4 v[198:199], off
	v_lshl_add_u64 v[246:247], s[56:57], 0, v[134:135]
	s_mov_b32 m0, s27
	s_nop 0
	global_load_lds_dwordx4 v[246:247], off
	s_barrier
	s_waitcnt lgkmcnt(0)
	v_mfma_f32_16x16x32_bf16 v[62:65], v[170:173], v[186:189], v[62:65]
	v_mfma_f32_16x16x32_bf16 v[58:61], v[178:181], v[186:189], v[58:61]
	v_mfma_f32_16x16x32_bf16 v[46:49], v[170:173], v[194:197], v[46:49]
	v_mfma_f32_16x16x32_bf16 v[42:45], v[178:181], v[194:197], v[42:45]
	v_mfma_f32_16x16x32_bf16 v[30:33], v[170:173], v[214:217], v[30:33]
	v_mfma_f32_16x16x32_bf16 v[26:29], v[178:181], v[214:217], v[26:29]
	v_mfma_f32_16x16x32_bf16 v[14:17], v[170:173], v[222:225], v[14:17]
	v_mfma_f32_16x16x32_bf16 v[10:13], v[178:181], v[222:225], v[10:13]
	v_mfma_f32_16x16x32_bf16 v[62:65], v[174:177], v[190:193], v[62:65]
	v_mfma_f32_16x16x32_bf16 v[58:61], v[182:185], v[190:193], v[58:61]
	v_mfma_f32_16x16x32_bf16 v[46:49], v[174:177], v[210:213], v[46:49]
	v_mfma_f32_16x16x32_bf16 v[42:45], v[182:185], v[210:213], v[42:45]
	v_mfma_f32_16x16x32_bf16 v[30:33], v[174:177], v[218:221], v[30:33]
	v_mfma_f32_16x16x32_bf16 v[26:29], v[182:185], v[218:221], v[26:29]
	v_mfma_f32_16x16x32_bf16 v[14:17], v[174:177], v[226:229], v[14:17]
	v_mfma_f32_16x16x32_bf16 v[10:13], v[182:185], v[226:229], v[10:13]
	s_barrier
; #define PG8_STAGE(bufoff, gbase, voff) do { _Pragma("unroll") for (int _i = 0; _i < 2; ++_i) \
;         __builtin_amdgcn_global_load_lds((const unsigned*)((const char*)(gbase) + (voff)[_i]), (LAS unsigned*)(lds + (bufoff) + ldsw + _i * 8192), 16, 0, 0); } while (0)
; #define PG8_LDA(dst, b, h) do { _Pragma("unroll") for (int m = 0; m < 4; ++m) _Pragma("unroll") for (int k = 0; k < 2; ++k) dst[m][k] = *(const LAS bf16x8*)(lds + PG8_SA(b, h) + aoff + m * 2048 + k * 1024); } while (0)
; #define PG8_LDB(dst, b, h) do { _Pragma("unroll") for (int n = 0; n < 2; ++n) _Pragma("unroll") for (int k = 0; k < 2; ++k) dst[n][k] = *(const LAS bf16x8*)(lds + PG8_SB(b, h) + boff + n * 2048 + k * 1024); } while (0)
; #define PG8_MMA(ai, bj, At, Bt) do { __builtin_amdgcn_s_setprio(1); _Pragma("unroll") for (int m = 0; m < 4; ++m) _Pragma("unroll") for (int n = 0; n < 2; ++n) _Pragma("unroll") for (int k = 0; k < 2; ++k) \
;         acc[ai][bj][m][n] = __builtin_amdgcn_mfma_f32_16x16x32_bf16(Bt[n][k], At[m][k], acc[ai][bj][m][n], 0, 0, 0); __builtin_amdgcn_s_setprio(0); } while (0)
; #define PG8_WAIT_V(n) asm volatile("s_waitcnt vmcnt(" #n ")" ::: "memory")
; #define PG8_WAIT_L(n) asm volatile("s_waitcnt lgkmcnt(" #n ")" ::: "memory")
; #define PG8_BAR __builtin_amdgcn_s_barrier()
; #define PG8_SCHED __builtin_amdgcn_sched_barrier(0)
; template <class Epi, class Sched>
; __device__ __forceinline__ void gemm_phase(LAS unsigned char* lds, const Gemm g, const Sched& S, const Epi& E) {
;     ...
;             PG8_WAIT_V(6); PG8_BAR; PG8_MMA(1, 1, At, B1); PG8_BAR;
;             PG8_LDB(B0, 1, 0); PG8_SCHED; PG8_LDA(At, 1, 0); PG8_STAGE(PG8_SA(0, 1), a2 + hstepA, voffA);
;             PG8_WAIT_L(8); PG8_BAR; PG8_WAIT_L(0); PG8_MMA(0, 0, At, B0); PG8_BAR; PG8_SCHED;
;             PG8_LDB(B1, 1, 1); PG8_STAGE(PG8_SB(1, 0), b3, voffB);
;             PG8_BAR; PG8_WAIT_L(0); PG8_MMA(0, 1, At, B1); PG8_BAR;
;             PG8_LDA(At, 1, 1); PG8_STAGE(PG8_SA(1, 0), a3, voffA);
	s_add_u32 s84, s54, 0x80000
	s_addc_u32 s85, s55, 0
	s_add_i32 s23, s23, s25
	v_lshl_add_u64 v[170:171], s[84:85], 0, v[132:133]
	s_mov_b32 m0, s23
	s_nop 0
	global_load_lds_dwordx4 v[170:171], off
	v_lshl_add_u64 v[170:171], s[84:85], 0, v[136:137]
	s_add_i32 m0, s23, 0x2000
	s_nop 0
	global_load_lds_dwordx4 v[170:171], off
	s_waitcnt vmcnt(6)
	s_barrier
	v_mfma_f32_16x16x32_bf16 v[54:57], v[230:233], v[186:189], v[54:57]
	v_mfma_f32_16x16x32_bf16 v[50:53], v[238:241], v[186:189], v[50:53]
	v_mfma_f32_16x16x32_bf16 v[38:41], v[230:233], v[194:197], v[38:41]
	v_mfma_f32_16x16x32_bf16 v[34:37], v[238:241], v[194:197], v[34:37]
	v_mfma_f32_16x16x32_bf16 v[22:25], v[230:233], v[214:217], v[22:25]
	v_mfma_f32_16x16x32_bf16 v[18:21], v[238:241], v[214:217], v[18:21]
	v_mfma_f32_16x16x32_bf16 v[6:9], v[230:233], v[222:225], v[6:9]
	v_mfma_f32_16x16x32_bf16 v[2:5], v[238:241], v[222:225], v[2:5]
	v_mfma_f32_16x16x32_bf16 v[54:57], v[234:237], v[190:193], v[54:57]
	v_mfma_f32_16x16x32_bf16 v[50:53], v[242:245], v[190:193], v[50:53]
	v_mfma_f32_16x16x32_bf16 v[38:41], v[234:237], v[210:213], v[38:41]
	v_mfma_f32_16x16x32_bf16 v[34:37], v[242:245], v[210:213], v[34:37]
	v_mfma_f32_16x16x32_bf16 v[22:25], v[234:237], v[218:221], v[22:25]
	v_mfma_f32_16x16x32_bf16 v[18:21], v[242:245], v[218:221], v[18:21]
	v_mfma_f32_16x16x32_bf16 v[6:9], v[234:237], v[226:229], v[6:9]
	v_mfma_f32_16x16x32_bf16 v[2:5], v[242:245], v[226:229], v[2:5]
	s_add_i32 s23, 0, 0x18000
	v_add_u32_e32 v151, s23, v139
	s_barrier
	ds_read_b128 v[170:173], v151
	ds_read_b128 v[174:177], v151 offset:1024
	ds_read_b128 v[178:181], v151 offset:2048
	ds_read_b128 v[182:185], v151 offset:3072
	s_add_u32 s56, s56, 0x80000
	s_addc_u32 s57, s57, 0
	s_mov_b32 m0, s28
	v_lshl_add_u64 v[230:231], s[56:57], 0, v[130:131]
	ds_read_b128 v[186:189], v150 offset:32768
	ds_read_b128 v[190:193], v150 offset:33792
	ds_read_b128 v[194:197], v150 offset:34816
	ds_read_b128 v[210:213], v150 offset:35840
	ds_read_b128 v[214:217], v150 offset:36864
	ds_read_b128 v[218:221], v150 offset:37888
	ds_read_b128 v[222:225], v150 offset:38912
	ds_read_b128 v[226:229], v150 offset:39936
	global_load_lds_dwordx4 v[230:231], off
	v_lshl_add_u64 v[230:231], s[56:57], 0, v[134:135]
	s_mov_b32 m0, s29
	s_nop 0
	global_load_lds_dwordx4 v[230:231], off
	s_waitcnt lgkmcnt(8)
	s_barrier
	s_waitcnt lgkmcnt(0)
	v_mfma_f32_16x16x32_bf16 v[126:129], v[170:173], v[186:189], v[126:129]
	v_mfma_f32_16x16x32_bf16 v[122:125], v[178:181], v[186:189], v[122:125]
	v_mfma_f32_16x16x32_bf16 v[110:113], v[170:173], v[194:197], v[110:113]
	v_mfma_f32_16x16x32_bf16 v[106:109], v[178:181], v[194:197], v[106:109]
	v_mfma_f32_16x16x32_bf16 v[94:97], v[170:173], v[214:217], v[94:97]
	v_mfma_f32_16x16x32_bf16 v[90:93], v[178:181], v[214:217], v[90:93]
	v_mfma_f32_16x16x32_bf16 v[78:81], v[170:173], v[222:225], v[78:81]
	v_mfma_f32_16x16x32_bf16 v[74:77], v[178:181], v[222:225], v[74:77]
	v_mfma_f32_16x16x32_bf16 v[126:129], v[174:177], v[190:193], v[126:129]
	v_mfma_f32_16x16x32_bf16 v[122:125], v[182:185], v[190:193], v[122:125]
	v_mfma_f32_16x16x32_bf16 v[110:113], v[174:177], v[210:213], v[110:113]
	v_mfma_f32_16x16x32_bf16 v[106:109], v[182:185], v[210:213], v[106:109]
	v_mfma_f32_16x16x32_bf16 v[94:97], v[174:177], v[218:221], v[94:97]
	v_mfma_f32_16x16x32_bf16 v[90:93], v[182:185], v[218:221], v[90:93]
	v_mfma_f32_16x16x32_bf16 v[78:81], v[174:177], v[226:229], v[78:81]
	v_mfma_f32_16x16x32_bf16 v[74:77], v[182:185], v[226:229], v[74:77]
	s_barrier
	s_add_i32 s56, 0, 0x1c000
	s_add_i32 s23, s23, s25
	v_add_u32_e32 v151, s56, v139
	v_lshl_add_u64 v[146:147], v[146:147], 0, s[10:11]
	s_mov_b32 m0, s23
	ds_read_b128 v[230:233], v151
	ds_read_b128 v[234:237], v151 offset:1024
	ds_read_b128 v[238:241], v151 offset:2048
	ds_read_b128 v[242:245], v151 offset:3072
	global_load_lds_dwordx4 v[146:147], off
	v_lshl_add_u64 v[146:147], v[152:153], 0, s[10:11]
	s_add_i32 m0, s23, 0x2000
	s_nop 0
	global_load_lds_dwordx4 v[146:147], off
	s_barrier
; #define PG8_STAGE(bufoff, gbase, voff) do { _Pragma("unroll") for (int _i = 0; _i < 2; ++_i) \
;         __builtin_amdgcn_global_load_lds((const unsigned*)((const char*)(gbase) + (voff)[_i]), (LAS unsigned*)(lds + (bufoff) + ldsw + _i * 8192), 16, 0, 0); } while (0)
; #define PG8_MMA(ai, bj, At, Bt) do { __builtin_amdgcn_s_setprio(1); _Pragma("unroll") for (int m = 0; m < 4; ++m) _Pragma("unroll") for (int n = 0; n < 2; ++n) _Pragma("unroll") for (int k = 0; k < 2; ++k) \
;         acc[ai][bj][m][n] = __builtin_amdgcn_mfma_f32_16x16x32_bf16(Bt[n][k], At[m][k], acc[ai][bj][m][n], 0, 0, 0); __builtin_amdgcn_s_setprio(0); } while (0)
; #define PG8_WAIT_V(n) asm volatile("s_waitcnt vmcnt(" #n ")" ::: "memory")
; #define PG8_WAIT_L(n) asm volatile("s_waitcnt lgkmcnt(" #n ")" ::: "memory")
; #define PG8_BAR __builtin_amdgcn_s_barrier()
; #define PG8_SCHED __builtin_amdgcn_sched_barrier(0)
;     __device__ __forceinline__ void operator()(const f32x4 (&acc)[2][2][4][2], const Unit& u, int ui, const LAS float* rtab, int wr, int wc, int fr, int fq) const {
;         const int row0 = u.pm * BM + wr * 64 + fr; const int colt = u.pn * BM; const int t = colt >> shift; const int lc0 = (colt & ((1 << shift) - 1)) + wc * 32 + 8 * fq;
;         bf16_t* base = (t == 0) ? Q : ((t == 1) ? K : V);
; template <class Epi, class Sched>
; __device__ __forceinline__ void gemm_phase(LAS unsigned char* lds, const Gemm g, const Sched& S, const Epi& E) {
;     ...
;             PG8_BAR; PG8_WAIT_L(0); PG8_MMA(1, 0, At, B0); PG8_BAR; PG8_SCHED;
;             PG8_STAGE(PG8_SB(1, 1), b3 + hstepB, voffB);
;             PG8_WAIT_V(6); PG8_BAR; PG8_MMA(1, 1, At, B1); PG8_BAR;
	s_waitcnt lgkmcnt(0)
	v_mfma_f32_16x16x32_bf16 v[118:121], v[230:233], v[186:189], v[118:121]
	v_mfma_f32_16x16x32_bf16 v[114:117], v[238:241], v[186:189], v[114:117]
	v_mfma_f32_16x16x32_bf16 v[102:105], v[230:233], v[194:197], v[102:105]
	v_mfma_f32_16x16x32_bf16 v[98:101], v[238:241], v[194:197], v[98:101]
	v_mfma_f32_16x16x32_bf16 v[86:89], v[230:233], v[214:217], v[86:89]
	v_mfma_f32_16x16x32_bf16 v[82:85], v[238:241], v[214:217], v[82:85]
	v_mfma_f32_16x16x32_bf16 v[70:73], v[230:233], v[222:225], v[70:73]
	v_mfma_f32_16x16x32_bf16 v[66:69], v[238:241], v[222:225], v[66:69]
	v_mfma_f32_16x16x32_bf16 v[118:121], v[234:237], v[190:193], v[118:121]
	v_mfma_f32_16x16x32_bf16 v[114:117], v[242:245], v[190:193], v[114:117]
	v_mfma_f32_16x16x32_bf16 v[102:105], v[234:237], v[210:213], v[102:105]
	v_mfma_f32_16x16x32_bf16 v[98:101], v[242:245], v[210:213], v[98:101]
	v_mfma_f32_16x16x32_bf16 v[86:89], v[234:237], v[218:221], v[86:89]
	v_mfma_f32_16x16x32_bf16 v[82:85], v[242:245], v[218:221], v[82:85]
	v_mfma_f32_16x16x32_bf16 v[70:73], v[234:237], v[226:229], v[70:73]
	v_mfma_f32_16x16x32_bf16 v[66:69], v[242:245], v[226:229], v[66:69]
	s_mov_b32 m0, s35
	v_lshl_add_u64 v[146:147], v[198:199], 0, s[10:11]
	s_barrier
	ds_read_b128 v[186:189], v150 offset:49152
	ds_read_b128 v[190:193], v150 offset:50176
	ds_read_b128 v[194:197], v150 offset:51200
	ds_read_b128 v[210:213], v150 offset:52224
	ds_read_b128 v[214:217], v150 offset:53248
	ds_read_b128 v[218:221], v150 offset:54272
	ds_read_b128 v[222:225], v150 offset:55296
	ds_read_b128 v[226:229], v150 offset:56320
	global_load_lds_dwordx4 v[146:147], off
	v_lshl_add_u64 v[146:147], v[246:247], 0, s[10:11]
	s_mov_b32 m0, s45
	s_nop 0
	global_load_lds_dwordx4 v[146:147], off
	s_barrier
	s_waitcnt lgkmcnt(0)
	v_mfma_f32_16x16x32_bf16 v[62:65], v[170:173], v[186:189], v[62:65]
	v_mfma_f32_16x16x32_bf16 v[58:61], v[178:181], v[186:189], v[58:61]
	v_mfma_f32_16x16x32_bf16 v[46:49], v[170:173], v[194:197], v[46:49]
	v_mfma_f32_16x16x32_bf16 v[42:45], v[178:181], v[194:197], v[42:45]
	v_mfma_f32_16x16x32_bf16 v[30:33], v[170:173], v[214:217], v[30:33]
	v_mfma_f32_16x16x32_bf16 v[26:29], v[178:181], v[214:217], v[26:29]
	v_mfma_f32_16x16x32_bf16 v[14:17], v[170:173], v[222:225], v[14:17]
	v_mfma_f32_16x16x32_bf16 v[10:13], v[178:181], v[222:225], v[10:13]
	v_mfma_f32_16x16x32_bf16 v[62:65], v[174:177], v[190:193], v[62:65]
	v_mfma_f32_16x16x32_bf16 v[58:61], v[182:185], v[190:193], v[58:61]
	v_mfma_f32_16x16x32_bf16 v[46:49], v[174:177], v[210:213], v[46:49]
	v_mfma_f32_16x16x32_bf16 v[42:45], v[182:185], v[210:213], v[42:45]
	v_mfma_f32_16x16x32_bf16 v[30:33], v[174:177], v[218:221], v[30:33]
	v_mfma_f32_16x16x32_bf16 v[26:29], v[182:185], v[218:221], v[26:29]
	v_mfma_f32_16x16x32_bf16 v[14:17], v[174:177], v[226:229], v[14:17]
	v_mfma_f32_16x16x32_bf16 v[10:13], v[182:185], v[226:229], v[10:13]
	s_barrier
	s_add_u32 s54, s54, 0x80080
	s_addc_u32 s55, s55, 0
	s_add_i32 s23, s56, s25
	v_lshl_add_u64 v[146:147], s[54:55], 0, v[132:133]
	s_mov_b32 m0, s23
	s_nop 0
	global_load_lds_dwordx4 v[146:147], off
	v_lshl_add_u64 v[146:147], s[54:55], 0, v[136:137]
	s_add_i32 m0, s23, 0x2000
	s_nop 0
	global_load_lds_dwordx4 v[146:147], off
	s_waitcnt vmcnt(6)
	s_barrier
	v_mfma_f32_16x16x32_bf16 v[54:57], v[230:233], v[186:189], v[54:57]
	v_mfma_f32_16x16x32_bf16 v[50:53], v[238:241], v[186:189], v[50:53]
	v_mfma_f32_16x16x32_bf16 v[38:41], v[230:233], v[194:197], v[38:41]
	v_mfma_f32_16x16x32_bf16 v[34:37], v[238:241], v[194:197], v[34:37]
	v_mfma_f32_16x16x32_bf16 v[22:25], v[230:233], v[214:217], v[22:25]
	v_mfma_f32_16x16x32_bf16 v[18:21], v[238:241], v[214:217], v[18:21]
	v_mfma_f32_16x16x32_bf16 v[6:9], v[230:233], v[222:225], v[6:9]
	v_mfma_f32_16x16x32_bf16 v[2:5], v[238:241], v[222:225], v[2:5]
	v_mfma_f32_16x16x32_bf16 v[54:57], v[234:237], v[190:193], v[54:57]
	v_mfma_f32_16x16x32_bf16 v[50:53], v[242:245], v[190:193], v[50:53]
	v_mfma_f32_16x16x32_bf16 v[38:41], v[234:237], v[210:213], v[38:41]
	v_mfma_f32_16x16x32_bf16 v[34:37], v[242:245], v[210:213], v[34:37]
	v_mfma_f32_16x16x32_bf16 v[22:25], v[234:237], v[218:221], v[22:25]
	v_mfma_f32_16x16x32_bf16 v[18:21], v[242:245], v[218:221], v[18:21]
	v_mfma_f32_16x16x32_bf16 v[6:9], v[234:237], v[226:229], v[6:9]
	v_mfma_f32_16x16x32_bf16 v[2:5], v[242:245], v[226:229], v[2:5]
	s_add_i32 s66, s66, 2
	s_add_u32 s52, s52, 0x100
	s_addc_u32 s53, s53, 0
	s_add_u32 vcc_lo, vcc_lo, 0x100
	s_addc_u32 vcc_hi, vcc_hi, 0
	s_cmp_gt_u32 s66, 29
	s_barrier
	s_cbranch_scc0 .LBB0_197
	s_lshl_b32 s37, s50, 8
	s_ashr_i32 s1, s37, s31
	s_cmp_lt_i32 s1, 1
	s_cbranch_scc1 .LBB0_202
	s_cmp_eq_u32 s1, 1
	s_mov_b64 s[52:53], -1
	s_cbranch_scc0 .LBB0_201
	s_mov_b64 s[52:53], 0

; __device__ __forceinline__ void xcd_barrier(const XcdBarrier& b) {
;     asm volatile("s_waitcnt vmcnt(0)" ::: "memory");
;     __syncthreads();
;     if (threadIdx.x == 0) {
;         unsigned* bar = b.bar;
;         __builtin_amdgcn_s_waitcnt(0);
;         unsigned nloc = b.st[0], nx = b.st[1];
;         if (nloc == 0u) { xcd_barrier_complete(bar, b.x, nloc, nx); b.st[0] = nloc; b.st[1] = nx; }
.LBB0_273:
	s_waitcnt vmcnt(0)
	s_barrier
	s_mov_b64 s[0:1], exec
	v_readlane_b32 s12, v253, 8
	v_readlane_b32 s13, v253, 9
	s_and_b64 s[12:13], s[0:1], s[12:13]
	s_mov_b64 exec, s[12:13]
	s_cbranch_execz .LBB0_325
	v_readlane_b32 s12, v252, 20
	s_waitcnt vmcnt(0) expcnt(0) lgkmcnt(0)
	s_nop 0
	v_mov_b32_e32 v1, s12
	ds_read_b32 v3, v1
	v_readlane_b32 s12, v252, 21
	s_waitcnt lgkmcnt(0)
	v_cmp_ne_u32_e32 vcc, 0, v3
	v_mov_b32_e32 v1, s12
	ds_read_b32 v2, v1
	s_cbranch_vccnz .LBB0_289
	s_mov_b32 s12, 1
	s_branch .LBB0_277

; #define PG8_STAGE(bufoff, gbase, voff) do { _Pragma("unroll") for (int _i = 0; _i < 2; ++_i) \
;         __builtin_amdgcn_global_load_lds((const unsigned*)((const char*)(gbase) + (voff)[_i]), (LAS unsigned*)(lds + (bufoff) + ldsw + _i * 8192), 16, 0, 0); } while (0)
; #define PG8_LDA(dst, b, h) do { _Pragma("unroll") for (int m = 0; m < 4; ++m) _Pragma("unroll") for (int k = 0; k < 2; ++k) dst[m][k] = *(const LAS bf16x8*)(lds + PG8_SA(b, h) + aoff + m * 2048 + k * 1024); } while (0)
; #define PG8_LDB(dst, b, h) do { _Pragma("unroll") for (int n = 0; n < 2; ++n) _Pragma("unroll") for (int k = 0; k < 2; ++k) dst[n][k] = *(const LAS bf16x8*)(lds + PG8_SB(b, h) + boff + n * 2048 + k * 1024); } while (0)
; #define PG8_MMA(ai, bj, At, Bt) do { __builtin_amdgcn_s_setprio(1); _Pragma("unroll") for (int m = 0; m < 4; ++m) _Pragma("unroll") for (int n = 0; n < 2; ++n) _Pragma("unroll") for (int k = 0; k < 2; ++k) \
;         acc[ai][bj][m][n] = __builtin_amdgcn_mfma_f32_16x16x32_bf16(Bt[n][k], At[m][k], acc[ai][bj][m][n], 0, 0, 0); __builtin_amdgcn_s_setprio(0); } while (0)
; #define PG8_WAIT_V(n) asm volatile("s_waitcnt vmcnt(" #n ")" ::: "memory")
; #define PG8_WAIT_L(n) asm volatile("s_waitcnt lgkmcnt(" #n ")" ::: "memory")
; #define PG8_BAR __builtin_amdgcn_s_barrier()
; #define PG8_SCHED __builtin_amdgcn_sched_barrier(0)
; template <class Epi, class Sched>
; __device__ __forceinline__ void gemm_phase(LAS unsigned char* lds, const Gemm g, const Sched& S, const Epi& E) {
;     ...
;             PG8_LDB(B0, 0, 0); PG8_SCHED; PG8_LDA(At, 0, 0); PG8_STAGE(PG8_SA(1, 1), a1 + hstepA, voffA);
;             PG8_WAIT_L(8); PG8_BAR; PG8_WAIT_L(0); PG8_MMA(0, 0, At, B0); PG8_BAR; PG8_SCHED;
;             PG8_LDB(B1, 0, 1); PG8_STAGE(PG8_SB(0, 0), b2, voffB);
;             PG8_BAR; PG8_WAIT_L(0); PG8_MMA(0, 1, At, B1); PG8_BAR;
;             PG8_LDA(At, 0, 1); PG8_STAGE(PG8_SA(0, 0), a2, voffA);
;             PG8_BAR; PG8_WAIT_L(0); PG8_MMA(1, 0, At, B0); PG8_BAR; PG8_SCHED;
;             PG8_STAGE(PG8_SB(0, 1), b2 + hstepB, voffB);
;             PG8_WAIT_V(6); PG8_BAR; PG8_MMA(1, 1, At, B1); PG8_BAR;
.LBB0_580:
	s_add_u32 s42, s40, 0x100
	s_addc_u32 s43, s41, 0
	s_add_i32 s24, 0, 0x10000
	v_add_u32_e32 v162, s24, v144
	ds_read_b128 v[146:149], v162
	ds_read_b128 v[150:153], v162 offset:1024
	ds_read_b128 v[170:173], v162 offset:2048
	ds_read_b128 v[174:177], v162 offset:3072
	s_cmp_eq_u32 s58, 4
	s_cselect_b32 s47, s1, s43
	s_cselect_b32 s46, s0, s42
	s_cselect_b32 s45, s54, s57
	s_cselect_b32 s44, s55, s56
	v_lshl_add_u64 v[198:199], s[40:41], 0, v[140:141]
	s_add_i32 m0, s28, 0xc000
	ds_read_b128 v[178:181], v145
	ds_read_b128 v[182:185], v145 offset:1024
	ds_read_b128 v[186:189], v145 offset:2048
	ds_read_b128 v[190:193], v145 offset:3072
	ds_read_b128 v[194:197], v145 offset:4096
	ds_read_b128 v[210:213], v145 offset:5120
	ds_read_b128 v[214:217], v145 offset:6144
	ds_read_b128 v[218:221], v145 offset:7168
	global_load_lds_dwordx4 v[198:199], off
	v_lshl_add_u64 v[198:199], s[40:41], 0, v[142:143]
	s_add_i32 m0, s28, 0xe000
	s_nop 0
	global_load_lds_dwordx4 v[198:199], off
	s_waitcnt lgkmcnt(8)
	s_barrier
	s_waitcnt lgkmcnt(0)
	v_mfma_f32_16x16x32_bf16 v[126:129], v[146:149], v[178:181], v[126:129]
	v_mfma_f32_16x16x32_bf16 v[122:125], v[170:173], v[178:181], v[122:125]
	v_mfma_f32_16x16x32_bf16 v[118:121], v[146:149], v[186:189], v[118:121]
	v_mfma_f32_16x16x32_bf16 v[114:117], v[170:173], v[186:189], v[114:117]
	v_mfma_f32_16x16x32_bf16 v[106:109], v[146:149], v[194:197], v[106:109]
	v_mfma_f32_16x16x32_bf16 v[98:101], v[170:173], v[194:197], v[98:101]
	v_mfma_f32_16x16x32_bf16 v[90:93], v[146:149], v[214:217], v[90:93]
	v_mfma_f32_16x16x32_bf16 v[82:85], v[170:173], v[214:217], v[82:85]
	v_mfma_f32_16x16x32_bf16 v[126:129], v[150:153], v[182:185], v[126:129]
	v_mfma_f32_16x16x32_bf16 v[122:125], v[174:177], v[182:185], v[122:125]
	v_mfma_f32_16x16x32_bf16 v[118:121], v[150:153], v[190:193], v[118:121]
	v_mfma_f32_16x16x32_bf16 v[114:117], v[174:177], v[190:193], v[114:117]
	v_mfma_f32_16x16x32_bf16 v[106:109], v[150:153], v[210:213], v[106:109]
	v_mfma_f32_16x16x32_bf16 v[98:101], v[174:177], v[210:213], v[98:101]
	v_mfma_f32_16x16x32_bf16 v[90:93], v[150:153], v[218:221], v[90:93]
	v_mfma_f32_16x16x32_bf16 v[82:85], v[174:177], v[218:221], v[82:85]
	s_barrier
	s_add_i32 s25, 0, 0x14000
	s_add_i32 s23, s24, s26
	v_add_u32_e32 v162, s25, v144
	v_lshl_add_u64 v[198:199], s[44:45], 0, v[134:135]
	s_mov_b32 m0, s23
	ds_read_b128 v[222:225], v162
	ds_read_b128 v[226:229], v162 offset:1024
	ds_read_b128 v[230:233], v162 offset:2048
	ds_read_b128 v[234:237], v162 offset:3072
	global_load_lds_dwordx4 v[198:199], off
	v_lshl_add_u64 v[238:239], s[44:45], 0, v[130:131]
	s_add_i32 m0, s23, 0x2000
	s_nop 0
	global_load_lds_dwordx4 v[238:239], off
	s_barrier
	s_waitcnt lgkmcnt(0)
	v_mfma_f32_16x16x32_bf16 v[110:113], v[222:225], v[178:181], v[110:113]
	v_mfma_f32_16x16x32_bf16 v[102:105], v[230:233], v[178:181], v[102:105]
	v_mfma_f32_16x16x32_bf16 v[94:97], v[222:225], v[186:189], v[94:97]
	v_mfma_f32_16x16x32_bf16 v[86:89], v[230:233], v[186:189], v[86:89]
	v_mfma_f32_16x16x32_bf16 v[78:81], v[222:225], v[194:197], v[78:81]
	v_mfma_f32_16x16x32_bf16 v[74:77], v[230:233], v[194:197], v[74:77]
	v_mfma_f32_16x16x32_bf16 v[70:73], v[222:225], v[214:217], v[70:73]
	v_mfma_f32_16x16x32_bf16 v[66:69], v[230:233], v[214:217], v[66:69]
	v_mfma_f32_16x16x32_bf16 v[110:113], v[226:229], v[182:185], v[110:113]
	v_mfma_f32_16x16x32_bf16 v[102:105], v[234:237], v[182:185], v[102:105]
	v_mfma_f32_16x16x32_bf16 v[94:97], v[226:229], v[190:193], v[94:97]
	v_mfma_f32_16x16x32_bf16 v[86:89], v[234:237], v[190:193], v[86:89]
	v_mfma_f32_16x16x32_bf16 v[78:81], v[226:229], v[210:213], v[78:81]
	v_mfma_f32_16x16x32_bf16 v[74:77], v[234:237], v[210:213], v[74:77]
	v_mfma_f32_16x16x32_bf16 v[70:73], v[226:229], v[218:221], v[70:73]
	v_mfma_f32_16x16x32_bf16 v[66:69], v[234:237], v[218:221], v[66:69]
	s_mov_b32 m0, s28
	v_lshl_add_u64 v[240:241], s[46:47], 0, v[136:137]
	s_barrier
	ds_read_b128 v[178:181], v145 offset:16384
	ds_read_b128 v[182:185], v145 offset:17408
	ds_read_b128 v[186:189], v145 offset:18432
	ds_read_b128 v[190:193], v145 offset:19456
	ds_read_b128 v[194:197], v145 offset:20480
	ds_read_b128 v[210:213], v145 offset:21504
	ds_read_b128 v[214:217], v145 offset:22528
	ds_read_b128 v[218:221], v145 offset:23552
	global_load_lds_dwordx4 v[240:241], off
	v_lshl_add_u64 v[242:243], s[46:47], 0, v[132:133]
	s_mov_b32 m0, s29
	s_nop 0
	global_load_lds_dwordx4 v[242:243], off
	s_barrier
	s_waitcnt lgkmcnt(0)
	v_mfma_f32_16x16x32_bf16 v[62:65], v[146:149], v[178:181], v[62:65]
	v_mfma_f32_16x16x32_bf16 v[58:61], v[170:173], v[178:181], v[58:61]
	v_mfma_f32_16x16x32_bf16 v[54:57], v[146:149], v[186:189], v[54:57]
	v_mfma_f32_16x16x32_bf16 v[50:53], v[170:173], v[186:189], v[50:53]
	v_mfma_f32_16x16x32_bf16 v[38:41], v[146:149], v[194:197], v[38:41]
	v_mfma_f32_16x16x32_bf16 v[34:37], v[170:173], v[194:197], v[34:37]
	v_mfma_f32_16x16x32_bf16 v[22:25], v[146:149], v[214:217], v[22:25]
	v_mfma_f32_16x16x32_bf16 v[18:21], v[170:173], v[214:217], v[18:21]
	v_mfma_f32_16x16x32_bf16 v[62:65], v[150:153], v[182:185], v[62:65]
	v_mfma_f32_16x16x32_bf16 v[58:61], v[174:177], v[182:185], v[58:61]
	v_mfma_f32_16x16x32_bf16 v[54:57], v[150:153], v[190:193], v[54:57]
	v_mfma_f32_16x16x32_bf16 v[50:53], v[174:177], v[190:193], v[50:53]
	v_mfma_f32_16x16x32_bf16 v[38:41], v[150:153], v[210:213], v[38:41]
	v_mfma_f32_16x16x32_bf16 v[34:37], v[174:177], v[210:213], v[34:37]
	v_mfma_f32_16x16x32_bf16 v[22:25], v[150:153], v[218:221], v[22:25]
	v_mfma_f32_16x16x32_bf16 v[18:21], v[174:177], v[218:221], v[18:21]
	s_barrier
; #define PG8_STAGE(bufoff, gbase, voff) do { _Pragma("unroll") for (int _i = 0; _i < 2; ++_i) \
;         __builtin_amdgcn_global_load_lds((const unsigned*)((const char*)(gbase) + (voff)[_i]), (LAS unsigned*)(lds + (bufoff) + ldsw + _i * 8192), 16, 0, 0); } while (0)
; #define PG8_LDA(dst, b, h) do { _Pragma("unroll") for (int m = 0; m < 4; ++m) _Pragma("unroll") for (int k = 0; k < 2; ++k) dst[m][k] = *(const LAS bf16x8*)(lds + PG8_SA(b, h) + aoff + m * 2048 + k * 1024); } while (0)
; #define PG8_LDB(dst, b, h) do { _Pragma("unroll") for (int n = 0; n < 2; ++n) _Pragma("unroll") for (int k = 0; k < 2; ++k) dst[n][k] = *(const LAS bf16x8*)(lds + PG8_SB(b, h) + boff + n * 2048 + k * 1024); } while (0)
; #define PG8_MMA(ai, bj, At, Bt) do { __builtin_amdgcn_s_setprio(1); _Pragma("unroll") for (int m = 0; m < 4; ++m) _Pragma("unroll") for (int n = 0; n < 2; ++n) _Pragma("unroll") for (int k = 0; k < 2; ++k) \
;         acc[ai][bj][m][n] = __builtin_amdgcn_mfma_f32_16x16x32_bf16(Bt[n][k], At[m][k], acc[ai][bj][m][n], 0, 0, 0); __builtin_amdgcn_s_setprio(0); } while (0)
; #define PG8_WAIT_V(n) asm volatile("s_waitcnt vmcnt(" #n ")" ::: "memory")
; #define PG8_WAIT_L(n) asm volatile("s_waitcnt lgkmcnt(" #n ")" ::: "memory")
; #define PG8_BAR __builtin_amdgcn_s_barrier()
; #define PG8_SCHED __builtin_amdgcn_sched_barrier(0)
; template <class Epi, class Sched>
; __device__ __forceinline__ void gemm_phase(LAS unsigned char* lds, const Gemm g, const Sched& S, const Epi& E) {
;     ...
;             PG8_WAIT_V(6); PG8_BAR; PG8_MMA(1, 1, At, B1); PG8_BAR;
;             PG8_LDB(B0, 1, 0); PG8_SCHED; PG8_LDA(At, 1, 0); PG8_STAGE(PG8_SA(0, 1), a2 + hstepA, voffA);
;             PG8_WAIT_L(8); PG8_BAR; PG8_WAIT_L(0); PG8_MMA(0, 0, At, B0); PG8_BAR; PG8_SCHED;
;             PG8_LDB(B1, 1, 1); PG8_STAGE(PG8_SB(1, 0), b3, voffB);
;             PG8_BAR; PG8_WAIT_L(0); PG8_MMA(0, 1, At, B1); PG8_BAR;
;             PG8_LDA(At, 1, 1); PG8_STAGE(PG8_SA(1, 0), a3, voffA);
	s_add_u32 s40, s44, 0x20000
	s_addc_u32 s41, s45, 0
	s_add_i32 s23, s25, s26
	v_lshl_add_u64 v[146:147], s[40:41], 0, v[134:135]
	s_mov_b32 m0, s23
	s_nop 0
	global_load_lds_dwordx4 v[146:147], off
	v_lshl_add_u64 v[146:147], s[40:41], 0, v[130:131]
	s_add_i32 m0, s23, 0x2000
	s_nop 0
	global_load_lds_dwordx4 v[146:147], off
	s_waitcnt vmcnt(6)
	s_barrier
	v_mfma_f32_16x16x32_bf16 v[46:49], v[222:225], v[178:181], v[46:49]
	v_mfma_f32_16x16x32_bf16 v[42:45], v[230:233], v[178:181], v[42:45]
	v_mfma_f32_16x16x32_bf16 v[30:33], v[222:225], v[186:189], v[30:33]
	v_mfma_f32_16x16x32_bf16 v[26:29], v[230:233], v[186:189], v[26:29]
	v_mfma_f32_16x16x32_bf16 v[14:17], v[222:225], v[194:197], v[14:17]
	v_mfma_f32_16x16x32_bf16 v[10:13], v[230:233], v[194:197], v[10:13]
	v_mfma_f32_16x16x32_bf16 v[6:9], v[222:225], v[214:217], v[6:9]
	v_mfma_f32_16x16x32_bf16 v[2:5], v[230:233], v[214:217], v[2:5]
	v_mfma_f32_16x16x32_bf16 v[46:49], v[226:229], v[182:185], v[46:49]
	v_mfma_f32_16x16x32_bf16 v[42:45], v[234:237], v[182:185], v[42:45]
	v_mfma_f32_16x16x32_bf16 v[30:33], v[226:229], v[190:193], v[30:33]
	v_mfma_f32_16x16x32_bf16 v[26:29], v[234:237], v[190:193], v[26:29]
	v_mfma_f32_16x16x32_bf16 v[14:17], v[226:229], v[210:213], v[14:17]
	v_mfma_f32_16x16x32_bf16 v[10:13], v[234:237], v[210:213], v[10:13]
	v_mfma_f32_16x16x32_bf16 v[6:9], v[226:229], v[218:221], v[6:9]
	v_mfma_f32_16x16x32_bf16 v[2:5], v[234:237], v[218:221], v[2:5]
	s_add_i32 s27, 0, 0x18000
	v_add_u32_e32 v162, s27, v144
	s_barrier
	ds_read_b128 v[146:149], v162
	ds_read_b128 v[150:153], v162 offset:1024
	ds_read_b128 v[170:173], v162 offset:2048
	ds_read_b128 v[174:177], v162 offset:3072
	s_add_u32 s40, s46, 0x30000
	s_addc_u32 s41, s47, 0
	s_mov_b32 m0, s35
	v_lshl_add_u64 v[222:223], s[40:41], 0, v[136:137]
	ds_read_b128 v[178:181], v145 offset:32768
	ds_read_b128 v[182:185], v145 offset:33792
	ds_read_b128 v[186:189], v145 offset:34816
	ds_read_b128 v[190:193], v145 offset:35840
	ds_read_b128 v[194:197], v145 offset:36864
	ds_read_b128 v[210:213], v145 offset:37888
	ds_read_b128 v[214:217], v145 offset:38912
	ds_read_b128 v[218:221], v145 offset:39936
	global_load_lds_dwordx4 v[222:223], off
	v_lshl_add_u64 v[222:223], s[40:41], 0, v[132:133]
	s_mov_b32 m0, s48
	s_nop 0
	global_load_lds_dwordx4 v[222:223], off
	s_waitcnt lgkmcnt(8)
	s_barrier
	s_waitcnt lgkmcnt(0)
	v_mfma_f32_16x16x32_bf16 v[126:129], v[146:149], v[178:181], v[126:129]
	v_mfma_f32_16x16x32_bf16 v[122:125], v[170:173], v[178:181], v[122:125]
	v_mfma_f32_16x16x32_bf16 v[118:121], v[146:149], v[186:189], v[118:121]
	v_mfma_f32_16x16x32_bf16 v[114:117], v[170:173], v[186:189], v[114:117]
	v_mfma_f32_16x16x32_bf16 v[106:109], v[146:149], v[194:197], v[106:109]
	v_mfma_f32_16x16x32_bf16 v[98:101], v[170:173], v[194:197], v[98:101]
	v_mfma_f32_16x16x32_bf16 v[90:93], v[146:149], v[214:217], v[90:93]
	v_mfma_f32_16x16x32_bf16 v[82:85], v[170:173], v[214:217], v[82:85]
	v_mfma_f32_16x16x32_bf16 v[126:129], v[150:153], v[182:185], v[126:129]
	v_mfma_f32_16x16x32_bf16 v[122:125], v[174:177], v[182:185], v[122:125]
	v_mfma_f32_16x16x32_bf16 v[118:121], v[150:153], v[190:193], v[118:121]
	v_mfma_f32_16x16x32_bf16 v[114:117], v[174:177], v[190:193], v[114:117]
	v_mfma_f32_16x16x32_bf16 v[106:109], v[150:153], v[210:213], v[106:109]
	v_mfma_f32_16x16x32_bf16 v[98:101], v[174:177], v[210:213], v[98:101]
	v_mfma_f32_16x16x32_bf16 v[90:93], v[150:153], v[218:221], v[90:93]
	v_mfma_f32_16x16x32_bf16 v[82:85], v[174:177], v[218:221], v[82:85]
	s_barrier
	s_add_i32 s31, 0, 0x1c000
	s_add_i32 s23, s27, s26
	v_add_u32_e32 v162, s31, v144
	v_lshl_add_u64 v[198:199], v[198:199], 0, s[10:11]
	s_mov_b32 m0, s23
	ds_read_b128 v[222:225], v162
	ds_read_b128 v[226:229], v162 offset:1024
	ds_read_b128 v[230:233], v162 offset:2048
	ds_read_b128 v[234:237], v162 offset:3072
	global_load_lds_dwordx4 v[198:199], off
	v_lshl_add_u64 v[198:199], v[238:239], 0, s[10:11]
	s_add_i32 m0, s23, 0x2000
	s_nop 0
	global_load_lds_dwordx4 v[198:199], off
	s_barrier
; #define PG8_STAGE(bufoff, gbase, voff) do { _Pragma("unroll") for (int _i = 0; _i < 2; ++_i) \
;         __builtin_amdgcn_global_load_lds((const unsigned*)((const char*)(gbase) + (voff)[_i]), (LAS unsigned*)(lds + (bufoff) + ldsw + _i * 8192), 16, 0, 0); } while (0)
; #define PG8_LDA(dst, b, h) do { _Pragma("unroll") for (int m = 0; m < 4; ++m) _Pragma("unroll") for (int k = 0; k < 2; ++k) dst[m][k] = *(const LAS bf16x8*)(lds + PG8_SA(b, h) + aoff + m * 2048 + k * 1024); } while (0)
; #define PG8_MMA(ai, bj, At, Bt) do { __builtin_amdgcn_s_setprio(1); _Pragma("unroll") for (int m = 0; m < 4; ++m) _Pragma("unroll") for (int n = 0; n < 2; ++n) _Pragma("unroll") for (int k = 0; k < 2; ++k) \
;         acc[ai][bj][m][n] = __builtin_amdgcn_mfma_f32_16x16x32_bf16(Bt[n][k], At[m][k], acc[ai][bj][m][n], 0, 0, 0); __builtin_amdgcn_s_setprio(0); } while (0)
; #define PG8_WAIT_V(n) asm volatile("s_waitcnt vmcnt(" #n ")" ::: "memory")
; #define PG8_WAIT_L(n) asm volatile("s_waitcnt lgkmcnt(" #n ")" ::: "memory")
; #define PG8_BAR __builtin_amdgcn_s_barrier()
; #define PG8_SCHED __builtin_amdgcn_sched_barrier(0)
; template <class Epi, class Sched>
; __device__ __forceinline__ void gemm_phase(LAS unsigned char* lds, const Gemm g, const Sched& S, const Epi& E) {
;     ...
;             PG8_BAR; PG8_WAIT_L(0); PG8_MMA(0, 1, At, B1); PG8_BAR;
;             PG8_LDA(At, 1, 1); PG8_STAGE(PG8_SA(1, 0), a3, voffA);
;             PG8_BAR; PG8_WAIT_L(0); PG8_MMA(1, 0, At, B0); PG8_BAR; PG8_SCHED;
;             PG8_STAGE(PG8_SB(1, 1), b3 + hstepB, voffB);
;             PG8_WAIT_V(6); PG8_BAR; PG8_MMA(1, 1, At, B1); PG8_BAR;
;     ...
;     PG8_WAIT_V(0);
;     if (wr == 0) PG8_BAR;
	s_waitcnt lgkmcnt(0)
	v_mfma_f32_16x16x32_bf16 v[110:113], v[222:225], v[178:181], v[110:113]
	v_mfma_f32_16x16x32_bf16 v[102:105], v[230:233], v[178:181], v[102:105]
	v_mfma_f32_16x16x32_bf16 v[94:97], v[222:225], v[186:189], v[94:97]
	v_mfma_f32_16x16x32_bf16 v[86:89], v[230:233], v[186:189], v[86:89]
	v_mfma_f32_16x16x32_bf16 v[78:81], v[222:225], v[194:197], v[78:81]
	v_mfma_f32_16x16x32_bf16 v[74:77], v[230:233], v[194:197], v[74:77]
	v_mfma_f32_16x16x32_bf16 v[70:73], v[222:225], v[214:217], v[70:73]
	v_mfma_f32_16x16x32_bf16 v[66:69], v[230:233], v[214:217], v[66:69]
	v_mfma_f32_16x16x32_bf16 v[110:113], v[226:229], v[182:185], v[110:113]
	v_mfma_f32_16x16x32_bf16 v[102:105], v[234:237], v[182:185], v[102:105]
	v_mfma_f32_16x16x32_bf16 v[94:97], v[226:229], v[190:193], v[94:97]
	v_mfma_f32_16x16x32_bf16 v[86:89], v[234:237], v[190:193], v[86:89]
	v_mfma_f32_16x16x32_bf16 v[78:81], v[226:229], v[210:213], v[78:81]
	v_mfma_f32_16x16x32_bf16 v[74:77], v[234:237], v[210:213], v[74:77]
	v_mfma_f32_16x16x32_bf16 v[70:73], v[226:229], v[218:221], v[70:73]
	v_mfma_f32_16x16x32_bf16 v[66:69], v[234:237], v[218:221], v[66:69]
	s_mov_b32 m0, s49
	v_lshl_add_u64 v[198:199], v[240:241], 0, s[10:11]
	s_barrier
	ds_read_b128 v[178:181], v145 offset:49152
	ds_read_b128 v[182:185], v145 offset:50176
	ds_read_b128 v[186:189], v145 offset:51200
	ds_read_b128 v[190:193], v145 offset:52224
	ds_read_b128 v[194:197], v145 offset:53248
	ds_read_b128 v[210:213], v145 offset:54272
	ds_read_b128 v[214:217], v145 offset:55296
	ds_read_b128 v[218:221], v145 offset:56320
	global_load_lds_dwordx4 v[198:199], off
	v_lshl_add_u64 v[198:199], v[242:243], 0, s[10:11]
	s_mov_b32 m0, s50
	s_nop 0
	global_load_lds_dwordx4 v[198:199], off
	s_barrier
	s_waitcnt lgkmcnt(0)
	v_mfma_f32_16x16x32_bf16 v[62:65], v[146:149], v[178:181], v[62:65]
	v_mfma_f32_16x16x32_bf16 v[58:61], v[170:173], v[178:181], v[58:61]
	v_mfma_f32_16x16x32_bf16 v[54:57], v[146:149], v[186:189], v[54:57]
	v_mfma_f32_16x16x32_bf16 v[50:53], v[170:173], v[186:189], v[50:53]
	v_mfma_f32_16x16x32_bf16 v[38:41], v[146:149], v[194:197], v[38:41]
	v_mfma_f32_16x16x32_bf16 v[34:37], v[170:173], v[194:197], v[34:37]
	v_mfma_f32_16x16x32_bf16 v[22:25], v[146:149], v[214:217], v[22:25]
	v_mfma_f32_16x16x32_bf16 v[18:21], v[170:173], v[214:217], v[18:21]
	v_mfma_f32_16x16x32_bf16 v[62:65], v[150:153], v[182:185], v[62:65]
	v_mfma_f32_16x16x32_bf16 v[58:61], v[174:177], v[182:185], v[58:61]
	v_mfma_f32_16x16x32_bf16 v[54:57], v[150:153], v[190:193], v[54:57]
	v_mfma_f32_16x16x32_bf16 v[50:53], v[174:177], v[190:193], v[50:53]
	v_mfma_f32_16x16x32_bf16 v[38:41], v[150:153], v[210:213], v[38:41]
	v_mfma_f32_16x16x32_bf16 v[34:37], v[174:177], v[210:213], v[34:37]
	v_mfma_f32_16x16x32_bf16 v[22:25], v[150:153], v[218:221], v[22:25]
	v_mfma_f32_16x16x32_bf16 v[18:21], v[174:177], v[218:221], v[18:21]
	s_barrier
	s_add_u32 s40, s44, 0x20080
	s_addc_u32 s41, s45, 0
	s_add_i32 s23, s31, s26
	v_lshl_add_u64 v[146:147], s[40:41], 0, v[134:135]
	s_mov_b32 m0, s23
	s_nop 0
	global_load_lds_dwordx4 v[146:147], off
	v_lshl_add_u64 v[146:147], s[40:41], 0, v[130:131]
	s_add_i32 m0, s23, 0x2000
	s_nop 0
	global_load_lds_dwordx4 v[146:147], off
	s_waitcnt vmcnt(6)
	s_barrier
	v_mfma_f32_16x16x32_bf16 v[46:49], v[222:225], v[178:181], v[46:49]
	v_mfma_f32_16x16x32_bf16 v[42:45], v[230:233], v[178:181], v[42:45]
	v_mfma_f32_16x16x32_bf16 v[30:33], v[222:225], v[186:189], v[30:33]
	v_mfma_f32_16x16x32_bf16 v[26:29], v[230:233], v[186:189], v[26:29]
	v_mfma_f32_16x16x32_bf16 v[14:17], v[222:225], v[194:197], v[14:17]
	v_mfma_f32_16x16x32_bf16 v[10:13], v[230:233], v[194:197], v[10:13]
	v_mfma_f32_16x16x32_bf16 v[6:9], v[222:225], v[214:217], v[6:9]
	v_mfma_f32_16x16x32_bf16 v[2:5], v[230:233], v[214:217], v[2:5]
	v_mfma_f32_16x16x32_bf16 v[46:49], v[226:229], v[182:185], v[46:49]
	v_mfma_f32_16x16x32_bf16 v[42:45], v[234:237], v[182:185], v[42:45]
	v_mfma_f32_16x16x32_bf16 v[30:33], v[226:229], v[190:193], v[30:33]
	v_mfma_f32_16x16x32_bf16 v[26:29], v[234:237], v[190:193], v[26:29]
	v_mfma_f32_16x16x32_bf16 v[14:17], v[226:229], v[210:213], v[14:17]
	v_mfma_f32_16x16x32_bf16 v[10:13], v[234:237], v[210:213], v[10:13]
	v_mfma_f32_16x16x32_bf16 v[6:9], v[226:229], v[218:221], v[6:9]
	v_mfma_f32_16x16x32_bf16 v[2:5], v[234:237], v[218:221], v[2:5]
	s_add_i32 s58, s58, 2
	s_add_u32 s56, s56, 0x100
	s_addc_u32 s57, s57, 0
	s_cmp_gt_u32 s58, 5
	s_mov_b64 s[40:41], s[42:43]
	s_barrier
	s_cbranch_scc0 .LBB0_580
	s_mov_b32 s23, 0x20000
	s_mov_b64 s[40:41], 0x20000
	s_mov_b32 s53, s52
	s_mov_b32 s46, s52
	s_mov_b64 s[42:43], s[36:37]
	s_nop 0
	s_nop 1
	s_mov_b32 s23, 0x24000
	s_nop 0
	s_mov_b64 s[40:41], 0x24000
	s_nop 0
	s_mov_b32 s23, 0x28000
	s_nop 0
	s_mov_b64 s[40:41], 0x28000
	s_nop 0
	s_nop 0
	s_mov_b64 s[40:41], 0x2c000
	s_nop 0
	s_nop 0
	s_and_b64 vcc, exec, s[20:21]
	s_mov_b64 s[40:41], s[0:1]
	s_cbranch_vccz .LBB0_577
	s_waitcnt vmcnt(0)
	s_cmpk_gt_u32 s34, 0xff
	s_cbranch_scc1 .LBB0_584
	s_barrier

; #define PG8_STAGE(bufoff, gbase, voff) do { _Pragma("unroll") for (int _i = 0; _i < 2; ++_i) \
;         __builtin_amdgcn_global_load_lds((const unsigned*)((const char*)(gbase) + (voff)[_i]), (LAS unsigned*)(lds + (bufoff) + ldsw + _i * 8192), 16, 0, 0); } while (0)
; #define PG8_LDA(dst, b, h) do { _Pragma("unroll") for (int m = 0; m < 4; ++m) _Pragma("unroll") for (int k = 0; k < 2; ++k) dst[m][k] = *(const LAS bf16x8*)(lds + PG8_SA(b, h) + aoff + m * 2048 + k * 1024); } while (0)
; #define PG8_LDB(dst, b, h) do { _Pragma("unroll") for (int n = 0; n < 2; ++n) _Pragma("unroll") for (int k = 0; k < 2; ++k) dst[n][k] = *(const LAS bf16x8*)(lds + PG8_SB(b, h) + boff + n * 2048 + k * 1024); } while (0)
; #define PG8_MMA(ai, bj, At, Bt) do { __builtin_amdgcn_s_setprio(1); _Pragma("unroll") for (int m = 0; m < 4; ++m) _Pragma("unroll") for (int n = 0; n < 2; ++n) _Pragma("unroll") for (int k = 0; k < 2; ++k) \
;         acc[ai][bj][m][n] = __builtin_amdgcn_mfma_f32_16x16x32_bf16(Bt[n][k], At[m][k], acc[ai][bj][m][n], 0, 0, 0); __builtin_amdgcn_s_setprio(0); } while (0)
; #define PG8_WAIT_V(n) asm volatile("s_waitcnt vmcnt(" #n ")" ::: "memory")
; #define PG8_WAIT_L(n) asm volatile("s_waitcnt lgkmcnt(" #n ")" ::: "memory")
; #define PG8_BAR __builtin_amdgcn_s_barrier()
; #define PG8_SCHED __builtin_amdgcn_sched_barrier(0)
; template <class Epi, class Sched>
; __device__ __forceinline__ void gemm_phase(LAS unsigned char* lds, const Gemm g, const Sched& S, const Epi& E) {
;     ...
;             PG8_LDB(B0, 0, 0); PG8_SCHED; PG8_LDA(At, 0, 0); PG8_STAGE(PG8_SA(1, 1), a1 + hstepA, voffA);
;             PG8_WAIT_L(8); PG8_BAR; PG8_WAIT_L(0); PG8_MMA(0, 0, At, B0); PG8_BAR; PG8_SCHED;
;             PG8_LDB(B1, 0, 1); PG8_STAGE(PG8_SB(0, 0), b2, voffB);
;             PG8_BAR; PG8_WAIT_L(0); PG8_MMA(0, 1, At, B1); PG8_BAR;
;             PG8_LDA(At, 0, 1); PG8_STAGE(PG8_SA(0, 0), a2, voffA);
;             PG8_BAR; PG8_WAIT_L(0); PG8_MMA(1, 0, At, B0); PG8_BAR; PG8_SCHED;
;             PG8_STAGE(PG8_SB(0, 1), b2 + hstepB, voffB);
;             PG8_WAIT_V(6); PG8_BAR; PG8_MMA(1, 1, At, B1); PG8_BAR;
.LBB0_595:
	v_add_u32_e32 v144, s24, v1
	ds_read_b128 v[172:175], v144
	ds_read_b128 v[176:179], v144 offset:1024
	ds_read_b128 v[180:183], v144 offset:2048
	ds_read_b128 v[184:187], v144 offset:3072
	s_add_u32 s42, s36, 0x100
	s_addc_u32 s43, s37, 0
	s_cmp_eq_u32 s54, 8
	s_cselect_b32 s47, s21, s43
	s_cselect_b32 s46, s20, s42
	s_cselect_b32 s45, s1, s29
	s_cselect_b32 s44, s0, s28
	v_lshl_add_u64 v[144:145], s[36:37], 0, v[140:141]
	s_add_i32 m0, s34, 0xc000
	ds_read_b128 v[188:191], v170
	ds_read_b128 v[192:195], v170 offset:1024
	ds_read_b128 v[196:199], v170 offset:2048
	ds_read_b128 v[210:213], v170 offset:3072
	ds_read_b128 v[214:217], v170 offset:4096
	ds_read_b128 v[218:221], v170 offset:5120
	ds_read_b128 v[222:225], v170 offset:6144
	ds_read_b128 v[226:229], v170 offset:7168
	global_load_lds_dwordx4 v[144:145], off
	v_lshl_add_u64 v[144:145], s[36:37], 0, v[142:143]
	s_add_i32 m0, s34, 0xe000
	s_nop 0
	global_load_lds_dwordx4 v[144:145], off
	s_waitcnt lgkmcnt(8)
	s_barrier
	s_waitcnt lgkmcnt(0)
	v_mfma_f32_16x16x32_bf16 v[126:129], v[172:175], v[188:191], v[126:129]
	v_mfma_f32_16x16x32_bf16 v[122:125], v[180:183], v[188:191], v[122:125]
	v_mfma_f32_16x16x32_bf16 v[110:113], v[172:175], v[196:199], v[110:113]
	v_mfma_f32_16x16x32_bf16 v[106:109], v[180:183], v[196:199], v[106:109]
	v_mfma_f32_16x16x32_bf16 v[94:97], v[172:175], v[214:217], v[94:97]
	v_mfma_f32_16x16x32_bf16 v[90:93], v[180:183], v[214:217], v[90:93]
	v_mfma_f32_16x16x32_bf16 v[78:81], v[172:175], v[222:225], v[78:81]
	v_mfma_f32_16x16x32_bf16 v[74:77], v[180:183], v[222:225], v[74:77]
	v_mfma_f32_16x16x32_bf16 v[126:129], v[176:179], v[192:195], v[126:129]
	v_mfma_f32_16x16x32_bf16 v[122:125], v[184:187], v[192:195], v[122:125]
	v_mfma_f32_16x16x32_bf16 v[110:113], v[176:179], v[210:213], v[110:113]
	v_mfma_f32_16x16x32_bf16 v[106:109], v[184:187], v[210:213], v[106:109]
	v_mfma_f32_16x16x32_bf16 v[94:97], v[176:179], v[218:221], v[94:97]
	v_mfma_f32_16x16x32_bf16 v[90:93], v[184:187], v[218:221], v[90:93]
	v_mfma_f32_16x16x32_bf16 v[78:81], v[176:179], v[226:229], v[78:81]
	v_mfma_f32_16x16x32_bf16 v[74:77], v[184:187], v[226:229], v[74:77]
	s_barrier
	v_add_u32_e32 v144, s25, v1
	s_add_i32 s23, s24, s13
	ds_read_b128 v[230:233], v144
	ds_read_b128 v[234:237], v144 offset:1024
	ds_read_b128 v[238:241], v144 offset:2048
	ds_read_b128 v[242:245], v144 offset:3072
	v_lshl_add_u64 v[144:145], s[44:45], 0, v[132:133]
	s_mov_b32 m0, s23
	v_lshl_add_u64 v[246:247], s[44:45], 0, v[136:137]
	global_load_lds_dwordx4 v[144:145], off
	s_add_i32 m0, s23, 0x2000
	s_nop 0
	global_load_lds_dwordx4 v[246:247], off
	s_barrier
	s_waitcnt lgkmcnt(0)
	v_mfma_f32_16x16x32_bf16 v[118:121], v[230:233], v[188:191], v[118:121]
	v_mfma_f32_16x16x32_bf16 v[114:117], v[238:241], v[188:191], v[114:117]
	v_mfma_f32_16x16x32_bf16 v[102:105], v[230:233], v[196:199], v[102:105]
	v_mfma_f32_16x16x32_bf16 v[98:101], v[238:241], v[196:199], v[98:101]
	v_mfma_f32_16x16x32_bf16 v[86:89], v[230:233], v[214:217], v[86:89]
	v_mfma_f32_16x16x32_bf16 v[82:85], v[238:241], v[214:217], v[82:85]
	v_mfma_f32_16x16x32_bf16 v[70:73], v[230:233], v[222:225], v[70:73]
	v_mfma_f32_16x16x32_bf16 v[66:69], v[238:241], v[222:225], v[66:69]
	v_mfma_f32_16x16x32_bf16 v[118:121], v[234:237], v[192:195], v[118:121]
	v_mfma_f32_16x16x32_bf16 v[114:117], v[242:245], v[192:195], v[114:117]
	v_mfma_f32_16x16x32_bf16 v[102:105], v[234:237], v[210:213], v[102:105]
	v_mfma_f32_16x16x32_bf16 v[98:101], v[242:245], v[210:213], v[98:101]
	v_mfma_f32_16x16x32_bf16 v[86:89], v[234:237], v[218:221], v[86:89]
	v_mfma_f32_16x16x32_bf16 v[82:85], v[242:245], v[218:221], v[82:85]
	v_mfma_f32_16x16x32_bf16 v[70:73], v[234:237], v[226:229], v[70:73]
	v_mfma_f32_16x16x32_bf16 v[66:69], v[242:245], v[226:229], v[66:69]
	s_mov_b32 m0, s34
	v_lshl_add_u64 v[248:249], s[46:47], 0, v[130:131]
	s_barrier
	ds_read_b128 v[188:191], v170 offset:16384
	ds_read_b128 v[192:195], v170 offset:17408
	ds_read_b128 v[196:199], v170 offset:18432
	ds_read_b128 v[210:213], v170 offset:19456
	ds_read_b128 v[214:217], v170 offset:20480
	ds_read_b128 v[218:221], v170 offset:21504
	ds_read_b128 v[222:225], v170 offset:22528
	ds_read_b128 v[226:229], v170 offset:23552
	global_load_lds_dwordx4 v[248:249], off
	v_lshl_add_u64 v[250:251], s[46:47], 0, v[134:135]
	s_mov_b32 m0, s35
	s_nop 0
	global_load_lds_dwordx4 v[250:251], off
	s_barrier
	s_waitcnt lgkmcnt(0)
	v_mfma_f32_16x16x32_bf16 v[62:65], v[172:175], v[188:191], v[62:65]
	v_mfma_f32_16x16x32_bf16 v[58:61], v[180:183], v[188:191], v[58:61]
	v_mfma_f32_16x16x32_bf16 v[46:49], v[172:175], v[196:199], v[46:49]
	v_mfma_f32_16x16x32_bf16 v[42:45], v[180:183], v[196:199], v[42:45]
	v_mfma_f32_16x16x32_bf16 v[30:33], v[172:175], v[214:217], v[30:33]
	v_mfma_f32_16x16x32_bf16 v[26:29], v[180:183], v[214:217], v[26:29]
	v_mfma_f32_16x16x32_bf16 v[14:17], v[172:175], v[222:225], v[14:17]
	v_mfma_f32_16x16x32_bf16 v[10:13], v[180:183], v[222:225], v[10:13]
	v_mfma_f32_16x16x32_bf16 v[62:65], v[176:179], v[192:195], v[62:65]
	v_mfma_f32_16x16x32_bf16 v[58:61], v[184:187], v[192:195], v[58:61]
	v_mfma_f32_16x16x32_bf16 v[46:49], v[176:179], v[210:213], v[46:49]
	v_mfma_f32_16x16x32_bf16 v[42:45], v[184:187], v[210:213], v[42:45]
	v_mfma_f32_16x16x32_bf16 v[30:33], v[176:179], v[218:221], v[30:33]
	v_mfma_f32_16x16x32_bf16 v[26:29], v[184:187], v[218:221], v[26:29]
	v_mfma_f32_16x16x32_bf16 v[14:17], v[176:179], v[226:229], v[14:17]
	v_mfma_f32_16x16x32_bf16 v[10:13], v[184:187], v[226:229], v[10:13]
	s_barrier
; #define PG8_STAGE(bufoff, gbase, voff) do { _Pragma("unroll") for (int _i = 0; _i < 2; ++_i) \
;         __builtin_amdgcn_global_load_lds((const unsigned*)((const char*)(gbase) + (voff)[_i]), (LAS unsigned*)(lds + (bufoff) + ldsw + _i * 8192), 16, 0, 0); } while (0)
; #define PG8_LDA(dst, b, h) do { _Pragma("unroll") for (int m = 0; m < 4; ++m) _Pragma("unroll") for (int k = 0; k < 2; ++k) dst[m][k] = *(const LAS bf16x8*)(lds + PG8_SA(b, h) + aoff + m * 2048 + k * 1024); } while (0)
; #define PG8_LDB(dst, b, h) do { _Pragma("unroll") for (int n = 0; n < 2; ++n) _Pragma("unroll") for (int k = 0; k < 2; ++k) dst[n][k] = *(const LAS bf16x8*)(lds + PG8_SB(b, h) + boff + n * 2048 + k * 1024); } while (0)
; #define PG8_MMA(ai, bj, At, Bt) do { __builtin_amdgcn_s_setprio(1); _Pragma("unroll") for (int m = 0; m < 4; ++m) _Pragma("unroll") for (int n = 0; n < 2; ++n) _Pragma("unroll") for (int k = 0; k < 2; ++k) \
;         acc[ai][bj][m][n] = __builtin_amdgcn_mfma_f32_16x16x32_bf16(Bt[n][k], At[m][k], acc[ai][bj][m][n], 0, 0, 0); __builtin_amdgcn_s_setprio(0); } while (0)
; #define PG8_WAIT_L(n) asm volatile("s_waitcnt lgkmcnt(" #n ")" ::: "memory")
; #define PG8_BAR __builtin_amdgcn_s_barrier()
; #define PG8_SCHED __builtin_amdgcn_sched_barrier(0)
; template <class Epi, class Sched>
; __device__ __forceinline__ void gemm_phase(LAS unsigned char* lds, const Gemm g, const Sched& S, const Epi& E) {
;     ...
;             PG8_LDB(B0, 1, 0); PG8_SCHED; PG8_LDA(At, 1, 0); PG8_STAGE(PG8_SA(0, 1), a2 + hstepA, voffA);
;             PG8_WAIT_L(8); PG8_BAR; PG8_WAIT_L(0); PG8_MMA(0, 0, At, B0); PG8_BAR; PG8_SCHED;
;             PG8_LDB(B1, 1, 1); PG8_STAGE(PG8_SB(1, 0), b3, voffB);
;             PG8_BAR; PG8_WAIT_L(0); PG8_MMA(0, 1, At, B1); PG8_BAR;
;             PG8_LDA(At, 1, 1); PG8_STAGE(PG8_SA(1, 0), a3, voffA);
;             PG8_BAR; PG8_WAIT_L(0); PG8_MMA(1, 0, At, B0); PG8_BAR; PG8_SCHED;
	s_add_u32 s36, s44, 0x30000
	s_addc_u32 s37, s45, 0
	s_add_i32 s23, s25, s13
	v_lshl_add_u64 v[172:173], s[36:37], 0, v[132:133]
	s_mov_b32 m0, s23
	s_nop 0
	global_load_lds_dwordx4 v[172:173], off
	v_lshl_add_u64 v[172:173], s[36:37], 0, v[136:137]
	s_add_i32 m0, s23, 0x2000
	s_nop 0
	global_load_lds_dwordx4 v[172:173], off
	s_waitcnt vmcnt(6)
	s_barrier
	v_mfma_f32_16x16x32_bf16 v[54:57], v[230:233], v[188:191], v[54:57]
	v_mfma_f32_16x16x32_bf16 v[50:53], v[238:241], v[188:191], v[50:53]
	v_mfma_f32_16x16x32_bf16 v[38:41], v[230:233], v[196:199], v[38:41]
	v_mfma_f32_16x16x32_bf16 v[34:37], v[238:241], v[196:199], v[34:37]
	v_mfma_f32_16x16x32_bf16 v[22:25], v[230:233], v[214:217], v[22:25]
	v_mfma_f32_16x16x32_bf16 v[18:21], v[238:241], v[214:217], v[18:21]
	v_mfma_f32_16x16x32_bf16 v[6:9], v[230:233], v[222:225], v[6:9]
	v_mfma_f32_16x16x32_bf16 v[2:5], v[238:241], v[222:225], v[2:5]
	v_mfma_f32_16x16x32_bf16 v[54:57], v[234:237], v[192:195], v[54:57]
	v_mfma_f32_16x16x32_bf16 v[50:53], v[242:245], v[192:195], v[50:53]
	v_mfma_f32_16x16x32_bf16 v[38:41], v[234:237], v[210:213], v[38:41]
	v_mfma_f32_16x16x32_bf16 v[34:37], v[242:245], v[210:213], v[34:37]
	v_mfma_f32_16x16x32_bf16 v[22:25], v[234:237], v[218:221], v[22:25]
	v_mfma_f32_16x16x32_bf16 v[18:21], v[242:245], v[218:221], v[18:21]
	v_mfma_f32_16x16x32_bf16 v[6:9], v[234:237], v[226:229], v[6:9]
	v_mfma_f32_16x16x32_bf16 v[2:5], v[242:245], v[226:229], v[2:5]
	v_add_u32_e32 v171, s27, v1
	s_barrier
	ds_read_b128 v[172:175], v171
	ds_read_b128 v[176:179], v171 offset:1024
	ds_read_b128 v[180:183], v171 offset:2048
	ds_read_b128 v[184:187], v171 offset:3072
	s_add_u32 s36, s46, 0x30000
	s_addc_u32 s37, s47, 0
	s_mov_b32 m0, s48
	v_lshl_add_u64 v[230:231], s[36:37], 0, v[130:131]
	ds_read_b128 v[188:191], v170 offset:32768
	ds_read_b128 v[192:195], v170 offset:33792
	ds_read_b128 v[196:199], v170 offset:34816
	ds_read_b128 v[210:213], v170 offset:35840
	ds_read_b128 v[214:217], v170 offset:36864
	ds_read_b128 v[218:221], v170 offset:37888
	ds_read_b128 v[222:225], v170 offset:38912
	ds_read_b128 v[226:229], v170 offset:39936
	global_load_lds_dwordx4 v[230:231], off
	v_lshl_add_u64 v[230:231], s[36:37], 0, v[134:135]
	s_mov_b32 m0, s49
	s_nop 0
	global_load_lds_dwordx4 v[230:231], off
	s_waitcnt lgkmcnt(8)
	s_barrier
	s_waitcnt lgkmcnt(0)
	v_mfma_f32_16x16x32_bf16 v[126:129], v[172:175], v[188:191], v[126:129]
	v_mfma_f32_16x16x32_bf16 v[122:125], v[180:183], v[188:191], v[122:125]
	v_mfma_f32_16x16x32_bf16 v[110:113], v[172:175], v[196:199], v[110:113]
	v_mfma_f32_16x16x32_bf16 v[106:109], v[180:183], v[196:199], v[106:109]
	v_mfma_f32_16x16x32_bf16 v[94:97], v[172:175], v[214:217], v[94:97]
	v_mfma_f32_16x16x32_bf16 v[90:93], v[180:183], v[214:217], v[90:93]
	v_mfma_f32_16x16x32_bf16 v[78:81], v[172:175], v[222:225], v[78:81]
	v_mfma_f32_16x16x32_bf16 v[74:77], v[180:183], v[222:225], v[74:77]
	v_mfma_f32_16x16x32_bf16 v[126:129], v[176:179], v[192:195], v[126:129]
	v_mfma_f32_16x16x32_bf16 v[122:125], v[184:187], v[192:195], v[122:125]
	v_mfma_f32_16x16x32_bf16 v[110:113], v[176:179], v[210:213], v[110:113]
	v_mfma_f32_16x16x32_bf16 v[106:109], v[184:187], v[210:213], v[106:109]
	v_mfma_f32_16x16x32_bf16 v[94:97], v[176:179], v[218:221], v[94:97]
	v_mfma_f32_16x16x32_bf16 v[90:93], v[184:187], v[218:221], v[90:93]
	v_mfma_f32_16x16x32_bf16 v[78:81], v[176:179], v[226:229], v[78:81]
	v_mfma_f32_16x16x32_bf16 v[74:77], v[184:187], v[226:229], v[74:77]
	s_barrier
	s_add_i32 s23, s27, s13
	v_add_u32_e32 v171, s31, v1
	v_lshl_add_u64 v[144:145], v[144:145], 0, s[10:11]
	s_mov_b32 m0, s23
	ds_read_b128 v[230:233], v171
	ds_read_b128 v[234:237], v171 offset:1024
	ds_read_b128 v[238:241], v171 offset:2048
	ds_read_b128 v[242:245], v171 offset:3072
	global_load_lds_dwordx4 v[144:145], off
	v_lshl_add_u64 v[144:145], v[246:247], 0, s[10:11]
	s_add_i32 m0, s23, 0x2000
	s_nop 0
	global_load_lds_dwordx4 v[144:145], off
	s_barrier
	s_waitcnt lgkmcnt(0)
	v_mfma_f32_16x16x32_bf16 v[118:121], v[230:233], v[188:191], v[118:121]
	v_mfma_f32_16x16x32_bf16 v[114:117], v[238:241], v[188:191], v[114:117]
	v_mfma_f32_16x16x32_bf16 v[102:105], v[230:233], v[196:199], v[102:105]
	v_mfma_f32_16x16x32_bf16 v[98:101], v[238:241], v[196:199], v[98:101]
	v_mfma_f32_16x16x32_bf16 v[86:89], v[230:233], v[214:217], v[86:89]
	v_mfma_f32_16x16x32_bf16 v[82:85], v[238:241], v[214:217], v[82:85]
	v_mfma_f32_16x16x32_bf16 v[70:73], v[230:233], v[222:225], v[70:73]
	v_mfma_f32_16x16x32_bf16 v[66:69], v[238:241], v[222:225], v[66:69]
	v_mfma_f32_16x16x32_bf16 v[118:121], v[234:237], v[192:195], v[118:121]
	v_mfma_f32_16x16x32_bf16 v[114:117], v[242:245], v[192:195], v[114:117]
	v_mfma_f32_16x16x32_bf16 v[102:105], v[234:237], v[210:213], v[102:105]
	v_mfma_f32_16x16x32_bf16 v[98:101], v[242:245], v[210:213], v[98:101]
	v_mfma_f32_16x16x32_bf16 v[86:89], v[234:237], v[218:221], v[86:89]
	v_mfma_f32_16x16x32_bf16 v[82:85], v[242:245], v[218:221], v[82:85]
	v_mfma_f32_16x16x32_bf16 v[70:73], v[234:237], v[226:229], v[70:73]
	v_mfma_f32_16x16x32_bf16 v[66:69], v[242:245], v[226:229], v[66:69]
	s_mov_b32 m0, s50
	v_lshl_add_u64 v[144:145], v[248:249], 0, s[10:11]
	s_barrier
	ds_read_b128 v[188:191], v170 offset:49152
	ds_read_b128 v[192:195], v170 offset:50176
	ds_read_b128 v[196:199], v170 offset:51200
	ds_read_b128 v[210:213], v170 offset:52224
	ds_read_b128 v[214:217], v170 offset:53248
	ds_read_b128 v[218:221], v170 offset:54272
	ds_read_b128 v[222:225], v170 offset:55296
	ds_read_b128 v[226:229], v170 offset:56320
	global_load_lds_dwordx4 v[144:145], off
	v_lshl_add_u64 v[144:145], v[250:251], 0, s[10:11]
	s_mov_b32 m0, s51
	s_nop 0
	global_load_lds_dwordx4 v[144:145], off
	s_barrier
; #define LAS __attribute__((address_space(3)))
; __device__ __forceinline__ unsigned cvt_pk_bf16(float lo, float hi) { unsigned r; asm volatile("v_cvt_pk_bf16_f32 %0, %1, %2" : "=v"(r) : "v"(lo), "v"(hi)); return r; }
; __device__ __forceinline__ float gelu_tanh(float x) { const float z = 0.7978845608f * (x + 0.044715f * x * x * x); const float th = 1.0f - 2.0f / (__expf(2.0f * z) + 1.0f); return 0.5f * x * (1.0f + th); }
; #define PG8_STAGE(bufoff, gbase, voff) do { _Pragma("unroll") for (int _i = 0; _i < 2; ++_i) \
;         __builtin_amdgcn_global_load_lds((const unsigned*)((const char*)(gbase) + (voff)[_i]), (LAS unsigned*)(lds + (bufoff) + ldsw + _i * 8192), 16, 0, 0); } while (0)
; #define PG8_WAIT_V(n) asm volatile("s_waitcnt vmcnt(" #n ")" ::: "memory")
; #define PG8_WAIT_L(n) asm volatile("s_waitcnt lgkmcnt(" #n ")" ::: "memory")
; #define PG8_BAR __builtin_amdgcn_s_barrier()
; #define PG8_SCHED __builtin_amdgcn_sched_barrier(0)
;     __device__ __forceinline__ void operator()(const f32x4 (&acc)[2][2][4][2], const Unit& u, int ui, const LAS float* rtab, int wr, int wc, int fr, int fq) const {
;         const int g = u.pm; const int n0 = wr * 64 + fr; const int lc0 = (u.pn & 1) * 256 + wc * 32 + 8 * fq;
; #pragma unroll
;         for (int ai = 0; ai < 2; ++ai)
; #pragma unroll
;             for (int m = 0; m < 4; ++m) {
;                 const int n = n0 + ai * HALF + m * 16;
; #pragma unroll
;                 for (int bj = 0; bj < 2; ++bj) {
;                     const int lc = lc0 + bj * HALF, t = lc >> 4, co = lc & 15; const int token = n * 32 + t;
;                     const f32x4 a0 = acc[ai][bj][m][0], a1 = acc[ai][bj][m][1];
;                     u32x4 w; w.x = cvt_pk_bf16(gelu_tanh(a0[0]), gelu_tanh(a0[1])); w.y = cvt_pk_bf16(gelu_tanh(a0[2]), gelu_tanh(a0[3]));
;                     w.z = cvt_pk_bf16(gelu_tanh(a1[0]), gelu_tanh(a1[1])); w.w = cvt_pk_bf16(gelu_tanh(a1[2]), gelu_tanh(a1[3]));
;                     *(u32x4*)(Y + (size_t)token * 1024 + 16 * g + co) = w;
; template <class Epi, class Sched>
; __device__ __forceinline__ void gemm_phase(LAS unsigned char* lds, const Gemm g, const Sched& S, const Epi& E) {
;     ...
;             PG8_BAR; PG8_WAIT_L(0); PG8_MMA(1, 0, At, B0); PG8_BAR; PG8_SCHED;
;             PG8_STAGE(PG8_SB(1, 1), b3 + hstepB, voffB);
;             PG8_WAIT_V(6); PG8_BAR; PG8_MMA(1, 1, At, B1); PG8_BAR;
	s_waitcnt lgkmcnt(0)
	v_mfma_f32_16x16x32_bf16 v[62:65], v[172:175], v[188:191], v[62:65]
	v_mfma_f32_16x16x32_bf16 v[58:61], v[180:183], v[188:191], v[58:61]
	v_mfma_f32_16x16x32_bf16 v[46:49], v[172:175], v[196:199], v[46:49]
	v_mfma_f32_16x16x32_bf16 v[42:45], v[180:183], v[196:199], v[42:45]
	v_mfma_f32_16x16x32_bf16 v[30:33], v[172:175], v[214:217], v[30:33]
	v_mfma_f32_16x16x32_bf16 v[26:29], v[180:183], v[214:217], v[26:29]
	v_mfma_f32_16x16x32_bf16 v[14:17], v[172:175], v[222:225], v[14:17]
	v_mfma_f32_16x16x32_bf16 v[10:13], v[180:183], v[222:225], v[10:13]
	v_mfma_f32_16x16x32_bf16 v[62:65], v[176:179], v[192:195], v[62:65]
	v_mfma_f32_16x16x32_bf16 v[58:61], v[184:187], v[192:195], v[58:61]
	v_mfma_f32_16x16x32_bf16 v[46:49], v[176:179], v[210:213], v[46:49]
	v_mfma_f32_16x16x32_bf16 v[42:45], v[184:187], v[210:213], v[42:45]
	v_mfma_f32_16x16x32_bf16 v[30:33], v[176:179], v[218:221], v[30:33]
	v_mfma_f32_16x16x32_bf16 v[26:29], v[184:187], v[218:221], v[26:29]
	v_mfma_f32_16x16x32_bf16 v[14:17], v[176:179], v[226:229], v[14:17]
	v_mfma_f32_16x16x32_bf16 v[10:13], v[184:187], v[226:229], v[10:13]
	s_barrier
	s_add_u32 s36, s44, 0x30080
	s_addc_u32 s37, s45, 0
	s_add_i32 s23, s31, s13
	v_lshl_add_u64 v[144:145], s[36:37], 0, v[132:133]
	s_mov_b32 m0, s23
	s_nop 0
	global_load_lds_dwordx4 v[144:145], off
	v_lshl_add_u64 v[144:145], s[36:37], 0, v[136:137]
	s_add_i32 m0, s23, 0x2000
	s_nop 0
	global_load_lds_dwordx4 v[144:145], off
	s_waitcnt vmcnt(6)
	s_barrier
	v_mfma_f32_16x16x32_bf16 v[54:57], v[230:233], v[188:191], v[54:57]
	v_mfma_f32_16x16x32_bf16 v[50:53], v[238:241], v[188:191], v[50:53]
	v_mfma_f32_16x16x32_bf16 v[38:41], v[230:233], v[196:199], v[38:41]
	v_mfma_f32_16x16x32_bf16 v[34:37], v[238:241], v[196:199], v[34:37]
	v_mfma_f32_16x16x32_bf16 v[22:25], v[230:233], v[214:217], v[22:25]
	v_mfma_f32_16x16x32_bf16 v[18:21], v[238:241], v[214:217], v[18:21]
	v_mfma_f32_16x16x32_bf16 v[6:9], v[230:233], v[222:225], v[6:9]
	v_mfma_f32_16x16x32_bf16 v[2:5], v[238:241], v[222:225], v[2:5]
	v_mfma_f32_16x16x32_bf16 v[54:57], v[234:237], v[192:195], v[54:57]
	v_mfma_f32_16x16x32_bf16 v[50:53], v[242:245], v[192:195], v[50:53]
	v_mfma_f32_16x16x32_bf16 v[38:41], v[234:237], v[210:213], v[38:41]
	v_mfma_f32_16x16x32_bf16 v[34:37], v[242:245], v[210:213], v[34:37]
	v_mfma_f32_16x16x32_bf16 v[22:25], v[234:237], v[218:221], v[22:25]
	v_mfma_f32_16x16x32_bf16 v[18:21], v[242:245], v[218:221], v[18:21]
	v_mfma_f32_16x16x32_bf16 v[6:9], v[234:237], v[226:229], v[6:9]
	v_mfma_f32_16x16x32_bf16 v[2:5], v[242:245], v[226:229], v[2:5]
	s_add_i32 s54, s54, 2
	s_add_u32 s28, s28, 0x100
	s_addc_u32 s29, s29, 0
	s_cmp_gt_u32 s54, 9
	s_mov_b64 s[36:37], s[42:43]
	s_barrier
	s_cbranch_scc0 .LBB0_595
	v_mul_f32_e32 v144, 0x3d372713, v126
	v_mul_f32_e32 v144, v126, v144
	v_fma_f32 v144, v126, v144, v126
	v_mul_f32_e32 v144, 0x3f4c422a, v144
	v_add_f32_e32 v144, v144, v144
	v_mul_f32_e32 v144, 0x3fb8aa3b, v144
	v_exp_f32_e32 v144, v144
	v_mul_f32_e32 v126, 0.5, v126
	s_lshl_b32 s23, s26, 8
	s_and_b32 s23, s23, 0x100
	v_add_f32_e32 v145, 1.0, v144
	v_div_scale_f32 v172, s[28:29], v145, v145, 2.0
	v_rcp_f32_e32 v173, v172
	v_or_b32_e32 v144, s23, v162
	v_lshrrev_b32_e32 v171, 4, v144
	v_or_b32_e32 v144, v171, v146
	v_fma_f32 v174, -v172, v173, 1.0
	v_fmac_f32_e32 v173, v174, v173
	v_div_scale_f32 v174, vcc, 2.0, v145, 2.0
	v_mul_f32_e32 v175, v174, v173
	v_fma_f32 v176, -v172, v175, v174
	v_fmac_f32_e32 v175, v176, v173
	v_fma_f32 v172, -v172, v175, v174
	v_mul_f32_e32 v174, 0x3d372713, v127
	v_mul_f32_e32 v174, v127, v174
	v_fma_f32 v174, v127, v174, v127
	v_mul_f32_e32 v174, 0x3f4c422a, v174
	v_add_f32_e32 v174, v174, v174
	v_mul_f32_e32 v174, 0x3fb8aa3b, v174
	v_exp_f32_e32 v174, v174
	v_div_fmas_f32 v172, v172, v173, v175
	v_div_fixup_f32 v145, v172, v145, 2.0
	v_sub_f32_e32 v145, 1.0, v145
	v_add_f32_e32 v172, 1.0, v174
	v_div_scale_f32 v173, s[28:29], v172, v172, 2.0
	v_rcp_f32_e32 v174, v173
	v_add_f32_e32 v145, 1.0, v145
	v_mul_f32_e32 v126, v126, v145
	v_mul_f32_e32 v127, 0.5, v127
	v_fma_f32 v145, -v173, v174, 1.0
	v_fmac_f32_e32 v174, v145, v174
	v_div_scale_f32 v145, vcc, 2.0, v172, 2.0
	v_mul_f32_e32 v175, v145, v174
	v_fma_f32 v176, -v173, v175, v145
	v_fmac_f32_e32 v175, v176, v174
	v_fma_f32 v145, -v173, v175, v145
	v_mul_f32_e32 v173, 0x3d372713, v128
	v_mul_f32_e32 v173, v128, v173
	v_fma_f32 v173, v128, v173, v128
	v_mul_f32_e32 v173, 0x3f4c422a, v173
	v_add_f32_e32 v173, v173, v173
	v_mul_f32_e32 v173, 0x3fb8aa3b, v173
	v_exp_f32_e32 v173, v173
	v_div_fmas_f32 v145, v145, v174, v175
	v_div_fixup_f32 v145, v145, v172, 2.0
	v_sub_f32_e32 v145, 1.0, v145
	v_add_f32_e32 v172, 1.0, v173
	v_div_scale_f32 v173, s[28:29], v172, v172, 2.0
	v_rcp_f32_e32 v174, v173
	v_add_f32_e32 v145, 1.0, v145
	v_mul_f32_e32 v127, v127, v145
	v_cvt_pk_bf16_f32 v126, v126, v127
	v_fma_f32 v127, -v173, v174, 1.0
	v_fmac_f32_e32 v174, v127, v174
	v_div_scale_f32 v127, vcc, 2.0, v172, 2.0
	v_mul_f32_e32 v145, v127, v174
	v_fma_f32 v175, -v173, v145, v127
	v_fmac_f32_e32 v145, v175, v174
	v_fma_f32 v127, -v173, v145, v127
	v_mul_f32_e32 v173, 0x3d372713, v129
	v_mul_f32_e32 v173, v129, v173
	v_fma_f32 v173, v129, v173, v129
	v_mul_f32_e32 v173, 0x3f4c422a, v173
	v_add_f32_e32 v173, v173, v173
	v_mul_f32_e32 v173, 0x3fb8aa3b, v173
	v_exp_f32_e32 v173, v173
	v_div_fmas_f32 v127, v127, v174, v145
	v_div_fixup_f32 v127, v127, v172, 2.0
	v_sub_f32_e32 v127, 1.0, v127
	v_add_f32_e32 v145, 1.0, v173
	v_div_scale_f32 v172, s[28:29], v145, v145, 2.0
	v_rcp_f32_e32 v173, v172
	v_mul_f32_e32 v128, 0.5, v128
	v_add_f32_e32 v127, 1.0, v127
	v_mul_f32_e32 v127, v128, v127
; #define LAS __attribute__((address_space(3)))
; __device__ __forceinline__ unsigned cvt_pk_bf16(float lo, float hi) { unsigned r; asm volatile("v_cvt_pk_bf16_f32 %0, %1, %2" : "=v"(r) : "v"(lo), "v"(hi)); return r; }
; __device__ __forceinline__ float gelu_tanh(float x) { const float z = 0.7978845608f * (x + 0.044715f * x * x * x); const float th = 1.0f - 2.0f / (__expf(2.0f * z) + 1.0f); return 0.5f * x * (1.0f + th); }
;     __device__ __forceinline__ void operator()(const f32x4 (&acc)[2][2][4][2], const Unit& u, int ui, const LAS float* rtab, int wr, int wc, int fr, int fq) const {
;         const int g = u.pm; const int n0 = wr * 64 + fr; const int lc0 = (u.pn & 1) * 256 + wc * 32 + 8 * fq;
; #pragma unroll
;         for (int ai = 0; ai < 2; ++ai)
; #pragma unroll
;             for (int m = 0; m < 4; ++m) {
;                 const int n = n0 + ai * HALF + m * 16;
; #pragma unroll
;                 for (int bj = 0; bj < 2; ++bj) {
;                     const int lc = lc0 + bj * HALF, t = lc >> 4, co = lc & 15; const int token = n * 32 + t;
;                     const f32x4 a0 = acc[ai][bj][m][0], a1 = acc[ai][bj][m][1];
;                     u32x4 w; w.x = cvt_pk_bf16(gelu_tanh(a0[0]), gelu_tanh(a0[1])); w.y = cvt_pk_bf16(gelu_tanh(a0[2]), gelu_tanh(a0[3]));
;                     w.z = cvt_pk_bf16(gelu_tanh(a1[0]), gelu_tanh(a1[1])); w.w = cvt_pk_bf16(gelu_tanh(a1[2]), gelu_tanh(a1[3]));
;                     *(u32x4*)(Y + (size_t)token * 1024 + 16 * g + co) = w;
	v_fma_f32 v128, -v172, v173, 1.0
	v_fmac_f32_e32 v173, v128, v173
	v_div_scale_f32 v128, vcc, 2.0, v145, 2.0
	v_mul_f32_e32 v174, v128, v173
	v_fma_f32 v175, -v172, v174, v128
	v_fmac_f32_e32 v174, v175, v173
	v_fma_f32 v128, -v172, v174, v128
	v_mul_f32_e32 v172, 0x3d372713, v122
	v_mul_f32_e32 v172, v122, v172
	v_fma_f32 v172, v122, v172, v122
	v_mul_f32_e32 v172, 0x3f4c422a, v172
	v_add_f32_e32 v172, v172, v172
	v_mul_f32_e32 v172, 0x3fb8aa3b, v172
	v_exp_f32_e32 v172, v172
	v_div_fmas_f32 v128, v128, v173, v174
	v_div_fixup_f32 v128, v128, v145, 2.0
	v_sub_f32_e32 v128, 1.0, v128
	v_add_f32_e32 v145, 1.0, v172
	v_div_scale_f32 v172, s[28:29], v145, v145, 2.0
	v_rcp_f32_e32 v173, v172
	v_mul_f32_e32 v129, 0.5, v129
	v_add_f32_e32 v128, 1.0, v128
	v_mul_f32_e32 v128, v129, v128
	v_cvt_pk_bf16_f32 v127, v127, v128
	v_fma_f32 v128, -v172, v173, 1.0
	v_fmac_f32_e32 v173, v128, v173
	v_div_scale_f32 v128, vcc, 2.0, v145, 2.0
	v_mul_f32_e32 v129, v128, v173
	v_fma_f32 v174, -v172, v129, v128
	v_fmac_f32_e32 v129, v174, v173
	v_fma_f32 v128, -v172, v129, v128
	v_mul_f32_e32 v172, 0x3d372713, v123
	v_mul_f32_e32 v172, v123, v172
	v_fma_f32 v172, v123, v172, v123
	v_mul_f32_e32 v172, 0x3f4c422a, v172
	v_add_f32_e32 v172, v172, v172
	v_mul_f32_e32 v172, 0x3fb8aa3b, v172
	v_exp_f32_e32 v172, v172
	v_div_fmas_f32 v128, v128, v173, v129
	v_div_fixup_f32 v128, v128, v145, 2.0
	v_sub_f32_e32 v128, 1.0, v128
	v_add_f32_e32 v129, 1.0, v172
	v_div_scale_f32 v145, s[28:29], v129, v129, 2.0
	v_rcp_f32_e32 v172, v145
	v_mul_f32_e32 v122, 0.5, v122
	v_add_f32_e32 v128, 1.0, v128
	v_mul_f32_e32 v122, v122, v128
	v_fma_f32 v128, -v145, v172, 1.0
	v_fmac_f32_e32 v172, v128, v172
	v_div_scale_f32 v128, vcc, 2.0, v129, 2.0
	v_mul_f32_e32 v173, v128, v172
	v_fma_f32 v174, -v145, v173, v128
	v_fmac_f32_e32 v173, v174, v172
	v_fma_f32 v128, -v145, v173, v128
	v_mul_f32_e32 v145, 0x3d372713, v124
	v_mul_f32_e32 v145, v124, v145
	v_fma_f32 v145, v124, v145, v124
	v_mul_f32_e32 v145, 0x3f4c422a, v145
	v_add_f32_e32 v145, v145, v145
	v_mul_f32_e32 v145, 0x3fb8aa3b, v145
	v_exp_f32_e32 v145, v145
	v_div_fmas_f32 v128, v128, v172, v173
	v_div_fixup_f32 v128, v128, v129, 2.0
	v_sub_f32_e32 v128, 1.0, v128
	v_add_f32_e32 v129, 1.0, v145
	v_div_scale_f32 v145, s[28:29], v129, v129, 2.0
	v_rcp_f32_e32 v172, v145
	v_mul_f32_e32 v123, 0.5, v123
	v_add_f32_e32 v128, 1.0, v128
	v_mul_f32_e32 v123, v123, v128
	v_cvt_pk_bf16_f32 v128, v122, v123
	v_fma_f32 v122, -v145, v172, 1.0
	v_fmac_f32_e32 v172, v122, v172
	v_div_scale_f32 v122, vcc, 2.0, v129, 2.0
	v_mul_f32_e32 v123, v122, v172
	v_fma_f32 v173, -v145, v123, v122
	v_fmac_f32_e32 v123, v173, v172
	v_fma_f32 v122, -v145, v123, v122
	v_mul_f32_e32 v145, 0x3d372713, v125
	v_mul_f32_e32 v145, v125, v145
	v_fma_f32 v145, v125, v145, v125
	v_mul_f32_e32 v145, 0x3f4c422a, v145
	v_add_f32_e32 v145, v145, v145
	v_mul_f32_e32 v145, 0x3fb8aa3b, v145
	v_exp_f32_e32 v145, v145
	v_div_fmas_f32 v122, v122, v172, v123
	v_div_fixup_f32 v122, v122, v129, 2.0
	v_sub_f32_e32 v122, 1.0, v122
	v_add_f32_e32 v123, 1.0, v145
	v_div_scale_f32 v129, s[28:29], v123, v123, 2.0
	v_rcp_f32_e32 v145, v129
	v_mul_f32_e32 v124, 0.5, v124
	v_add_f32_e32 v122, 1.0, v122
	v_mul_f32_e32 v122, v124, v122
	v_fma_f32 v124, -v129, v145, 1.0
	v_fmac_f32_e32 v145, v124, v145
	v_div_scale_f32 v124, vcc, 2.0, v123, 2.0
	v_mul_f32_e32 v172, v124, v145
	v_fma_f32 v173, -v129, v172, v124
	v_fmac_f32_e32 v172, v173, v145
	v_fma_f32 v124, -v129, v172, v124
	v_div_fmas_f32 v124, v124, v145, v172
	v_div_fixup_f32 v123, v124, v123, 2.0
	v_sub_f32_e32 v123, 1.0, v123
	v_mul_f32_e32 v124, 0.5, v125
	v_add_f32_e32 v123, 1.0, v123
	v_mul_f32_e32 v123, v124, v123
	v_cvt_pk_bf16_f32 v129, v122, v123
	v_mul_f32_e32 v122, 0x3d372713, v118
	v_mul_f32_e32 v122, v118, v122
	v_fma_f32 v122, v118, v122, v118
	v_mul_f32_e32 v122, 0x3f4c422a, v122
	v_add_f32_e32 v122, v122, v122
	v_mul_f32_e32 v122, 0x3fb8aa3b, v122
	v_exp_f32_e32 v124, v122
	v_ashrrev_i32_e32 v145, 31, v144
	v_lshlrev_b64 v[122:123], 11, v[144:145]
	v_lshl_add_u64 v[122:123], v[138:139], 0, v[122:123]
	v_add_f32_e32 v125, 1.0, v124
	v_div_scale_f32 v144, s[28:29], v125, v125, 2.0
	v_rcp_f32_e32 v145, v144
	global_store_dwordx4 v[122:123], v[126:129], off
	v_mul_f32_e32 v118, 0.5, v118
	v_or_b32_e32 v124, 8, v171
	v_fma_f32 v123, -v144, v145, 1.0
	v_fmac_f32_e32 v145, v123, v145
	v_div_scale_f32 v123, vcc, 2.0, v125, 2.0
	v_mul_f32_e32 v126, v123, v145
	v_fma_f32 v127, -v144, v126, v123
	v_fmac_f32_e32 v126, v127, v145
	v_mul_f32_e32 v127, 0x3d372713, v119
	v_mul_f32_e32 v127, v119, v127
	v_fma_f32 v127, v119, v127, v119
	v_mul_f32_e32 v127, 0x3f4c422a, v127
	v_add_f32_e32 v127, v127, v127
	v_mul_f32_e32 v127, 0x3fb8aa3b, v127
	v_exp_f32_e32 v127, v127
	v_fma_f32 v123, -v144, v126, v123
	v_div_fmas_f32 v123, v123, v145, v126
	v_div_fixup_f32 v123, v123, v125, 2.0
	v_add_f32_e32 v125, 1.0, v127
	v_div_scale_f32 v126, s[28:29], v125, v125, 2.0
	v_rcp_f32_e32 v127, v126
	v_sub_f32_e32 v123, 1.0, v123
	v_add_f32_e32 v123, 1.0, v123
	v_mul_f32_e32 v118, v118, v123
	v_fma_f32 v123, -v126, v127, 1.0
	v_fmac_f32_e32 v127, v123, v127
	v_div_scale_f32 v123, vcc, 2.0, v125, 2.0
	v_mul_f32_e32 v128, v123, v127
	v_fma_f32 v129, -v126, v128, v123
	v_fmac_f32_e32 v128, v129, v127
	v_fma_f32 v123, -v126, v128, v123
	v_mul_f32_e32 v126, 0x3d372713, v120
	v_mul_f32_e32 v126, v120, v126
	v_fma_f32 v126, v120, v126, v120
	v_mul_f32_e32 v126, 0x3f4c422a, v126
	v_add_f32_e32 v126, v126, v126
	v_mul_f32_e32 v126, 0x3fb8aa3b, v126
	v_exp_f32_e32 v126, v126
	v_div_fmas_f32 v123, v123, v127, v128
	v_div_fixup_f32 v123, v123, v125, 2.0
; #define LAS __attribute__((address_space(3)))
; __device__ __forceinline__ unsigned cvt_pk_bf16(float lo, float hi) { unsigned r; asm volatile("v_cvt_pk_bf16_f32 %0, %1, %2" : "=v"(r) : "v"(lo), "v"(hi)); return r; }
; __device__ __forceinline__ float gelu_tanh(float x) { const float z = 0.7978845608f * (x + 0.044715f * x * x * x); const float th = 1.0f - 2.0f / (__expf(2.0f * z) + 1.0f); return 0.5f * x * (1.0f + th); }
;     __device__ __forceinline__ void operator()(const f32x4 (&acc)[2][2][4][2], const Unit& u, int ui, const LAS float* rtab, int wr, int wc, int fr, int fq) const {
;         const int g = u.pm; const int n0 = wr * 64 + fr; const int lc0 = (u.pn & 1) * 256 + wc * 32 + 8 * fq;
; #pragma unroll
;         for (int ai = 0; ai < 2; ++ai)
; #pragma unroll
;             for (int m = 0; m < 4; ++m) {
;                 const int n = n0 + ai * HALF + m * 16;
; #pragma unroll
;                 for (int bj = 0; bj < 2; ++bj) {
;                     const int lc = lc0 + bj * HALF, t = lc >> 4, co = lc & 15; const int token = n * 32 + t;
;                     const f32x4 a0 = acc[ai][bj][m][0], a1 = acc[ai][bj][m][1];
;                     u32x4 w; w.x = cvt_pk_bf16(gelu_tanh(a0[0]), gelu_tanh(a0[1])); w.y = cvt_pk_bf16(gelu_tanh(a0[2]), gelu_tanh(a0[3]));
;                     w.z = cvt_pk_bf16(gelu_tanh(a1[0]), gelu_tanh(a1[1])); w.w = cvt_pk_bf16(gelu_tanh(a1[2]), gelu_tanh(a1[3]));
;                     *(u32x4*)(Y + (size_t)token * 1024 + 16 * g + co) = w;
	v_sub_f32_e32 v123, 1.0, v123
	v_add_f32_e32 v125, 1.0, v126
	v_div_scale_f32 v126, s[28:29], v125, v125, 2.0
	v_rcp_f32_e32 v127, v126
	v_mul_f32_e32 v119, 0.5, v119
	v_add_f32_e32 v123, 1.0, v123
	v_mul_f32_e32 v119, v119, v123
	v_cvt_pk_bf16_f32 v118, v118, v119
	v_fma_f32 v119, -v126, v127, 1.0
	v_fmac_f32_e32 v127, v119, v127
	v_div_scale_f32 v119, vcc, 2.0, v125, 2.0
	v_mul_f32_e32 v123, v119, v127
	v_fma_f32 v128, -v126, v123, v119
	v_fmac_f32_e32 v123, v128, v127
	v_fma_f32 v119, -v126, v123, v119
	v_mul_f32_e32 v126, 0x3d372713, v121
	v_mul_f32_e32 v126, v121, v126
	v_fma_f32 v126, v121, v126, v121
	v_mul_f32_e32 v126, 0x3f4c422a, v126
	v_add_f32_e32 v126, v126, v126
	v_mul_f32_e32 v126, 0x3fb8aa3b, v126
	v_exp_f32_e32 v126, v126
	v_div_fmas_f32 v119, v119, v127, v123
	v_div_fixup_f32 v119, v119, v125, 2.0
	v_sub_f32_e32 v119, 1.0, v119
	v_add_f32_e32 v123, 1.0, v126
	v_div_scale_f32 v125, s[28:29], v123, v123, 2.0
	v_rcp_f32_e32 v126, v125
	v_mul_f32_e32 v120, 0.5, v120
	v_add_f32_e32 v119, 1.0, v119
	v_mul_f32_e32 v119, v120, v119
	v_fma_f32 v120, -v125, v126, 1.0
	v_fmac_f32_e32 v126, v120, v126
	v_div_scale_f32 v120, vcc, 2.0, v123, 2.0
	v_mul_f32_e32 v127, v120, v126
	v_fma_f32 v128, -v125, v127, v120
	v_fmac_f32_e32 v127, v128, v126
	v_fma_f32 v120, -v125, v127, v120
	v_mul_f32_e32 v125, 0x3d372713, v114
	v_mul_f32_e32 v125, v114, v125
	v_fma_f32 v125, v114, v125, v114
	v_mul_f32_e32 v125, 0x3f4c422a, v125
	v_add_f32_e32 v125, v125, v125
	v_mul_f32_e32 v125, 0x3fb8aa3b, v125
	v_exp_f32_e32 v125, v125
	v_div_fmas_f32 v120, v120, v126, v127
	v_div_fixup_f32 v120, v120, v123, 2.0
	v_sub_f32_e32 v120, 1.0, v120
	v_add_f32_e32 v123, 1.0, v125
	v_div_scale_f32 v125, s[28:29], v123, v123, 2.0
	v_rcp_f32_e32 v126, v125
	v_mul_f32_e32 v121, 0.5, v121
	v_add_f32_e32 v120, 1.0, v120
	v_mul_f32_e32 v120, v121, v120
	v_cvt_pk_bf16_f32 v119, v119, v120
	v_fma_f32 v120, -v125, v126, 1.0
	v_fmac_f32_e32 v126, v120, v126
	v_div_scale_f32 v120, vcc, 2.0, v123, 2.0
	v_mul_f32_e32 v121, v120, v126
	v_fma_f32 v127, -v125, v121, v120
	v_fmac_f32_e32 v121, v127, v126
	v_fma_f32 v120, -v125, v121, v120
	v_mul_f32_e32 v125, 0x3d372713, v115
	v_mul_f32_e32 v125, v115, v125
	v_fma_f32 v125, v115, v125, v115
	v_mul_f32_e32 v125, 0x3f4c422a, v125
	v_add_f32_e32 v125, v125, v125
	v_mul_f32_e32 v125, 0x3fb8aa3b, v125
	v_exp_f32_e32 v125, v125
	v_div_fmas_f32 v120, v120, v126, v121
	v_div_fixup_f32 v120, v120, v123, 2.0
	v_sub_f32_e32 v120, 1.0, v120
	v_add_f32_e32 v121, 1.0, v125
	v_div_scale_f32 v123, s[28:29], v121, v121, 2.0
	v_rcp_f32_e32 v125, v123
	v_mul_f32_e32 v114, 0.5, v114
	v_add_f32_e32 v120, 1.0, v120
	v_mul_f32_e32 v114, v114, v120
	v_fma_f32 v120, -v123, v125, 1.0
	v_fmac_f32_e32 v125, v120, v125
	v_div_scale_f32 v120, vcc, 2.0, v121, 2.0
	v_mul_f32_e32 v126, v120, v125
	v_fma_f32 v127, -v123, v126, v120
	v_fmac_f32_e32 v126, v127, v125
	v_fma_f32 v120, -v123, v126, v120
	v_mul_f32_e32 v123, 0x3d372713, v116
	v_mul_f32_e32 v123, v116, v123
	v_fma_f32 v123, v116, v123, v116
	v_mul_f32_e32 v123, 0x3f4c422a, v123
	v_add_f32_e32 v123, v123, v123
	v_mul_f32_e32 v123, 0x3fb8aa3b, v123
	v_exp_f32_e32 v123, v123
	v_div_fmas_f32 v120, v120, v125, v126
	v_div_fixup_f32 v120, v120, v121, 2.0
	v_sub_f32_e32 v120, 1.0, v120
	v_add_f32_e32 v121, 1.0, v123
	v_div_scale_f32 v123, s[28:29], v121, v121, 2.0
	v_rcp_f32_e32 v125, v123
	v_mul_f32_e32 v115, 0.5, v115
	v_add_f32_e32 v120, 1.0, v120
	v_mul_f32_e32 v115, v115, v120
	v_cvt_pk_bf16_f32 v120, v114, v115
	v_fma_f32 v114, -v123, v125, 1.0
	v_fmac_f32_e32 v125, v114, v125
	v_div_scale_f32 v114, vcc, 2.0, v121, 2.0
	v_mul_f32_e32 v115, v114, v125
	v_fma_f32 v126, -v123, v115, v114
	v_fmac_f32_e32 v115, v126, v125
	v_fma_f32 v114, -v123, v115, v114
	v_mul_f32_e32 v123, 0x3d372713, v117
	v_mul_f32_e32 v123, v117, v123
	v_fma_f32 v123, v117, v123, v117
	v_mul_f32_e32 v123, 0x3f4c422a, v123
	v_add_f32_e32 v123, v123, v123
	v_mul_f32_e32 v123, 0x3fb8aa3b, v123
	v_exp_f32_e32 v123, v123
	v_div_fmas_f32 v114, v114, v125, v115
	v_div_fixup_f32 v114, v114, v121, 2.0
	v_sub_f32_e32 v114, 1.0, v114
	v_add_f32_e32 v115, 1.0, v123
	v_div_scale_f32 v121, s[28:29], v115, v115, 2.0
	v_rcp_f32_e32 v123, v121
	v_mul_f32_e32 v116, 0.5, v116
	v_add_f32_e32 v114, 1.0, v114
	v_mul_f32_e32 v114, v116, v114
	v_fma_f32 v116, -v121, v123, 1.0
	v_fmac_f32_e32 v123, v116, v123
	v_div_scale_f32 v116, vcc, 2.0, v115, 2.0
	v_mul_f32_e32 v125, v116, v123
	v_fma_f32 v126, -v121, v125, v116
	v_fmac_f32_e32 v125, v126, v123
	v_fma_f32 v116, -v121, v125, v116
	v_div_fmas_f32 v116, v116, v123, v125
	v_div_fixup_f32 v115, v116, v115, 2.0
	v_sub_f32_e32 v115, 1.0, v115
	v_mul_f32_e32 v116, 0.5, v117
	v_add_f32_e32 v115, 1.0, v115
	v_mul_f32_e32 v115, v116, v115
	v_mul_f32_e32 v116, 0x3d372713, v110
	v_mul_f32_e32 v116, v110, v116
	v_fma_f32 v116, v110, v116, v110
	v_mul_f32_e32 v116, 0x3f4c422a, v116
	v_add_f32_e32 v116, v116, v116
	v_mul_f32_e32 v116, 0x3fb8aa3b, v116
	v_exp_f32_e32 v116, v116
	v_or_b32_e32 v122, v124, v146
	v_ashrrev_i32_e32 v123, 31, v122
	v_cvt_pk_bf16_f32 v121, v114, v115
	v_add_f32_e32 v116, 1.0, v116
	v_div_scale_f32 v117, s[28:29], v116, v116, 2.0
	v_lshlrev_b64 v[114:115], 11, v[122:123]
	v_rcp_f32_e32 v122, v117
	v_lshl_add_u64 v[114:115], v[138:139], 0, v[114:115]
	global_store_dwordx4 v[114:115], v[118:121], off
	v_mul_f32_e32 v110, 0.5, v110
	v_fma_f32 v115, -v117, v122, 1.0
	v_fmac_f32_e32 v122, v115, v122
	v_div_scale_f32 v115, vcc, 2.0, v116, 2.0
	v_mul_f32_e32 v118, v115, v122
	v_fma_f32 v119, -v117, v118, v115
	v_fmac_f32_e32 v118, v119, v122
	v_fma_f32 v115, -v117, v118, v115
	v_mul_f32_e32 v117, 0x3d372713, v111
; #define LAS __attribute__((address_space(3)))
; __device__ __forceinline__ unsigned cvt_pk_bf16(float lo, float hi) { unsigned r; asm volatile("v_cvt_pk_bf16_f32 %0, %1, %2" : "=v"(r) : "v"(lo), "v"(hi)); return r; }
; __device__ __forceinline__ float gelu_tanh(float x) { const float z = 0.7978845608f * (x + 0.044715f * x * x * x); const float th = 1.0f - 2.0f / (__expf(2.0f * z) + 1.0f); return 0.5f * x * (1.0f + th); }
;     __device__ __forceinline__ void operator()(const f32x4 (&acc)[2][2][4][2], const Unit& u, int ui, const LAS float* rtab, int wr, int wc, int fr, int fq) const {
;         const int g = u.pm; const int n0 = wr * 64 + fr; const int lc0 = (u.pn & 1) * 256 + wc * 32 + 8 * fq;
; #pragma unroll
;         for (int ai = 0; ai < 2; ++ai)
; #pragma unroll
;             for (int m = 0; m < 4; ++m) {
;                 const int n = n0 + ai * HALF + m * 16;
; #pragma unroll
;                 for (int bj = 0; bj < 2; ++bj) {
;                     const int lc = lc0 + bj * HALF, t = lc >> 4, co = lc & 15; const int token = n * 32 + t;
;                     const f32x4 a0 = acc[ai][bj][m][0], a1 = acc[ai][bj][m][1];
;                     u32x4 w; w.x = cvt_pk_bf16(gelu_tanh(a0[0]), gelu_tanh(a0[1])); w.y = cvt_pk_bf16(gelu_tanh(a0[2]), gelu_tanh(a0[3]));
;                     w.z = cvt_pk_bf16(gelu_tanh(a1[0]), gelu_tanh(a1[1])); w.w = cvt_pk_bf16(gelu_tanh(a1[2]), gelu_tanh(a1[3]));
;                     *(u32x4*)(Y + (size_t)token * 1024 + 16 * g + co) = w;
	v_mul_f32_e32 v117, v111, v117
	v_fma_f32 v117, v111, v117, v111
	v_mul_f32_e32 v117, 0x3f4c422a, v117
	v_add_f32_e32 v117, v117, v117
	v_mul_f32_e32 v117, 0x3fb8aa3b, v117
	v_exp_f32_e32 v117, v117
	v_div_fmas_f32 v115, v115, v122, v118
	v_div_fixup_f32 v115, v115, v116, 2.0
	v_sub_f32_e32 v115, 1.0, v115
	v_add_f32_e32 v116, 1.0, v117
	v_div_scale_f32 v117, s[28:29], v116, v116, 2.0
	v_rcp_f32_e32 v118, v117
	v_add_f32_e32 v115, 1.0, v115
	v_mul_f32_e32 v110, v110, v115
	v_mul_f32_e32 v111, 0.5, v111
	v_fma_f32 v115, -v117, v118, 1.0
	v_fmac_f32_e32 v118, v115, v118
	v_div_scale_f32 v115, vcc, 2.0, v116, 2.0
	v_mul_f32_e32 v119, v115, v118
	v_fma_f32 v120, -v117, v119, v115
	v_fmac_f32_e32 v119, v120, v118
	v_fma_f32 v115, -v117, v119, v115
	v_mul_f32_e32 v117, 0x3d372713, v112
	v_mul_f32_e32 v117, v112, v117
	v_fma_f32 v117, v112, v117, v112
	v_mul_f32_e32 v117, 0x3f4c422a, v117
	v_add_f32_e32 v117, v117, v117
	v_mul_f32_e32 v117, 0x3fb8aa3b, v117
	v_exp_f32_e32 v117, v117
	v_div_fmas_f32 v115, v115, v118, v119
	v_div_fixup_f32 v115, v115, v116, 2.0
	v_sub_f32_e32 v115, 1.0, v115
	v_add_f32_e32 v116, 1.0, v117
	v_div_scale_f32 v117, s[28:29], v116, v116, 2.0
	v_rcp_f32_e32 v118, v117
	v_add_f32_e32 v115, 1.0, v115
	v_mul_f32_e32 v111, v111, v115
	v_cvt_pk_bf16_f32 v110, v110, v111
	v_fma_f32 v111, -v117, v118, 1.0
	v_fmac_f32_e32 v118, v111, v118
	v_div_scale_f32 v111, vcc, 2.0, v116, 2.0
	v_mul_f32_e32 v115, v111, v118
	v_fma_f32 v119, -v117, v115, v111
	v_fmac_f32_e32 v115, v119, v118
	v_fma_f32 v111, -v117, v115, v111
	v_mul_f32_e32 v117, 0x3d372713, v113
	v_mul_f32_e32 v117, v113, v117
	v_fma_f32 v117, v113, v117, v113
	v_mul_f32_e32 v117, 0x3f4c422a, v117
	v_add_f32_e32 v117, v117, v117
	v_mul_f32_e32 v117, 0x3fb8aa3b, v117
	v_exp_f32_e32 v117, v117
	v_div_fmas_f32 v111, v111, v118, v115
	v_div_fixup_f32 v111, v111, v116, 2.0
	v_sub_f32_e32 v111, 1.0, v111
	v_add_f32_e32 v115, 1.0, v117
	v_div_scale_f32 v116, s[28:29], v115, v115, 2.0
	v_rcp_f32_e32 v117, v116
	v_mul_f32_e32 v112, 0.5, v112
	v_add_f32_e32 v111, 1.0, v111
	v_mul_f32_e32 v111, v112, v111
	v_fma_f32 v112, -v116, v117, 1.0
	v_fmac_f32_e32 v117, v112, v117
	v_div_scale_f32 v112, vcc, 2.0, v115, 2.0
	v_mul_f32_e32 v118, v112, v117
	v_fma_f32 v119, -v116, v118, v112
	v_fmac_f32_e32 v118, v119, v117
	v_fma_f32 v112, -v116, v118, v112
	v_mul_f32_e32 v116, 0x3d372713, v106
	v_mul_f32_e32 v116, v106, v116
	v_fma_f32 v116, v106, v116, v106
	v_mul_f32_e32 v116, 0x3f4c422a, v116
	v_add_f32_e32 v116, v116, v116
	v_mul_f32_e32 v116, 0x3fb8aa3b, v116
	v_exp_f32_e32 v116, v116
	v_div_fmas_f32 v112, v112, v117, v118
	v_div_fixup_f32 v112, v112, v115, 2.0
	v_sub_f32_e32 v112, 1.0, v112
	v_add_f32_e32 v115, 1.0, v116
	v_div_scale_f32 v116, s[28:29], v115, v115, 2.0
	v_rcp_f32_e32 v117, v116
	v_mul_f32_e32 v113, 0.5, v113
	v_add_f32_e32 v112, 1.0, v112
	v_mul_f32_e32 v112, v113, v112
	v_cvt_pk_bf16_f32 v111, v111, v112
	v_fma_f32 v112, -v116, v117, 1.0
	v_fmac_f32_e32 v117, v112, v117
	v_div_scale_f32 v112, vcc, 2.0, v115, 2.0
	v_mul_f32_e32 v113, v112, v117
	v_fma_f32 v118, -v116, v113, v112
	v_fmac_f32_e32 v113, v118, v117
	v_fma_f32 v112, -v116, v113, v112
	v_mul_f32_e32 v116, 0x3d372713, v107
	v_mul_f32_e32 v116, v107, v116
	v_fma_f32 v116, v107, v116, v107
	v_mul_f32_e32 v116, 0x3f4c422a, v116
	v_add_f32_e32 v116, v116, v116
	v_mul_f32_e32 v116, 0x3fb8aa3b, v116
	v_exp_f32_e32 v116, v116
	v_div_fmas_f32 v112, v112, v117, v113
	v_div_fixup_f32 v112, v112, v115, 2.0
	v_sub_f32_e32 v112, 1.0, v112
	v_add_f32_e32 v113, 1.0, v116
	v_div_scale_f32 v115, s[28:29], v113, v113, 2.0
	v_rcp_f32_e32 v116, v115
	v_mul_f32_e32 v106, 0.5, v106
	v_add_f32_e32 v112, 1.0, v112
	v_mul_f32_e32 v106, v106, v112
	v_fma_f32 v112, -v115, v116, 1.0
	v_fmac_f32_e32 v116, v112, v116
	v_div_scale_f32 v112, vcc, 2.0, v113, 2.0
	v_mul_f32_e32 v117, v112, v116
	v_fma_f32 v118, -v115, v117, v112
	v_fmac_f32_e32 v117, v118, v116
	v_fma_f32 v112, -v115, v117, v112
	v_mul_f32_e32 v115, 0x3d372713, v108
	v_mul_f32_e32 v115, v108, v115
	v_fma_f32 v115, v108, v115, v108
	v_mul_f32_e32 v115, 0x3f4c422a, v115
	v_add_f32_e32 v115, v115, v115
	v_mul_f32_e32 v115, 0x3fb8aa3b, v115
	v_exp_f32_e32 v115, v115
	v_div_fmas_f32 v112, v112, v116, v117
	v_div_fixup_f32 v112, v112, v113, 2.0
	v_sub_f32_e32 v112, 1.0, v112
	v_add_f32_e32 v113, 1.0, v115
	v_div_scale_f32 v115, s[28:29], v113, v113, 2.0
	v_rcp_f32_e32 v116, v115
	v_mul_f32_e32 v107, 0.5, v107
	v_add_f32_e32 v112, 1.0, v112
	v_mul_f32_e32 v107, v107, v112
	v_cvt_pk_bf16_f32 v112, v106, v107
	v_fma_f32 v106, -v115, v116, 1.0
	v_fmac_f32_e32 v116, v106, v116
	v_div_scale_f32 v106, vcc, 2.0, v113, 2.0
	v_mul_f32_e32 v107, v106, v116
	v_fma_f32 v117, -v115, v107, v106
	v_fmac_f32_e32 v107, v117, v116
	v_fma_f32 v106, -v115, v107, v106
	v_mul_f32_e32 v115, 0x3d372713, v109
	v_mul_f32_e32 v115, v109, v115
	v_fma_f32 v115, v109, v115, v109
	v_mul_f32_e32 v115, 0x3f4c422a, v115
	v_add_f32_e32 v115, v115, v115
	v_mul_f32_e32 v115, 0x3fb8aa3b, v115
	v_exp_f32_e32 v115, v115
	v_div_fmas_f32 v106, v106, v116, v107
	v_div_fixup_f32 v106, v106, v113, 2.0
	v_sub_f32_e32 v106, 1.0, v106
	v_add_f32_e32 v107, 1.0, v115
	v_div_scale_f32 v113, s[28:29], v107, v107, 2.0
	v_rcp_f32_e32 v115, v113
	v_mul_f32_e32 v108, 0.5, v108
	v_add_f32_e32 v106, 1.0, v106
	v_mul_f32_e32 v106, v108, v106
	v_fma_f32 v108, -v113, v115, 1.0
	v_fmac_f32_e32 v115, v108, v115
	v_div_scale_f32 v108, vcc, 2.0, v107, 2.0
	v_mul_f32_e32 v116, v108, v115
	v_fma_f32 v117, -v113, v116, v108
	v_fmac_f32_e32 v116, v117, v115
	v_fma_f32 v108, -v113, v116, v108
	v_div_fmas_f32 v108, v108, v115, v116
; #define LAS __attribute__((address_space(3)))
; __device__ __forceinline__ unsigned cvt_pk_bf16(float lo, float hi) { unsigned r; asm volatile("v_cvt_pk_bf16_f32 %0, %1, %2" : "=v"(r) : "v"(lo), "v"(hi)); return r; }
; __device__ __forceinline__ float gelu_tanh(float x) { const float z = 0.7978845608f * (x + 0.044715f * x * x * x); const float th = 1.0f - 2.0f / (__expf(2.0f * z) + 1.0f); return 0.5f * x * (1.0f + th); }
;     __device__ __forceinline__ void operator()(const f32x4 (&acc)[2][2][4][2], const Unit& u, int ui, const LAS float* rtab, int wr, int wc, int fr, int fq) const {
;         const int g = u.pm; const int n0 = wr * 64 + fr; const int lc0 = (u.pn & 1) * 256 + wc * 32 + 8 * fq;
; #pragma unroll
;         for (int ai = 0; ai < 2; ++ai)
; #pragma unroll
;             for (int m = 0; m < 4; ++m) {
;                 const int n = n0 + ai * HALF + m * 16;
; #pragma unroll
;                 for (int bj = 0; bj < 2; ++bj) {
;                     const int lc = lc0 + bj * HALF, t = lc >> 4, co = lc & 15; const int token = n * 32 + t;
;                     const f32x4 a0 = acc[ai][bj][m][0], a1 = acc[ai][bj][m][1];
;                     u32x4 w; w.x = cvt_pk_bf16(gelu_tanh(a0[0]), gelu_tanh(a0[1])); w.y = cvt_pk_bf16(gelu_tanh(a0[2]), gelu_tanh(a0[3]));
;                     w.z = cvt_pk_bf16(gelu_tanh(a1[0]), gelu_tanh(a1[1])); w.w = cvt_pk_bf16(gelu_tanh(a1[2]), gelu_tanh(a1[3]));
;                     *(u32x4*)(Y + (size_t)token * 1024 + 16 * g + co) = w;
	v_div_fixup_f32 v107, v108, v107, 2.0
	v_sub_f32_e32 v107, 1.0, v107
	v_mul_f32_e32 v108, 0.5, v109
	v_add_f32_e32 v107, 1.0, v107
	v_mul_f32_e32 v107, v108, v107
	v_mul_f32_e32 v108, 0x3d372713, v102
	v_mul_f32_e32 v108, v102, v108
	v_fma_f32 v108, v102, v108, v102
	v_mul_f32_e32 v108, 0x3f4c422a, v108
	v_add_f32_e32 v108, v108, v108
	v_mul_f32_e32 v108, 0x3fb8aa3b, v108
	v_exp_f32_e32 v108, v108
	v_or_b32_e32 v114, v171, v147
	v_ashrrev_i32_e32 v115, 31, v114
	v_cvt_pk_bf16_f32 v113, v106, v107
	v_add_f32_e32 v108, 1.0, v108
	v_div_scale_f32 v109, s[28:29], v108, v108, 2.0
	v_lshlrev_b64 v[106:107], 11, v[114:115]
	v_rcp_f32_e32 v114, v109
	v_lshl_add_u64 v[106:107], v[138:139], 0, v[106:107]
	global_store_dwordx4 v[106:107], v[110:113], off
	v_mul_f32_e32 v102, 0.5, v102
	v_fma_f32 v107, -v109, v114, 1.0
	v_fmac_f32_e32 v114, v107, v114
	v_div_scale_f32 v107, vcc, 2.0, v108, 2.0
	v_mul_f32_e32 v110, v107, v114
	v_fma_f32 v111, -v109, v110, v107
	v_fmac_f32_e32 v110, v111, v114
	v_fma_f32 v107, -v109, v110, v107
	v_mul_f32_e32 v109, 0x3d372713, v103
	v_mul_f32_e32 v109, v103, v109
	v_fma_f32 v109, v103, v109, v103
	v_mul_f32_e32 v109, 0x3f4c422a, v109
	v_add_f32_e32 v109, v109, v109
	v_mul_f32_e32 v109, 0x3fb8aa3b, v109
	v_exp_f32_e32 v109, v109
	v_div_fmas_f32 v107, v107, v114, v110
	v_div_fixup_f32 v107, v107, v108, 2.0
	v_sub_f32_e32 v107, 1.0, v107
	v_add_f32_e32 v108, 1.0, v109
	v_div_scale_f32 v109, s[28:29], v108, v108, 2.0
	v_rcp_f32_e32 v110, v109
	v_add_f32_e32 v107, 1.0, v107
	v_mul_f32_e32 v102, v102, v107
	v_mul_f32_e32 v103, 0.5, v103
	v_fma_f32 v107, -v109, v110, 1.0
	v_fmac_f32_e32 v110, v107, v110
	v_div_scale_f32 v107, vcc, 2.0, v108, 2.0
	v_mul_f32_e32 v111, v107, v110
	v_fma_f32 v112, -v109, v111, v107
	v_fmac_f32_e32 v111, v112, v110
	v_fma_f32 v107, -v109, v111, v107
	v_mul_f32_e32 v109, 0x3d372713, v104
	v_mul_f32_e32 v109, v104, v109
	v_fma_f32 v109, v104, v109, v104
	v_mul_f32_e32 v109, 0x3f4c422a, v109
	v_add_f32_e32 v109, v109, v109
	v_mul_f32_e32 v109, 0x3fb8aa3b, v109
	v_exp_f32_e32 v109, v109
	v_div_fmas_f32 v107, v107, v110, v111
	v_div_fixup_f32 v107, v107, v108, 2.0
	v_sub_f32_e32 v107, 1.0, v107
	v_add_f32_e32 v108, 1.0, v109
	v_div_scale_f32 v109, s[28:29], v108, v108, 2.0
	v_rcp_f32_e32 v110, v109
	v_add_f32_e32 v107, 1.0, v107
	v_mul_f32_e32 v103, v103, v107
	v_cvt_pk_bf16_f32 v102, v102, v103
	v_fma_f32 v103, -v109, v110, 1.0
	v_fmac_f32_e32 v110, v103, v110
	v_div_scale_f32 v103, vcc, 2.0, v108, 2.0
	v_mul_f32_e32 v107, v103, v110
	v_fma_f32 v111, -v109, v107, v103
	v_fmac_f32_e32 v107, v111, v110
	v_fma_f32 v103, -v109, v107, v103
	v_mul_f32_e32 v109, 0x3d372713, v105
	v_mul_f32_e32 v109, v105, v109
	v_fma_f32 v109, v105, v109, v105
	v_mul_f32_e32 v109, 0x3f4c422a, v109
	v_add_f32_e32 v109, v109, v109
	v_mul_f32_e32 v109, 0x3fb8aa3b, v109
	v_exp_f32_e32 v109, v109
	v_div_fmas_f32 v103, v103, v110, v107
	v_div_fixup_f32 v103, v103, v108, 2.0
	v_sub_f32_e32 v103, 1.0, v103
	v_add_f32_e32 v107, 1.0, v109
	v_div_scale_f32 v108, s[28:29], v107, v107, 2.0
	v_rcp_f32_e32 v109, v108
	v_mul_f32_e32 v104, 0.5, v104
	v_add_f32_e32 v103, 1.0, v103
	v_mul_f32_e32 v103, v104, v103
	v_fma_f32 v104, -v108, v109, 1.0
	v_fmac_f32_e32 v109, v104, v109
	v_div_scale_f32 v104, vcc, 2.0, v107, 2.0
	v_mul_f32_e32 v110, v104, v109
	v_fma_f32 v111, -v108, v110, v104
	v_fmac_f32_e32 v110, v111, v109
	v_fma_f32 v104, -v108, v110, v104
	v_mul_f32_e32 v108, 0x3d372713, v98
	v_mul_f32_e32 v108, v98, v108
	v_fma_f32 v108, v98, v108, v98
	v_mul_f32_e32 v108, 0x3f4c422a, v108
	v_add_f32_e32 v108, v108, v108
	v_mul_f32_e32 v108, 0x3fb8aa3b, v108
	v_exp_f32_e32 v108, v108
	v_div_fmas_f32 v104, v104, v109, v110
	v_div_fixup_f32 v104, v104, v107, 2.0
	v_sub_f32_e32 v104, 1.0, v104
	v_add_f32_e32 v107, 1.0, v108
	v_div_scale_f32 v108, s[28:29], v107, v107, 2.0
	v_rcp_f32_e32 v109, v108
	v_mul_f32_e32 v105, 0.5, v105
	v_add_f32_e32 v104, 1.0, v104
	v_mul_f32_e32 v104, v105, v104
	v_cvt_pk_bf16_f32 v103, v103, v104
	v_fma_f32 v104, -v108, v109, 1.0
	v_fmac_f32_e32 v109, v104, v109
	v_div_scale_f32 v104, vcc, 2.0, v107, 2.0
	v_mul_f32_e32 v105, v104, v109
	v_fma_f32 v110, -v108, v105, v104
	v_fmac_f32_e32 v105, v110, v109
	v_fma_f32 v104, -v108, v105, v104
	v_mul_f32_e32 v108, 0x3d372713, v99
	v_mul_f32_e32 v108, v99, v108
	v_fma_f32 v108, v99, v108, v99
	v_mul_f32_e32 v108, 0x3f4c422a, v108
	v_add_f32_e32 v108, v108, v108
	v_mul_f32_e32 v108, 0x3fb8aa3b, v108
	v_exp_f32_e32 v108, v108
	v_div_fmas_f32 v104, v104, v109, v105
	v_div_fixup_f32 v104, v104, v107, 2.0
	v_sub_f32_e32 v104, 1.0, v104
	v_add_f32_e32 v105, 1.0, v108
	v_div_scale_f32 v107, s[28:29], v105, v105, 2.0
	v_rcp_f32_e32 v108, v107
	v_mul_f32_e32 v98, 0.5, v98
	v_add_f32_e32 v104, 1.0, v104
	v_mul_f32_e32 v98, v98, v104
	v_fma_f32 v104, -v107, v108, 1.0
	v_fmac_f32_e32 v108, v104, v108
	v_div_scale_f32 v104, vcc, 2.0, v105, 2.0
	v_mul_f32_e32 v109, v104, v108
	v_fma_f32 v110, -v107, v109, v104
	v_fmac_f32_e32 v109, v110, v108
	v_fma_f32 v104, -v107, v109, v104
	v_mul_f32_e32 v107, 0x3d372713, v100
	v_mul_f32_e32 v107, v100, v107
	v_fma_f32 v107, v100, v107, v100
	v_mul_f32_e32 v107, 0x3f4c422a, v107
	v_add_f32_e32 v107, v107, v107
	v_mul_f32_e32 v107, 0x3fb8aa3b, v107
	v_exp_f32_e32 v107, v107
	v_div_fmas_f32 v104, v104, v108, v109
	v_div_fixup_f32 v104, v104, v105, 2.0
	v_sub_f32_e32 v104, 1.0, v104
	v_add_f32_e32 v105, 1.0, v107
	v_div_scale_f32 v107, s[28:29], v105, v105, 2.0
	v_rcp_f32_e32 v108, v107
	v_mul_f32_e32 v99, 0.5, v99
	v_add_f32_e32 v104, 1.0, v104
	v_mul_f32_e32 v99, v99, v104
	v_cvt_pk_bf16_f32 v104, v98, v99
	v_fma_f32 v98, -v107, v108, 1.0
; #define LAS __attribute__((address_space(3)))
; __device__ __forceinline__ unsigned cvt_pk_bf16(float lo, float hi) { unsigned r; asm volatile("v_cvt_pk_bf16_f32 %0, %1, %2" : "=v"(r) : "v"(lo), "v"(hi)); return r; }
; __device__ __forceinline__ float gelu_tanh(float x) { const float z = 0.7978845608f * (x + 0.044715f * x * x * x); const float th = 1.0f - 2.0f / (__expf(2.0f * z) + 1.0f); return 0.5f * x * (1.0f + th); }
;     __device__ __forceinline__ void operator()(const f32x4 (&acc)[2][2][4][2], const Unit& u, int ui, const LAS float* rtab, int wr, int wc, int fr, int fq) const {
;         const int g = u.pm; const int n0 = wr * 64 + fr; const int lc0 = (u.pn & 1) * 256 + wc * 32 + 8 * fq;
; #pragma unroll
;         for (int ai = 0; ai < 2; ++ai)
; #pragma unroll
;             for (int m = 0; m < 4; ++m) {
;                 const int n = n0 + ai * HALF + m * 16;
; #pragma unroll
;                 for (int bj = 0; bj < 2; ++bj) {
;                     const int lc = lc0 + bj * HALF, t = lc >> 4, co = lc & 15; const int token = n * 32 + t;
;                     const f32x4 a0 = acc[ai][bj][m][0], a1 = acc[ai][bj][m][1];
;                     u32x4 w; w.x = cvt_pk_bf16(gelu_tanh(a0[0]), gelu_tanh(a0[1])); w.y = cvt_pk_bf16(gelu_tanh(a0[2]), gelu_tanh(a0[3]));
;                     w.z = cvt_pk_bf16(gelu_tanh(a1[0]), gelu_tanh(a1[1])); w.w = cvt_pk_bf16(gelu_tanh(a1[2]), gelu_tanh(a1[3]));
;                     *(u32x4*)(Y + (size_t)token * 1024 + 16 * g + co) = w;
	v_fmac_f32_e32 v108, v98, v108
	v_div_scale_f32 v98, vcc, 2.0, v105, 2.0
	v_mul_f32_e32 v99, v98, v108
	v_fma_f32 v109, -v107, v99, v98
	v_fmac_f32_e32 v99, v109, v108
	v_fma_f32 v98, -v107, v99, v98
	v_mul_f32_e32 v107, 0x3d372713, v101
	v_mul_f32_e32 v107, v101, v107
	v_fma_f32 v107, v101, v107, v101
	v_mul_f32_e32 v107, 0x3f4c422a, v107
	v_add_f32_e32 v107, v107, v107
	v_mul_f32_e32 v107, 0x3fb8aa3b, v107
	v_exp_f32_e32 v107, v107
	v_div_fmas_f32 v98, v98, v108, v99
	v_div_fixup_f32 v98, v98, v105, 2.0
	v_sub_f32_e32 v98, 1.0, v98
	v_add_f32_e32 v99, 1.0, v107
	v_div_scale_f32 v105, s[28:29], v99, v99, 2.0
	v_rcp_f32_e32 v107, v105
	v_mul_f32_e32 v100, 0.5, v100
	v_add_f32_e32 v98, 1.0, v98
	v_mul_f32_e32 v98, v100, v98
	v_fma_f32 v100, -v105, v107, 1.0
	v_fmac_f32_e32 v107, v100, v107
	v_div_scale_f32 v100, vcc, 2.0, v99, 2.0
	v_mul_f32_e32 v108, v100, v107
	v_fma_f32 v109, -v105, v108, v100
	v_fmac_f32_e32 v108, v109, v107
	v_fma_f32 v100, -v105, v108, v100
	v_div_fmas_f32 v100, v100, v107, v108
	v_div_fixup_f32 v99, v100, v99, 2.0
	v_sub_f32_e32 v99, 1.0, v99
	v_mul_f32_e32 v100, 0.5, v101
	v_add_f32_e32 v99, 1.0, v99
	v_mul_f32_e32 v99, v100, v99
	v_mul_f32_e32 v100, 0x3d372713, v94
	v_mul_f32_e32 v100, v94, v100
	v_fma_f32 v100, v94, v100, v94
	v_mul_f32_e32 v100, 0x3f4c422a, v100
	v_add_f32_e32 v100, v100, v100
	v_mul_f32_e32 v100, 0x3fb8aa3b, v100
	v_exp_f32_e32 v100, v100
	v_or_b32_e32 v106, v124, v147
	v_ashrrev_i32_e32 v107, 31, v106
	v_cvt_pk_bf16_f32 v105, v98, v99
	v_add_f32_e32 v100, 1.0, v100
	v_div_scale_f32 v101, s[28:29], v100, v100, 2.0
	v_lshlrev_b64 v[98:99], 11, v[106:107]
	v_rcp_f32_e32 v106, v101
	v_lshl_add_u64 v[98:99], v[138:139], 0, v[98:99]
	global_store_dwordx4 v[98:99], v[102:105], off
	v_mul_f32_e32 v94, 0.5, v94
	v_fma_f32 v99, -v101, v106, 1.0
	v_fmac_f32_e32 v106, v99, v106
	v_div_scale_f32 v99, vcc, 2.0, v100, 2.0
	v_mul_f32_e32 v102, v99, v106
	v_fma_f32 v103, -v101, v102, v99
	v_fmac_f32_e32 v102, v103, v106
	v_fma_f32 v99, -v101, v102, v99
	v_mul_f32_e32 v101, 0x3d372713, v95
	v_mul_f32_e32 v101, v95, v101
	v_fma_f32 v101, v95, v101, v95
	v_mul_f32_e32 v101, 0x3f4c422a, v101
	v_add_f32_e32 v101, v101, v101
	v_mul_f32_e32 v101, 0x3fb8aa3b, v101
	v_exp_f32_e32 v101, v101
	v_div_fmas_f32 v99, v99, v106, v102
	v_div_fixup_f32 v99, v99, v100, 2.0
	v_sub_f32_e32 v99, 1.0, v99
	v_add_f32_e32 v100, 1.0, v101
	v_div_scale_f32 v101, s[28:29], v100, v100, 2.0
	v_rcp_f32_e32 v102, v101
	v_add_f32_e32 v99, 1.0, v99
	v_mul_f32_e32 v94, v94, v99
	v_mul_f32_e32 v95, 0.5, v95
	v_fma_f32 v99, -v101, v102, 1.0
	v_fmac_f32_e32 v102, v99, v102
	v_div_scale_f32 v99, vcc, 2.0, v100, 2.0
	v_mul_f32_e32 v103, v99, v102
	v_fma_f32 v104, -v101, v103, v99
	v_fmac_f32_e32 v103, v104, v102
	v_fma_f32 v99, -v101, v103, v99
	v_mul_f32_e32 v101, 0x3d372713, v96
	v_mul_f32_e32 v101, v96, v101
	v_fma_f32 v101, v96, v101, v96
	v_mul_f32_e32 v101, 0x3f4c422a, v101
	v_add_f32_e32 v101, v101, v101
	v_mul_f32_e32 v101, 0x3fb8aa3b, v101
	v_exp_f32_e32 v101, v101
	v_div_fmas_f32 v99, v99, v102, v103
	v_div_fixup_f32 v99, v99, v100, 2.0
	v_sub_f32_e32 v99, 1.0, v99
	v_add_f32_e32 v100, 1.0, v101
	v_div_scale_f32 v101, s[28:29], v100, v100, 2.0
	v_rcp_f32_e32 v102, v101
	v_add_f32_e32 v99, 1.0, v99
	v_mul_f32_e32 v95, v95, v99
	v_cvt_pk_bf16_f32 v94, v94, v95
	v_fma_f32 v95, -v101, v102, 1.0
	v_fmac_f32_e32 v102, v95, v102
	v_div_scale_f32 v95, vcc, 2.0, v100, 2.0
	v_mul_f32_e32 v99, v95, v102
	v_fma_f32 v103, -v101, v99, v95
	v_fmac_f32_e32 v99, v103, v102
	v_fma_f32 v95, -v101, v99, v95
	v_mul_f32_e32 v101, 0x3d372713, v97
	v_mul_f32_e32 v101, v97, v101
	v_fma_f32 v101, v97, v101, v97
	v_mul_f32_e32 v101, 0x3f4c422a, v101
	v_add_f32_e32 v101, v101, v101
	v_mul_f32_e32 v101, 0x3fb8aa3b, v101
	v_exp_f32_e32 v101, v101
	v_div_fmas_f32 v95, v95, v102, v99
	v_div_fixup_f32 v95, v95, v100, 2.0
	v_sub_f32_e32 v95, 1.0, v95
	v_add_f32_e32 v99, 1.0, v101
	v_div_scale_f32 v100, s[28:29], v99, v99, 2.0
	v_rcp_f32_e32 v101, v100
	v_mul_f32_e32 v96, 0.5, v96
	v_add_f32_e32 v95, 1.0, v95
	v_mul_f32_e32 v95, v96, v95
	v_fma_f32 v96, -v100, v101, 1.0
	v_fmac_f32_e32 v101, v96, v101
	v_div_scale_f32 v96, vcc, 2.0, v99, 2.0
	v_mul_f32_e32 v102, v96, v101
	v_fma_f32 v103, -v100, v102, v96
	v_fmac_f32_e32 v102, v103, v101
	v_fma_f32 v96, -v100, v102, v96
	v_mul_f32_e32 v100, 0x3d372713, v90
	v_mul_f32_e32 v100, v90, v100
	v_fma_f32 v100, v90, v100, v90
	v_mul_f32_e32 v100, 0x3f4c422a, v100
	v_add_f32_e32 v100, v100, v100
	v_mul_f32_e32 v100, 0x3fb8aa3b, v100
	v_exp_f32_e32 v100, v100
	v_div_fmas_f32 v96, v96, v101, v102
	v_div_fixup_f32 v96, v96, v99, 2.0
	v_sub_f32_e32 v96, 1.0, v96
	v_add_f32_e32 v99, 1.0, v100
	v_div_scale_f32 v100, s[28:29], v99, v99, 2.0
	v_rcp_f32_e32 v101, v100
	v_mul_f32_e32 v97, 0.5, v97
	v_add_f32_e32 v96, 1.0, v96
	v_mul_f32_e32 v96, v97, v96
	v_cvt_pk_bf16_f32 v95, v95, v96
	v_fma_f32 v96, -v100, v101, 1.0
	v_fmac_f32_e32 v101, v96, v101
	v_div_scale_f32 v96, vcc, 2.0, v99, 2.0
	v_mul_f32_e32 v97, v96, v101
	v_fma_f32 v102, -v100, v97, v96
	v_fmac_f32_e32 v97, v102, v101
	v_fma_f32 v96, -v100, v97, v96
	v_mul_f32_e32 v100, 0x3d372713, v91
	v_mul_f32_e32 v100, v91, v100
	v_fma_f32 v100, v91, v100, v91
	v_mul_f32_e32 v100, 0x3f4c422a, v100
	v_add_f32_e32 v100, v100, v100
	v_mul_f32_e32 v100, 0x3fb8aa3b, v100
	v_exp_f32_e32 v100, v100
	v_div_fmas_f32 v96, v96, v101, v97
	v_div_fixup_f32 v96, v96, v99, 2.0
	v_sub_f32_e32 v96, 1.0, v96
	v_add_f32_e32 v97, 1.0, v100
	v_div_scale_f32 v99, s[28:29], v97, v97, 2.0
	v_rcp_f32_e32 v100, v99
	v_mul_f32_e32 v90, 0.5, v90
	v_add_f32_e32 v96, 1.0, v96
	v_mul_f32_e32 v90, v90, v96
; #define LAS __attribute__((address_space(3)))
; __device__ __forceinline__ unsigned cvt_pk_bf16(float lo, float hi) { unsigned r; asm volatile("v_cvt_pk_bf16_f32 %0, %1, %2" : "=v"(r) : "v"(lo), "v"(hi)); return r; }
; __device__ __forceinline__ float gelu_tanh(float x) { const float z = 0.7978845608f * (x + 0.044715f * x * x * x); const float th = 1.0f - 2.0f / (__expf(2.0f * z) + 1.0f); return 0.5f * x * (1.0f + th); }
;     __device__ __forceinline__ void operator()(const f32x4 (&acc)[2][2][4][2], const Unit& u, int ui, const LAS float* rtab, int wr, int wc, int fr, int fq) const {
;         const int g = u.pm; const int n0 = wr * 64 + fr; const int lc0 = (u.pn & 1) * 256 + wc * 32 + 8 * fq;
; #pragma unroll
;         for (int ai = 0; ai < 2; ++ai)
; #pragma unroll
;             for (int m = 0; m < 4; ++m) {
;                 const int n = n0 + ai * HALF + m * 16;
; #pragma unroll
;                 for (int bj = 0; bj < 2; ++bj) {
;                     const int lc = lc0 + bj * HALF, t = lc >> 4, co = lc & 15; const int token = n * 32 + t;
;                     const f32x4 a0 = acc[ai][bj][m][0], a1 = acc[ai][bj][m][1];
;                     u32x4 w; w.x = cvt_pk_bf16(gelu_tanh(a0[0]), gelu_tanh(a0[1])); w.y = cvt_pk_bf16(gelu_tanh(a0[2]), gelu_tanh(a0[3]));
;                     w.z = cvt_pk_bf16(gelu_tanh(a1[0]), gelu_tanh(a1[1])); w.w = cvt_pk_bf16(gelu_tanh(a1[2]), gelu_tanh(a1[3]));
;                     *(u32x4*)(Y + (size_t)token * 1024 + 16 * g + co) = w;
	v_fma_f32 v96, -v99, v100, 1.0
	v_fmac_f32_e32 v100, v96, v100
	v_div_scale_f32 v96, vcc, 2.0, v97, 2.0
	v_mul_f32_e32 v101, v96, v100
	v_fma_f32 v102, -v99, v101, v96
	v_fmac_f32_e32 v101, v102, v100
	v_fma_f32 v96, -v99, v101, v96
	v_mul_f32_e32 v99, 0x3d372713, v92
	v_mul_f32_e32 v99, v92, v99
	v_fma_f32 v99, v92, v99, v92
	v_mul_f32_e32 v99, 0x3f4c422a, v99
	v_add_f32_e32 v99, v99, v99
	v_mul_f32_e32 v99, 0x3fb8aa3b, v99
	v_exp_f32_e32 v99, v99
	v_div_fmas_f32 v96, v96, v100, v101
	v_div_fixup_f32 v96, v96, v97, 2.0
	v_sub_f32_e32 v96, 1.0, v96
	v_add_f32_e32 v97, 1.0, v99
	v_div_scale_f32 v99, s[28:29], v97, v97, 2.0
	v_rcp_f32_e32 v100, v99
	v_mul_f32_e32 v91, 0.5, v91
	v_add_f32_e32 v96, 1.0, v96
	v_mul_f32_e32 v91, v91, v96
	v_cvt_pk_bf16_f32 v96, v90, v91
	v_fma_f32 v90, -v99, v100, 1.0
	v_fmac_f32_e32 v100, v90, v100
	v_div_scale_f32 v90, vcc, 2.0, v97, 2.0
	v_mul_f32_e32 v91, v90, v100
	v_fma_f32 v101, -v99, v91, v90
	v_fmac_f32_e32 v91, v101, v100
	v_fma_f32 v90, -v99, v91, v90
	v_mul_f32_e32 v99, 0x3d372713, v93
	v_mul_f32_e32 v99, v93, v99
	v_fma_f32 v99, v93, v99, v93
	v_mul_f32_e32 v99, 0x3f4c422a, v99
	v_add_f32_e32 v99, v99, v99
	v_mul_f32_e32 v99, 0x3fb8aa3b, v99
	v_exp_f32_e32 v99, v99
	v_div_fmas_f32 v90, v90, v100, v91
	v_div_fixup_f32 v90, v90, v97, 2.0
	v_sub_f32_e32 v90, 1.0, v90
	v_add_f32_e32 v91, 1.0, v99
	v_div_scale_f32 v97, s[28:29], v91, v91, 2.0
	v_rcp_f32_e32 v99, v97
	v_mul_f32_e32 v92, 0.5, v92
	v_add_f32_e32 v90, 1.0, v90
	v_mul_f32_e32 v90, v92, v90
	v_fma_f32 v92, -v97, v99, 1.0
	v_fmac_f32_e32 v99, v92, v99
	v_div_scale_f32 v92, vcc, 2.0, v91, 2.0
	v_mul_f32_e32 v100, v92, v99
	v_fma_f32 v101, -v97, v100, v92
	v_fmac_f32_e32 v100, v101, v99
	v_fma_f32 v92, -v97, v100, v92
	v_div_fmas_f32 v92, v92, v99, v100
	v_div_fixup_f32 v91, v92, v91, 2.0
	v_sub_f32_e32 v91, 1.0, v91
	v_mul_f32_e32 v92, 0.5, v93
	v_add_f32_e32 v91, 1.0, v91
	v_mul_f32_e32 v91, v92, v91
	v_mul_f32_e32 v92, 0x3d372713, v86
	v_mul_f32_e32 v92, v86, v92
	v_fma_f32 v92, v86, v92, v86
	v_mul_f32_e32 v92, 0x3f4c422a, v92
	v_add_f32_e32 v92, v92, v92
	v_mul_f32_e32 v92, 0x3fb8aa3b, v92
	v_exp_f32_e32 v92, v92
	v_or_b32_e32 v98, v171, v148
	v_ashrrev_i32_e32 v99, 31, v98
	v_cvt_pk_bf16_f32 v97, v90, v91
	v_add_f32_e32 v92, 1.0, v92
	v_div_scale_f32 v93, s[28:29], v92, v92, 2.0
	v_lshlrev_b64 v[90:91], 11, v[98:99]
	v_rcp_f32_e32 v98, v93
	v_lshl_add_u64 v[90:91], v[138:139], 0, v[90:91]
	global_store_dwordx4 v[90:91], v[94:97], off
	v_mul_f32_e32 v86, 0.5, v86
	v_fma_f32 v91, -v93, v98, 1.0
	v_fmac_f32_e32 v98, v91, v98
	v_div_scale_f32 v91, vcc, 2.0, v92, 2.0
	v_mul_f32_e32 v94, v91, v98
	v_fma_f32 v95, -v93, v94, v91
	v_fmac_f32_e32 v94, v95, v98
	v_fma_f32 v91, -v93, v94, v91
	v_mul_f32_e32 v93, 0x3d372713, v87
	v_mul_f32_e32 v93, v87, v93
	v_fma_f32 v93, v87, v93, v87
	v_mul_f32_e32 v93, 0x3f4c422a, v93
	v_add_f32_e32 v93, v93, v93
	v_mul_f32_e32 v93, 0x3fb8aa3b, v93
	v_exp_f32_e32 v93, v93
	v_div_fmas_f32 v91, v91, v98, v94
	v_div_fixup_f32 v91, v91, v92, 2.0
	v_sub_f32_e32 v91, 1.0, v91
	v_add_f32_e32 v92, 1.0, v93
	v_div_scale_f32 v93, s[28:29], v92, v92, 2.0
	v_rcp_f32_e32 v94, v93
	v_add_f32_e32 v91, 1.0, v91
	v_mul_f32_e32 v86, v86, v91
	v_mul_f32_e32 v87, 0.5, v87
	v_fma_f32 v91, -v93, v94, 1.0
	v_fmac_f32_e32 v94, v91, v94
	v_div_scale_f32 v91, vcc, 2.0, v92, 2.0
	v_mul_f32_e32 v95, v91, v94
	v_fma_f32 v96, -v93, v95, v91
	v_fmac_f32_e32 v95, v96, v94
	v_fma_f32 v91, -v93, v95, v91
	v_mul_f32_e32 v93, 0x3d372713, v88
	v_mul_f32_e32 v93, v88, v93
	v_fma_f32 v93, v88, v93, v88
	v_mul_f32_e32 v93, 0x3f4c422a, v93
	v_add_f32_e32 v93, v93, v93
	v_mul_f32_e32 v93, 0x3fb8aa3b, v93
	v_exp_f32_e32 v93, v93
	v_div_fmas_f32 v91, v91, v94, v95
	v_div_fixup_f32 v91, v91, v92, 2.0
	v_sub_f32_e32 v91, 1.0, v91
	v_add_f32_e32 v92, 1.0, v93
	v_div_scale_f32 v93, s[28:29], v92, v92, 2.0
	v_rcp_f32_e32 v94, v93
	v_add_f32_e32 v91, 1.0, v91
	v_mul_f32_e32 v87, v87, v91
	v_cvt_pk_bf16_f32 v86, v86, v87
	v_fma_f32 v87, -v93, v94, 1.0
	v_fmac_f32_e32 v94, v87, v94
	v_div_scale_f32 v87, vcc, 2.0, v92, 2.0
	v_mul_f32_e32 v91, v87, v94
	v_fma_f32 v95, -v93, v91, v87
	v_fmac_f32_e32 v91, v95, v94
	v_fma_f32 v87, -v93, v91, v87
	v_mul_f32_e32 v93, 0x3d372713, v89
	v_mul_f32_e32 v93, v89, v93
	v_fma_f32 v93, v89, v93, v89
	v_mul_f32_e32 v93, 0x3f4c422a, v93
	v_add_f32_e32 v93, v93, v93
	v_mul_f32_e32 v93, 0x3fb8aa3b, v93
	v_exp_f32_e32 v93, v93
	v_div_fmas_f32 v87, v87, v94, v91
	v_div_fixup_f32 v87, v87, v92, 2.0
	v_sub_f32_e32 v87, 1.0, v87
	v_add_f32_e32 v91, 1.0, v93
	v_div_scale_f32 v92, s[28:29], v91, v91, 2.0
	v_rcp_f32_e32 v93, v92
	v_mul_f32_e32 v88, 0.5, v88
	v_add_f32_e32 v87, 1.0, v87
	v_mul_f32_e32 v87, v88, v87
	v_fma_f32 v88, -v92, v93, 1.0
	v_fmac_f32_e32 v93, v88, v93
	v_div_scale_f32 v88, vcc, 2.0, v91, 2.0
	v_mul_f32_e32 v94, v88, v93
	v_fma_f32 v95, -v92, v94, v88
	v_fmac_f32_e32 v94, v95, v93
	v_fma_f32 v88, -v92, v94, v88
	v_mul_f32_e32 v92, 0x3d372713, v82
	v_mul_f32_e32 v92, v82, v92
	v_fma_f32 v92, v82, v92, v82
	v_mul_f32_e32 v92, 0x3f4c422a, v92
	v_add_f32_e32 v92, v92, v92
	v_mul_f32_e32 v92, 0x3fb8aa3b, v92
	v_exp_f32_e32 v92, v92
	v_div_fmas_f32 v88, v88, v93, v94
	v_div_fixup_f32 v88, v88, v91, 2.0
	v_sub_f32_e32 v88, 1.0, v88
	v_add_f32_e32 v91, 1.0, v92
	v_div_scale_f32 v92, s[28:29], v91, v91, 2.0
	v_rcp_f32_e32 v93, v92
	v_mul_f32_e32 v89, 0.5, v89
	v_add_f32_e32 v88, 1.0, v88
	v_mul_f32_e32 v88, v89, v88
	v_cvt_pk_bf16_f32 v87, v87, v88
	v_fma_f32 v88, -v92, v93, 1.0
	v_fmac_f32_e32 v93, v88, v93
	v_div_scale_f32 v88, vcc, 2.0, v91, 2.0
	v_mul_f32_e32 v89, v88, v93
	v_fma_f32 v94, -v92, v89, v88
	v_fmac_f32_e32 v89, v94, v93
; #define LAS __attribute__((address_space(3)))
; __device__ __forceinline__ unsigned cvt_pk_bf16(float lo, float hi) { unsigned r; asm volatile("v_cvt_pk_bf16_f32 %0, %1, %2" : "=v"(r) : "v"(lo), "v"(hi)); return r; }
; __device__ __forceinline__ float gelu_tanh(float x) { const float z = 0.7978845608f * (x + 0.044715f * x * x * x); const float th = 1.0f - 2.0f / (__expf(2.0f * z) + 1.0f); return 0.5f * x * (1.0f + th); }
;     __device__ __forceinline__ void operator()(const f32x4 (&acc)[2][2][4][2], const Unit& u, int ui, const LAS float* rtab, int wr, int wc, int fr, int fq) const {
;         const int g = u.pm; const int n0 = wr * 64 + fr; const int lc0 = (u.pn & 1) * 256 + wc * 32 + 8 * fq;
; #pragma unroll
;         for (int ai = 0; ai < 2; ++ai)
; #pragma unroll
;             for (int m = 0; m < 4; ++m) {
;                 const int n = n0 + ai * HALF + m * 16;
; #pragma unroll
;                 for (int bj = 0; bj < 2; ++bj) {
;                     const int lc = lc0 + bj * HALF, t = lc >> 4, co = lc & 15; const int token = n * 32 + t;
;                     const f32x4 a0 = acc[ai][bj][m][0], a1 = acc[ai][bj][m][1];
;                     u32x4 w; w.x = cvt_pk_bf16(gelu_tanh(a0[0]), gelu_tanh(a0[1])); w.y = cvt_pk_bf16(gelu_tanh(a0[2]), gelu_tanh(a0[3]));
;                     w.z = cvt_pk_bf16(gelu_tanh(a1[0]), gelu_tanh(a1[1])); w.w = cvt_pk_bf16(gelu_tanh(a1[2]), gelu_tanh(a1[3]));
;                     *(u32x4*)(Y + (size_t)token * 1024 + 16 * g + co) = w;
	v_fma_f32 v88, -v92, v89, v88
	v_mul_f32_e32 v92, 0x3d372713, v83
	v_mul_f32_e32 v92, v83, v92
	v_fma_f32 v92, v83, v92, v83
	v_mul_f32_e32 v92, 0x3f4c422a, v92
	v_add_f32_e32 v92, v92, v92
	v_mul_f32_e32 v92, 0x3fb8aa3b, v92
	v_exp_f32_e32 v92, v92
	v_div_fmas_f32 v88, v88, v93, v89
	v_div_fixup_f32 v88, v88, v91, 2.0
	v_sub_f32_e32 v88, 1.0, v88
	v_add_f32_e32 v89, 1.0, v92
	v_div_scale_f32 v91, s[28:29], v89, v89, 2.0
	v_rcp_f32_e32 v92, v91
	v_mul_f32_e32 v82, 0.5, v82
	v_add_f32_e32 v88, 1.0, v88
	v_mul_f32_e32 v82, v82, v88
	v_fma_f32 v88, -v91, v92, 1.0
	v_fmac_f32_e32 v92, v88, v92
	v_div_scale_f32 v88, vcc, 2.0, v89, 2.0
	v_mul_f32_e32 v93, v88, v92
	v_fma_f32 v94, -v91, v93, v88
	v_fmac_f32_e32 v93, v94, v92
	v_fma_f32 v88, -v91, v93, v88
	v_mul_f32_e32 v91, 0x3d372713, v84
	v_mul_f32_e32 v91, v84, v91
	v_fma_f32 v91, v84, v91, v84
	v_mul_f32_e32 v91, 0x3f4c422a, v91
	v_add_f32_e32 v91, v91, v91
	v_mul_f32_e32 v91, 0x3fb8aa3b, v91
	v_exp_f32_e32 v91, v91
	v_div_fmas_f32 v88, v88, v92, v93
	v_div_fixup_f32 v88, v88, v89, 2.0
	v_sub_f32_e32 v88, 1.0, v88
	v_add_f32_e32 v89, 1.0, v91
	v_div_scale_f32 v91, s[28:29], v89, v89, 2.0
	v_rcp_f32_e32 v92, v91
	v_mul_f32_e32 v83, 0.5, v83
	v_add_f32_e32 v88, 1.0, v88
	v_mul_f32_e32 v83, v83, v88
	v_cvt_pk_bf16_f32 v88, v82, v83
	v_fma_f32 v82, -v91, v92, 1.0
	v_fmac_f32_e32 v92, v82, v92
	v_div_scale_f32 v82, vcc, 2.0, v89, 2.0
	v_mul_f32_e32 v83, v82, v92
	v_fma_f32 v93, -v91, v83, v82
	v_fmac_f32_e32 v83, v93, v92
	v_fma_f32 v82, -v91, v83, v82
	v_mul_f32_e32 v91, 0x3d372713, v85
	v_mul_f32_e32 v91, v85, v91
	v_fma_f32 v91, v85, v91, v85
	v_mul_f32_e32 v91, 0x3f4c422a, v91
	v_add_f32_e32 v91, v91, v91
	v_mul_f32_e32 v91, 0x3fb8aa3b, v91
	v_exp_f32_e32 v91, v91
	v_div_fmas_f32 v82, v82, v92, v83
	v_div_fixup_f32 v82, v82, v89, 2.0
	v_sub_f32_e32 v82, 1.0, v82
	v_add_f32_e32 v83, 1.0, v91
	v_div_scale_f32 v89, s[28:29], v83, v83, 2.0
	v_rcp_f32_e32 v91, v89
	v_mul_f32_e32 v84, 0.5, v84
	v_add_f32_e32 v82, 1.0, v82
	v_mul_f32_e32 v82, v84, v82
	v_fma_f32 v84, -v89, v91, 1.0
	v_fmac_f32_e32 v91, v84, v91
	v_div_scale_f32 v84, vcc, 2.0, v83, 2.0
	v_mul_f32_e32 v92, v84, v91
	v_fma_f32 v93, -v89, v92, v84
	v_fmac_f32_e32 v92, v93, v91
	v_fma_f32 v84, -v89, v92, v84
	v_div_fmas_f32 v84, v84, v91, v92
	v_div_fixup_f32 v83, v84, v83, 2.0
	v_sub_f32_e32 v83, 1.0, v83
	v_mul_f32_e32 v84, 0.5, v85
	v_add_f32_e32 v83, 1.0, v83
	v_mul_f32_e32 v83, v84, v83
	v_mul_f32_e32 v84, 0x3d372713, v78
	v_mul_f32_e32 v84, v78, v84
	v_fma_f32 v84, v78, v84, v78
	v_mul_f32_e32 v84, 0x3f4c422a, v84
	v_add_f32_e32 v84, v84, v84
	v_mul_f32_e32 v84, 0x3fb8aa3b, v84
	v_exp_f32_e32 v84, v84
	v_or_b32_e32 v90, v124, v148
	v_ashrrev_i32_e32 v91, 31, v90
	v_cvt_pk_bf16_f32 v89, v82, v83
	v_add_f32_e32 v84, 1.0, v84
	v_div_scale_f32 v85, s[28:29], v84, v84, 2.0
	v_lshlrev_b64 v[82:83], 11, v[90:91]
	v_rcp_f32_e32 v90, v85
	v_lshl_add_u64 v[82:83], v[138:139], 0, v[82:83]
	global_store_dwordx4 v[82:83], v[86:89], off
	v_mul_f32_e32 v78, 0.5, v78
	v_fma_f32 v83, -v85, v90, 1.0
	v_fmac_f32_e32 v90, v83, v90
	v_div_scale_f32 v83, vcc, 2.0, v84, 2.0
	v_mul_f32_e32 v86, v83, v90
	v_fma_f32 v87, -v85, v86, v83
	v_fmac_f32_e32 v86, v87, v90
	v_fma_f32 v83, -v85, v86, v83
	v_mul_f32_e32 v85, 0x3d372713, v79
	v_mul_f32_e32 v85, v79, v85
	v_fma_f32 v85, v79, v85, v79
	v_mul_f32_e32 v85, 0x3f4c422a, v85
	v_add_f32_e32 v85, v85, v85
	v_mul_f32_e32 v85, 0x3fb8aa3b, v85
	v_exp_f32_e32 v85, v85
	v_div_fmas_f32 v83, v83, v90, v86
	v_div_fixup_f32 v83, v83, v84, 2.0
	v_sub_f32_e32 v83, 1.0, v83
	v_add_f32_e32 v84, 1.0, v85
	v_div_scale_f32 v85, s[28:29], v84, v84, 2.0
	v_rcp_f32_e32 v86, v85
	v_add_f32_e32 v83, 1.0, v83
	v_mul_f32_e32 v78, v78, v83
	v_mul_f32_e32 v79, 0.5, v79
	v_fma_f32 v83, -v85, v86, 1.0
	v_fmac_f32_e32 v86, v83, v86
	v_div_scale_f32 v83, vcc, 2.0, v84, 2.0
	v_mul_f32_e32 v87, v83, v86
	v_fma_f32 v88, -v85, v87, v83
	v_fmac_f32_e32 v87, v88, v86
	v_fma_f32 v83, -v85, v87, v83
	v_mul_f32_e32 v85, 0x3d372713, v80
	v_mul_f32_e32 v85, v80, v85
	v_fma_f32 v85, v80, v85, v80
	v_mul_f32_e32 v85, 0x3f4c422a, v85
	v_add_f32_e32 v85, v85, v85
	v_mul_f32_e32 v85, 0x3fb8aa3b, v85
	v_exp_f32_e32 v85, v85
	v_div_fmas_f32 v83, v83, v86, v87
	v_div_fixup_f32 v83, v83, v84, 2.0
	v_sub_f32_e32 v83, 1.0, v83
	v_add_f32_e32 v84, 1.0, v85
	v_div_scale_f32 v85, s[28:29], v84, v84, 2.0
	v_rcp_f32_e32 v86, v85
	v_add_f32_e32 v83, 1.0, v83
	v_mul_f32_e32 v79, v79, v83
	v_cvt_pk_bf16_f32 v78, v78, v79
	v_fma_f32 v79, -v85, v86, 1.0
	v_fmac_f32_e32 v86, v79, v86
	v_div_scale_f32 v79, vcc, 2.0, v84, 2.0
	v_mul_f32_e32 v83, v79, v86
	v_fma_f32 v87, -v85, v83, v79
	v_fmac_f32_e32 v83, v87, v86
	v_fma_f32 v79, -v85, v83, v79
	v_mul_f32_e32 v85, 0x3d372713, v81
	v_mul_f32_e32 v85, v81, v85
	v_fma_f32 v85, v81, v85, v81
	v_mul_f32_e32 v85, 0x3f4c422a, v85
	v_add_f32_e32 v85, v85, v85
	v_mul_f32_e32 v85, 0x3fb8aa3b, v85
	v_exp_f32_e32 v85, v85
	v_div_fmas_f32 v79, v79, v86, v83
	v_div_fixup_f32 v79, v79, v84, 2.0
	v_sub_f32_e32 v79, 1.0, v79
	v_add_f32_e32 v83, 1.0, v85
	v_div_scale_f32 v84, s[28:29], v83, v83, 2.0
	v_rcp_f32_e32 v85, v84
	v_mul_f32_e32 v80, 0.5, v80
	v_add_f32_e32 v79, 1.0, v79
	v_mul_f32_e32 v79, v80, v79
	v_fma_f32 v80, -v84, v85, 1.0
	v_fmac_f32_e32 v85, v80, v85
	v_div_scale_f32 v80, vcc, 2.0, v83, 2.0
	v_mul_f32_e32 v86, v80, v85
	v_fma_f32 v87, -v84, v86, v80
	v_fmac_f32_e32 v86, v87, v85
	v_fma_f32 v80, -v84, v86, v80
	v_mul_f32_e32 v84, 0x3d372713, v74
	v_mul_f32_e32 v84, v74, v84
	v_fma_f32 v84, v74, v84, v74
	v_mul_f32_e32 v84, 0x3f4c422a, v84
	v_add_f32_e32 v84, v84, v84
	v_mul_f32_e32 v84, 0x3fb8aa3b, v84
	v_exp_f32_e32 v84, v84
; #define LAS __attribute__((address_space(3)))
; __device__ __forceinline__ unsigned cvt_pk_bf16(float lo, float hi) { unsigned r; asm volatile("v_cvt_pk_bf16_f32 %0, %1, %2" : "=v"(r) : "v"(lo), "v"(hi)); return r; }
; __device__ __forceinline__ float gelu_tanh(float x) { const float z = 0.7978845608f * (x + 0.044715f * x * x * x); const float th = 1.0f - 2.0f / (__expf(2.0f * z) + 1.0f); return 0.5f * x * (1.0f + th); }
;     __device__ __forceinline__ void operator()(const f32x4 (&acc)[2][2][4][2], const Unit& u, int ui, const LAS float* rtab, int wr, int wc, int fr, int fq) const {
;         const int g = u.pm; const int n0 = wr * 64 + fr; const int lc0 = (u.pn & 1) * 256 + wc * 32 + 8 * fq;
; #pragma unroll
;         for (int ai = 0; ai < 2; ++ai)
; #pragma unroll
;             for (int m = 0; m < 4; ++m) {
;                 const int n = n0 + ai * HALF + m * 16;
; #pragma unroll
;                 for (int bj = 0; bj < 2; ++bj) {
;                     const int lc = lc0 + bj * HALF, t = lc >> 4, co = lc & 15; const int token = n * 32 + t;
;                     const f32x4 a0 = acc[ai][bj][m][0], a1 = acc[ai][bj][m][1];
;                     u32x4 w; w.x = cvt_pk_bf16(gelu_tanh(a0[0]), gelu_tanh(a0[1])); w.y = cvt_pk_bf16(gelu_tanh(a0[2]), gelu_tanh(a0[3]));
;                     w.z = cvt_pk_bf16(gelu_tanh(a1[0]), gelu_tanh(a1[1])); w.w = cvt_pk_bf16(gelu_tanh(a1[2]), gelu_tanh(a1[3]));
;                     *(u32x4*)(Y + (size_t)token * 1024 + 16 * g + co) = w;
	v_div_fmas_f32 v80, v80, v85, v86
	v_div_fixup_f32 v80, v80, v83, 2.0
	v_sub_f32_e32 v80, 1.0, v80
	v_add_f32_e32 v83, 1.0, v84
	v_div_scale_f32 v84, s[28:29], v83, v83, 2.0
	v_rcp_f32_e32 v85, v84
	v_mul_f32_e32 v81, 0.5, v81
	v_add_f32_e32 v80, 1.0, v80
	v_mul_f32_e32 v80, v81, v80
	v_cvt_pk_bf16_f32 v79, v79, v80
	v_fma_f32 v80, -v84, v85, 1.0
	v_fmac_f32_e32 v85, v80, v85
	v_div_scale_f32 v80, vcc, 2.0, v83, 2.0
	v_mul_f32_e32 v81, v80, v85
	v_fma_f32 v86, -v84, v81, v80
	v_fmac_f32_e32 v81, v86, v85
	v_fma_f32 v80, -v84, v81, v80
	v_mul_f32_e32 v84, 0x3d372713, v75
	v_mul_f32_e32 v84, v75, v84
	v_fma_f32 v84, v75, v84, v75
	v_mul_f32_e32 v84, 0x3f4c422a, v84
	v_add_f32_e32 v84, v84, v84
	v_mul_f32_e32 v84, 0x3fb8aa3b, v84
	v_exp_f32_e32 v84, v84
	v_div_fmas_f32 v80, v80, v85, v81
	v_div_fixup_f32 v80, v80, v83, 2.0
	v_sub_f32_e32 v80, 1.0, v80
	v_add_f32_e32 v81, 1.0, v84
	v_div_scale_f32 v83, s[28:29], v81, v81, 2.0
	v_rcp_f32_e32 v84, v83
	v_mul_f32_e32 v74, 0.5, v74
	v_add_f32_e32 v80, 1.0, v80
	v_mul_f32_e32 v74, v74, v80
	v_fma_f32 v80, -v83, v84, 1.0
	v_fmac_f32_e32 v84, v80, v84
	v_div_scale_f32 v80, vcc, 2.0, v81, 2.0
	v_mul_f32_e32 v85, v80, v84
	v_fma_f32 v86, -v83, v85, v80
	v_fmac_f32_e32 v85, v86, v84
	v_fma_f32 v80, -v83, v85, v80
	v_mul_f32_e32 v83, 0x3d372713, v76
	v_mul_f32_e32 v83, v76, v83
	v_fma_f32 v83, v76, v83, v76
	v_mul_f32_e32 v83, 0x3f4c422a, v83
	v_add_f32_e32 v83, v83, v83
	v_mul_f32_e32 v83, 0x3fb8aa3b, v83
	v_exp_f32_e32 v83, v83
	v_div_fmas_f32 v80, v80, v84, v85
	v_div_fixup_f32 v80, v80, v81, 2.0
	v_sub_f32_e32 v80, 1.0, v80
	v_add_f32_e32 v81, 1.0, v83
	v_div_scale_f32 v83, s[28:29], v81, v81, 2.0
	v_rcp_f32_e32 v84, v83
	v_mul_f32_e32 v75, 0.5, v75
	v_add_f32_e32 v80, 1.0, v80
	v_mul_f32_e32 v75, v75, v80
	v_cvt_pk_bf16_f32 v80, v74, v75
	v_fma_f32 v74, -v83, v84, 1.0
	v_fmac_f32_e32 v84, v74, v84
	v_div_scale_f32 v74, vcc, 2.0, v81, 2.0
	v_mul_f32_e32 v75, v74, v84
	v_fma_f32 v85, -v83, v75, v74
	v_fmac_f32_e32 v75, v85, v84
	v_fma_f32 v74, -v83, v75, v74
	v_mul_f32_e32 v83, 0x3d372713, v77
	v_mul_f32_e32 v83, v77, v83
	v_fma_f32 v83, v77, v83, v77
	v_mul_f32_e32 v83, 0x3f4c422a, v83
	v_add_f32_e32 v83, v83, v83
	v_mul_f32_e32 v83, 0x3fb8aa3b, v83
	v_exp_f32_e32 v83, v83
	v_div_fmas_f32 v74, v74, v84, v75
	v_div_fixup_f32 v74, v74, v81, 2.0
	v_sub_f32_e32 v74, 1.0, v74
	v_add_f32_e32 v75, 1.0, v83
	v_div_scale_f32 v81, s[28:29], v75, v75, 2.0
	v_rcp_f32_e32 v83, v81
	v_mul_f32_e32 v76, 0.5, v76
	v_add_f32_e32 v74, 1.0, v74
	v_mul_f32_e32 v74, v76, v74
	v_fma_f32 v76, -v81, v83, 1.0
	v_fmac_f32_e32 v83, v76, v83
	v_div_scale_f32 v76, vcc, 2.0, v75, 2.0
	v_mul_f32_e32 v84, v76, v83
	v_fma_f32 v85, -v81, v84, v76
	v_fmac_f32_e32 v84, v85, v83
	v_fma_f32 v76, -v81, v84, v76
	v_div_fmas_f32 v76, v76, v83, v84
	v_div_fixup_f32 v75, v76, v75, 2.0
	v_sub_f32_e32 v75, 1.0, v75
	v_mul_f32_e32 v76, 0.5, v77
	v_add_f32_e32 v75, 1.0, v75
	v_mul_f32_e32 v75, v76, v75
	v_mul_f32_e32 v76, 0x3d372713, v70
	v_mul_f32_e32 v76, v70, v76
	v_fma_f32 v76, v70, v76, v70
	v_mul_f32_e32 v76, 0x3f4c422a, v76
	v_add_f32_e32 v76, v76, v76
	v_mul_f32_e32 v76, 0x3fb8aa3b, v76
	v_exp_f32_e32 v76, v76
	v_or_b32_e32 v82, v171, v149
	v_ashrrev_i32_e32 v83, 31, v82
	v_cvt_pk_bf16_f32 v81, v74, v75
	v_add_f32_e32 v76, 1.0, v76
	v_div_scale_f32 v77, s[28:29], v76, v76, 2.0
	v_lshlrev_b64 v[74:75], 11, v[82:83]
	v_rcp_f32_e32 v82, v77
	v_lshl_add_u64 v[74:75], v[138:139], 0, v[74:75]
	global_store_dwordx4 v[74:75], v[78:81], off
	v_mul_f32_e32 v70, 0.5, v70
	v_fma_f32 v75, -v77, v82, 1.0
	v_fmac_f32_e32 v82, v75, v82
	v_div_scale_f32 v75, vcc, 2.0, v76, 2.0
	v_mul_f32_e32 v78, v75, v82
	v_fma_f32 v79, -v77, v78, v75
	v_fmac_f32_e32 v78, v79, v82
	v_fma_f32 v75, -v77, v78, v75
	v_mul_f32_e32 v77, 0x3d372713, v71
	v_mul_f32_e32 v77, v71, v77
	v_fma_f32 v77, v71, v77, v71
	v_mul_f32_e32 v77, 0x3f4c422a, v77
	v_add_f32_e32 v77, v77, v77
	v_mul_f32_e32 v77, 0x3fb8aa3b, v77
	v_exp_f32_e32 v77, v77
	v_div_fmas_f32 v75, v75, v82, v78
	v_div_fixup_f32 v75, v75, v76, 2.0
	v_sub_f32_e32 v75, 1.0, v75
	v_add_f32_e32 v76, 1.0, v77
	v_div_scale_f32 v77, s[28:29], v76, v76, 2.0
	v_rcp_f32_e32 v78, v77
	v_add_f32_e32 v75, 1.0, v75
	v_mul_f32_e32 v70, v70, v75
	v_mul_f32_e32 v71, 0.5, v71
	v_fma_f32 v75, -v77, v78, 1.0
	v_fmac_f32_e32 v78, v75, v78
	v_div_scale_f32 v75, vcc, 2.0, v76, 2.0
	v_mul_f32_e32 v79, v75, v78
	v_fma_f32 v80, -v77, v79, v75
	v_fmac_f32_e32 v79, v80, v78
	v_fma_f32 v75, -v77, v79, v75
	v_mul_f32_e32 v77, 0x3d372713, v72
	v_mul_f32_e32 v77, v72, v77
	v_fma_f32 v77, v72, v77, v72
	v_mul_f32_e32 v77, 0x3f4c422a, v77
	v_add_f32_e32 v77, v77, v77
	v_mul_f32_e32 v77, 0x3fb8aa3b, v77
	v_exp_f32_e32 v77, v77
	v_div_fmas_f32 v75, v75, v78, v79
	v_div_fixup_f32 v75, v75, v76, 2.0
	v_sub_f32_e32 v75, 1.0, v75
	v_add_f32_e32 v76, 1.0, v77
	v_div_scale_f32 v77, s[28:29], v76, v76, 2.0
	v_rcp_f32_e32 v78, v77
	v_add_f32_e32 v75, 1.0, v75
	v_mul_f32_e32 v71, v71, v75
	v_cvt_pk_bf16_f32 v70, v70, v71
	v_fma_f32 v71, -v77, v78, 1.0
	v_fmac_f32_e32 v78, v71, v78
	v_div_scale_f32 v71, vcc, 2.0, v76, 2.0
	v_mul_f32_e32 v75, v71, v78
	v_fma_f32 v79, -v77, v75, v71
	v_fmac_f32_e32 v75, v79, v78
	v_fma_f32 v71, -v77, v75, v71
	v_mul_f32_e32 v77, 0x3d372713, v73
	v_mul_f32_e32 v77, v73, v77
	v_fma_f32 v77, v73, v77, v73
	v_mul_f32_e32 v77, 0x3f4c422a, v77
	v_add_f32_e32 v77, v77, v77
	v_mul_f32_e32 v77, 0x3fb8aa3b, v77
	v_exp_f32_e32 v77, v77
	v_div_fmas_f32 v71, v71, v78, v75
	v_div_fixup_f32 v71, v71, v76, 2.0
	v_sub_f32_e32 v71, 1.0, v71
	v_add_f32_e32 v75, 1.0, v77
	v_div_scale_f32 v76, s[28:29], v75, v75, 2.0
	v_rcp_f32_e32 v77, v76
; #define LAS __attribute__((address_space(3)))
; __device__ __forceinline__ unsigned cvt_pk_bf16(float lo, float hi) { unsigned r; asm volatile("v_cvt_pk_bf16_f32 %0, %1, %2" : "=v"(r) : "v"(lo), "v"(hi)); return r; }
; __device__ __forceinline__ float gelu_tanh(float x) { const float z = 0.7978845608f * (x + 0.044715f * x * x * x); const float th = 1.0f - 2.0f / (__expf(2.0f * z) + 1.0f); return 0.5f * x * (1.0f + th); }
;     __device__ __forceinline__ void operator()(const f32x4 (&acc)[2][2][4][2], const Unit& u, int ui, const LAS float* rtab, int wr, int wc, int fr, int fq) const {
;         const int g = u.pm; const int n0 = wr * 64 + fr; const int lc0 = (u.pn & 1) * 256 + wc * 32 + 8 * fq;
; #pragma unroll
;         for (int ai = 0; ai < 2; ++ai)
; #pragma unroll
;             for (int m = 0; m < 4; ++m) {
;                 const int n = n0 + ai * HALF + m * 16;
; #pragma unroll
;                 for (int bj = 0; bj < 2; ++bj) {
;                     const int lc = lc0 + bj * HALF, t = lc >> 4, co = lc & 15; const int token = n * 32 + t;
;                     const f32x4 a0 = acc[ai][bj][m][0], a1 = acc[ai][bj][m][1];
;                     u32x4 w; w.x = cvt_pk_bf16(gelu_tanh(a0[0]), gelu_tanh(a0[1])); w.y = cvt_pk_bf16(gelu_tanh(a0[2]), gelu_tanh(a0[3]));
;                     w.z = cvt_pk_bf16(gelu_tanh(a1[0]), gelu_tanh(a1[1])); w.w = cvt_pk_bf16(gelu_tanh(a1[2]), gelu_tanh(a1[3]));
;                     *(u32x4*)(Y + (size_t)token * 1024 + 16 * g + co) = w;
	v_mul_f32_e32 v72, 0.5, v72
	v_add_f32_e32 v71, 1.0, v71
	v_mul_f32_e32 v71, v72, v71
	v_fma_f32 v72, -v76, v77, 1.0
	v_fmac_f32_e32 v77, v72, v77
	v_div_scale_f32 v72, vcc, 2.0, v75, 2.0
	v_mul_f32_e32 v78, v72, v77
	v_fma_f32 v79, -v76, v78, v72
	v_fmac_f32_e32 v78, v79, v77
	v_fma_f32 v72, -v76, v78, v72
	v_mul_f32_e32 v76, 0x3d372713, v66
	v_mul_f32_e32 v76, v66, v76
	v_fma_f32 v76, v66, v76, v66
	v_mul_f32_e32 v76, 0x3f4c422a, v76
	v_add_f32_e32 v76, v76, v76
	v_mul_f32_e32 v76, 0x3fb8aa3b, v76
	v_exp_f32_e32 v76, v76
	v_div_fmas_f32 v72, v72, v77, v78
	v_div_fixup_f32 v72, v72, v75, 2.0
	v_sub_f32_e32 v72, 1.0, v72
	v_add_f32_e32 v75, 1.0, v76
	v_div_scale_f32 v76, s[28:29], v75, v75, 2.0
	v_rcp_f32_e32 v77, v76
	v_mul_f32_e32 v73, 0.5, v73
	v_add_f32_e32 v72, 1.0, v72
	v_mul_f32_e32 v72, v73, v72
	v_cvt_pk_bf16_f32 v71, v71, v72
	v_fma_f32 v72, -v76, v77, 1.0
	v_fmac_f32_e32 v77, v72, v77
	v_div_scale_f32 v72, vcc, 2.0, v75, 2.0
	v_mul_f32_e32 v73, v72, v77
	v_fma_f32 v78, -v76, v73, v72
	v_fmac_f32_e32 v73, v78, v77
	v_fma_f32 v72, -v76, v73, v72
	v_mul_f32_e32 v76, 0x3d372713, v67
	v_mul_f32_e32 v76, v67, v76
	v_fma_f32 v76, v67, v76, v67
	v_mul_f32_e32 v76, 0x3f4c422a, v76
	v_add_f32_e32 v76, v76, v76
	v_mul_f32_e32 v76, 0x3fb8aa3b, v76
	v_exp_f32_e32 v76, v76
	v_div_fmas_f32 v72, v72, v77, v73
	v_div_fixup_f32 v72, v72, v75, 2.0
	v_sub_f32_e32 v72, 1.0, v72
	v_add_f32_e32 v73, 1.0, v76
	v_div_scale_f32 v75, s[28:29], v73, v73, 2.0
	v_rcp_f32_e32 v76, v75
	v_mul_f32_e32 v66, 0.5, v66
	v_add_f32_e32 v72, 1.0, v72
	v_mul_f32_e32 v66, v66, v72
	v_fma_f32 v72, -v75, v76, 1.0
	v_fmac_f32_e32 v76, v72, v76
	v_div_scale_f32 v72, vcc, 2.0, v73, 2.0
	v_mul_f32_e32 v77, v72, v76
	v_fma_f32 v78, -v75, v77, v72
	v_fmac_f32_e32 v77, v78, v76
	v_fma_f32 v72, -v75, v77, v72
	v_mul_f32_e32 v75, 0x3d372713, v68
	v_mul_f32_e32 v75, v68, v75
	v_fma_f32 v75, v68, v75, v68
	v_mul_f32_e32 v75, 0x3f4c422a, v75
	v_add_f32_e32 v75, v75, v75
	v_mul_f32_e32 v75, 0x3fb8aa3b, v75
	v_exp_f32_e32 v75, v75
	v_div_fmas_f32 v72, v72, v76, v77
	v_div_fixup_f32 v72, v72, v73, 2.0
	v_sub_f32_e32 v72, 1.0, v72
	v_add_f32_e32 v73, 1.0, v75
	v_div_scale_f32 v75, s[28:29], v73, v73, 2.0
	v_rcp_f32_e32 v76, v75
	v_mul_f32_e32 v67, 0.5, v67
	v_add_f32_e32 v72, 1.0, v72
	v_mul_f32_e32 v67, v67, v72
	v_cvt_pk_bf16_f32 v72, v66, v67
	v_fma_f32 v66, -v75, v76, 1.0
	v_fmac_f32_e32 v76, v66, v76
	v_div_scale_f32 v66, vcc, 2.0, v73, 2.0
	v_mul_f32_e32 v67, v66, v76
	v_fma_f32 v77, -v75, v67, v66
	v_fmac_f32_e32 v67, v77, v76
	v_fma_f32 v66, -v75, v67, v66
	v_mul_f32_e32 v75, 0x3d372713, v69
	v_mul_f32_e32 v75, v69, v75
	v_fma_f32 v75, v69, v75, v69
	v_mul_f32_e32 v75, 0x3f4c422a, v75
	v_add_f32_e32 v75, v75, v75
	v_mul_f32_e32 v75, 0x3fb8aa3b, v75
	v_exp_f32_e32 v75, v75
	v_div_fmas_f32 v66, v66, v76, v67
	v_div_fixup_f32 v66, v66, v73, 2.0
	v_sub_f32_e32 v66, 1.0, v66
	v_add_f32_e32 v67, 1.0, v75
	v_div_scale_f32 v73, s[28:29], v67, v67, 2.0
	v_rcp_f32_e32 v75, v73
	v_mul_f32_e32 v68, 0.5, v68
	v_add_f32_e32 v66, 1.0, v66
	v_mul_f32_e32 v66, v68, v66
	v_fma_f32 v68, -v73, v75, 1.0
	v_fmac_f32_e32 v75, v68, v75
	v_div_scale_f32 v68, vcc, 2.0, v67, 2.0
	v_mul_f32_e32 v76, v68, v75
	v_fma_f32 v77, -v73, v76, v68
	v_fmac_f32_e32 v76, v77, v75
	v_fma_f32 v68, -v73, v76, v68
	v_div_fmas_f32 v68, v68, v75, v76
	v_div_fixup_f32 v67, v68, v67, 2.0
	v_sub_f32_e32 v67, 1.0, v67
	v_mul_f32_e32 v68, 0.5, v69
	v_add_f32_e32 v67, 1.0, v67
	v_mul_f32_e32 v67, v68, v67
	v_mul_f32_e32 v68, 0x3d372713, v62
	v_mul_f32_e32 v68, v62, v68
	v_fma_f32 v68, v62, v68, v62
	v_mul_f32_e32 v68, 0x3f4c422a, v68
	v_add_f32_e32 v68, v68, v68
	v_mul_f32_e32 v68, 0x3fb8aa3b, v68
	v_exp_f32_e32 v68, v68
	v_or_b32_e32 v74, v124, v149
	v_ashrrev_i32_e32 v75, 31, v74
	v_cvt_pk_bf16_f32 v73, v66, v67
	v_add_f32_e32 v68, 1.0, v68
	v_div_scale_f32 v69, s[28:29], v68, v68, 2.0
	v_lshlrev_b64 v[66:67], 11, v[74:75]
	v_rcp_f32_e32 v74, v69
	v_lshl_add_u64 v[66:67], v[138:139], 0, v[66:67]
	global_store_dwordx4 v[66:67], v[70:73], off
	v_mul_f32_e32 v62, 0.5, v62
	v_fma_f32 v67, -v69, v74, 1.0
	v_fmac_f32_e32 v74, v67, v74
	v_div_scale_f32 v67, vcc, 2.0, v68, 2.0
	v_mul_f32_e32 v70, v67, v74
	v_fma_f32 v71, -v69, v70, v67
	v_fmac_f32_e32 v70, v71, v74
	v_fma_f32 v67, -v69, v70, v67
	v_mul_f32_e32 v69, 0x3d372713, v63
	v_mul_f32_e32 v69, v63, v69
	v_fma_f32 v69, v63, v69, v63
	v_mul_f32_e32 v69, 0x3f4c422a, v69
	v_add_f32_e32 v69, v69, v69
	v_mul_f32_e32 v69, 0x3fb8aa3b, v69
	v_exp_f32_e32 v69, v69
	v_div_fmas_f32 v67, v67, v74, v70
	v_div_fixup_f32 v67, v67, v68, 2.0
	v_sub_f32_e32 v67, 1.0, v67
	v_add_f32_e32 v68, 1.0, v69
	v_div_scale_f32 v69, s[28:29], v68, v68, 2.0
	v_rcp_f32_e32 v70, v69
	v_add_f32_e32 v67, 1.0, v67
	v_mul_f32_e32 v62, v62, v67
	v_mul_f32_e32 v63, 0.5, v63
	v_fma_f32 v67, -v69, v70, 1.0
	v_fmac_f32_e32 v70, v67, v70
	v_div_scale_f32 v67, vcc, 2.0, v68, 2.0
	v_mul_f32_e32 v71, v67, v70
	v_fma_f32 v72, -v69, v71, v67
	v_fmac_f32_e32 v71, v72, v70
	v_fma_f32 v67, -v69, v71, v67
	v_mul_f32_e32 v69, 0x3d372713, v64
	v_mul_f32_e32 v69, v64, v69
	v_fma_f32 v69, v64, v69, v64
	v_mul_f32_e32 v69, 0x3f4c422a, v69
	v_add_f32_e32 v69, v69, v69
	v_mul_f32_e32 v69, 0x3fb8aa3b, v69
	v_exp_f32_e32 v69, v69
	v_div_fmas_f32 v67, v67, v70, v71
	v_div_fixup_f32 v67, v67, v68, 2.0
	v_sub_f32_e32 v67, 1.0, v67
	v_add_f32_e32 v68, 1.0, v69
	v_div_scale_f32 v69, s[28:29], v68, v68, 2.0
	v_rcp_f32_e32 v70, v69
	v_add_f32_e32 v67, 1.0, v67
	v_mul_f32_e32 v63, v63, v67
	v_cvt_pk_bf16_f32 v62, v62, v63
	v_fma_f32 v63, -v69, v70, 1.0
	v_fmac_f32_e32 v70, v63, v70
	v_div_scale_f32 v63, vcc, 2.0, v68, 2.0
	v_mul_f32_e32 v67, v63, v70
; #define LAS __attribute__((address_space(3)))
; __device__ __forceinline__ unsigned cvt_pk_bf16(float lo, float hi) { unsigned r; asm volatile("v_cvt_pk_bf16_f32 %0, %1, %2" : "=v"(r) : "v"(lo), "v"(hi)); return r; }
; __device__ __forceinline__ float gelu_tanh(float x) { const float z = 0.7978845608f * (x + 0.044715f * x * x * x); const float th = 1.0f - 2.0f / (__expf(2.0f * z) + 1.0f); return 0.5f * x * (1.0f + th); }
;     __device__ __forceinline__ void operator()(const f32x4 (&acc)[2][2][4][2], const Unit& u, int ui, const LAS float* rtab, int wr, int wc, int fr, int fq) const {
;         const int g = u.pm; const int n0 = wr * 64 + fr; const int lc0 = (u.pn & 1) * 256 + wc * 32 + 8 * fq;
; #pragma unroll
;         for (int ai = 0; ai < 2; ++ai)
; #pragma unroll
;             for (int m = 0; m < 4; ++m) {
;                 const int n = n0 + ai * HALF + m * 16;
; #pragma unroll
;                 for (int bj = 0; bj < 2; ++bj) {
;                     const int lc = lc0 + bj * HALF, t = lc >> 4, co = lc & 15; const int token = n * 32 + t;
;                     const f32x4 a0 = acc[ai][bj][m][0], a1 = acc[ai][bj][m][1];
;                     u32x4 w; w.x = cvt_pk_bf16(gelu_tanh(a0[0]), gelu_tanh(a0[1])); w.y = cvt_pk_bf16(gelu_tanh(a0[2]), gelu_tanh(a0[3]));
;                     w.z = cvt_pk_bf16(gelu_tanh(a1[0]), gelu_tanh(a1[1])); w.w = cvt_pk_bf16(gelu_tanh(a1[2]), gelu_tanh(a1[3]));
;                     *(u32x4*)(Y + (size_t)token * 1024 + 16 * g + co) = w;
	v_fma_f32 v71, -v69, v67, v63
	v_fmac_f32_e32 v67, v71, v70
	v_fma_f32 v63, -v69, v67, v63
	v_mul_f32_e32 v69, 0x3d372713, v65
	v_mul_f32_e32 v69, v65, v69
	v_fma_f32 v69, v65, v69, v65
	v_mul_f32_e32 v69, 0x3f4c422a, v69
	v_add_f32_e32 v69, v69, v69
	v_mul_f32_e32 v69, 0x3fb8aa3b, v69
	v_exp_f32_e32 v69, v69
	v_div_fmas_f32 v63, v63, v70, v67
	v_div_fixup_f32 v63, v63, v68, 2.0
	v_sub_f32_e32 v63, 1.0, v63
	v_add_f32_e32 v67, 1.0, v69
	v_div_scale_f32 v68, s[28:29], v67, v67, 2.0
	v_rcp_f32_e32 v69, v68
	v_mul_f32_e32 v64, 0.5, v64
	v_add_f32_e32 v63, 1.0, v63
	v_mul_f32_e32 v63, v64, v63
	v_fma_f32 v64, -v68, v69, 1.0
	v_fmac_f32_e32 v69, v64, v69
	v_div_scale_f32 v64, vcc, 2.0, v67, 2.0
	v_mul_f32_e32 v70, v64, v69
	v_fma_f32 v71, -v68, v70, v64
	v_fmac_f32_e32 v70, v71, v69
	v_fma_f32 v64, -v68, v70, v64
	v_mul_f32_e32 v68, 0x3d372713, v58
	v_mul_f32_e32 v68, v58, v68
	v_fma_f32 v68, v58, v68, v58
	v_mul_f32_e32 v68, 0x3f4c422a, v68
	v_add_f32_e32 v68, v68, v68
	v_mul_f32_e32 v68, 0x3fb8aa3b, v68
	v_exp_f32_e32 v68, v68
	v_div_fmas_f32 v64, v64, v69, v70
	v_div_fixup_f32 v64, v64, v67, 2.0
	v_sub_f32_e32 v64, 1.0, v64
	v_add_f32_e32 v67, 1.0, v68
	v_div_scale_f32 v68, s[28:29], v67, v67, 2.0
	v_rcp_f32_e32 v69, v68
	v_mul_f32_e32 v65, 0.5, v65
	v_add_f32_e32 v64, 1.0, v64
	v_mul_f32_e32 v64, v65, v64
	v_cvt_pk_bf16_f32 v63, v63, v64
	v_fma_f32 v64, -v68, v69, 1.0
	v_fmac_f32_e32 v69, v64, v69
	v_div_scale_f32 v64, vcc, 2.0, v67, 2.0
	v_mul_f32_e32 v65, v64, v69
	v_fma_f32 v70, -v68, v65, v64
	v_fmac_f32_e32 v65, v70, v69
	v_fma_f32 v64, -v68, v65, v64
	v_mul_f32_e32 v68, 0x3d372713, v59
	v_mul_f32_e32 v68, v59, v68
	v_fma_f32 v68, v59, v68, v59
	v_mul_f32_e32 v68, 0x3f4c422a, v68
	v_add_f32_e32 v68, v68, v68
	v_mul_f32_e32 v68, 0x3fb8aa3b, v68
	v_exp_f32_e32 v68, v68
	v_div_fmas_f32 v64, v64, v69, v65
	v_div_fixup_f32 v64, v64, v67, 2.0
	v_sub_f32_e32 v64, 1.0, v64
	v_add_f32_e32 v65, 1.0, v68
	v_div_scale_f32 v67, s[28:29], v65, v65, 2.0
	v_rcp_f32_e32 v68, v67
	v_mul_f32_e32 v58, 0.5, v58
	v_add_f32_e32 v64, 1.0, v64
	v_mul_f32_e32 v58, v58, v64
	v_fma_f32 v64, -v67, v68, 1.0
	v_fmac_f32_e32 v68, v64, v68
	v_div_scale_f32 v64, vcc, 2.0, v65, 2.0
	v_mul_f32_e32 v69, v64, v68
	v_fma_f32 v70, -v67, v69, v64
	v_fmac_f32_e32 v69, v70, v68
	v_fma_f32 v64, -v67, v69, v64
	v_mul_f32_e32 v67, 0x3d372713, v60
	v_mul_f32_e32 v67, v60, v67
	v_fma_f32 v67, v60, v67, v60
	v_mul_f32_e32 v67, 0x3f4c422a, v67
	v_add_f32_e32 v67, v67, v67
	v_mul_f32_e32 v67, 0x3fb8aa3b, v67
	v_exp_f32_e32 v67, v67
	v_div_fmas_f32 v64, v64, v68, v69
	v_div_fixup_f32 v64, v64, v65, 2.0
	v_sub_f32_e32 v64, 1.0, v64
	v_add_f32_e32 v65, 1.0, v67
	v_div_scale_f32 v67, s[28:29], v65, v65, 2.0
	v_rcp_f32_e32 v68, v67
	v_mul_f32_e32 v59, 0.5, v59
	v_add_f32_e32 v64, 1.0, v64
	v_mul_f32_e32 v59, v59, v64
	v_cvt_pk_bf16_f32 v64, v58, v59
	v_fma_f32 v58, -v67, v68, 1.0
	v_fmac_f32_e32 v68, v58, v68
	v_div_scale_f32 v58, vcc, 2.0, v65, 2.0
	v_mul_f32_e32 v59, v58, v68
	v_fma_f32 v69, -v67, v59, v58
	v_fmac_f32_e32 v59, v69, v68
	v_fma_f32 v58, -v67, v59, v58
	v_mul_f32_e32 v67, 0x3d372713, v61
	v_mul_f32_e32 v67, v61, v67
	v_fma_f32 v67, v61, v67, v61
	v_mul_f32_e32 v67, 0x3f4c422a, v67
	v_add_f32_e32 v67, v67, v67
	v_mul_f32_e32 v67, 0x3fb8aa3b, v67
	v_exp_f32_e32 v67, v67
	v_div_fmas_f32 v58, v58, v68, v59
	v_div_fixup_f32 v58, v58, v65, 2.0
	v_sub_f32_e32 v58, 1.0, v58
	v_add_f32_e32 v59, 1.0, v67
	v_div_scale_f32 v65, s[28:29], v59, v59, 2.0
	v_rcp_f32_e32 v67, v65
	v_mul_f32_e32 v60, 0.5, v60
	v_add_f32_e32 v58, 1.0, v58
	v_mul_f32_e32 v58, v60, v58
	v_fma_f32 v60, -v65, v67, 1.0
	v_fmac_f32_e32 v67, v60, v67
	v_div_scale_f32 v60, vcc, 2.0, v59, 2.0
	v_mul_f32_e32 v68, v60, v67
	v_fma_f32 v69, -v65, v68, v60
	v_fmac_f32_e32 v68, v69, v67
	v_fma_f32 v60, -v65, v68, v60
	v_div_fmas_f32 v60, v60, v67, v68
	v_div_fixup_f32 v59, v60, v59, 2.0
	v_sub_f32_e32 v59, 1.0, v59
	v_mul_f32_e32 v60, 0.5, v61
	v_add_f32_e32 v59, 1.0, v59
	v_mul_f32_e32 v59, v60, v59
	v_mul_f32_e32 v60, 0x3d372713, v54
	v_mul_f32_e32 v60, v54, v60
	v_fma_f32 v60, v54, v60, v54
	v_mul_f32_e32 v60, 0x3f4c422a, v60
	v_add_f32_e32 v60, v60, v60
	v_mul_f32_e32 v60, 0x3fb8aa3b, v60
	v_exp_f32_e32 v60, v60
	v_or_b32_e32 v66, v171, v150
	v_ashrrev_i32_e32 v67, 31, v66
	v_cvt_pk_bf16_f32 v65, v58, v59
	v_add_f32_e32 v60, 1.0, v60
	v_div_scale_f32 v61, s[28:29], v60, v60, 2.0
	v_lshlrev_b64 v[58:59], 11, v[66:67]
	v_rcp_f32_e32 v66, v61
	v_lshl_add_u64 v[58:59], v[138:139], 0, v[58:59]
	global_store_dwordx4 v[58:59], v[62:65], off
	v_mul_f32_e32 v54, 0.5, v54
	v_fma_f32 v59, -v61, v66, 1.0
	v_fmac_f32_e32 v66, v59, v66
	v_div_scale_f32 v59, vcc, 2.0, v60, 2.0
	v_mul_f32_e32 v62, v59, v66
	v_fma_f32 v63, -v61, v62, v59
	v_fmac_f32_e32 v62, v63, v66
	v_fma_f32 v59, -v61, v62, v59
	v_mul_f32_e32 v61, 0x3d372713, v55
	v_mul_f32_e32 v61, v55, v61
	v_fma_f32 v61, v55, v61, v55
	v_mul_f32_e32 v61, 0x3f4c422a, v61
	v_add_f32_e32 v61, v61, v61
	v_mul_f32_e32 v61, 0x3fb8aa3b, v61
	v_exp_f32_e32 v61, v61
	v_div_fmas_f32 v59, v59, v66, v62
	v_div_fixup_f32 v59, v59, v60, 2.0
	v_sub_f32_e32 v59, 1.0, v59
	v_add_f32_e32 v60, 1.0, v61
	v_div_scale_f32 v61, s[28:29], v60, v60, 2.0
	v_rcp_f32_e32 v62, v61
	v_add_f32_e32 v59, 1.0, v59
	v_mul_f32_e32 v54, v54, v59
	v_mul_f32_e32 v55, 0.5, v55
	v_fma_f32 v59, -v61, v62, 1.0
	v_fmac_f32_e32 v62, v59, v62
	v_div_scale_f32 v59, vcc, 2.0, v60, 2.0
	v_mul_f32_e32 v63, v59, v62
	v_fma_f32 v64, -v61, v63, v59
	v_fmac_f32_e32 v63, v64, v62
	v_fma_f32 v59, -v61, v63, v59
	v_mul_f32_e32 v61, 0x3d372713, v56
	v_mul_f32_e32 v61, v56, v61
	v_fma_f32 v61, v56, v61, v56
	v_mul_f32_e32 v61, 0x3f4c422a, v61
; #define LAS __attribute__((address_space(3)))
; __device__ __forceinline__ unsigned cvt_pk_bf16(float lo, float hi) { unsigned r; asm volatile("v_cvt_pk_bf16_f32 %0, %1, %2" : "=v"(r) : "v"(lo), "v"(hi)); return r; }
; __device__ __forceinline__ float gelu_tanh(float x) { const float z = 0.7978845608f * (x + 0.044715f * x * x * x); const float th = 1.0f - 2.0f / (__expf(2.0f * z) + 1.0f); return 0.5f * x * (1.0f + th); }
;     __device__ __forceinline__ void operator()(const f32x4 (&acc)[2][2][4][2], const Unit& u, int ui, const LAS float* rtab, int wr, int wc, int fr, int fq) const {
;         const int g = u.pm; const int n0 = wr * 64 + fr; const int lc0 = (u.pn & 1) * 256 + wc * 32 + 8 * fq;
; #pragma unroll
;         for (int ai = 0; ai < 2; ++ai)
; #pragma unroll
;             for (int m = 0; m < 4; ++m) {
;                 const int n = n0 + ai * HALF + m * 16;
; #pragma unroll
;                 for (int bj = 0; bj < 2; ++bj) {
;                     const int lc = lc0 + bj * HALF, t = lc >> 4, co = lc & 15; const int token = n * 32 + t;
;                     const f32x4 a0 = acc[ai][bj][m][0], a1 = acc[ai][bj][m][1];
;                     u32x4 w; w.x = cvt_pk_bf16(gelu_tanh(a0[0]), gelu_tanh(a0[1])); w.y = cvt_pk_bf16(gelu_tanh(a0[2]), gelu_tanh(a0[3]));
;                     w.z = cvt_pk_bf16(gelu_tanh(a1[0]), gelu_tanh(a1[1])); w.w = cvt_pk_bf16(gelu_tanh(a1[2]), gelu_tanh(a1[3]));
;                     *(u32x4*)(Y + (size_t)token * 1024 + 16 * g + co) = w;
;                 }
;             }
;     }
	v_add_f32_e32 v61, v61, v61
	v_mul_f32_e32 v61, 0x3fb8aa3b, v61
	v_exp_f32_e32 v61, v61
	v_div_fmas_f32 v59, v59, v62, v63
	v_div_fixup_f32 v59, v59, v60, 2.0
	v_sub_f32_e32 v59, 1.0, v59
	v_add_f32_e32 v60, 1.0, v61
	v_div_scale_f32 v61, s[28:29], v60, v60, 2.0
	v_rcp_f32_e32 v62, v61
	v_add_f32_e32 v59, 1.0, v59
	v_mul_f32_e32 v55, v55, v59
	v_cvt_pk_bf16_f32 v54, v54, v55
	v_fma_f32 v55, -v61, v62, 1.0
	v_fmac_f32_e32 v62, v55, v62
	v_div_scale_f32 v55, vcc, 2.0, v60, 2.0
	v_mul_f32_e32 v59, v55, v62
	v_fma_f32 v63, -v61, v59, v55
	v_fmac_f32_e32 v59, v63, v62
	v_fma_f32 v55, -v61, v59, v55
	v_mul_f32_e32 v61, 0x3d372713, v57
	v_mul_f32_e32 v61, v57, v61
	v_fma_f32 v61, v57, v61, v57
	v_mul_f32_e32 v61, 0x3f4c422a, v61
	v_add_f32_e32 v61, v61, v61
	v_mul_f32_e32 v61, 0x3fb8aa3b, v61
	v_exp_f32_e32 v61, v61
	v_div_fmas_f32 v55, v55, v62, v59
	v_div_fixup_f32 v55, v55, v60, 2.0
	v_sub_f32_e32 v55, 1.0, v55
	v_add_f32_e32 v59, 1.0, v61
	v_div_scale_f32 v60, s[28:29], v59, v59, 2.0
	v_rcp_f32_e32 v61, v60
	v_mul_f32_e32 v56, 0.5, v56
	v_add_f32_e32 v55, 1.0, v55
	v_mul_f32_e32 v55, v56, v55
	v_fma_f32 v56, -v60, v61, 1.0
	v_fmac_f32_e32 v61, v56, v61
	v_div_scale_f32 v56, vcc, 2.0, v59, 2.0
	v_mul_f32_e32 v62, v56, v61
	v_fma_f32 v63, -v60, v62, v56
	v_fmac_f32_e32 v62, v63, v61
	v_fma_f32 v56, -v60, v62, v56
	v_mul_f32_e32 v60, 0x3d372713, v50
	v_mul_f32_e32 v60, v50, v60
	v_fma_f32 v60, v50, v60, v50
	v_mul_f32_e32 v60, 0x3f4c422a, v60
	v_add_f32_e32 v60, v60, v60
	v_mul_f32_e32 v60, 0x3fb8aa3b, v60
	v_exp_f32_e32 v60, v60
	v_div_fmas_f32 v56, v56, v61, v62
	v_div_fixup_f32 v56, v56, v59, 2.0
	v_sub_f32_e32 v56, 1.0, v56
	v_add_f32_e32 v59, 1.0, v60
	v_div_scale_f32 v60, s[28:29], v59, v59, 2.0
	v_rcp_f32_e32 v61, v60
	v_mul_f32_e32 v57, 0.5, v57
	v_add_f32_e32 v56, 1.0, v56
	v_mul_f32_e32 v56, v57, v56
	v_cvt_pk_bf16_f32 v55, v55, v56
	v_fma_f32 v56, -v60, v61, 1.0
	v_fmac_f32_e32 v61, v56, v61
	v_div_scale_f32 v56, vcc, 2.0, v59, 2.0
	v_mul_f32_e32 v57, v56, v61
	v_fma_f32 v62, -v60, v57, v56
	v_fmac_f32_e32 v57, v62, v61
	v_fma_f32 v56, -v60, v57, v56
	v_mul_f32_e32 v60, 0x3d372713, v51
	v_mul_f32_e32 v60, v51, v60
	v_fma_f32 v60, v51, v60, v51
	v_mul_f32_e32 v60, 0x3f4c422a, v60
	v_add_f32_e32 v60, v60, v60
	v_mul_f32_e32 v60, 0x3fb8aa3b, v60
	v_exp_f32_e32 v60, v60
	v_div_fmas_f32 v56, v56, v61, v57
	v_div_fixup_f32 v56, v56, v59, 2.0
	v_sub_f32_e32 v56, 1.0, v56
	v_add_f32_e32 v57, 1.0, v60
	v_div_scale_f32 v59, s[28:29], v57, v57, 2.0
	v_rcp_f32_e32 v60, v59
	v_mul_f32_e32 v50, 0.5, v50
	v_add_f32_e32 v56, 1.0, v56
	v_mul_f32_e32 v50, v50, v56
	v_fma_f32 v56, -v59, v60, 1.0
	v_fmac_f32_e32 v60, v56, v60
	v_div_scale_f32 v56, vcc, 2.0, v57, 2.0
	v_mul_f32_e32 v61, v56, v60
	v_fma_f32 v62, -v59, v61, v56
	v_fmac_f32_e32 v61, v62, v60
	v_fma_f32 v56, -v59, v61, v56
	v_mul_f32_e32 v59, 0x3d372713, v52
	v_mul_f32_e32 v59, v52, v59
	v_fma_f32 v59, v52, v59, v52
	v_mul_f32_e32 v59, 0x3f4c422a, v59
	v_add_f32_e32 v59, v59, v59
	v_mul_f32_e32 v59, 0x3fb8aa3b, v59
	v_exp_f32_e32 v59, v59
	v_div_fmas_f32 v56, v56, v60, v61
	v_div_fixup_f32 v56, v56, v57, 2.0
	v_sub_f32_e32 v56, 1.0, v56
	v_add_f32_e32 v57, 1.0, v59
	v_div_scale_f32 v59, s[28:29], v57, v57, 2.0
	v_rcp_f32_e32 v60, v59
	v_mul_f32_e32 v51, 0.5, v51
	v_add_f32_e32 v56, 1.0, v56
	v_mul_f32_e32 v51, v51, v56
	v_cvt_pk_bf16_f32 v56, v50, v51
	v_fma_f32 v50, -v59, v60, 1.0
	v_fmac_f32_e32 v60, v50, v60
	v_div_scale_f32 v50, vcc, 2.0, v57, 2.0
	v_mul_f32_e32 v51, v50, v60
	v_fma_f32 v61, -v59, v51, v50
	v_fmac_f32_e32 v51, v61, v60
	v_fma_f32 v50, -v59, v51, v50
	v_mul_f32_e32 v59, 0x3d372713, v53
	v_mul_f32_e32 v59, v53, v59
	v_fma_f32 v59, v53, v59, v53
	v_mul_f32_e32 v59, 0x3f4c422a, v59
	v_add_f32_e32 v59, v59, v59
	v_mul_f32_e32 v59, 0x3fb8aa3b, v59
	v_exp_f32_e32 v59, v59
	v_div_fmas_f32 v50, v50, v60, v51
	v_div_fixup_f32 v50, v50, v57, 2.0
	v_sub_f32_e32 v50, 1.0, v50
	v_add_f32_e32 v51, 1.0, v59
	v_div_scale_f32 v57, s[28:29], v51, v51, 2.0
	v_rcp_f32_e32 v59, v57
	v_mul_f32_e32 v52, 0.5, v52
	v_add_f32_e32 v50, 1.0, v50
	v_mul_f32_e32 v50, v52, v50
	v_fma_f32 v52, -v57, v59, 1.0
	v_fmac_f32_e32 v59, v52, v59
	v_div_scale_f32 v52, vcc, 2.0, v51, 2.0
	v_mul_f32_e32 v60, v52, v59
	v_fma_f32 v61, -v57, v60, v52
	v_fmac_f32_e32 v60, v61, v59
	v_fma_f32 v52, -v57, v60, v52
	v_div_fmas_f32 v52, v52, v59, v60
	v_div_fixup_f32 v51, v52, v51, 2.0
	v_sub_f32_e32 v51, 1.0, v51
	v_mul_f32_e32 v52, 0.5, v53
	v_add_f32_e32 v51, 1.0, v51
	v_mul_f32_e32 v51, v52, v51
	v_mul_f32_e32 v52, 0x3d372713, v46
	v_mul_f32_e32 v52, v46, v52
	v_fma_f32 v52, v46, v52, v46
	v_mul_f32_e32 v52, 0x3f4c422a, v52
	v_add_f32_e32 v52, v52, v52
	v_mul_f32_e32 v52, 0x3fb8aa3b, v52
	v_exp_f32_e32 v52, v52
	v_or_b32_e32 v58, v124, v150
	v_ashrrev_i32_e32 v59, 31, v58
	v_cvt_pk_bf16_f32 v57, v50, v51
	v_add_f32_e32 v52, 1.0, v52
	v_div_scale_f32 v53, s[28:29], v52, v52, 2.0
	v_lshlrev_b64 v[50:51], 11, v[58:59]
	v_rcp_f32_e32 v58, v53
	v_lshl_add_u64 v[50:51], v[138:139], 0, v[50:51]
	global_store_dwordx4 v[50:51], v[54:57], off
	v_mul_f32_e32 v46, 0.5, v46
	v_fma_f32 v51, -v53, v58, 1.0
	v_fmac_f32_e32 v58, v51, v58
	v_div_scale_f32 v51, vcc, 2.0, v52, 2.0
	v_mul_f32_e32 v54, v51, v58
	v_fma_f32 v55, -v53, v54, v51
	v_fmac_f32_e32 v54, v55, v58
	v_fma_f32 v51, -v53, v54, v51
	v_mul_f32_e32 v53, 0x3d372713, v47
	v_mul_f32_e32 v53, v47, v53
	v_fma_f32 v53, v47, v53, v47
	v_mul_f32_e32 v53, 0x3f4c422a, v53
	v_add_f32_e32 v53, v53, v53
	v_mul_f32_e32 v53, 0x3fb8aa3b, v53
	v_exp_f32_e32 v53, v53
	v_div_fmas_f32 v51, v51, v58, v54
	v_div_fixup_f32 v51, v51, v52, 2.0
	v_sub_f32_e32 v51, 1.0, v51
	v_add_f32_e32 v52, 1.0, v53
; #define LAS __attribute__((address_space(3)))
; __device__ __forceinline__ unsigned cvt_pk_bf16(float lo, float hi) { unsigned r; asm volatile("v_cvt_pk_bf16_f32 %0, %1, %2" : "=v"(r) : "v"(lo), "v"(hi)); return r; }
; __device__ __forceinline__ float gelu_tanh(float x) { const float z = 0.7978845608f * (x + 0.044715f * x * x * x); const float th = 1.0f - 2.0f / (__expf(2.0f * z) + 1.0f); return 0.5f * x * (1.0f + th); }
;     __device__ __forceinline__ void operator()(const f32x4 (&acc)[2][2][4][2], const Unit& u, int ui, const LAS float* rtab, int wr, int wc, int fr, int fq) const {
;         const int g = u.pm; const int n0 = wr * 64 + fr; const int lc0 = (u.pn & 1) * 256 + wc * 32 + 8 * fq;
; #pragma unroll
;         for (int ai = 0; ai < 2; ++ai)
; #pragma unroll
;             for (int m = 0; m < 4; ++m) {
;                 const int n = n0 + ai * HALF + m * 16;
; #pragma unroll
;                 for (int bj = 0; bj < 2; ++bj) {
;                     const int lc = lc0 + bj * HALF, t = lc >> 4, co = lc & 15; const int token = n * 32 + t;
;                     const f32x4 a0 = acc[ai][bj][m][0], a1 = acc[ai][bj][m][1];
;                     u32x4 w; w.x = cvt_pk_bf16(gelu_tanh(a0[0]), gelu_tanh(a0[1])); w.y = cvt_pk_bf16(gelu_tanh(a0[2]), gelu_tanh(a0[3]));
;                     w.z = cvt_pk_bf16(gelu_tanh(a1[0]), gelu_tanh(a1[1])); w.w = cvt_pk_bf16(gelu_tanh(a1[2]), gelu_tanh(a1[3]));
;                     *(u32x4*)(Y + (size_t)token * 1024 + 16 * g + co) = w;
;                 }
;             }
;     }
	v_div_scale_f32 v53, s[28:29], v52, v52, 2.0
	v_rcp_f32_e32 v54, v53
	v_add_f32_e32 v51, 1.0, v51
	v_mul_f32_e32 v46, v46, v51
	v_mul_f32_e32 v47, 0.5, v47
	v_fma_f32 v51, -v53, v54, 1.0
	v_fmac_f32_e32 v54, v51, v54
	v_div_scale_f32 v51, vcc, 2.0, v52, 2.0
	v_mul_f32_e32 v55, v51, v54
	v_fma_f32 v56, -v53, v55, v51
	v_fmac_f32_e32 v55, v56, v54
	v_fma_f32 v51, -v53, v55, v51
	v_mul_f32_e32 v53, 0x3d372713, v48
	v_mul_f32_e32 v53, v48, v53
	v_fma_f32 v53, v48, v53, v48
	v_mul_f32_e32 v53, 0x3f4c422a, v53
	v_add_f32_e32 v53, v53, v53
	v_mul_f32_e32 v53, 0x3fb8aa3b, v53
	v_exp_f32_e32 v53, v53
	v_div_fmas_f32 v51, v51, v54, v55
	v_div_fixup_f32 v51, v51, v52, 2.0
	v_sub_f32_e32 v51, 1.0, v51
	v_add_f32_e32 v52, 1.0, v53
	v_div_scale_f32 v53, s[28:29], v52, v52, 2.0
	v_rcp_f32_e32 v54, v53
	v_add_f32_e32 v51, 1.0, v51
	v_mul_f32_e32 v47, v47, v51
	v_cvt_pk_bf16_f32 v46, v46, v47
	v_fma_f32 v47, -v53, v54, 1.0
	v_fmac_f32_e32 v54, v47, v54
	v_div_scale_f32 v47, vcc, 2.0, v52, 2.0
	v_mul_f32_e32 v51, v47, v54
	v_fma_f32 v55, -v53, v51, v47
	v_fmac_f32_e32 v51, v55, v54
	v_fma_f32 v47, -v53, v51, v47
	v_mul_f32_e32 v53, 0x3d372713, v49
	v_mul_f32_e32 v53, v49, v53
	v_fma_f32 v53, v49, v53, v49
	v_mul_f32_e32 v53, 0x3f4c422a, v53
	v_add_f32_e32 v53, v53, v53
	v_mul_f32_e32 v53, 0x3fb8aa3b, v53
	v_exp_f32_e32 v53, v53
	v_div_fmas_f32 v47, v47, v54, v51
	v_div_fixup_f32 v47, v47, v52, 2.0
	v_sub_f32_e32 v47, 1.0, v47
	v_add_f32_e32 v51, 1.0, v53
	v_div_scale_f32 v52, s[28:29], v51, v51, 2.0
	v_rcp_f32_e32 v53, v52
	v_mul_f32_e32 v48, 0.5, v48
	v_add_f32_e32 v47, 1.0, v47
	v_mul_f32_e32 v47, v48, v47
	v_fma_f32 v48, -v52, v53, 1.0
	v_fmac_f32_e32 v53, v48, v53
	v_div_scale_f32 v48, vcc, 2.0, v51, 2.0
	v_mul_f32_e32 v54, v48, v53
	v_fma_f32 v55, -v52, v54, v48
	v_fmac_f32_e32 v54, v55, v53
	v_fma_f32 v48, -v52, v54, v48
	v_mul_f32_e32 v52, 0x3d372713, v42
	v_mul_f32_e32 v52, v42, v52
	v_fma_f32 v52, v42, v52, v42
	v_mul_f32_e32 v52, 0x3f4c422a, v52
	v_add_f32_e32 v52, v52, v52
	v_mul_f32_e32 v52, 0x3fb8aa3b, v52
	v_exp_f32_e32 v52, v52
	v_div_fmas_f32 v48, v48, v53, v54
	v_div_fixup_f32 v48, v48, v51, 2.0
	v_sub_f32_e32 v48, 1.0, v48
	v_add_f32_e32 v51, 1.0, v52
	v_div_scale_f32 v52, s[28:29], v51, v51, 2.0
	v_rcp_f32_e32 v53, v52
	v_mul_f32_e32 v49, 0.5, v49
	v_add_f32_e32 v48, 1.0, v48
	v_mul_f32_e32 v48, v49, v48
	v_cvt_pk_bf16_f32 v47, v47, v48
	v_fma_f32 v48, -v52, v53, 1.0
	v_fmac_f32_e32 v53, v48, v53
	v_div_scale_f32 v48, vcc, 2.0, v51, 2.0
	v_mul_f32_e32 v49, v48, v53
	v_fma_f32 v54, -v52, v49, v48
	v_fmac_f32_e32 v49, v54, v53
	v_fma_f32 v48, -v52, v49, v48
	v_mul_f32_e32 v52, 0x3d372713, v43
	v_mul_f32_e32 v52, v43, v52
	v_fma_f32 v52, v43, v52, v43
	v_mul_f32_e32 v52, 0x3f4c422a, v52
	v_add_f32_e32 v52, v52, v52
	v_mul_f32_e32 v52, 0x3fb8aa3b, v52
	v_exp_f32_e32 v52, v52
	v_div_fmas_f32 v48, v48, v53, v49
	v_div_fixup_f32 v48, v48, v51, 2.0
	v_sub_f32_e32 v48, 1.0, v48
	v_add_f32_e32 v49, 1.0, v52
	v_div_scale_f32 v51, s[28:29], v49, v49, 2.0
	v_rcp_f32_e32 v52, v51
	v_mul_f32_e32 v42, 0.5, v42
	v_add_f32_e32 v48, 1.0, v48
	v_mul_f32_e32 v42, v42, v48
	v_fma_f32 v48, -v51, v52, 1.0
	v_fmac_f32_e32 v52, v48, v52
	v_div_scale_f32 v48, vcc, 2.0, v49, 2.0
	v_mul_f32_e32 v53, v48, v52
	v_fma_f32 v54, -v51, v53, v48
	v_fmac_f32_e32 v53, v54, v52
	v_fma_f32 v48, -v51, v53, v48
	v_mul_f32_e32 v51, 0x3d372713, v44
	v_mul_f32_e32 v51, v44, v51
	v_fma_f32 v51, v44, v51, v44
	v_mul_f32_e32 v51, 0x3f4c422a, v51
	v_add_f32_e32 v51, v51, v51
	v_mul_f32_e32 v51, 0x3fb8aa3b, v51
	v_exp_f32_e32 v51, v51
	v_div_fmas_f32 v48, v48, v52, v53
	v_div_fixup_f32 v48, v48, v49, 2.0
	v_sub_f32_e32 v48, 1.0, v48
	v_add_f32_e32 v49, 1.0, v51
	v_div_scale_f32 v51, s[28:29], v49, v49, 2.0
	v_rcp_f32_e32 v52, v51
	v_mul_f32_e32 v43, 0.5, v43
	v_add_f32_e32 v48, 1.0, v48
	v_mul_f32_e32 v43, v43, v48
	v_cvt_pk_bf16_f32 v48, v42, v43
	v_fma_f32 v42, -v51, v52, 1.0
	v_fmac_f32_e32 v52, v42, v52
	v_div_scale_f32 v42, vcc, 2.0, v49, 2.0
	v_mul_f32_e32 v43, v42, v52
	v_fma_f32 v53, -v51, v43, v42
	v_fmac_f32_e32 v43, v53, v52
	v_fma_f32 v42, -v51, v43, v42
	v_mul_f32_e32 v51, 0x3d372713, v45
	v_mul_f32_e32 v51, v45, v51
	v_fma_f32 v51, v45, v51, v45
	v_mul_f32_e32 v51, 0x3f4c422a, v51
	v_add_f32_e32 v51, v51, v51
	v_mul_f32_e32 v51, 0x3fb8aa3b, v51
	v_exp_f32_e32 v51, v51
	v_div_fmas_f32 v42, v42, v52, v43
	v_div_fixup_f32 v42, v42, v49, 2.0
	v_sub_f32_e32 v42, 1.0, v42
	v_add_f32_e32 v43, 1.0, v51
	v_div_scale_f32 v49, s[28:29], v43, v43, 2.0
	v_rcp_f32_e32 v51, v49
	v_mul_f32_e32 v44, 0.5, v44
	v_add_f32_e32 v42, 1.0, v42
	v_mul_f32_e32 v42, v44, v42
	v_fma_f32 v44, -v49, v51, 1.0
	v_fmac_f32_e32 v51, v44, v51
	v_div_scale_f32 v44, vcc, 2.0, v43, 2.0
	v_mul_f32_e32 v52, v44, v51
	v_fma_f32 v53, -v49, v52, v44
	v_fmac_f32_e32 v52, v53, v51
	v_fma_f32 v44, -v49, v52, v44
	v_div_fmas_f32 v44, v44, v51, v52
	v_div_fixup_f32 v43, v44, v43, 2.0
	v_sub_f32_e32 v43, 1.0, v43
	v_mul_f32_e32 v44, 0.5, v45
	v_add_f32_e32 v43, 1.0, v43
	v_mul_f32_e32 v43, v44, v43
	v_mul_f32_e32 v44, 0x3d372713, v38
	v_mul_f32_e32 v44, v38, v44
	v_fma_f32 v44, v38, v44, v38
	v_mul_f32_e32 v44, 0x3f4c422a, v44
	v_add_f32_e32 v44, v44, v44
	v_mul_f32_e32 v44, 0x3fb8aa3b, v44
	v_exp_f32_e32 v44, v44
	v_or_b32_e32 v50, v171, v151
	v_ashrrev_i32_e32 v51, 31, v50
	v_cvt_pk_bf16_f32 v49, v42, v43
	v_add_f32_e32 v44, 1.0, v44
	v_div_scale_f32 v45, s[28:29], v44, v44, 2.0
	v_lshlrev_b64 v[42:43], 11, v[50:51]
	v_rcp_f32_e32 v50, v45
	v_lshl_add_u64 v[42:43], v[138:139], 0, v[42:43]
	global_store_dwordx4 v[42:43], v[46:49], off
	v_mul_f32_e32 v38, 0.5, v38
	v_fma_f32 v43, -v45, v50, 1.0
	v_fmac_f32_e32 v50, v43, v50
; #define LAS __attribute__((address_space(3)))
; __device__ __forceinline__ unsigned cvt_pk_bf16(float lo, float hi) { unsigned r; asm volatile("v_cvt_pk_bf16_f32 %0, %1, %2" : "=v"(r) : "v"(lo), "v"(hi)); return r; }
; __device__ __forceinline__ float gelu_tanh(float x) { const float z = 0.7978845608f * (x + 0.044715f * x * x * x); const float th = 1.0f - 2.0f / (__expf(2.0f * z) + 1.0f); return 0.5f * x * (1.0f + th); }
;     __device__ __forceinline__ void operator()(const f32x4 (&acc)[2][2][4][2], const Unit& u, int ui, const LAS float* rtab, int wr, int wc, int fr, int fq) const {
;         const int g = u.pm; const int n0 = wr * 64 + fr; const int lc0 = (u.pn & 1) * 256 + wc * 32 + 8 * fq;
; #pragma unroll
;         for (int ai = 0; ai < 2; ++ai)
; #pragma unroll
;             for (int m = 0; m < 4; ++m) {
;                 const int n = n0 + ai * HALF + m * 16;
; #pragma unroll
;                 for (int bj = 0; bj < 2; ++bj) {
;                     const int lc = lc0 + bj * HALF, t = lc >> 4, co = lc & 15; const int token = n * 32 + t;
;                     const f32x4 a0 = acc[ai][bj][m][0], a1 = acc[ai][bj][m][1];
;                     u32x4 w; w.x = cvt_pk_bf16(gelu_tanh(a0[0]), gelu_tanh(a0[1])); w.y = cvt_pk_bf16(gelu_tanh(a0[2]), gelu_tanh(a0[3]));
;                     w.z = cvt_pk_bf16(gelu_tanh(a1[0]), gelu_tanh(a1[1])); w.w = cvt_pk_bf16(gelu_tanh(a1[2]), gelu_tanh(a1[3]));
;                     *(u32x4*)(Y + (size_t)token * 1024 + 16 * g + co) = w;
;                 }
;             }
;     }
	v_div_scale_f32 v43, vcc, 2.0, v44, 2.0
	v_mul_f32_e32 v46, v43, v50
	v_fma_f32 v47, -v45, v46, v43
	v_fmac_f32_e32 v46, v47, v50
	v_fma_f32 v43, -v45, v46, v43
	v_mul_f32_e32 v45, 0x3d372713, v39
	v_mul_f32_e32 v45, v39, v45
	v_fma_f32 v45, v39, v45, v39
	v_mul_f32_e32 v45, 0x3f4c422a, v45
	v_add_f32_e32 v45, v45, v45
	v_mul_f32_e32 v45, 0x3fb8aa3b, v45
	v_exp_f32_e32 v45, v45
	v_div_fmas_f32 v43, v43, v50, v46
	v_div_fixup_f32 v43, v43, v44, 2.0
	v_sub_f32_e32 v43, 1.0, v43
	v_add_f32_e32 v44, 1.0, v45
	v_div_scale_f32 v45, s[28:29], v44, v44, 2.0
	v_rcp_f32_e32 v46, v45
	v_add_f32_e32 v43, 1.0, v43
	v_mul_f32_e32 v38, v38, v43
	v_mul_f32_e32 v39, 0.5, v39
	v_fma_f32 v43, -v45, v46, 1.0
	v_fmac_f32_e32 v46, v43, v46
	v_div_scale_f32 v43, vcc, 2.0, v44, 2.0
	v_mul_f32_e32 v47, v43, v46
	v_fma_f32 v48, -v45, v47, v43
	v_fmac_f32_e32 v47, v48, v46
	v_fma_f32 v43, -v45, v47, v43
	v_mul_f32_e32 v45, 0x3d372713, v40
	v_mul_f32_e32 v45, v40, v45
	v_fma_f32 v45, v40, v45, v40
	v_mul_f32_e32 v45, 0x3f4c422a, v45
	v_add_f32_e32 v45, v45, v45
	v_mul_f32_e32 v45, 0x3fb8aa3b, v45
	v_exp_f32_e32 v45, v45
	v_div_fmas_f32 v43, v43, v46, v47
	v_div_fixup_f32 v43, v43, v44, 2.0
	v_sub_f32_e32 v43, 1.0, v43
	v_add_f32_e32 v44, 1.0, v45
	v_div_scale_f32 v45, s[28:29], v44, v44, 2.0
	v_rcp_f32_e32 v46, v45
	v_add_f32_e32 v43, 1.0, v43
	v_mul_f32_e32 v39, v39, v43
	v_cvt_pk_bf16_f32 v38, v38, v39
	v_fma_f32 v39, -v45, v46, 1.0
	v_fmac_f32_e32 v46, v39, v46
	v_div_scale_f32 v39, vcc, 2.0, v44, 2.0
	v_mul_f32_e32 v43, v39, v46
	v_fma_f32 v47, -v45, v43, v39
	v_fmac_f32_e32 v43, v47, v46
	v_fma_f32 v39, -v45, v43, v39
	v_mul_f32_e32 v45, 0x3d372713, v41
	v_mul_f32_e32 v45, v41, v45
	v_fma_f32 v45, v41, v45, v41
	v_mul_f32_e32 v45, 0x3f4c422a, v45
	v_add_f32_e32 v45, v45, v45
	v_mul_f32_e32 v45, 0x3fb8aa3b, v45
	v_exp_f32_e32 v45, v45
	v_div_fmas_f32 v39, v39, v46, v43
	v_div_fixup_f32 v39, v39, v44, 2.0
	v_sub_f32_e32 v39, 1.0, v39
	v_add_f32_e32 v43, 1.0, v45
	v_div_scale_f32 v44, s[28:29], v43, v43, 2.0
	v_rcp_f32_e32 v45, v44
	v_mul_f32_e32 v40, 0.5, v40
	v_add_f32_e32 v39, 1.0, v39
	v_mul_f32_e32 v39, v40, v39
	v_fma_f32 v40, -v44, v45, 1.0
	v_fmac_f32_e32 v45, v40, v45
	v_div_scale_f32 v40, vcc, 2.0, v43, 2.0
	v_mul_f32_e32 v46, v40, v45
	v_fma_f32 v47, -v44, v46, v40
	v_fmac_f32_e32 v46, v47, v45
	v_fma_f32 v40, -v44, v46, v40
	v_mul_f32_e32 v44, 0x3d372713, v34
	v_mul_f32_e32 v44, v34, v44
	v_fma_f32 v44, v34, v44, v34
	v_mul_f32_e32 v44, 0x3f4c422a, v44
	v_add_f32_e32 v44, v44, v44
	v_mul_f32_e32 v44, 0x3fb8aa3b, v44
	v_exp_f32_e32 v44, v44
	v_div_fmas_f32 v40, v40, v45, v46
	v_div_fixup_f32 v40, v40, v43, 2.0
	v_sub_f32_e32 v40, 1.0, v40
	v_add_f32_e32 v43, 1.0, v44
	v_div_scale_f32 v44, s[28:29], v43, v43, 2.0
	v_rcp_f32_e32 v45, v44
	v_mul_f32_e32 v41, 0.5, v41
	v_add_f32_e32 v40, 1.0, v40
	v_mul_f32_e32 v40, v41, v40
	v_cvt_pk_bf16_f32 v39, v39, v40
	v_fma_f32 v40, -v44, v45, 1.0
	v_fmac_f32_e32 v45, v40, v45
	v_div_scale_f32 v40, vcc, 2.0, v43, 2.0
	v_mul_f32_e32 v41, v40, v45
	v_fma_f32 v46, -v44, v41, v40
	v_fmac_f32_e32 v41, v46, v45
	v_fma_f32 v40, -v44, v41, v40
	v_mul_f32_e32 v44, 0x3d372713, v35
	v_mul_f32_e32 v44, v35, v44
	v_fma_f32 v44, v35, v44, v35
	v_mul_f32_e32 v44, 0x3f4c422a, v44
	v_add_f32_e32 v44, v44, v44
	v_mul_f32_e32 v44, 0x3fb8aa3b, v44
	v_exp_f32_e32 v44, v44
	v_div_fmas_f32 v40, v40, v45, v41
	v_div_fixup_f32 v40, v40, v43, 2.0
	v_sub_f32_e32 v40, 1.0, v40
	v_add_f32_e32 v41, 1.0, v44
	v_div_scale_f32 v43, s[28:29], v41, v41, 2.0
	v_rcp_f32_e32 v44, v43
	v_mul_f32_e32 v34, 0.5, v34
	v_add_f32_e32 v40, 1.0, v40
	v_mul_f32_e32 v34, v34, v40
	v_fma_f32 v40, -v43, v44, 1.0
	v_fmac_f32_e32 v44, v40, v44
	v_div_scale_f32 v40, vcc, 2.0, v41, 2.0
	v_mul_f32_e32 v45, v40, v44
	v_fma_f32 v46, -v43, v45, v40
	v_fmac_f32_e32 v45, v46, v44
	v_fma_f32 v40, -v43, v45, v40
	v_mul_f32_e32 v43, 0x3d372713, v36
	v_mul_f32_e32 v43, v36, v43
	v_fma_f32 v43, v36, v43, v36
	v_mul_f32_e32 v43, 0x3f4c422a, v43
	v_add_f32_e32 v43, v43, v43
	v_mul_f32_e32 v43, 0x3fb8aa3b, v43
	v_exp_f32_e32 v43, v43
	v_div_fmas_f32 v40, v40, v44, v45
	v_div_fixup_f32 v40, v40, v41, 2.0
	v_sub_f32_e32 v40, 1.0, v40
	v_add_f32_e32 v41, 1.0, v43
	v_div_scale_f32 v43, s[28:29], v41, v41, 2.0
	v_rcp_f32_e32 v44, v43
	v_mul_f32_e32 v35, 0.5, v35
	v_add_f32_e32 v40, 1.0, v40
	v_mul_f32_e32 v35, v35, v40
	v_cvt_pk_bf16_f32 v40, v34, v35
	v_fma_f32 v34, -v43, v44, 1.0
	v_fmac_f32_e32 v44, v34, v44
	v_div_scale_f32 v34, vcc, 2.0, v41, 2.0
	v_mul_f32_e32 v35, v34, v44
	v_fma_f32 v45, -v43, v35, v34
	v_fmac_f32_e32 v35, v45, v44
	v_fma_f32 v34, -v43, v35, v34
	v_mul_f32_e32 v43, 0x3d372713, v37
	v_mul_f32_e32 v43, v37, v43
	v_fma_f32 v43, v37, v43, v37
	v_mul_f32_e32 v43, 0x3f4c422a, v43
	v_add_f32_e32 v43, v43, v43
	v_mul_f32_e32 v43, 0x3fb8aa3b, v43
	v_exp_f32_e32 v43, v43
	v_div_fmas_f32 v34, v34, v44, v35
	v_div_fixup_f32 v34, v34, v41, 2.0
	v_sub_f32_e32 v34, 1.0, v34
	v_add_f32_e32 v35, 1.0, v43
	v_div_scale_f32 v41, s[28:29], v35, v35, 2.0
	v_rcp_f32_e32 v43, v41
	v_mul_f32_e32 v36, 0.5, v36
	v_add_f32_e32 v34, 1.0, v34
	v_mul_f32_e32 v34, v36, v34
	v_fma_f32 v36, -v41, v43, 1.0
	v_fmac_f32_e32 v43, v36, v43
	v_div_scale_f32 v36, vcc, 2.0, v35, 2.0
	v_mul_f32_e32 v44, v36, v43
	v_fma_f32 v45, -v41, v44, v36
	v_fmac_f32_e32 v44, v45, v43
	v_fma_f32 v36, -v41, v44, v36
	v_div_fmas_f32 v36, v36, v43, v44
	v_div_fixup_f32 v35, v36, v35, 2.0
	v_sub_f32_e32 v35, 1.0, v35
	v_mul_f32_e32 v36, 0.5, v37
	v_add_f32_e32 v35, 1.0, v35
	v_mul_f32_e32 v35, v36, v35
	v_mul_f32_e32 v36, 0x3d372713, v30
	v_mul_f32_e32 v36, v30, v36
	v_fma_f32 v36, v30, v36, v30
	v_mul_f32_e32 v36, 0x3f4c422a, v36
; #define LAS __attribute__((address_space(3)))
; __device__ __forceinline__ unsigned cvt_pk_bf16(float lo, float hi) { unsigned r; asm volatile("v_cvt_pk_bf16_f32 %0, %1, %2" : "=v"(r) : "v"(lo), "v"(hi)); return r; }
; __device__ __forceinline__ float gelu_tanh(float x) { const float z = 0.7978845608f * (x + 0.044715f * x * x * x); const float th = 1.0f - 2.0f / (__expf(2.0f * z) + 1.0f); return 0.5f * x * (1.0f + th); }
;     __device__ __forceinline__ void operator()(const f32x4 (&acc)[2][2][4][2], const Unit& u, int ui, const LAS float* rtab, int wr, int wc, int fr, int fq) const {
;         const int g = u.pm; const int n0 = wr * 64 + fr; const int lc0 = (u.pn & 1) * 256 + wc * 32 + 8 * fq;
; #pragma unroll
;         for (int ai = 0; ai < 2; ++ai)
; #pragma unroll
;             for (int m = 0; m < 4; ++m) {
;                 const int n = n0 + ai * HALF + m * 16;
; #pragma unroll
;                 for (int bj = 0; bj < 2; ++bj) {
;                     const int lc = lc0 + bj * HALF, t = lc >> 4, co = lc & 15; const int token = n * 32 + t;
;                     const f32x4 a0 = acc[ai][bj][m][0], a1 = acc[ai][bj][m][1];
;                     u32x4 w; w.x = cvt_pk_bf16(gelu_tanh(a0[0]), gelu_tanh(a0[1])); w.y = cvt_pk_bf16(gelu_tanh(a0[2]), gelu_tanh(a0[3]));
;                     w.z = cvt_pk_bf16(gelu_tanh(a1[0]), gelu_tanh(a1[1])); w.w = cvt_pk_bf16(gelu_tanh(a1[2]), gelu_tanh(a1[3]));
;                     *(u32x4*)(Y + (size_t)token * 1024 + 16 * g + co) = w;
;                 }
;             }
;     }
	v_add_f32_e32 v36, v36, v36
	v_mul_f32_e32 v36, 0x3fb8aa3b, v36
	v_exp_f32_e32 v36, v36
	v_or_b32_e32 v42, v124, v151
	v_ashrrev_i32_e32 v43, 31, v42
	v_cvt_pk_bf16_f32 v41, v34, v35
	v_add_f32_e32 v36, 1.0, v36
	v_div_scale_f32 v37, s[28:29], v36, v36, 2.0
	v_lshlrev_b64 v[34:35], 11, v[42:43]
	v_rcp_f32_e32 v42, v37
	v_lshl_add_u64 v[34:35], v[138:139], 0, v[34:35]
	global_store_dwordx4 v[34:35], v[38:41], off
	v_mul_f32_e32 v30, 0.5, v30
	v_fma_f32 v35, -v37, v42, 1.0
	v_fmac_f32_e32 v42, v35, v42
	v_div_scale_f32 v35, vcc, 2.0, v36, 2.0
	v_mul_f32_e32 v38, v35, v42
	v_fma_f32 v39, -v37, v38, v35
	v_fmac_f32_e32 v38, v39, v42
	v_fma_f32 v35, -v37, v38, v35
	v_mul_f32_e32 v37, 0x3d372713, v31
	v_mul_f32_e32 v37, v31, v37
	v_fma_f32 v37, v31, v37, v31
	v_mul_f32_e32 v37, 0x3f4c422a, v37
	v_add_f32_e32 v37, v37, v37
	v_mul_f32_e32 v37, 0x3fb8aa3b, v37
	v_exp_f32_e32 v37, v37
	v_div_fmas_f32 v35, v35, v42, v38
	v_div_fixup_f32 v35, v35, v36, 2.0
	v_sub_f32_e32 v35, 1.0, v35
	v_add_f32_e32 v36, 1.0, v37
	v_div_scale_f32 v37, s[28:29], v36, v36, 2.0
	v_rcp_f32_e32 v38, v37
	v_add_f32_e32 v35, 1.0, v35
	v_mul_f32_e32 v30, v30, v35
	v_mul_f32_e32 v31, 0.5, v31
	v_fma_f32 v35, -v37, v38, 1.0
	v_fmac_f32_e32 v38, v35, v38
	v_div_scale_f32 v35, vcc, 2.0, v36, 2.0
	v_mul_f32_e32 v39, v35, v38
	v_fma_f32 v40, -v37, v39, v35
	v_fmac_f32_e32 v39, v40, v38
	v_fma_f32 v35, -v37, v39, v35
	v_mul_f32_e32 v37, 0x3d372713, v32
	v_mul_f32_e32 v37, v32, v37
	v_fma_f32 v37, v32, v37, v32
	v_mul_f32_e32 v37, 0x3f4c422a, v37
	v_add_f32_e32 v37, v37, v37
	v_mul_f32_e32 v37, 0x3fb8aa3b, v37
	v_exp_f32_e32 v37, v37
	v_div_fmas_f32 v35, v35, v38, v39
	v_div_fixup_f32 v35, v35, v36, 2.0
	v_sub_f32_e32 v35, 1.0, v35
	v_add_f32_e32 v36, 1.0, v37
	v_div_scale_f32 v37, s[28:29], v36, v36, 2.0
	v_rcp_f32_e32 v38, v37
	v_add_f32_e32 v35, 1.0, v35
	v_mul_f32_e32 v31, v31, v35
	v_cvt_pk_bf16_f32 v30, v30, v31
	v_fma_f32 v31, -v37, v38, 1.0
	v_fmac_f32_e32 v38, v31, v38
	v_div_scale_f32 v31, vcc, 2.0, v36, 2.0
	v_mul_f32_e32 v35, v31, v38
	v_fma_f32 v39, -v37, v35, v31
	v_fmac_f32_e32 v35, v39, v38
	v_fma_f32 v31, -v37, v35, v31
	v_mul_f32_e32 v37, 0x3d372713, v33
	v_mul_f32_e32 v37, v33, v37
	v_fma_f32 v37, v33, v37, v33
	v_mul_f32_e32 v37, 0x3f4c422a, v37
	v_add_f32_e32 v37, v37, v37
	v_mul_f32_e32 v37, 0x3fb8aa3b, v37
	v_exp_f32_e32 v37, v37
	v_div_fmas_f32 v31, v31, v38, v35
	v_div_fixup_f32 v31, v31, v36, 2.0
	v_sub_f32_e32 v31, 1.0, v31
	v_add_f32_e32 v35, 1.0, v37
	v_div_scale_f32 v36, s[28:29], v35, v35, 2.0
	v_rcp_f32_e32 v37, v36
	v_mul_f32_e32 v32, 0.5, v32
	v_add_f32_e32 v31, 1.0, v31
	v_mul_f32_e32 v31, v32, v31
	v_fma_f32 v32, -v36, v37, 1.0
	v_fmac_f32_e32 v37, v32, v37
	v_div_scale_f32 v32, vcc, 2.0, v35, 2.0
	v_mul_f32_e32 v38, v32, v37
	v_fma_f32 v39, -v36, v38, v32
	v_fmac_f32_e32 v38, v39, v37
	v_fma_f32 v32, -v36, v38, v32
	v_mul_f32_e32 v36, 0x3d372713, v26
	v_mul_f32_e32 v36, v26, v36
	v_fma_f32 v36, v26, v36, v26
	v_mul_f32_e32 v36, 0x3f4c422a, v36
	v_add_f32_e32 v36, v36, v36
	v_mul_f32_e32 v36, 0x3fb8aa3b, v36
	v_exp_f32_e32 v36, v36
	v_div_fmas_f32 v32, v32, v37, v38
	v_div_fixup_f32 v32, v32, v35, 2.0
	v_sub_f32_e32 v32, 1.0, v32
	v_add_f32_e32 v35, 1.0, v36
	v_div_scale_f32 v36, s[28:29], v35, v35, 2.0
	v_rcp_f32_e32 v37, v36
	v_mul_f32_e32 v33, 0.5, v33
	v_add_f32_e32 v32, 1.0, v32
	v_mul_f32_e32 v32, v33, v32
	v_cvt_pk_bf16_f32 v31, v31, v32
	v_fma_f32 v32, -v36, v37, 1.0
	v_fmac_f32_e32 v37, v32, v37
	v_div_scale_f32 v32, vcc, 2.0, v35, 2.0
	v_mul_f32_e32 v33, v32, v37
	v_fma_f32 v38, -v36, v33, v32
	v_fmac_f32_e32 v33, v38, v37
	v_fma_f32 v32, -v36, v33, v32
	v_mul_f32_e32 v36, 0x3d372713, v27
	v_mul_f32_e32 v36, v27, v36
	v_fma_f32 v36, v27, v36, v27
	v_mul_f32_e32 v36, 0x3f4c422a, v36
	v_add_f32_e32 v36, v36, v36
	v_mul_f32_e32 v36, 0x3fb8aa3b, v36
	v_exp_f32_e32 v36, v36
	v_div_fmas_f32 v32, v32, v37, v33
	v_div_fixup_f32 v32, v32, v35, 2.0
	v_sub_f32_e32 v32, 1.0, v32
	v_add_f32_e32 v33, 1.0, v36
	v_div_scale_f32 v35, s[28:29], v33, v33, 2.0
	v_rcp_f32_e32 v36, v35
	v_mul_f32_e32 v26, 0.5, v26
	v_add_f32_e32 v32, 1.0, v32
	v_mul_f32_e32 v26, v26, v32
	v_fma_f32 v32, -v35, v36, 1.0
	v_fmac_f32_e32 v36, v32, v36
	v_div_scale_f32 v32, vcc, 2.0, v33, 2.0
	v_mul_f32_e32 v37, v32, v36
	v_fma_f32 v38, -v35, v37, v32
	v_fmac_f32_e32 v37, v38, v36
	v_fma_f32 v32, -v35, v37, v32
	v_mul_f32_e32 v35, 0x3d372713, v28
	v_mul_f32_e32 v35, v28, v35
	v_fma_f32 v35, v28, v35, v28
	v_mul_f32_e32 v35, 0x3f4c422a, v35
	v_add_f32_e32 v35, v35, v35
	v_mul_f32_e32 v35, 0x3fb8aa3b, v35
	v_exp_f32_e32 v35, v35
	v_div_fmas_f32 v32, v32, v36, v37
	v_div_fixup_f32 v32, v32, v33, 2.0
	v_sub_f32_e32 v32, 1.0, v32
	v_add_f32_e32 v33, 1.0, v35
	v_div_scale_f32 v35, s[28:29], v33, v33, 2.0
	v_rcp_f32_e32 v36, v35
	v_mul_f32_e32 v27, 0.5, v27
	v_add_f32_e32 v32, 1.0, v32
	v_mul_f32_e32 v27, v27, v32
	v_cvt_pk_bf16_f32 v32, v26, v27
	v_fma_f32 v26, -v35, v36, 1.0
	v_fmac_f32_e32 v36, v26, v36
	v_div_scale_f32 v26, vcc, 2.0, v33, 2.0
	v_mul_f32_e32 v27, v26, v36
	v_fma_f32 v37, -v35, v27, v26
	v_fmac_f32_e32 v27, v37, v36
	v_fma_f32 v26, -v35, v27, v26
	v_mul_f32_e32 v35, 0x3d372713, v29
	v_mul_f32_e32 v35, v29, v35
	v_fma_f32 v35, v29, v35, v29
	v_mul_f32_e32 v35, 0x3f4c422a, v35
	v_add_f32_e32 v35, v35, v35
	v_mul_f32_e32 v35, 0x3fb8aa3b, v35
	v_exp_f32_e32 v35, v35
	v_div_fmas_f32 v26, v26, v36, v27
	v_div_fixup_f32 v26, v26, v33, 2.0
	v_sub_f32_e32 v26, 1.0, v26
	v_add_f32_e32 v27, 1.0, v35
	v_div_scale_f32 v33, s[28:29], v27, v27, 2.0
	v_rcp_f32_e32 v35, v33
	v_mul_f32_e32 v28, 0.5, v28
	v_add_f32_e32 v26, 1.0, v26
	v_mul_f32_e32 v26, v28, v26
	v_fma_f32 v28, -v33, v35, 1.0
; #define LAS __attribute__((address_space(3)))
; __device__ __forceinline__ unsigned cvt_pk_bf16(float lo, float hi) { unsigned r; asm volatile("v_cvt_pk_bf16_f32 %0, %1, %2" : "=v"(r) : "v"(lo), "v"(hi)); return r; }
; __device__ __forceinline__ float gelu_tanh(float x) { const float z = 0.7978845608f * (x + 0.044715f * x * x * x); const float th = 1.0f - 2.0f / (__expf(2.0f * z) + 1.0f); return 0.5f * x * (1.0f + th); }
;     __device__ __forceinline__ void operator()(const f32x4 (&acc)[2][2][4][2], const Unit& u, int ui, const LAS float* rtab, int wr, int wc, int fr, int fq) const {
;         const int g = u.pm; const int n0 = wr * 64 + fr; const int lc0 = (u.pn & 1) * 256 + wc * 32 + 8 * fq;
; #pragma unroll
;         for (int ai = 0; ai < 2; ++ai)
; #pragma unroll
;             for (int m = 0; m < 4; ++m) {
;                 const int n = n0 + ai * HALF + m * 16;
; #pragma unroll
;                 for (int bj = 0; bj < 2; ++bj) {
;                     const int lc = lc0 + bj * HALF, t = lc >> 4, co = lc & 15; const int token = n * 32 + t;
;                     const f32x4 a0 = acc[ai][bj][m][0], a1 = acc[ai][bj][m][1];
;                     u32x4 w; w.x = cvt_pk_bf16(gelu_tanh(a0[0]), gelu_tanh(a0[1])); w.y = cvt_pk_bf16(gelu_tanh(a0[2]), gelu_tanh(a0[3]));
;                     w.z = cvt_pk_bf16(gelu_tanh(a1[0]), gelu_tanh(a1[1])); w.w = cvt_pk_bf16(gelu_tanh(a1[2]), gelu_tanh(a1[3]));
;                     *(u32x4*)(Y + (size_t)token * 1024 + 16 * g + co) = w;
;                 }
;             }
;     }
	v_fmac_f32_e32 v35, v28, v35
	v_div_scale_f32 v28, vcc, 2.0, v27, 2.0
	v_mul_f32_e32 v36, v28, v35
	v_fma_f32 v37, -v33, v36, v28
	v_fmac_f32_e32 v36, v37, v35
	v_fma_f32 v28, -v33, v36, v28
	v_div_fmas_f32 v28, v28, v35, v36
	v_div_fixup_f32 v27, v28, v27, 2.0
	v_sub_f32_e32 v27, 1.0, v27
	v_mul_f32_e32 v28, 0.5, v29
	v_add_f32_e32 v27, 1.0, v27
	v_mul_f32_e32 v27, v28, v27
	v_mul_f32_e32 v28, 0x3d372713, v22
	v_mul_f32_e32 v28, v22, v28
	v_fma_f32 v28, v22, v28, v22
	v_mul_f32_e32 v28, 0x3f4c422a, v28
	v_add_f32_e32 v28, v28, v28
	v_mul_f32_e32 v28, 0x3fb8aa3b, v28
	v_exp_f32_e32 v28, v28
	v_or_b32_e32 v34, v171, v152
	v_ashrrev_i32_e32 v35, 31, v34
	v_cvt_pk_bf16_f32 v33, v26, v27
	v_add_f32_e32 v28, 1.0, v28
	v_div_scale_f32 v29, s[28:29], v28, v28, 2.0
	v_lshlrev_b64 v[26:27], 11, v[34:35]
	v_rcp_f32_e32 v34, v29
	v_lshl_add_u64 v[26:27], v[138:139], 0, v[26:27]
	global_store_dwordx4 v[26:27], v[30:33], off
	v_mul_f32_e32 v22, 0.5, v22
	v_fma_f32 v27, -v29, v34, 1.0
	v_fmac_f32_e32 v34, v27, v34
	v_div_scale_f32 v27, vcc, 2.0, v28, 2.0
	v_mul_f32_e32 v30, v27, v34
	v_fma_f32 v31, -v29, v30, v27
	v_fmac_f32_e32 v30, v31, v34
	v_fma_f32 v27, -v29, v30, v27
	v_mul_f32_e32 v29, 0x3d372713, v23
	v_mul_f32_e32 v29, v23, v29
	v_fma_f32 v29, v23, v29, v23
	v_mul_f32_e32 v29, 0x3f4c422a, v29
	v_add_f32_e32 v29, v29, v29
	v_mul_f32_e32 v29, 0x3fb8aa3b, v29
	v_exp_f32_e32 v29, v29
	v_div_fmas_f32 v27, v27, v34, v30
	v_div_fixup_f32 v27, v27, v28, 2.0
	v_sub_f32_e32 v27, 1.0, v27
	v_add_f32_e32 v28, 1.0, v29
	v_div_scale_f32 v29, s[28:29], v28, v28, 2.0
	v_rcp_f32_e32 v30, v29
	v_add_f32_e32 v27, 1.0, v27
	v_mul_f32_e32 v22, v22, v27
	v_mul_f32_e32 v23, 0.5, v23
	v_fma_f32 v27, -v29, v30, 1.0
	v_fmac_f32_e32 v30, v27, v30
	v_div_scale_f32 v27, vcc, 2.0, v28, 2.0
	v_mul_f32_e32 v31, v27, v30
	v_fma_f32 v32, -v29, v31, v27
	v_fmac_f32_e32 v31, v32, v30
	v_fma_f32 v27, -v29, v31, v27
	v_mul_f32_e32 v29, 0x3d372713, v24
	v_mul_f32_e32 v29, v24, v29
	v_fma_f32 v29, v24, v29, v24
	v_mul_f32_e32 v29, 0x3f4c422a, v29
	v_add_f32_e32 v29, v29, v29
	v_mul_f32_e32 v29, 0x3fb8aa3b, v29
	v_exp_f32_e32 v29, v29
	v_div_fmas_f32 v27, v27, v30, v31
	v_div_fixup_f32 v27, v27, v28, 2.0
	v_sub_f32_e32 v27, 1.0, v27
	v_add_f32_e32 v28, 1.0, v29
	v_div_scale_f32 v29, s[28:29], v28, v28, 2.0
	v_rcp_f32_e32 v30, v29
	v_add_f32_e32 v27, 1.0, v27
	v_mul_f32_e32 v23, v23, v27
	v_cvt_pk_bf16_f32 v22, v22, v23
	v_fma_f32 v23, -v29, v30, 1.0
	v_fmac_f32_e32 v30, v23, v30
	v_div_scale_f32 v23, vcc, 2.0, v28, 2.0
	v_mul_f32_e32 v27, v23, v30
	v_fma_f32 v31, -v29, v27, v23
	v_fmac_f32_e32 v27, v31, v30
	v_fma_f32 v23, -v29, v27, v23
	v_mul_f32_e32 v29, 0x3d372713, v25
	v_mul_f32_e32 v29, v25, v29
	v_fma_f32 v29, v25, v29, v25
	v_mul_f32_e32 v29, 0x3f4c422a, v29
	v_add_f32_e32 v29, v29, v29
	v_mul_f32_e32 v29, 0x3fb8aa3b, v29
	v_exp_f32_e32 v29, v29
	v_div_fmas_f32 v23, v23, v30, v27
	v_div_fixup_f32 v23, v23, v28, 2.0
	v_sub_f32_e32 v23, 1.0, v23
	v_add_f32_e32 v27, 1.0, v29
	v_div_scale_f32 v28, s[28:29], v27, v27, 2.0
	v_rcp_f32_e32 v29, v28
	v_mul_f32_e32 v24, 0.5, v24
	v_add_f32_e32 v23, 1.0, v23
	v_mul_f32_e32 v23, v24, v23
	v_fma_f32 v24, -v28, v29, 1.0
	v_fmac_f32_e32 v29, v24, v29
	v_div_scale_f32 v24, vcc, 2.0, v27, 2.0
	v_mul_f32_e32 v30, v24, v29
	v_fma_f32 v31, -v28, v30, v24
	v_fmac_f32_e32 v30, v31, v29
	v_fma_f32 v24, -v28, v30, v24
	v_mul_f32_e32 v28, 0x3d372713, v18
	v_mul_f32_e32 v28, v18, v28
	v_fma_f32 v28, v18, v28, v18
	v_mul_f32_e32 v28, 0x3f4c422a, v28
	v_add_f32_e32 v28, v28, v28
	v_mul_f32_e32 v28, 0x3fb8aa3b, v28
	v_exp_f32_e32 v28, v28
	v_div_fmas_f32 v24, v24, v29, v30
	v_div_fixup_f32 v24, v24, v27, 2.0
	v_sub_f32_e32 v24, 1.0, v24
	v_add_f32_e32 v27, 1.0, v28
	v_div_scale_f32 v28, s[28:29], v27, v27, 2.0
	v_rcp_f32_e32 v29, v28
	v_mul_f32_e32 v25, 0.5, v25
	v_add_f32_e32 v24, 1.0, v24
	v_mul_f32_e32 v24, v25, v24
	v_cvt_pk_bf16_f32 v23, v23, v24
	v_fma_f32 v24, -v28, v29, 1.0
	v_fmac_f32_e32 v29, v24, v29
	v_div_scale_f32 v24, vcc, 2.0, v27, 2.0
	v_mul_f32_e32 v25, v24, v29
	v_fma_f32 v30, -v28, v25, v24
	v_fmac_f32_e32 v25, v30, v29
	v_fma_f32 v24, -v28, v25, v24
	v_mul_f32_e32 v28, 0x3d372713, v19
	v_mul_f32_e32 v28, v19, v28
	v_fma_f32 v28, v19, v28, v19
	v_mul_f32_e32 v28, 0x3f4c422a, v28
	v_add_f32_e32 v28, v28, v28
	v_mul_f32_e32 v28, 0x3fb8aa3b, v28
	v_exp_f32_e32 v28, v28
	v_div_fmas_f32 v24, v24, v29, v25
	v_div_fixup_f32 v24, v24, v27, 2.0
	v_sub_f32_e32 v24, 1.0, v24
	v_add_f32_e32 v25, 1.0, v28
	v_div_scale_f32 v27, s[28:29], v25, v25, 2.0
	v_rcp_f32_e32 v28, v27
	v_mul_f32_e32 v18, 0.5, v18
	v_add_f32_e32 v24, 1.0, v24
	v_mul_f32_e32 v18, v18, v24
	v_fma_f32 v24, -v27, v28, 1.0
	v_fmac_f32_e32 v28, v24, v28
	v_div_scale_f32 v24, vcc, 2.0, v25, 2.0
	v_mul_f32_e32 v29, v24, v28
	v_fma_f32 v30, -v27, v29, v24
	v_fmac_f32_e32 v29, v30, v28
	v_fma_f32 v24, -v27, v29, v24
	v_mul_f32_e32 v27, 0x3d372713, v20
	v_mul_f32_e32 v27, v20, v27
	v_fma_f32 v27, v20, v27, v20
	v_mul_f32_e32 v27, 0x3f4c422a, v27
	v_add_f32_e32 v27, v27, v27
	v_mul_f32_e32 v27, 0x3fb8aa3b, v27
	v_exp_f32_e32 v27, v27
	v_div_fmas_f32 v24, v24, v28, v29
	v_div_fixup_f32 v24, v24, v25, 2.0
	v_sub_f32_e32 v24, 1.0, v24
	v_add_f32_e32 v25, 1.0, v27
	v_div_scale_f32 v27, s[28:29], v25, v25, 2.0
	v_rcp_f32_e32 v28, v27
	v_mul_f32_e32 v19, 0.5, v19
	v_add_f32_e32 v24, 1.0, v24
	v_mul_f32_e32 v19, v19, v24
	v_cvt_pk_bf16_f32 v24, v18, v19
	v_fma_f32 v18, -v27, v28, 1.0
	v_fmac_f32_e32 v28, v18, v28
	v_div_scale_f32 v18, vcc, 2.0, v25, 2.0
	v_mul_f32_e32 v19, v18, v28
	v_fma_f32 v29, -v27, v19, v18
	v_fmac_f32_e32 v19, v29, v28
	v_fma_f32 v18, -v27, v19, v18
; #define LAS __attribute__((address_space(3)))
; __device__ __forceinline__ unsigned cvt_pk_bf16(float lo, float hi) { unsigned r; asm volatile("v_cvt_pk_bf16_f32 %0, %1, %2" : "=v"(r) : "v"(lo), "v"(hi)); return r; }
; __device__ __forceinline__ float gelu_tanh(float x) { const float z = 0.7978845608f * (x + 0.044715f * x * x * x); const float th = 1.0f - 2.0f / (__expf(2.0f * z) + 1.0f); return 0.5f * x * (1.0f + th); }
;     __device__ __forceinline__ void operator()(const f32x4 (&acc)[2][2][4][2], const Unit& u, int ui, const LAS float* rtab, int wr, int wc, int fr, int fq) const {
;         const int g = u.pm; const int n0 = wr * 64 + fr; const int lc0 = (u.pn & 1) * 256 + wc * 32 + 8 * fq;
; #pragma unroll
;         for (int ai = 0; ai < 2; ++ai)
; #pragma unroll
;             for (int m = 0; m < 4; ++m) {
;                 const int n = n0 + ai * HALF + m * 16;
; #pragma unroll
;                 for (int bj = 0; bj < 2; ++bj) {
;                     const int lc = lc0 + bj * HALF, t = lc >> 4, co = lc & 15; const int token = n * 32 + t;
;                     const f32x4 a0 = acc[ai][bj][m][0], a1 = acc[ai][bj][m][1];
;                     u32x4 w; w.x = cvt_pk_bf16(gelu_tanh(a0[0]), gelu_tanh(a0[1])); w.y = cvt_pk_bf16(gelu_tanh(a0[2]), gelu_tanh(a0[3]));
;                     w.z = cvt_pk_bf16(gelu_tanh(a1[0]), gelu_tanh(a1[1])); w.w = cvt_pk_bf16(gelu_tanh(a1[2]), gelu_tanh(a1[3]));
;                     *(u32x4*)(Y + (size_t)token * 1024 + 16 * g + co) = w;
;                 }
;             }
;     }
	v_mul_f32_e32 v27, 0x3d372713, v21
	v_mul_f32_e32 v27, v21, v27
	v_fma_f32 v27, v21, v27, v21
	v_mul_f32_e32 v27, 0x3f4c422a, v27
	v_add_f32_e32 v27, v27, v27
	v_mul_f32_e32 v27, 0x3fb8aa3b, v27
	v_exp_f32_e32 v27, v27
	v_div_fmas_f32 v18, v18, v28, v19
	v_div_fixup_f32 v18, v18, v25, 2.0
	v_sub_f32_e32 v18, 1.0, v18
	v_add_f32_e32 v19, 1.0, v27
	v_div_scale_f32 v25, s[28:29], v19, v19, 2.0
	v_rcp_f32_e32 v27, v25
	v_mul_f32_e32 v20, 0.5, v20
	v_add_f32_e32 v18, 1.0, v18
	v_mul_f32_e32 v18, v20, v18
	v_fma_f32 v20, -v25, v27, 1.0
	v_fmac_f32_e32 v27, v20, v27
	v_div_scale_f32 v20, vcc, 2.0, v19, 2.0
	v_mul_f32_e32 v28, v20, v27
	v_fma_f32 v29, -v25, v28, v20
	v_fmac_f32_e32 v28, v29, v27
	v_fma_f32 v20, -v25, v28, v20
	v_div_fmas_f32 v20, v20, v27, v28
	v_div_fixup_f32 v19, v20, v19, 2.0
	v_sub_f32_e32 v19, 1.0, v19
	v_mul_f32_e32 v20, 0.5, v21
	v_add_f32_e32 v19, 1.0, v19
	v_mul_f32_e32 v19, v20, v19
	v_mul_f32_e32 v20, 0x3d372713, v14
	v_mul_f32_e32 v20, v14, v20
	v_fma_f32 v20, v14, v20, v14
	v_mul_f32_e32 v20, 0x3f4c422a, v20
	v_add_f32_e32 v20, v20, v20
	v_mul_f32_e32 v20, 0x3fb8aa3b, v20
	v_exp_f32_e32 v20, v20
	v_or_b32_e32 v26, v124, v152
	v_ashrrev_i32_e32 v27, 31, v26
	v_cvt_pk_bf16_f32 v25, v18, v19
	v_add_f32_e32 v20, 1.0, v20
	v_div_scale_f32 v21, s[28:29], v20, v20, 2.0
	v_lshlrev_b64 v[18:19], 11, v[26:27]
	v_rcp_f32_e32 v26, v21
	v_lshl_add_u64 v[18:19], v[138:139], 0, v[18:19]
	global_store_dwordx4 v[18:19], v[22:25], off
	v_mul_f32_e32 v14, 0.5, v14
	v_fma_f32 v19, -v21, v26, 1.0
	v_fmac_f32_e32 v26, v19, v26
	v_div_scale_f32 v19, vcc, 2.0, v20, 2.0
	v_mul_f32_e32 v22, v19, v26
	v_fma_f32 v23, -v21, v22, v19
	v_fmac_f32_e32 v22, v23, v26
	v_fma_f32 v19, -v21, v22, v19
	v_mul_f32_e32 v21, 0x3d372713, v15
	v_mul_f32_e32 v21, v15, v21
	v_fma_f32 v21, v15, v21, v15
	v_mul_f32_e32 v21, 0x3f4c422a, v21
	v_add_f32_e32 v21, v21, v21
	v_mul_f32_e32 v21, 0x3fb8aa3b, v21
	v_exp_f32_e32 v21, v21
	v_div_fmas_f32 v19, v19, v26, v22
	v_div_fixup_f32 v19, v19, v20, 2.0
	v_sub_f32_e32 v19, 1.0, v19
	v_add_f32_e32 v20, 1.0, v21
	v_div_scale_f32 v21, s[28:29], v20, v20, 2.0
	v_rcp_f32_e32 v22, v21
	v_add_f32_e32 v19, 1.0, v19
	v_mul_f32_e32 v14, v14, v19
	v_mul_f32_e32 v15, 0.5, v15
	v_fma_f32 v19, -v21, v22, 1.0
	v_fmac_f32_e32 v22, v19, v22
	v_div_scale_f32 v19, vcc, 2.0, v20, 2.0
	v_mul_f32_e32 v23, v19, v22
	v_fma_f32 v24, -v21, v23, v19
	v_fmac_f32_e32 v23, v24, v22
	v_fma_f32 v19, -v21, v23, v19
	v_mul_f32_e32 v21, 0x3d372713, v16
	v_mul_f32_e32 v21, v16, v21
	v_fma_f32 v21, v16, v21, v16
	v_mul_f32_e32 v21, 0x3f4c422a, v21
	v_add_f32_e32 v21, v21, v21
	v_mul_f32_e32 v21, 0x3fb8aa3b, v21
	v_exp_f32_e32 v21, v21
	v_div_fmas_f32 v19, v19, v22, v23
	v_div_fixup_f32 v19, v19, v20, 2.0
	v_sub_f32_e32 v19, 1.0, v19
	v_add_f32_e32 v20, 1.0, v21
	v_div_scale_f32 v21, s[28:29], v20, v20, 2.0
	v_rcp_f32_e32 v22, v21
	v_add_f32_e32 v19, 1.0, v19
	v_mul_f32_e32 v15, v15, v19
	v_cvt_pk_bf16_f32 v14, v14, v15
	v_fma_f32 v15, -v21, v22, 1.0
	v_fmac_f32_e32 v22, v15, v22
	v_div_scale_f32 v15, vcc, 2.0, v20, 2.0
	v_mul_f32_e32 v19, v15, v22
	v_fma_f32 v23, -v21, v19, v15
	v_fmac_f32_e32 v19, v23, v22
	v_fma_f32 v15, -v21, v19, v15
	v_mul_f32_e32 v21, 0x3d372713, v17
	v_mul_f32_e32 v21, v17, v21
	v_fma_f32 v21, v17, v21, v17
	v_mul_f32_e32 v21, 0x3f4c422a, v21
	v_add_f32_e32 v21, v21, v21
	v_mul_f32_e32 v21, 0x3fb8aa3b, v21
	v_exp_f32_e32 v21, v21
	v_div_fmas_f32 v15, v15, v22, v19
	v_div_fixup_f32 v15, v15, v20, 2.0
	v_sub_f32_e32 v15, 1.0, v15
	v_add_f32_e32 v19, 1.0, v21
	v_div_scale_f32 v20, s[28:29], v19, v19, 2.0
	v_rcp_f32_e32 v21, v20
	v_mul_f32_e32 v16, 0.5, v16
	v_add_f32_e32 v15, 1.0, v15
	v_mul_f32_e32 v15, v16, v15
	v_fma_f32 v16, -v20, v21, 1.0
	v_fmac_f32_e32 v21, v16, v21
	v_div_scale_f32 v16, vcc, 2.0, v19, 2.0
	v_mul_f32_e32 v22, v16, v21
	v_fma_f32 v23, -v20, v22, v16
	v_fmac_f32_e32 v22, v23, v21
	v_fma_f32 v16, -v20, v22, v16
	v_mul_f32_e32 v20, 0x3d372713, v10
	v_mul_f32_e32 v20, v10, v20
	v_fma_f32 v20, v10, v20, v10
	v_mul_f32_e32 v20, 0x3f4c422a, v20
	v_add_f32_e32 v20, v20, v20
	v_mul_f32_e32 v20, 0x3fb8aa3b, v20
	v_exp_f32_e32 v20, v20
	v_div_fmas_f32 v16, v16, v21, v22
	v_div_fixup_f32 v16, v16, v19, 2.0
	v_sub_f32_e32 v16, 1.0, v16
	v_add_f32_e32 v19, 1.0, v20
	v_div_scale_f32 v20, s[28:29], v19, v19, 2.0
	v_rcp_f32_e32 v21, v20
	v_mul_f32_e32 v17, 0.5, v17
	v_add_f32_e32 v16, 1.0, v16
	v_mul_f32_e32 v16, v17, v16
	v_cvt_pk_bf16_f32 v15, v15, v16
	v_fma_f32 v16, -v20, v21, 1.0
	v_fmac_f32_e32 v21, v16, v21
	v_div_scale_f32 v16, vcc, 2.0, v19, 2.0
	v_mul_f32_e32 v17, v16, v21
	v_fma_f32 v22, -v20, v17, v16
	v_fmac_f32_e32 v17, v22, v21
	v_fma_f32 v16, -v20, v17, v16
	v_mul_f32_e32 v20, 0x3d372713, v11
	v_mul_f32_e32 v20, v11, v20
	v_fma_f32 v20, v11, v20, v11
	v_mul_f32_e32 v20, 0x3f4c422a, v20
	v_add_f32_e32 v20, v20, v20
	v_mul_f32_e32 v20, 0x3fb8aa3b, v20
	v_exp_f32_e32 v20, v20
	v_div_fmas_f32 v16, v16, v21, v17
	v_div_fixup_f32 v16, v16, v19, 2.0
	v_sub_f32_e32 v16, 1.0, v16
	v_add_f32_e32 v17, 1.0, v20
	v_div_scale_f32 v19, s[28:29], v17, v17, 2.0
	v_rcp_f32_e32 v20, v19
	v_mul_f32_e32 v10, 0.5, v10
	v_add_f32_e32 v16, 1.0, v16
	v_mul_f32_e32 v10, v10, v16
	v_fma_f32 v16, -v19, v20, 1.0
	v_fmac_f32_e32 v20, v16, v20
	v_div_scale_f32 v16, vcc, 2.0, v17, 2.0
	v_mul_f32_e32 v21, v16, v20
	v_fma_f32 v22, -v19, v21, v16
	v_fmac_f32_e32 v21, v22, v20
	v_fma_f32 v16, -v19, v21, v16
	v_mul_f32_e32 v19, 0x3d372713, v12
	v_mul_f32_e32 v19, v12, v19
	v_fma_f32 v19, v12, v19, v12
	v_mul_f32_e32 v19, 0x3f4c422a, v19
	v_add_f32_e32 v19, v19, v19
	v_mul_f32_e32 v19, 0x3fb8aa3b, v19
	v_exp_f32_e32 v19, v19
	v_div_fmas_f32 v16, v16, v20, v21
; #define LAS __attribute__((address_space(3)))
; __device__ __forceinline__ unsigned cvt_pk_bf16(float lo, float hi) { unsigned r; asm volatile("v_cvt_pk_bf16_f32 %0, %1, %2" : "=v"(r) : "v"(lo), "v"(hi)); return r; }
; __device__ __forceinline__ float gelu_tanh(float x) { const float z = 0.7978845608f * (x + 0.044715f * x * x * x); const float th = 1.0f - 2.0f / (__expf(2.0f * z) + 1.0f); return 0.5f * x * (1.0f + th); }
;     __device__ __forceinline__ void operator()(const f32x4 (&acc)[2][2][4][2], const Unit& u, int ui, const LAS float* rtab, int wr, int wc, int fr, int fq) const {
;         const int g = u.pm; const int n0 = wr * 64 + fr; const int lc0 = (u.pn & 1) * 256 + wc * 32 + 8 * fq;
; #pragma unroll
;         for (int ai = 0; ai < 2; ++ai)
; #pragma unroll
;             for (int m = 0; m < 4; ++m) {
;                 const int n = n0 + ai * HALF + m * 16;
; #pragma unroll
;                 for (int bj = 0; bj < 2; ++bj) {
;                     const int lc = lc0 + bj * HALF, t = lc >> 4, co = lc & 15; const int token = n * 32 + t;
;                     const f32x4 a0 = acc[ai][bj][m][0], a1 = acc[ai][bj][m][1];
;                     u32x4 w; w.x = cvt_pk_bf16(gelu_tanh(a0[0]), gelu_tanh(a0[1])); w.y = cvt_pk_bf16(gelu_tanh(a0[2]), gelu_tanh(a0[3]));
;                     w.z = cvt_pk_bf16(gelu_tanh(a1[0]), gelu_tanh(a1[1])); w.w = cvt_pk_bf16(gelu_tanh(a1[2]), gelu_tanh(a1[3]));
;                     *(u32x4*)(Y + (size_t)token * 1024 + 16 * g + co) = w;
;                 }
;             }
;     }
	v_div_fixup_f32 v16, v16, v17, 2.0
	v_sub_f32_e32 v16, 1.0, v16
	v_add_f32_e32 v17, 1.0, v19
	v_div_scale_f32 v19, s[28:29], v17, v17, 2.0
	v_rcp_f32_e32 v20, v19
	v_mul_f32_e32 v11, 0.5, v11
	v_add_f32_e32 v16, 1.0, v16
	v_mul_f32_e32 v11, v11, v16
	v_cvt_pk_bf16_f32 v16, v10, v11
	v_fma_f32 v10, -v19, v20, 1.0
	v_fmac_f32_e32 v20, v10, v20
	v_div_scale_f32 v10, vcc, 2.0, v17, 2.0
	v_mul_f32_e32 v11, v10, v20
	v_fma_f32 v21, -v19, v11, v10
	v_fmac_f32_e32 v11, v21, v20
	v_fma_f32 v10, -v19, v11, v10
	v_mul_f32_e32 v19, 0x3d372713, v13
	v_mul_f32_e32 v19, v13, v19
	v_fma_f32 v19, v13, v19, v13
	v_mul_f32_e32 v19, 0x3f4c422a, v19
	v_add_f32_e32 v19, v19, v19
	v_mul_f32_e32 v19, 0x3fb8aa3b, v19
	v_exp_f32_e32 v19, v19
	v_div_fmas_f32 v10, v10, v20, v11
	v_div_fixup_f32 v10, v10, v17, 2.0
	v_sub_f32_e32 v10, 1.0, v10
	v_add_f32_e32 v11, 1.0, v19
	v_div_scale_f32 v17, s[28:29], v11, v11, 2.0
	v_rcp_f32_e32 v19, v17
	v_mul_f32_e32 v12, 0.5, v12
	v_add_f32_e32 v10, 1.0, v10
	v_mul_f32_e32 v10, v12, v10
	v_fma_f32 v12, -v17, v19, 1.0
	v_fmac_f32_e32 v19, v12, v19
	v_div_scale_f32 v12, vcc, 2.0, v11, 2.0
	v_mul_f32_e32 v20, v12, v19
	v_fma_f32 v21, -v17, v20, v12
	v_fmac_f32_e32 v20, v21, v19
	v_fma_f32 v12, -v17, v20, v12
	v_div_fmas_f32 v12, v12, v19, v20
	v_div_fixup_f32 v11, v12, v11, 2.0
	v_sub_f32_e32 v11, 1.0, v11
	v_mul_f32_e32 v12, 0.5, v13
	v_add_f32_e32 v11, 1.0, v11
	v_mul_f32_e32 v11, v12, v11
	v_mul_f32_e32 v12, 0x3d372713, v6
	v_mul_f32_e32 v12, v6, v12
	v_fma_f32 v12, v6, v12, v6
	v_mul_f32_e32 v12, 0x3f4c422a, v12
	v_add_f32_e32 v12, v12, v12
	v_mul_f32_e32 v12, 0x3fb8aa3b, v12
	v_exp_f32_e32 v12, v12
	v_or_b32_e32 v18, v171, v153
	v_ashrrev_i32_e32 v19, 31, v18
	v_cvt_pk_bf16_f32 v17, v10, v11
	v_add_f32_e32 v12, 1.0, v12
	v_div_scale_f32 v13, s[28:29], v12, v12, 2.0
	v_lshlrev_b64 v[10:11], 11, v[18:19]
	v_rcp_f32_e32 v18, v13
	v_lshl_add_u64 v[10:11], v[138:139], 0, v[10:11]
	global_store_dwordx4 v[10:11], v[14:17], off
	v_mul_f32_e32 v6, 0.5, v6
	v_fma_f32 v11, -v13, v18, 1.0
	v_fmac_f32_e32 v18, v11, v18
	v_div_scale_f32 v11, vcc, 2.0, v12, 2.0
	v_mul_f32_e32 v14, v11, v18
	v_fma_f32 v15, -v13, v14, v11
	v_fmac_f32_e32 v14, v15, v18
	v_fma_f32 v11, -v13, v14, v11
	v_mul_f32_e32 v13, 0x3d372713, v7
	v_mul_f32_e32 v13, v7, v13
	v_fma_f32 v13, v7, v13, v7
	v_mul_f32_e32 v13, 0x3f4c422a, v13
	v_add_f32_e32 v13, v13, v13
	v_mul_f32_e32 v13, 0x3fb8aa3b, v13
	v_exp_f32_e32 v13, v13
	v_div_fmas_f32 v11, v11, v18, v14
	v_div_fixup_f32 v11, v11, v12, 2.0
	v_sub_f32_e32 v11, 1.0, v11
	v_add_f32_e32 v12, 1.0, v13
	v_div_scale_f32 v13, s[28:29], v12, v12, 2.0
	v_rcp_f32_e32 v14, v13
	v_add_f32_e32 v11, 1.0, v11
	v_mul_f32_e32 v6, v6, v11
	v_mul_f32_e32 v7, 0.5, v7
	v_fma_f32 v11, -v13, v14, 1.0
	v_fmac_f32_e32 v14, v11, v14
	v_div_scale_f32 v11, vcc, 2.0, v12, 2.0
	v_mul_f32_e32 v15, v11, v14
	v_fma_f32 v16, -v13, v15, v11
	v_fmac_f32_e32 v15, v16, v14
	v_fma_f32 v11, -v13, v15, v11
	v_mul_f32_e32 v13, 0x3d372713, v8
	v_mul_f32_e32 v13, v8, v13
	v_fma_f32 v13, v8, v13, v8
	v_mul_f32_e32 v13, 0x3f4c422a, v13
	v_add_f32_e32 v13, v13, v13
	v_mul_f32_e32 v13, 0x3fb8aa3b, v13
	v_exp_f32_e32 v13, v13
	v_div_fmas_f32 v11, v11, v14, v15
	v_div_fixup_f32 v11, v11, v12, 2.0
	v_sub_f32_e32 v11, 1.0, v11
	v_add_f32_e32 v12, 1.0, v13
	v_div_scale_f32 v13, s[28:29], v12, v12, 2.0
	v_rcp_f32_e32 v14, v13
	v_add_f32_e32 v11, 1.0, v11
	v_mul_f32_e32 v7, v7, v11
	v_cvt_pk_bf16_f32 v6, v6, v7
	v_fma_f32 v7, -v13, v14, 1.0
	v_fmac_f32_e32 v14, v7, v14
	v_div_scale_f32 v7, vcc, 2.0, v12, 2.0
	v_mul_f32_e32 v11, v7, v14
	v_fma_f32 v15, -v13, v11, v7
	v_fmac_f32_e32 v11, v15, v14
	v_fma_f32 v7, -v13, v11, v7
	v_mul_f32_e32 v13, 0x3d372713, v9
	v_mul_f32_e32 v13, v9, v13
	v_fma_f32 v13, v9, v13, v9
	v_mul_f32_e32 v13, 0x3f4c422a, v13
	v_add_f32_e32 v13, v13, v13
	v_mul_f32_e32 v13, 0x3fb8aa3b, v13
	v_exp_f32_e32 v13, v13
	v_div_fmas_f32 v7, v7, v14, v11
; #define LAS __attribute__((address_space(3)))
; __device__ __forceinline__ unsigned cvt_pk_bf16(float lo, float hi) { unsigned r; asm volatile("v_cvt_pk_bf16_f32 %0, %1, %2" : "=v"(r) : "v"(lo), "v"(hi)); return r; }
; __device__ __forceinline__ float gelu_tanh(float x) { const float z = 0.7978845608f * (x + 0.044715f * x * x * x); const float th = 1.0f - 2.0f / (__expf(2.0f * z) + 1.0f); return 0.5f * x * (1.0f + th); }
; #define PG8_WAIT_V(n) asm volatile("s_waitcnt vmcnt(" #n ")" ::: "memory")
; #define PG8_BAR __builtin_amdgcn_s_barrier()
;     __device__ __forceinline__ void operator()(const f32x4 (&acc)[2][2][4][2], const Unit& u, int ui, const LAS float* rtab, int wr, int wc, int fr, int fq) const {
;         const int g = u.pm; const int n0 = wr * 64 + fr; const int lc0 = (u.pn & 1) * 256 + wc * 32 + 8 * fq;
; #pragma unroll
;         for (int ai = 0; ai < 2; ++ai)
; #pragma unroll
;             for (int m = 0; m < 4; ++m) {
;                 const int n = n0 + ai * HALF + m * 16;
; #pragma unroll
;                 for (int bj = 0; bj < 2; ++bj) {
;                     const int lc = lc0 + bj * HALF, t = lc >> 4, co = lc & 15; const int token = n * 32 + t;
;                     const f32x4 a0 = acc[ai][bj][m][0], a1 = acc[ai][bj][m][1];
;                     u32x4 w; w.x = cvt_pk_bf16(gelu_tanh(a0[0]), gelu_tanh(a0[1])); w.y = cvt_pk_bf16(gelu_tanh(a0[2]), gelu_tanh(a0[3]));
;                     w.z = cvt_pk_bf16(gelu_tanh(a1[0]), gelu_tanh(a1[1])); w.w = cvt_pk_bf16(gelu_tanh(a1[2]), gelu_tanh(a1[3]));
;                     *(u32x4*)(Y + (size_t)token * 1024 + 16 * g + co) = w;
;                 }
;             }
;     }
; template <class Epi, class Sched>
; __device__ __forceinline__ void gemm_phase(LAS unsigned char* lds, const Gemm g, const Sched& S, const Epi& E) {
;     ...
;         if (!has_next) break;
; #pragma unroll
;         for (int a = 0; a < 2; ++a)
; #pragma unroll
;             for (int b = 0; b < 2; ++b)
; #pragma unroll
;                 for (int m = 0; m < 4; ++m)
; #pragma unroll
;                     for (int n = 0; n < 2; ++n) acc[a][b][m][n] = (f32x4){0.f, 0.f, 0.f, 0.f};
;         cur = nxt; cA = nA; cB = nB; ++ui;
;     }
;     PG8_WAIT_V(0);
;     if (wr == 0) PG8_BAR;
;     PG8_BAR;
	v_div_fixup_f32 v7, v7, v12, 2.0
	v_sub_f32_e32 v7, 1.0, v7
	v_add_f32_e32 v11, 1.0, v13
	v_div_scale_f32 v12, s[28:29], v11, v11, 2.0
	v_rcp_f32_e32 v13, v12
	v_mul_f32_e32 v8, 0.5, v8
	v_add_f32_e32 v7, 1.0, v7
	v_mul_f32_e32 v7, v8, v7
	v_fma_f32 v8, -v12, v13, 1.0
	v_fmac_f32_e32 v13, v8, v13
	v_div_scale_f32 v8, vcc, 2.0, v11, 2.0
	v_mul_f32_e32 v14, v8, v13
	v_fma_f32 v15, -v12, v14, v8
	v_fmac_f32_e32 v14, v15, v13
	v_fma_f32 v8, -v12, v14, v8
	v_mul_f32_e32 v12, 0x3d372713, v2
	v_mul_f32_e32 v12, v2, v12
	v_fma_f32 v12, v2, v12, v2
	v_mul_f32_e32 v12, 0x3f4c422a, v12
	v_add_f32_e32 v12, v12, v12
	v_mul_f32_e32 v12, 0x3fb8aa3b, v12
	v_exp_f32_e32 v12, v12
	v_div_fmas_f32 v8, v8, v13, v14
	v_div_fixup_f32 v8, v8, v11, 2.0
	v_sub_f32_e32 v8, 1.0, v8
	v_add_f32_e32 v11, 1.0, v12
	v_div_scale_f32 v12, s[28:29], v11, v11, 2.0
	v_rcp_f32_e32 v13, v12
	v_mul_f32_e32 v9, 0.5, v9
	v_add_f32_e32 v8, 1.0, v8
	v_mul_f32_e32 v8, v9, v8
	v_cvt_pk_bf16_f32 v7, v7, v8
	v_fma_f32 v8, -v12, v13, 1.0
	v_fmac_f32_e32 v13, v8, v13
	v_div_scale_f32 v8, vcc, 2.0, v11, 2.0
	v_mul_f32_e32 v9, v8, v13
	v_fma_f32 v14, -v12, v9, v8
	v_fmac_f32_e32 v9, v14, v13
	v_fma_f32 v8, -v12, v9, v8
	v_mul_f32_e32 v12, 0x3d372713, v3
	v_mul_f32_e32 v12, v3, v12
	v_fma_f32 v12, v3, v12, v3
	v_mul_f32_e32 v12, 0x3f4c422a, v12
	v_add_f32_e32 v12, v12, v12
	v_mul_f32_e32 v12, 0x3fb8aa3b, v12
	v_exp_f32_e32 v12, v12
	v_div_fmas_f32 v8, v8, v13, v9
	v_div_fixup_f32 v8, v8, v11, 2.0
	v_sub_f32_e32 v8, 1.0, v8
	v_add_f32_e32 v9, 1.0, v12
	v_div_scale_f32 v11, s[28:29], v9, v9, 2.0
	v_rcp_f32_e32 v12, v11
	v_mul_f32_e32 v2, 0.5, v2
	v_add_f32_e32 v8, 1.0, v8
	v_mul_f32_e32 v2, v2, v8
	v_fma_f32 v8, -v11, v12, 1.0
	v_fmac_f32_e32 v12, v8, v12
	v_div_scale_f32 v8, vcc, 2.0, v9, 2.0
	v_mul_f32_e32 v13, v8, v12
	v_fma_f32 v14, -v11, v13, v8
	v_fmac_f32_e32 v13, v14, v12
	v_fma_f32 v8, -v11, v13, v8
	v_mul_f32_e32 v11, 0x3d372713, v4
	v_mul_f32_e32 v11, v4, v11
	v_fma_f32 v11, v4, v11, v4
	v_mul_f32_e32 v11, 0x3f4c422a, v11
	v_add_f32_e32 v11, v11, v11
	v_mul_f32_e32 v11, 0x3fb8aa3b, v11
	v_exp_f32_e32 v11, v11
	v_div_fmas_f32 v8, v8, v12, v13
	v_div_fixup_f32 v8, v8, v9, 2.0
	v_sub_f32_e32 v8, 1.0, v8
	v_add_f32_e32 v9, 1.0, v11
	v_div_scale_f32 v11, s[28:29], v9, v9, 2.0
	v_rcp_f32_e32 v12, v11
	v_mul_f32_e32 v3, 0.5, v3
	v_add_f32_e32 v8, 1.0, v8
	v_mul_f32_e32 v3, v3, v8
	v_cvt_pk_bf16_f32 v8, v2, v3
	v_fma_f32 v2, -v11, v12, 1.0
	v_fmac_f32_e32 v12, v2, v12
	v_div_scale_f32 v2, vcc, 2.0, v9, 2.0
	v_mul_f32_e32 v3, v2, v12
	v_fma_f32 v13, -v11, v3, v2
	v_fmac_f32_e32 v3, v13, v12
	v_fma_f32 v2, -v11, v3, v2
	v_mul_f32_e32 v11, 0x3d372713, v5
	v_mul_f32_e32 v11, v5, v11
	v_fma_f32 v11, v5, v11, v5
	v_mul_f32_e32 v11, 0x3f4c422a, v11
	v_add_f32_e32 v11, v11, v11
	v_mul_f32_e32 v11, 0x3fb8aa3b, v11
	v_exp_f32_e32 v11, v11
	v_div_fmas_f32 v2, v2, v12, v3
	v_div_fixup_f32 v2, v2, v9, 2.0
	v_sub_f32_e32 v2, 1.0, v2
	v_add_f32_e32 v3, 1.0, v11
	v_div_scale_f32 v9, s[28:29], v3, v3, 2.0
	v_rcp_f32_e32 v11, v9
	v_mul_f32_e32 v4, 0.5, v4
	v_add_f32_e32 v2, 1.0, v2
	v_mul_f32_e32 v2, v4, v2
	v_fma_f32 v4, -v9, v11, 1.0
	v_fmac_f32_e32 v11, v4, v11
	v_div_scale_f32 v4, vcc, 2.0, v3, 2.0
	v_mul_f32_e32 v12, v4, v11
	v_fma_f32 v13, -v9, v12, v4
	v_fmac_f32_e32 v12, v13, v11
	v_fma_f32 v4, -v9, v12, v4
	v_div_fmas_f32 v4, v4, v11, v12
	v_div_fixup_f32 v3, v4, v3, 2.0
	v_sub_f32_e32 v3, 1.0, v3
	v_or_b32_e32 v10, v124, v153
	v_mul_f32_e32 v4, 0.5, v5
	v_add_f32_e32 v3, 1.0, v3
	v_mul_f32_e32 v3, v4, v3
	v_ashrrev_i32_e32 v11, 31, v10
	v_cvt_pk_bf16_f32 v9, v2, v3
	v_lshlrev_b64 v[2:3], 11, v[10:11]
	v_lshl_add_u64 v[2:3], v[138:139], 0, v[2:3]
	s_mov_b64 s[42:43], 0
	s_and_b64 vcc, exec, s[40:41]
	v_readlane_b32 s26, v254, 32
	global_store_dwordx4 v[2:3], v[6:9], off
	s_cbranch_vccz .LBB0_594
	s_waitcnt vmcnt(0)
	s_cmpk_gt_u32 s12, 0xff
	s_cbranch_scc1 .LBB0_599
	s_barrier

; #define PG8_STAGE(bufoff, gbase, voff) do { _Pragma("unroll") for (int _i = 0; _i < 2; ++_i) \
;         __builtin_amdgcn_global_load_lds((const unsigned*)((const char*)(gbase) + (voff)[_i]), (LAS unsigned*)(lds + (bufoff) + ldsw + _i * 8192), 16, 0, 0); } while (0)
; #define PG8_LDA(dst, b, h) do { _Pragma("unroll") for (int m = 0; m < 4; ++m) _Pragma("unroll") for (int k = 0; k < 2; ++k) dst[m][k] = *(const LAS bf16x8*)(lds + PG8_SA(b, h) + aoff + m * 2048 + k * 1024); } while (0)
; #define PG8_WAIT_V(n) asm volatile("s_waitcnt vmcnt(" #n ")" ::: "memory")
; #define PG8_WAIT_L(n) asm volatile("s_waitcnt lgkmcnt(" #n ")" ::: "memory")
; template <class Epi, class Sched>
; __device__ __forceinline__ void gemm_phase(LAS unsigned char* lds, const Gemm g, const Sched& S, const Epi& E) {
;     ...
;         for (int t = 0; t < nt; t += 2) {
;             const bool last = (t == nt - 2);
;             const char* a1 = cA + (size_t)(t + 1) * kstep;
;             const char* a2 = last ? nA : cA + (size_t)(t + 2) * kstep; const char* b2 = last ? nB : cB + (size_t)(t + 2) * kstep;
;             const char* a3 = a2 + kstep; const char* b3 = b2 + kstep;
;             PG8_LDB(B0, 0, 0); PG8_SCHED; PG8_LDA(At, 0, 0); PG8_STAGE(PG8_SA(1, 1), a1 + hstepA, voffA);
;             PG8_WAIT_L(8); PG8_BAR; PG8_WAIT_L(0); PG8_MMA(0, 0, At, B0); PG8_BAR; PG8_SCHED;
;             PG8_LDB(B1, 0, 1); PG8_STAGE(PG8_SB(0, 0), b2, voffB);
;             PG8_BAR; PG8_WAIT_L(0); PG8_MMA(0, 1, At, B1); PG8_BAR;
;             PG8_LDA(At, 0, 1); PG8_STAGE(PG8_SA(0, 0), a2, voffA);
;             PG8_BAR; PG8_WAIT_L(0); PG8_MMA(1, 0, At, B0); PG8_BAR; PG8_SCHED;
;             PG8_STAGE(PG8_SB(0, 1), b2 + hstepB, voffB);
;             PG8_WAIT_V(6); PG8_BAR; PG8_MMA(1, 1, At, B1); PG8_BAR;
;             PG8_LDB(B0, 1, 0); PG8_SCHED; PG8_LDA(At, 1, 0); PG8_STAGE(PG8_SA(0, 1), a2 + hstepA, voffA);
;             PG8_WAIT_L(8); PG8_BAR; PG8_WAIT_L(0); PG8_MMA(0, 0, At, B0); PG8_BAR; PG8_SCHED;
;             PG8_LDB(B1, 1, 1); PG8_STAGE(PG8_SB(1, 0), b3, voffB);
;             PG8_BAR; PG8_WAIT_L(0); PG8_MMA(0, 1, At, B1); PG8_BAR;
;             PG8_LDA(At, 1, 1); PG8_STAGE(PG8_SA(1, 0), a3, voffA);
;             PG8_BAR; PG8_WAIT_L(0); PG8_MMA(1, 0, At, B0); PG8_BAR; PG8_SCHED;
;             PG8_STAGE(PG8_SB(1, 1), b3 + hstepB, voffB);
;             PG8_WAIT_V(6); PG8_BAR; PG8_MMA(1, 1, At, B1); PG8_BAR;
.LBB0_668:
	s_add_u32 s23, s20, 0xfffc0080
	s_addc_u32 s34, s21, -1
	s_add_i32 s43, 0, 0x10000
	v_add_u32_e32 v153, s43, v150
	ds_read_b128 v[142:145], v153
	ds_read_b128 v[146:149], v153 offset:1024
	ds_read_b128 v[170:173], v153 offset:2048
	ds_read_b128 v[174:177], v153 offset:3072
	s_cmp_eq_u32 s31, 12
	s_cselect_b32 s49, s24, s34
	s_cselect_b32 s48, s25, s23
	s_cselect_b32 s37, s1, s29
	s_cselect_b32 s36, s26, s28
	v_lshl_add_u64 v[198:199], s[20:21], 0, v[138:139]
	s_add_i32 m0, s52, 0xc000
	ds_read_b128 v[178:181], v152
	ds_read_b128 v[182:185], v152 offset:1024
	ds_read_b128 v[186:189], v152 offset:2048
	ds_read_b128 v[190:193], v152 offset:3072
	ds_read_b128 v[194:197], v152 offset:4096
	ds_read_b128 v[210:213], v152 offset:5120
	ds_read_b128 v[214:217], v152 offset:6144
	ds_read_b128 v[218:221], v152 offset:7168
	global_load_lds_dwordx4 v[198:199], off
	v_lshl_add_u64 v[198:199], s[20:21], 0, v[140:141]
	s_add_i32 m0, s52, 0xe000
	s_nop 0
	global_load_lds_dwordx4 v[198:199], off
	s_waitcnt lgkmcnt(8)
	s_barrier
	s_waitcnt lgkmcnt(0)
	v_mfma_f32_16x16x32_bf16 v[126:129], v[142:145], v[178:181], v[126:129]
	v_mfma_f32_16x16x32_bf16 v[122:125], v[170:173], v[178:181], v[122:125]
	v_mfma_f32_16x16x32_bf16 v[110:113], v[142:145], v[186:189], v[110:113]
	v_mfma_f32_16x16x32_bf16 v[106:109], v[170:173], v[186:189], v[106:109]
	v_mfma_f32_16x16x32_bf16 v[94:97], v[142:145], v[194:197], v[94:97]
	v_mfma_f32_16x16x32_bf16 v[90:93], v[170:173], v[194:197], v[90:93]
	v_mfma_f32_16x16x32_bf16 v[78:81], v[142:145], v[214:217], v[78:81]
	v_mfma_f32_16x16x32_bf16 v[74:77], v[170:173], v[214:217], v[74:77]
	v_mfma_f32_16x16x32_bf16 v[126:129], v[146:149], v[182:185], v[126:129]
	v_mfma_f32_16x16x32_bf16 v[122:125], v[174:177], v[182:185], v[122:125]
	v_mfma_f32_16x16x32_bf16 v[110:113], v[146:149], v[190:193], v[110:113]
	v_mfma_f32_16x16x32_bf16 v[106:109], v[174:177], v[190:193], v[106:109]
	v_mfma_f32_16x16x32_bf16 v[94:97], v[146:149], v[210:213], v[94:97]
	v_mfma_f32_16x16x32_bf16 v[90:93], v[174:177], v[210:213], v[90:93]
	v_mfma_f32_16x16x32_bf16 v[78:81], v[146:149], v[218:221], v[78:81]
	v_mfma_f32_16x16x32_bf16 v[74:77], v[174:177], v[218:221], v[74:77]
	s_barrier
	s_add_i32 s23, 0, 0x14000
	s_add_i32 s34, s43, s51
	v_add_u32_e32 v153, s23, v150
	v_lshl_add_u64 v[198:199], s[36:37], 0, v[134:135]
	s_mov_b32 m0, s34
	ds_read_b128 v[222:225], v153
	ds_read_b128 v[226:229], v153 offset:1024
	ds_read_b128 v[230:233], v153 offset:2048
	ds_read_b128 v[234:237], v153 offset:3072
	global_load_lds_dwordx4 v[198:199], off
	v_lshl_add_u64 v[238:239], s[36:37], 0, v[130:131]
	s_add_i32 m0, s34, 0x2000
	s_nop 0
	global_load_lds_dwordx4 v[238:239], off
	s_barrier
	s_waitcnt lgkmcnt(0)
	v_mfma_f32_16x16x32_bf16 v[118:121], v[222:225], v[178:181], v[118:121]
	v_mfma_f32_16x16x32_bf16 v[114:117], v[230:233], v[178:181], v[114:117]
	v_mfma_f32_16x16x32_bf16 v[102:105], v[222:225], v[186:189], v[102:105]
	v_mfma_f32_16x16x32_bf16 v[98:101], v[230:233], v[186:189], v[98:101]
	v_mfma_f32_16x16x32_bf16 v[86:89], v[222:225], v[194:197], v[86:89]
	v_mfma_f32_16x16x32_bf16 v[82:85], v[230:233], v[194:197], v[82:85]
	v_mfma_f32_16x16x32_bf16 v[70:73], v[222:225], v[214:217], v[70:73]
	v_mfma_f32_16x16x32_bf16 v[66:69], v[230:233], v[214:217], v[66:69]
	v_mfma_f32_16x16x32_bf16 v[118:121], v[226:229], v[182:185], v[118:121]
	v_mfma_f32_16x16x32_bf16 v[114:117], v[234:237], v[182:185], v[114:117]
	v_mfma_f32_16x16x32_bf16 v[102:105], v[226:229], v[190:193], v[102:105]
	v_mfma_f32_16x16x32_bf16 v[98:101], v[234:237], v[190:193], v[98:101]
	v_mfma_f32_16x16x32_bf16 v[86:89], v[226:229], v[210:213], v[86:89]
	v_mfma_f32_16x16x32_bf16 v[82:85], v[234:237], v[210:213], v[82:85]
	v_mfma_f32_16x16x32_bf16 v[70:73], v[226:229], v[218:221], v[70:73]
	v_mfma_f32_16x16x32_bf16 v[66:69], v[234:237], v[218:221], v[66:69]
	s_mov_b32 m0, s52
	v_lshl_add_u64 v[240:241], s[48:49], 0, v[136:137]
	s_barrier
	ds_read_b128 v[178:181], v152 offset:16384
	ds_read_b128 v[182:185], v152 offset:17408
	ds_read_b128 v[186:189], v152 offset:18432
	ds_read_b128 v[190:193], v152 offset:19456
	ds_read_b128 v[194:197], v152 offset:20480
	ds_read_b128 v[210:213], v152 offset:21504
	ds_read_b128 v[214:217], v152 offset:22528
	ds_read_b128 v[218:221], v152 offset:23552
	global_load_lds_dwordx4 v[240:241], off
	v_lshl_add_u64 v[242:243], s[48:49], 0, v[132:133]
	s_mov_b32 m0, s53
	s_nop 0
	global_load_lds_dwordx4 v[242:243], off
	s_barrier
	s_waitcnt lgkmcnt(0)
	v_mfma_f32_16x16x32_bf16 v[62:65], v[142:145], v[178:181], v[62:65]
	v_mfma_f32_16x16x32_bf16 v[58:61], v[170:173], v[178:181], v[58:61]
	v_mfma_f32_16x16x32_bf16 v[46:49], v[142:145], v[186:189], v[46:49]
	v_mfma_f32_16x16x32_bf16 v[42:45], v[170:173], v[186:189], v[42:45]
	v_mfma_f32_16x16x32_bf16 v[30:33], v[142:145], v[194:197], v[30:33]
	v_mfma_f32_16x16x32_bf16 v[26:29], v[170:173], v[194:197], v[26:29]
	v_mfma_f32_16x16x32_bf16 v[14:17], v[142:145], v[214:217], v[14:17]
	v_mfma_f32_16x16x32_bf16 v[10:13], v[170:173], v[214:217], v[10:13]
	v_mfma_f32_16x16x32_bf16 v[62:65], v[146:149], v[182:185], v[62:65]
	v_mfma_f32_16x16x32_bf16 v[58:61], v[174:177], v[182:185], v[58:61]
	v_mfma_f32_16x16x32_bf16 v[46:49], v[146:149], v[190:193], v[46:49]
	v_mfma_f32_16x16x32_bf16 v[42:45], v[174:177], v[190:193], v[42:45]
	v_mfma_f32_16x16x32_bf16 v[30:33], v[146:149], v[210:213], v[30:33]
	v_mfma_f32_16x16x32_bf16 v[26:29], v[174:177], v[210:213], v[26:29]
	v_mfma_f32_16x16x32_bf16 v[14:17], v[146:149], v[218:221], v[14:17]
	v_mfma_f32_16x16x32_bf16 v[10:13], v[174:177], v[218:221], v[10:13]
	s_barrier
; #define PG8_STAGE(bufoff, gbase, voff) do { _Pragma("unroll") for (int _i = 0; _i < 2; ++_i) \
;         __builtin_amdgcn_global_load_lds((const unsigned*)((const char*)(gbase) + (voff)[_i]), (LAS unsigned*)(lds + (bufoff) + ldsw + _i * 8192), 16, 0, 0); } while (0)
; #define PG8_LDA(dst, b, h) do { _Pragma("unroll") for (int m = 0; m < 4; ++m) _Pragma("unroll") for (int k = 0; k < 2; ++k) dst[m][k] = *(const LAS bf16x8*)(lds + PG8_SA(b, h) + aoff + m * 2048 + k * 1024); } while (0)
; #define PG8_LDB(dst, b, h) do { _Pragma("unroll") for (int n = 0; n < 2; ++n) _Pragma("unroll") for (int k = 0; k < 2; ++k) dst[n][k] = *(const LAS bf16x8*)(lds + PG8_SB(b, h) + boff + n * 2048 + k * 1024); } while (0)
; #define PG8_WAIT_V(n) asm volatile("s_waitcnt vmcnt(" #n ")" ::: "memory")
; #define PG8_WAIT_L(n) asm volatile("s_waitcnt lgkmcnt(" #n ")" ::: "memory")
; #define PG8_BAR __builtin_amdgcn_s_barrier()
; #define PG8_SCHED __builtin_amdgcn_sched_barrier(0)
; template <class Epi, class Sched>
; __device__ __forceinline__ void gemm_phase(LAS unsigned char* lds, const Gemm g, const Sched& S, const Epi& E) {
;     ...
;             PG8_LDB(B0, 0, 0); PG8_SCHED; PG8_LDA(At, 0, 0); PG8_STAGE(PG8_SA(1, 1), a1 + hstepA, voffA);
;             PG8_WAIT_L(8); PG8_BAR; PG8_WAIT_L(0); PG8_MMA(0, 0, At, B0); PG8_BAR; PG8_SCHED;
;             PG8_LDB(B1, 0, 1); PG8_STAGE(PG8_SB(0, 0), b2, voffB);
;             PG8_BAR; PG8_WAIT_L(0); PG8_MMA(0, 1, At, B1); PG8_BAR;
;             PG8_LDA(At, 0, 1); PG8_STAGE(PG8_SA(0, 0), a2, voffA);
;             PG8_BAR; PG8_WAIT_L(0); PG8_MMA(1, 0, At, B0); PG8_BAR; PG8_SCHED;
;             PG8_STAGE(PG8_SB(0, 1), b2 + hstepB, voffB);
;             PG8_WAIT_V(6); PG8_BAR; PG8_MMA(1, 1, At, B1); PG8_BAR;
;             PG8_LDB(B0, 1, 0); PG8_SCHED; PG8_LDA(At, 1, 0); PG8_STAGE(PG8_SA(0, 1), a2 + hstepA, voffA);
;             PG8_WAIT_L(8); PG8_BAR; PG8_WAIT_L(0); PG8_MMA(0, 0, At, B0); PG8_BAR; PG8_SCHED;
;             PG8_LDB(B1, 1, 1); PG8_STAGE(PG8_SB(1, 0), b3, voffB);
;             PG8_BAR; PG8_WAIT_L(0); PG8_MMA(0, 1, At, B1); PG8_BAR;
;             PG8_LDA(At, 1, 1); PG8_STAGE(PG8_SA(1, 0), a3, voffA);
;             PG8_BAR; PG8_WAIT_L(0); PG8_MMA(1, 0, At, B0); PG8_BAR; PG8_SCHED;
;             PG8_STAGE(PG8_SB(1, 1), b3 + hstepB, voffB);
;             PG8_WAIT_V(6); PG8_BAR; PG8_MMA(1, 1, At, B1); PG8_BAR;
	s_add_u32 s66, s36, 0x40000
	s_addc_u32 s67, s37, 0
	s_add_i32 s23, s23, s51
	v_lshl_add_u64 v[142:143], s[66:67], 0, v[134:135]
	s_mov_b32 m0, s23
	s_nop 0
	global_load_lds_dwordx4 v[142:143], off
	v_lshl_add_u64 v[142:143], s[66:67], 0, v[130:131]
	s_add_i32 m0, s23, 0x2000
	s_nop 0
	global_load_lds_dwordx4 v[142:143], off
	s_waitcnt vmcnt(6)
	s_barrier
	v_mfma_f32_16x16x32_bf16 v[54:57], v[222:225], v[178:181], v[54:57]
	v_mfma_f32_16x16x32_bf16 v[50:53], v[230:233], v[178:181], v[50:53]
	v_mfma_f32_16x16x32_bf16 v[38:41], v[222:225], v[186:189], v[38:41]
	v_mfma_f32_16x16x32_bf16 v[34:37], v[230:233], v[186:189], v[34:37]
	v_mfma_f32_16x16x32_bf16 v[22:25], v[222:225], v[194:197], v[22:25]
	v_mfma_f32_16x16x32_bf16 v[18:21], v[230:233], v[194:197], v[18:21]
	v_mfma_f32_16x16x32_bf16 v[6:9], v[222:225], v[214:217], v[6:9]
	v_mfma_f32_16x16x32_bf16 v[2:5], v[230:233], v[214:217], v[2:5]
	v_mfma_f32_16x16x32_bf16 v[54:57], v[226:229], v[182:185], v[54:57]
	v_mfma_f32_16x16x32_bf16 v[50:53], v[234:237], v[182:185], v[50:53]
	v_mfma_f32_16x16x32_bf16 v[38:41], v[226:229], v[190:193], v[38:41]
	v_mfma_f32_16x16x32_bf16 v[34:37], v[234:237], v[190:193], v[34:37]
	v_mfma_f32_16x16x32_bf16 v[22:25], v[226:229], v[210:213], v[22:25]
	v_mfma_f32_16x16x32_bf16 v[18:21], v[234:237], v[210:213], v[18:21]
	v_mfma_f32_16x16x32_bf16 v[6:9], v[226:229], v[218:221], v[6:9]
	v_mfma_f32_16x16x32_bf16 v[2:5], v[234:237], v[218:221], v[2:5]
	s_add_i32 s23, 0, 0x18000
	v_add_u32_e32 v153, s23, v150
	s_barrier
	ds_read_b128 v[142:145], v153
	ds_read_b128 v[146:149], v153 offset:1024
	ds_read_b128 v[170:173], v153 offset:2048
	ds_read_b128 v[174:177], v153 offset:3072
	s_add_u32 s48, s48, 0x40000
	s_addc_u32 s49, s49, 0
	s_mov_b32 m0, s54
	v_lshl_add_u64 v[222:223], s[48:49], 0, v[136:137]
	ds_read_b128 v[178:181], v152 offset:32768
	ds_read_b128 v[182:185], v152 offset:33792
	ds_read_b128 v[186:189], v152 offset:34816
	ds_read_b128 v[190:193], v152 offset:35840
	ds_read_b128 v[194:197], v152 offset:36864
	ds_read_b128 v[210:213], v152 offset:37888
	ds_read_b128 v[214:217], v152 offset:38912
	ds_read_b128 v[218:221], v152 offset:39936
	global_load_lds_dwordx4 v[222:223], off
	v_lshl_add_u64 v[222:223], s[48:49], 0, v[132:133]
	s_mov_b32 m0, s55
	s_nop 0
	global_load_lds_dwordx4 v[222:223], off
	s_waitcnt lgkmcnt(8)
	s_barrier
	s_waitcnt lgkmcnt(0)
	v_mfma_f32_16x16x32_bf16 v[126:129], v[142:145], v[178:181], v[126:129]
	v_mfma_f32_16x16x32_bf16 v[122:125], v[170:173], v[178:181], v[122:125]
	v_mfma_f32_16x16x32_bf16 v[110:113], v[142:145], v[186:189], v[110:113]
	v_mfma_f32_16x16x32_bf16 v[106:109], v[170:173], v[186:189], v[106:109]
	v_mfma_f32_16x16x32_bf16 v[94:97], v[142:145], v[194:197], v[94:97]
	v_mfma_f32_16x16x32_bf16 v[90:93], v[170:173], v[194:197], v[90:93]
	v_mfma_f32_16x16x32_bf16 v[78:81], v[142:145], v[214:217], v[78:81]
	v_mfma_f32_16x16x32_bf16 v[74:77], v[170:173], v[214:217], v[74:77]
	v_mfma_f32_16x16x32_bf16 v[126:129], v[146:149], v[182:185], v[126:129]
	v_mfma_f32_16x16x32_bf16 v[122:125], v[174:177], v[182:185], v[122:125]
	v_mfma_f32_16x16x32_bf16 v[110:113], v[146:149], v[190:193], v[110:113]
	v_mfma_f32_16x16x32_bf16 v[106:109], v[174:177], v[190:193], v[106:109]
	v_mfma_f32_16x16x32_bf16 v[94:97], v[146:149], v[210:213], v[94:97]
	v_mfma_f32_16x16x32_bf16 v[90:93], v[174:177], v[210:213], v[90:93]
	v_mfma_f32_16x16x32_bf16 v[78:81], v[146:149], v[218:221], v[78:81]
	v_mfma_f32_16x16x32_bf16 v[74:77], v[174:177], v[218:221], v[74:77]
	s_barrier
	s_add_i32 s34, 0, 0x1c000
	s_add_i32 s23, s23, s51
	v_add_u32_e32 v153, s34, v150
	v_lshl_add_u64 v[198:199], v[198:199], 0, s[10:11]
	s_mov_b32 m0, s23
	ds_read_b128 v[222:225], v153
	ds_read_b128 v[226:229], v153 offset:1024
	ds_read_b128 v[230:233], v153 offset:2048
	ds_read_b128 v[234:237], v153 offset:3072
	global_load_lds_dwordx4 v[198:199], off
	v_lshl_add_u64 v[198:199], v[238:239], 0, s[10:11]
	s_add_i32 m0, s23, 0x2000
	s_nop 0
	global_load_lds_dwordx4 v[198:199], off
	s_barrier
	s_waitcnt lgkmcnt(0)
	v_mfma_f32_16x16x32_bf16 v[118:121], v[222:225], v[178:181], v[118:121]
	v_mfma_f32_16x16x32_bf16 v[114:117], v[230:233], v[178:181], v[114:117]
	v_mfma_f32_16x16x32_bf16 v[102:105], v[222:225], v[186:189], v[102:105]
	v_mfma_f32_16x16x32_bf16 v[98:101], v[230:233], v[186:189], v[98:101]
	v_mfma_f32_16x16x32_bf16 v[86:89], v[222:225], v[194:197], v[86:89]
	v_mfma_f32_16x16x32_bf16 v[82:85], v[230:233], v[194:197], v[82:85]
	v_mfma_f32_16x16x32_bf16 v[70:73], v[222:225], v[214:217], v[70:73]
	v_mfma_f32_16x16x32_bf16 v[66:69], v[230:233], v[214:217], v[66:69]
	v_mfma_f32_16x16x32_bf16 v[118:121], v[226:229], v[182:185], v[118:121]
	v_mfma_f32_16x16x32_bf16 v[114:117], v[234:237], v[182:185], v[114:117]
	v_mfma_f32_16x16x32_bf16 v[102:105], v[226:229], v[190:193], v[102:105]
	v_mfma_f32_16x16x32_bf16 v[98:101], v[234:237], v[190:193], v[98:101]
	v_mfma_f32_16x16x32_bf16 v[86:89], v[226:229], v[210:213], v[86:89]
	v_mfma_f32_16x16x32_bf16 v[82:85], v[234:237], v[210:213], v[82:85]
	v_mfma_f32_16x16x32_bf16 v[70:73], v[226:229], v[218:221], v[70:73]
	v_mfma_f32_16x16x32_bf16 v[66:69], v[234:237], v[218:221], v[66:69]
	s_mov_b32 m0, s56
	v_lshl_add_u64 v[198:199], v[240:241], 0, s[10:11]
	s_barrier
	ds_read_b128 v[178:181], v152 offset:49152
	ds_read_b128 v[182:185], v152 offset:50176
	ds_read_b128 v[186:189], v152 offset:51200
	ds_read_b128 v[190:193], v152 offset:52224
	ds_read_b128 v[194:197], v152 offset:53248
	ds_read_b128 v[210:213], v152 offset:54272
	ds_read_b128 v[214:217], v152 offset:55296
	ds_read_b128 v[218:221], v152 offset:56320
	global_load_lds_dwordx4 v[198:199], off
	v_lshl_add_u64 v[198:199], v[242:243], 0, s[10:11]
	s_mov_b32 m0, s57
	s_nop 0
	global_load_lds_dwordx4 v[198:199], off
	s_barrier
; #define LAS __attribute__((address_space(3)))
; __device__ __forceinline__ float bf_lo(unsigned w) { return __uint_as_float(w << 16); }
; __device__ __forceinline__ float bf_hi(unsigned w) { return __uint_as_float(w & 0xffff0000u); }
; #define PG8_BAR __builtin_amdgcn_s_barrier()
;     __device__ __forceinline__ void operator()(const f32x4 (&acc)[2][2][4][2], const Unit& u, int ui, const LAS float* rtab, int wr, int wc, int fr, int fq) const {
;         const int row0 = u.pm * BM + wr * 64 + fr, col0 = u.pn * BM + wc * 32 + 8 * fq;
; #pragma unroll
;         for (int ai = 0; ai < 2; ++ai)
; #pragma unroll
;             for (int m = 0; m < 4; ++m) {
;                 const int row = row0 + ai * HALF + m * 16;
; #pragma unroll
;                 for (int bj = 0; bj < 2; ++bj) {
;                     const int col = col0 + bj * HALF; const u32x4 yv = *(const u32x4*)(Y + (size_t)row * 1024 + col);
;                     const f32x4 a0 = acc[ai][bj][m][0], a1 = acc[ai][bj][m][1]; float o[8];
;                     const float yy[8] = {bf_lo(yv.x), bf_hi(yv.x), bf_lo(yv.y), bf_hi(yv.y), bf_lo(yv.z), bf_hi(yv.z), bf_lo(yv.w), bf_hi(yv.w)};
; #pragma unroll
;                     for (int e = 0; e < 4; ++e) { o[e] = yy[e] / (1.0f + __expf(-a0[e])); o[4 + e] = yy[4 + e] / (1.0f + __expf(-a1[e])); }
; template <class Epi, class Sched>
; __device__ __forceinline__ void gemm_phase(LAS unsigned char* lds, const Gemm g, const Sched& S, const Epi& E) {
;     ...
;             PG8_BAR; PG8_WAIT_L(0); PG8_MMA(1, 0, At, B0); PG8_BAR; PG8_SCHED;
;             PG8_STAGE(PG8_SB(0, 1), b2 + hstepB, voffB);
;             PG8_WAIT_V(6); PG8_BAR; PG8_MMA(1, 1, At, B1); PG8_BAR;
;             PG8_LDB(B0, 1, 0); PG8_SCHED; PG8_LDA(At, 1, 0); PG8_STAGE(PG8_SA(0, 1), a2 + hstepA, voffA);
;             PG8_WAIT_L(8); PG8_BAR; PG8_WAIT_L(0); PG8_MMA(0, 0, At, B0); PG8_BAR; PG8_SCHED;
;             PG8_LDB(B1, 1, 1); PG8_STAGE(PG8_SB(1, 0), b3, voffB);
;             PG8_BAR; PG8_WAIT_L(0); PG8_MMA(0, 1, At, B1); PG8_BAR;
;             PG8_LDA(At, 1, 1); PG8_STAGE(PG8_SA(1, 0), a3, voffA);
;             PG8_BAR; PG8_WAIT_L(0); PG8_MMA(1, 0, At, B0); PG8_BAR; PG8_SCHED;
;             PG8_STAGE(PG8_SB(1, 1), b3 + hstepB, voffB);
;             PG8_WAIT_V(6); PG8_BAR; PG8_MMA(1, 1, At, B1); PG8_BAR;
;         }
;         E(acc, cur, ui, (const LAS float*)(lds + STAGE_BYTES), wr, wc, fr, fq);
	s_waitcnt lgkmcnt(0)
	v_mfma_f32_16x16x32_bf16 v[62:65], v[142:145], v[178:181], v[62:65]
	v_mfma_f32_16x16x32_bf16 v[58:61], v[170:173], v[178:181], v[58:61]
	v_mfma_f32_16x16x32_bf16 v[46:49], v[142:145], v[186:189], v[46:49]
	v_mfma_f32_16x16x32_bf16 v[42:45], v[170:173], v[186:189], v[42:45]
	v_mfma_f32_16x16x32_bf16 v[30:33], v[142:145], v[194:197], v[30:33]
	v_mfma_f32_16x16x32_bf16 v[26:29], v[170:173], v[194:197], v[26:29]
	v_mfma_f32_16x16x32_bf16 v[14:17], v[142:145], v[214:217], v[14:17]
	v_mfma_f32_16x16x32_bf16 v[10:13], v[170:173], v[214:217], v[10:13]
	v_mfma_f32_16x16x32_bf16 v[62:65], v[146:149], v[182:185], v[62:65]
	v_mfma_f32_16x16x32_bf16 v[58:61], v[174:177], v[182:185], v[58:61]
	v_mfma_f32_16x16x32_bf16 v[46:49], v[146:149], v[190:193], v[46:49]
	v_mfma_f32_16x16x32_bf16 v[42:45], v[174:177], v[190:193], v[42:45]
	v_mfma_f32_16x16x32_bf16 v[30:33], v[146:149], v[210:213], v[30:33]
	v_mfma_f32_16x16x32_bf16 v[26:29], v[174:177], v[210:213], v[26:29]
	v_mfma_f32_16x16x32_bf16 v[14:17], v[146:149], v[218:221], v[14:17]
	v_mfma_f32_16x16x32_bf16 v[10:13], v[174:177], v[218:221], v[10:13]
	s_barrier
	s_add_u32 s36, s36, 0x40080
	s_addc_u32 s37, s37, 0
	s_add_i32 s23, s34, s51
	v_lshl_add_u64 v[142:143], s[36:37], 0, v[134:135]
	s_mov_b32 m0, s23
	s_nop 0
	global_load_lds_dwordx4 v[142:143], off
	v_lshl_add_u64 v[142:143], s[36:37], 0, v[130:131]
	s_add_i32 m0, s23, 0x2000
	s_nop 0
	global_load_lds_dwordx4 v[142:143], off
	s_waitcnt vmcnt(6)
	s_barrier
	v_mfma_f32_16x16x32_bf16 v[54:57], v[222:225], v[178:181], v[54:57]
	v_mfma_f32_16x16x32_bf16 v[50:53], v[230:233], v[178:181], v[50:53]
	v_mfma_f32_16x16x32_bf16 v[38:41], v[222:225], v[186:189], v[38:41]
	v_mfma_f32_16x16x32_bf16 v[34:37], v[230:233], v[186:189], v[34:37]
	v_mfma_f32_16x16x32_bf16 v[22:25], v[222:225], v[194:197], v[22:25]
	v_mfma_f32_16x16x32_bf16 v[18:21], v[230:233], v[194:197], v[18:21]
	v_mfma_f32_16x16x32_bf16 v[6:9], v[222:225], v[214:217], v[6:9]
	v_mfma_f32_16x16x32_bf16 v[2:5], v[230:233], v[214:217], v[2:5]
	v_mfma_f32_16x16x32_bf16 v[54:57], v[226:229], v[182:185], v[54:57]
	v_mfma_f32_16x16x32_bf16 v[50:53], v[234:237], v[182:185], v[50:53]
	v_mfma_f32_16x16x32_bf16 v[38:41], v[226:229], v[190:193], v[38:41]
	v_mfma_f32_16x16x32_bf16 v[34:37], v[234:237], v[190:193], v[34:37]
	v_mfma_f32_16x16x32_bf16 v[22:25], v[226:229], v[210:213], v[22:25]
	v_mfma_f32_16x16x32_bf16 v[18:21], v[234:237], v[210:213], v[18:21]
	v_mfma_f32_16x16x32_bf16 v[6:9], v[226:229], v[218:221], v[6:9]
	v_mfma_f32_16x16x32_bf16 v[2:5], v[234:237], v[218:221], v[2:5]
	s_add_i32 s31, s31, 2
	s_add_u32 s20, s20, 0x100
	s_addc_u32 s21, s21, 0
	s_add_u32 s28, s28, 0x100
	s_addc_u32 s29, s29, 0
	s_cmp_gt_u32 s31, 13
	s_barrier
	s_cbranch_scc0 .LBB0_668
	v_lshl_add_u32 v144, s13, 8, v1
	v_lshl_or_b32 v142, s12, 8, v151
	v_ashrrev_i32_e32 v145, 31, v144
	v_lshlrev_b64 v[146:147], 11, v[144:145]
	v_ashrrev_i32_e32 v143, 31, v142
	v_lshl_add_u64 v[146:147], s[86:87], 0, v[146:147]
	v_lshlrev_b64 v[142:143], 1, v[142:143]
	v_lshl_add_u64 v[146:147], v[146:147], 0, v[142:143]
	global_load_dwordx4 v[170:173], v[146:147], off
	v_mul_f32_e32 v126, 0xbfb8aa3b, v126
	v_exp_f32_e32 v126, v126
	v_lshlrev_b64 v[148:149], 12, v[144:145]
	v_mul_f32_e32 v122, 0xbfb8aa3b, v122
	v_exp_f32_e32 v122, v122
	v_add_f32_e32 v126, 1.0, v126
	v_mul_f32_e32 v127, 0xbfb8aa3b, v127
	v_exp_f32_e32 v127, v127
	v_add_f32_e32 v122, 1.0, v122
	v_mul_f32_e32 v123, 0xbfb8aa3b, v123
	v_exp_f32_e32 v123, v123
	v_add_f32_e32 v127, 1.0, v127
	v_mul_f32_e32 v128, 0xbfb8aa3b, v128
	v_exp_f32_e32 v128, v128
	v_add_f32_e32 v123, 1.0, v123
	v_mul_f32_e32 v124, 0xbfb8aa3b, v124
	v_exp_f32_e32 v124, v124
	v_add_f32_e32 v128, 1.0, v128
	v_mul_f32_e32 v118, 0xbfb8aa3b, v118
	v_exp_f32_e32 v118, v118
	v_add_f32_e32 v124, 1.0, v124
	v_mul_f32_e32 v114, 0xbfb8aa3b, v114
	v_exp_f32_e32 v114, v114
	v_add_f32_e32 v118, 1.0, v118
	v_mul_f32_e32 v119, 0xbfb8aa3b, v119
	v_exp_f32_e32 v119, v119
	v_add_f32_e32 v114, 1.0, v114
	v_mul_f32_e32 v115, 0xbfb8aa3b, v115
	v_exp_f32_e32 v115, v115
	v_add_f32_e32 v119, 1.0, v119
	v_mul_f32_e32 v120, 0xbfb8aa3b, v120
	v_exp_f32_e32 v120, v120
	v_add_f32_e32 v115, 1.0, v115
	v_mul_f32_e32 v116, 0xbfb8aa3b, v116
	v_exp_f32_e32 v116, v116
	v_add_f32_e32 v120, 1.0, v120
	v_mul_f32_e32 v110, 0xbfb8aa3b, v110
	v_exp_f32_e32 v110, v110
	v_add_f32_e32 v116, 1.0, v116
	v_mul_f32_e32 v106, 0xbfb8aa3b, v106
	v_exp_f32_e32 v106, v106
	v_add_f32_e32 v110, 1.0, v110
	v_mul_f32_e32 v111, 0xbfb8aa3b, v111
	v_exp_f32_e32 v111, v111
	v_add_f32_e32 v106, 1.0, v106
	v_mul_f32_e32 v107, 0xbfb8aa3b, v107
	v_exp_f32_e32 v107, v107
	v_add_f32_e32 v111, 1.0, v111
	v_mul_f32_e32 v112, 0xbfb8aa3b, v112
	v_exp_f32_e32 v112, v112
	v_add_f32_e32 v107, 1.0, v107
	v_mul_f32_e32 v108, 0xbfb8aa3b, v108
	v_exp_f32_e32 v108, v108
	v_add_f32_e32 v112, 1.0, v112
	v_mul_f32_e32 v102, 0xbfb8aa3b, v102
	v_exp_f32_e32 v102, v102
	v_add_f32_e32 v108, 1.0, v108
	v_mul_f32_e32 v98, 0xbfb8aa3b, v98
	v_exp_f32_e32 v98, v98
	v_add_f32_e32 v102, 1.0, v102
	v_mul_f32_e32 v99, 0xbfb8aa3b, v99
	v_exp_f32_e32 v99, v99
	v_add_f32_e32 v98, 1.0, v98
	v_mul_f32_e32 v100, 0xbfb8aa3b, v100
	v_exp_f32_e32 v100, v100
	v_add_f32_e32 v99, 1.0, v99
	v_mul_f32_e32 v101, 0xbfb8aa3b, v101
	v_exp_f32_e32 v101, v101
	v_add_f32_e32 v100, 1.0, v100
	v_mul_f32_e32 v94, 0xbfb8aa3b, v94
	v_exp_f32_e32 v94, v94
	v_add_f32_e32 v101, 1.0, v101
	v_mul_f32_e32 v90, 0xbfb8aa3b, v90
	v_exp_f32_e32 v90, v90
	v_add_f32_e32 v94, 1.0, v94
	v_mul_f32_e32 v95, 0xbfb8aa3b, v95
	v_exp_f32_e32 v95, v95
	v_add_f32_e32 v90, 1.0, v90
	v_mul_f32_e32 v91, 0xbfb8aa3b, v91
	s_waitcnt vmcnt(0)
; #define LAS __attribute__((address_space(3)))
; __device__ __forceinline__ unsigned cvt_pk_bf16(float lo, float hi) { unsigned r; asm volatile("v_cvt_pk_bf16_f32 %0, %1, %2" : "=v"(r) : "v"(lo), "v"(hi)); return r; }
; __device__ __forceinline__ float bf_lo(unsigned w) { return __uint_as_float(w << 16); }
; __device__ __forceinline__ float bf_hi(unsigned w) { return __uint_as_float(w & 0xffff0000u); }
;     __device__ __forceinline__ void operator()(const f32x4 (&acc)[2][2][4][2], const Unit& u, int ui, const LAS float* rtab, int wr, int wc, int fr, int fq) const {
;         const int row0 = u.pm * BM + wr * 64 + fr, col0 = u.pn * BM + wc * 32 + 8 * fq;
; #pragma unroll
;         for (int ai = 0; ai < 2; ++ai)
; #pragma unroll
;             for (int m = 0; m < 4; ++m) {
;                 const int row = row0 + ai * HALF + m * 16;
; #pragma unroll
;                 for (int bj = 0; bj < 2; ++bj) {
;                     const int col = col0 + bj * HALF; const u32x4 yv = *(const u32x4*)(Y + (size_t)row * 1024 + col);
;                     const f32x4 a0 = acc[ai][bj][m][0], a1 = acc[ai][bj][m][1]; float o[8];
;                     const float yy[8] = {bf_lo(yv.x), bf_hi(yv.x), bf_lo(yv.y), bf_hi(yv.y), bf_lo(yv.z), bf_hi(yv.z), bf_lo(yv.w), bf_hi(yv.w)};
; #pragma unroll
;                     for (int e = 0; e < 4; ++e) { o[e] = yy[e] / (1.0f + __expf(-a0[e])); o[4 + e] = yy[4 + e] / (1.0f + __expf(-a1[e])); }
;                     u32x4 w; w.x = cvt_pk_bf16(o[0], o[1]); w.y = cvt_pk_bf16(o[2], o[3]); w.z = cvt_pk_bf16(o[4], o[5]); w.w = cvt_pk_bf16(o[6], o[7]);
;                     *(u32x4*)(MG + (size_t)row * DM + 1024 + col) = w;
;                 }
	v_lshlrev_b32_e32 v174, 16, v170
	v_lshlrev_b32_e32 v162, 16, v173
	v_and_b32_e32 v145, 0xffff0000, v173
	v_div_scale_f32 v173, s[12:13], v126, v126, v174
	v_rcp_f32_e32 v176, v173
	v_lshlrev_b32_e32 v175, 16, v171
	v_and_b32_e32 v153, 0xffff0000, v171
	v_lshlrev_b32_e32 v171, 16, v172
	v_fma_f32 v177, -v173, v176, 1.0
	v_fmac_f32_e32 v176, v177, v176
	v_div_scale_f32 v177, vcc, v174, v126, v174
	v_mul_f32_e32 v178, v177, v176
	v_fma_f32 v179, -v173, v178, v177
	v_fmac_f32_e32 v178, v179, v176
	v_fma_f32 v173, -v173, v178, v177
	v_div_fmas_f32 v173, v173, v176, v178
	v_div_fixup_f32 v126, v173, v126, v174
	v_div_scale_f32 v173, s[12:13], v122, v122, v171
	v_rcp_f32_e32 v174, v173
	v_and_b32_e32 v170, 0xffff0000, v170
	v_and_b32_e32 v172, 0xffff0000, v172
	v_add_f32_e32 v95, 1.0, v95
	v_fma_f32 v176, -v173, v174, 1.0
	v_fmac_f32_e32 v174, v176, v174
	v_div_scale_f32 v176, vcc, v171, v122, v171
	v_mul_f32_e32 v177, v176, v174
	v_fma_f32 v178, -v173, v177, v176
	v_fmac_f32_e32 v177, v178, v174
	v_fma_f32 v173, -v173, v177, v176
	v_div_fmas_f32 v173, v173, v174, v177
	v_div_fixup_f32 v122, v173, v122, v171
	v_div_scale_f32 v171, s[12:13], v127, v127, v170
	v_rcp_f32_e32 v173, v171
	v_exp_f32_e32 v91, v91
	v_mul_f32_e32 v96, 0xbfb8aa3b, v96
	v_exp_f32_e32 v96, v96
	v_fma_f32 v174, -v171, v173, 1.0
	v_fmac_f32_e32 v173, v174, v173
	v_div_scale_f32 v174, vcc, v170, v127, v170
	v_mul_f32_e32 v176, v174, v173
	v_fma_f32 v177, -v171, v176, v174
	v_fmac_f32_e32 v176, v177, v173
	v_fma_f32 v171, -v171, v176, v174
	v_div_fmas_f32 v171, v171, v173, v176
	v_div_fixup_f32 v127, v171, v127, v170
	v_div_scale_f32 v170, s[12:13], v123, v123, v172
	v_rcp_f32_e32 v171, v170
	v_add_f32_e32 v91, 1.0, v91
	v_add_f32_e32 v96, 1.0, v96
	v_mul_f32_e32 v92, 0xbfb8aa3b, v92
	v_fma_f32 v173, -v170, v171, 1.0
	v_fmac_f32_e32 v171, v173, v171
	v_div_scale_f32 v173, vcc, v172, v123, v172
	v_mul_f32_e32 v174, v173, v171
	v_fma_f32 v176, -v170, v174, v173
	v_fmac_f32_e32 v174, v176, v171
	v_fma_f32 v170, -v170, v174, v173
	v_div_fmas_f32 v170, v170, v171, v174
	v_div_fixup_f32 v123, v170, v123, v172
	v_div_scale_f32 v170, s[12:13], v128, v128, v175
	v_rcp_f32_e32 v171, v170
	v_exp_f32_e32 v92, v92
	v_mul_f32_e32 v86, 0xbfb8aa3b, v86
	v_exp_f32_e32 v86, v86
	v_fma_f32 v172, -v170, v171, 1.0
	v_fmac_f32_e32 v171, v172, v171
	v_div_scale_f32 v172, vcc, v175, v128, v175
	v_mul_f32_e32 v173, v172, v171
	v_fma_f32 v174, -v170, v173, v172
	v_fmac_f32_e32 v173, v174, v171
	v_fma_f32 v170, -v170, v173, v172
	v_div_fmas_f32 v170, v170, v171, v173
	v_div_fixup_f32 v128, v170, v128, v175
	v_div_scale_f32 v170, s[12:13], v124, v124, v162
	v_rcp_f32_e32 v171, v170
	v_add_f32_e32 v92, 1.0, v92
	v_add_f32_e32 v86, 1.0, v86
	v_mul_f32_e32 v82, 0xbfb8aa3b, v82
	v_fma_f32 v172, -v170, v171, 1.0
	v_fmac_f32_e32 v171, v172, v171
	v_div_scale_f32 v172, vcc, v162, v124, v162
	v_mul_f32_e32 v173, v172, v171
	v_fma_f32 v174, -v170, v173, v172
	v_fmac_f32_e32 v173, v174, v171
	v_fma_f32 v170, -v170, v173, v172
	v_div_fmas_f32 v170, v170, v171, v173
	v_div_fixup_f32 v162, v170, v124, v162
	v_mul_f32_e32 v124, 0xbfb8aa3b, v129
	v_exp_f32_e32 v124, v124
	v_exp_f32_e32 v82, v82
	v_mul_f32_e32 v83, 0xbfb8aa3b, v83
	v_exp_f32_e32 v83, v83
	v_add_f32_e32 v124, 1.0, v124
	v_div_scale_f32 v129, s[12:13], v124, v124, v153
	v_rcp_f32_e32 v170, v129
	v_add_f32_e32 v82, 1.0, v82
	v_add_f32_e32 v83, 1.0, v83
	v_mul_f32_e32 v84, 0xbfb8aa3b, v84
	v_fma_f32 v171, -v129, v170, 1.0
	v_fmac_f32_e32 v170, v171, v170
	v_div_scale_f32 v171, vcc, v153, v124, v153
	v_mul_f32_e32 v172, v171, v170
	v_fma_f32 v173, -v129, v172, v171
	v_fmac_f32_e32 v172, v173, v170
	v_fma_f32 v129, -v129, v172, v171
	v_div_fmas_f32 v129, v129, v170, v172
	v_div_fixup_f32 v129, v129, v124, v153
	v_mul_f32_e32 v124, 0xbfb8aa3b, v125
	v_exp_f32_e32 v124, v124
	v_exp_f32_e32 v84, v84
	v_mul_f32_e32 v85, 0xbfb8aa3b, v85
	v_exp_f32_e32 v85, v85
	v_add_f32_e32 v124, 1.0, v124
	v_div_scale_f32 v125, s[12:13], v124, v124, v145
	v_rcp_f32_e32 v153, v125
	v_add_f32_e32 v84, 1.0, v84
	v_add_f32_e32 v85, 1.0, v85
	v_mul_f32_e32 v78, 0xbfb8aa3b, v78
	v_fma_f32 v170, -v125, v153, 1.0
	v_fmac_f32_e32 v153, v170, v153
	v_div_scale_f32 v170, vcc, v145, v124, v145
	v_mul_f32_e32 v171, v170, v153
	v_fma_f32 v172, -v125, v171, v170
	v_fmac_f32_e32 v171, v172, v153
	v_fma_f32 v125, -v125, v171, v170
	v_div_fmas_f32 v125, v125, v153, v171
	v_div_fixup_f32 v145, v125, v124, v145
	v_cvt_pk_bf16_f32 v124, v126, v127
	v_cvt_pk_bf16_f32 v125, v128, v129
	v_cvt_pk_bf16_f32 v126, v122, v123
	v_lshl_add_u64 v[122:123], s[88:89], 0, v[148:149]
	v_cvt_pk_bf16_f32 v127, v162, v145
	v_lshl_add_u64 v[122:123], v[122:123], 0, v[142:143]
	global_store_dwordx4 v[122:123], v[124:127], off offset:2048
	global_load_dwordx4 v[124:127], v[146:147], off offset:256
	v_exp_f32_e32 v78, v78
	v_mul_f32_e32 v74, 0xbfb8aa3b, v74
	v_exp_f32_e32 v74, v74
	v_mul_f32_e32 v79, 0xbfb8aa3b, v79
	v_add_f32_e32 v78, 1.0, v78
	v_exp_f32_e32 v79, v79
	v_add_f32_e32 v74, 1.0, v74
	v_mul_f32_e32 v75, 0xbfb8aa3b, v75
	v_exp_f32_e32 v75, v75
	v_add_f32_e32 v79, 1.0, v79
	v_mul_f32_e32 v80, 0xbfb8aa3b, v80
	v_exp_f32_e32 v80, v80
	v_add_f32_e32 v75, 1.0, v75
	v_mul_f32_e32 v76, 0xbfb8aa3b, v76
	v_exp_f32_e32 v76, v76
	v_add_f32_e32 v80, 1.0, v80
	v_mul_f32_e32 v70, 0xbfb8aa3b, v70
	v_exp_f32_e32 v70, v70
	v_add_f32_e32 v76, 1.0, v76
	v_mul_f32_e32 v66, 0xbfb8aa3b, v66
	v_exp_f32_e32 v66, v66
	v_add_f32_e32 v70, 1.0, v70
	v_mul_f32_e32 v67, 0xbfb8aa3b, v67
	v_exp_f32_e32 v67, v67
	v_add_f32_e32 v66, 1.0, v66
	v_mul_f32_e32 v68, 0xbfb8aa3b, v68
	v_exp_f32_e32 v68, v68
	v_add_f32_e32 v67, 1.0, v67
; #define LAS __attribute__((address_space(3)))
; __device__ __forceinline__ unsigned cvt_pk_bf16(float lo, float hi) { unsigned r; asm volatile("v_cvt_pk_bf16_f32 %0, %1, %2" : "=v"(r) : "v"(lo), "v"(hi)); return r; }
; __device__ __forceinline__ float bf_lo(unsigned w) { return __uint_as_float(w << 16); }
; __device__ __forceinline__ float bf_hi(unsigned w) { return __uint_as_float(w & 0xffff0000u); }
;     __device__ __forceinline__ void operator()(const f32x4 (&acc)[2][2][4][2], const Unit& u, int ui, const LAS float* rtab, int wr, int wc, int fr, int fq) const {
;         const int row0 = u.pm * BM + wr * 64 + fr, col0 = u.pn * BM + wc * 32 + 8 * fq;
; #pragma unroll
;         for (int ai = 0; ai < 2; ++ai)
; #pragma unroll
;             for (int m = 0; m < 4; ++m) {
;                 const int row = row0 + ai * HALF + m * 16;
; #pragma unroll
;                 for (int bj = 0; bj < 2; ++bj) {
;                     const int col = col0 + bj * HALF; const u32x4 yv = *(const u32x4*)(Y + (size_t)row * 1024 + col);
;                     const f32x4 a0 = acc[ai][bj][m][0], a1 = acc[ai][bj][m][1]; float o[8];
;                     const float yy[8] = {bf_lo(yv.x), bf_hi(yv.x), bf_lo(yv.y), bf_hi(yv.y), bf_lo(yv.z), bf_hi(yv.z), bf_lo(yv.w), bf_hi(yv.w)};
; #pragma unroll
;                     for (int e = 0; e < 4; ++e) { o[e] = yy[e] / (1.0f + __expf(-a0[e])); o[4 + e] = yy[4 + e] / (1.0f + __expf(-a1[e])); }
;                     u32x4 w; w.x = cvt_pk_bf16(o[0], o[1]); w.y = cvt_pk_bf16(o[2], o[3]); w.z = cvt_pk_bf16(o[4], o[5]); w.w = cvt_pk_bf16(o[6], o[7]);
;                     *(u32x4*)(MG + (size_t)row * DM + 1024 + col) = w;
;                 }
	v_mul_f32_e32 v69, 0xbfb8aa3b, v69
	v_exp_f32_e32 v69, v69
	v_add_f32_e32 v68, 1.0, v68
	v_mul_f32_e32 v62, 0xbfb8aa3b, v62
	v_exp_f32_e32 v62, v62
	v_add_f32_e32 v69, 1.0, v69
	v_mul_f32_e32 v58, 0xbfb8aa3b, v58
	v_exp_f32_e32 v58, v58
	v_add_f32_e32 v62, 1.0, v62
	v_mul_f32_e32 v63, 0xbfb8aa3b, v63
	v_exp_f32_e32 v63, v63
	v_add_f32_e32 v58, 1.0, v58
	v_mul_f32_e32 v59, 0xbfb8aa3b, v59
	v_exp_f32_e32 v59, v59
	v_add_f32_e32 v63, 1.0, v63
	v_mul_f32_e32 v64, 0xbfb8aa3b, v64
	v_exp_f32_e32 v64, v64
	v_add_f32_e32 v59, 1.0, v59
	v_mul_f32_e32 v60, 0xbfb8aa3b, v60
	v_exp_f32_e32 v60, v60
	v_add_f32_e32 v64, 1.0, v64
	v_mul_f32_e32 v54, 0xbfb8aa3b, v54
	v_exp_f32_e32 v54, v54
	v_add_f32_e32 v60, 1.0, v60
	v_mul_f32_e32 v50, 0xbfb8aa3b, v50
	v_exp_f32_e32 v50, v50
	v_add_f32_e32 v54, 1.0, v54
	v_mul_f32_e32 v51, 0xbfb8aa3b, v51
	v_exp_f32_e32 v51, v51
	v_add_f32_e32 v50, 1.0, v50
	v_mul_f32_e32 v52, 0xbfb8aa3b, v52
	v_exp_f32_e32 v52, v52
	v_add_f32_e32 v51, 1.0, v51
	v_mul_f32_e32 v53, 0xbfb8aa3b, v53
	v_exp_f32_e32 v53, v53
	v_add_f32_e32 v52, 1.0, v52
	v_mul_f32_e32 v46, 0xbfb8aa3b, v46
	v_exp_f32_e32 v46, v46
	v_add_f32_e32 v53, 1.0, v53
	v_mul_f32_e32 v42, 0xbfb8aa3b, v42
	v_exp_f32_e32 v42, v42
	v_add_f32_e32 v46, 1.0, v46
	v_mul_f32_e32 v47, 0xbfb8aa3b, v47
	v_exp_f32_e32 v47, v47
	v_add_f32_e32 v42, 1.0, v42
	v_mul_f32_e32 v43, 0xbfb8aa3b, v43
	v_exp_f32_e32 v43, v43
	v_add_f32_e32 v47, 1.0, v47
	v_mul_f32_e32 v48, 0xbfb8aa3b, v48
	v_exp_f32_e32 v48, v48
	v_add_f32_e32 v43, 1.0, v43
	s_waitcnt vmcnt(0)
	v_lshlrev_b32_e32 v128, 16, v124
	v_and_b32_e32 v129, 0xffff0000, v124
	v_lshlrev_b32_e32 v146, 16, v126
	v_and_b32_e32 v147, 0xffff0000, v126
	v_lshlrev_b32_e32 v126, 16, v127
	v_and_b32_e32 v124, 0xffff0000, v127
	v_div_scale_f32 v127, s[12:13], v118, v118, v128
	v_rcp_f32_e32 v148, v127
	v_lshlrev_b32_e32 v145, 16, v125
	v_and_b32_e32 v125, 0xffff0000, v125
	v_add_f32_e32 v48, 1.0, v48
	v_fma_f32 v149, -v127, v148, 1.0
	v_fmac_f32_e32 v148, v149, v148
	v_div_scale_f32 v149, vcc, v128, v118, v128
	v_mul_f32_e32 v153, v149, v148
	v_fma_f32 v162, -v127, v153, v149
	v_fmac_f32_e32 v153, v162, v148
	v_fma_f32 v127, -v127, v153, v149
	v_div_fmas_f32 v127, v127, v148, v153
	v_div_fixup_f32 v118, v127, v118, v128
	v_div_scale_f32 v127, s[12:13], v114, v114, v146
	v_rcp_f32_e32 v128, v127
	v_mul_f32_e32 v44, 0xbfb8aa3b, v44
	v_exp_f32_e32 v44, v44
	v_mul_f32_e32 v38, 0xbfb8aa3b, v38
	v_fma_f32 v148, -v127, v128, 1.0
	v_fmac_f32_e32 v128, v148, v128
	v_div_scale_f32 v148, vcc, v146, v114, v146
	v_mul_f32_e32 v149, v148, v128
	v_fma_f32 v153, -v127, v149, v148
	v_fmac_f32_e32 v149, v153, v128
	v_fma_f32 v127, -v127, v149, v148
	v_div_fmas_f32 v127, v127, v128, v149
	v_div_fixup_f32 v114, v127, v114, v146
	v_div_scale_f32 v127, s[12:13], v119, v119, v129
	v_rcp_f32_e32 v128, v127
	v_add_f32_e32 v44, 1.0, v44
	v_exp_f32_e32 v38, v38
	v_mul_f32_e32 v34, 0xbfb8aa3b, v34
	v_fma_f32 v146, -v127, v128, 1.0
	v_fmac_f32_e32 v128, v146, v128
	v_div_scale_f32 v146, vcc, v129, v119, v129
	v_mul_f32_e32 v148, v146, v128
	v_fma_f32 v149, -v127, v148, v146
	v_fmac_f32_e32 v148, v149, v128
	v_fma_f32 v127, -v127, v148, v146
	v_div_fmas_f32 v127, v127, v128, v148
	v_div_fixup_f32 v119, v127, v119, v129
	v_div_scale_f32 v127, s[12:13], v115, v115, v147
	v_rcp_f32_e32 v128, v127
	v_add_f32_e32 v38, 1.0, v38
	v_exp_f32_e32 v34, v34
	v_mul_f32_e32 v35, 0xbfb8aa3b, v35
	v_fma_f32 v129, -v127, v128, 1.0
	v_fmac_f32_e32 v128, v129, v128
	v_div_scale_f32 v129, vcc, v147, v115, v147
	v_mul_f32_e32 v146, v129, v128
	v_fma_f32 v148, -v127, v146, v129
	v_fmac_f32_e32 v146, v148, v128
	v_fma_f32 v127, -v127, v146, v129
	v_div_fmas_f32 v127, v127, v128, v146
	v_div_fixup_f32 v115, v127, v115, v147
	v_div_scale_f32 v127, s[12:13], v120, v120, v145
	v_rcp_f32_e32 v128, v127
	v_add_f32_e32 v34, 1.0, v34
	v_exp_f32_e32 v35, v35
	v_mul_f32_e32 v36, 0xbfb8aa3b, v36
	v_fma_f32 v129, -v127, v128, 1.0
	v_fmac_f32_e32 v128, v129, v128
	v_div_scale_f32 v129, vcc, v145, v120, v145
	v_mul_f32_e32 v146, v129, v128
	v_fma_f32 v147, -v127, v146, v129
	v_fmac_f32_e32 v146, v147, v128
	v_fma_f32 v127, -v127, v146, v129
	v_div_fmas_f32 v127, v127, v128, v146
	v_div_fixup_f32 v120, v127, v120, v145
	v_div_scale_f32 v127, s[12:13], v116, v116, v126
	v_rcp_f32_e32 v128, v127
	v_add_f32_e32 v35, 1.0, v35
	v_exp_f32_e32 v36, v36
	v_mul_f32_e32 v37, 0xbfb8aa3b, v37
	v_fma_f32 v129, -v127, v128, 1.0
	v_fmac_f32_e32 v128, v129, v128
	v_div_scale_f32 v129, vcc, v126, v116, v126
	v_mul_f32_e32 v145, v129, v128
	v_fma_f32 v146, -v127, v145, v129
	v_fmac_f32_e32 v145, v146, v128
	v_fma_f32 v127, -v127, v145, v129
	v_div_fmas_f32 v127, v127, v128, v145
	v_div_fixup_f32 v126, v127, v116, v126
	v_mul_f32_e32 v116, 0xbfb8aa3b, v121
	v_exp_f32_e32 v116, v116
	v_add_f32_e32 v36, 1.0, v36
	v_exp_f32_e32 v37, v37
	v_mul_f32_e32 v30, 0xbfb8aa3b, v30
	v_add_f32_e32 v116, 1.0, v116
	v_div_scale_f32 v121, s[12:13], v116, v116, v125
	v_rcp_f32_e32 v127, v121
	v_add_f32_e32 v37, 1.0, v37
	v_exp_f32_e32 v30, v30
	v_mul_f32_e32 v26, 0xbfb8aa3b, v26
	v_fma_f32 v128, -v121, v127, 1.0
	v_fmac_f32_e32 v127, v128, v127
	v_div_scale_f32 v128, vcc, v125, v116, v125
	v_mul_f32_e32 v129, v128, v127
	v_fma_f32 v145, -v121, v129, v128
	v_fmac_f32_e32 v129, v145, v127
	v_fma_f32 v121, -v121, v129, v128
	v_div_fmas_f32 v121, v121, v127, v129
	v_div_fixup_f32 v121, v121, v116, v125
	v_mul_f32_e32 v116, 0xbfb8aa3b, v117
	v_exp_f32_e32 v116, v116
	v_add_f32_e32 v30, 1.0, v30
	v_exp_f32_e32 v26, v26
	v_mul_f32_e32 v31, 0xbfb8aa3b, v31
	v_add_f32_e32 v116, 1.0, v116
	v_div_scale_f32 v117, s[12:13], v116, v116, v124
	v_rcp_f32_e32 v125, v117
; #define LAS __attribute__((address_space(3)))
; __device__ __forceinline__ unsigned cvt_pk_bf16(float lo, float hi) { unsigned r; asm volatile("v_cvt_pk_bf16_f32 %0, %1, %2" : "=v"(r) : "v"(lo), "v"(hi)); return r; }
; __device__ __forceinline__ float bf_lo(unsigned w) { return __uint_as_float(w << 16); }
; __device__ __forceinline__ float bf_hi(unsigned w) { return __uint_as_float(w & 0xffff0000u); }
;     __device__ __forceinline__ void operator()(const f32x4 (&acc)[2][2][4][2], const Unit& u, int ui, const LAS float* rtab, int wr, int wc, int fr, int fq) const {
;         const int row0 = u.pm * BM + wr * 64 + fr, col0 = u.pn * BM + wc * 32 + 8 * fq;
; #pragma unroll
;         for (int ai = 0; ai < 2; ++ai)
; #pragma unroll
;             for (int m = 0; m < 4; ++m) {
;                 const int row = row0 + ai * HALF + m * 16;
; #pragma unroll
;                 for (int bj = 0; bj < 2; ++bj) {
;                     const int col = col0 + bj * HALF; const u32x4 yv = *(const u32x4*)(Y + (size_t)row * 1024 + col);
;                     const f32x4 a0 = acc[ai][bj][m][0], a1 = acc[ai][bj][m][1]; float o[8];
;                     const float yy[8] = {bf_lo(yv.x), bf_hi(yv.x), bf_lo(yv.y), bf_hi(yv.y), bf_lo(yv.z), bf_hi(yv.z), bf_lo(yv.w), bf_hi(yv.w)};
; #pragma unroll
;                     for (int e = 0; e < 4; ++e) { o[e] = yy[e] / (1.0f + __expf(-a0[e])); o[4 + e] = yy[4 + e] / (1.0f + __expf(-a1[e])); }
;                     u32x4 w; w.x = cvt_pk_bf16(o[0], o[1]); w.y = cvt_pk_bf16(o[2], o[3]); w.z = cvt_pk_bf16(o[4], o[5]); w.w = cvt_pk_bf16(o[6], o[7]);
;                     *(u32x4*)(MG + (size_t)row * DM + 1024 + col) = w;
;                 }
	v_add_f32_e32 v26, 1.0, v26
	v_exp_f32_e32 v31, v31
	v_mul_f32_e32 v27, 0xbfb8aa3b, v27
	v_fma_f32 v127, -v117, v125, 1.0
	v_fmac_f32_e32 v125, v127, v125
	v_div_scale_f32 v127, vcc, v124, v116, v124
	v_mul_f32_e32 v128, v127, v125
	v_fma_f32 v129, -v117, v128, v127
	v_fmac_f32_e32 v128, v129, v125
	v_fma_f32 v117, -v117, v128, v127
	v_div_fmas_f32 v117, v117, v125, v128
	v_div_fixup_f32 v124, v117, v116, v124
	v_cvt_pk_bf16_f32 v116, v118, v119
	v_cvt_pk_bf16_f32 v117, v120, v121
	v_cvt_pk_bf16_f32 v118, v114, v115
	v_or_b32_e32 v114, 16, v144
	v_cvt_pk_bf16_f32 v119, v126, v124
	v_ashrrev_i32_e32 v115, 31, v114
	global_store_dwordx4 v[122:123], v[116:119], off offset:2304
	v_add_f32_e32 v31, 1.0, v31
	v_exp_f32_e32 v27, v27
	v_lshlrev_b64 v[118:119], 11, v[114:115]
	v_lshlrev_b64 v[116:117], 12, v[114:115]
	v_lshl_add_u64 v[114:115], s[86:87], 0, v[118:119]
	v_lshl_add_u64 v[114:115], v[114:115], 0, v[142:143]
	global_load_dwordx4 v[118:121], v[114:115], off
	v_add_f32_e32 v27, 1.0, v27
	v_mul_f32_e32 v32, 0xbfb8aa3b, v32
	v_exp_f32_e32 v32, v32
	v_mul_f32_e32 v28, 0xbfb8aa3b, v28
	v_exp_f32_e32 v28, v28
	v_mul_f32_e32 v22, 0xbfb8aa3b, v22
	v_add_f32_e32 v32, 1.0, v32
	v_exp_f32_e32 v22, v22
	v_add_f32_e32 v28, 1.0, v28
	v_mul_f32_e32 v18, 0xbfb8aa3b, v18
	v_exp_f32_e32 v18, v18
	v_add_f32_e32 v22, 1.0, v22
	v_mul_f32_e32 v19, 0xbfb8aa3b, v19
	v_exp_f32_e32 v19, v19
	v_add_f32_e32 v18, 1.0, v18
	v_mul_f32_e32 v20, 0xbfb8aa3b, v20
	v_exp_f32_e32 v20, v20
	v_add_f32_e32 v19, 1.0, v19
	v_mul_f32_e32 v21, 0xbfb8aa3b, v21
	v_exp_f32_e32 v21, v21
	v_add_f32_e32 v20, 1.0, v20
	v_mul_f32_e32 v14, 0xbfb8aa3b, v14
	v_exp_f32_e32 v14, v14
	v_add_f32_e32 v21, 1.0, v21
	v_mul_f32_e32 v10, 0xbfb8aa3b, v10
	v_exp_f32_e32 v10, v10
	v_add_f32_e32 v14, 1.0, v14
	v_mul_f32_e32 v15, 0xbfb8aa3b, v15
	v_exp_f32_e32 v15, v15
	v_add_f32_e32 v10, 1.0, v10
	v_mul_f32_e32 v11, 0xbfb8aa3b, v11
	v_exp_f32_e32 v11, v11
	v_add_f32_e32 v15, 1.0, v15
	v_mul_f32_e32 v16, 0xbfb8aa3b, v16
	v_exp_f32_e32 v16, v16
	v_add_f32_e32 v11, 1.0, v11
	v_mul_f32_e32 v12, 0xbfb8aa3b, v12
	v_exp_f32_e32 v12, v12
	v_add_f32_e32 v16, 1.0, v16
	v_mul_f32_e32 v6, 0xbfb8aa3b, v6
	v_exp_f32_e32 v6, v6
	v_add_f32_e32 v12, 1.0, v12
	v_mul_f32_e32 v2, 0xbfb8aa3b, v2
	v_exp_f32_e32 v2, v2
	v_add_f32_e32 v6, 1.0, v6
	v_mul_f32_e32 v3, 0xbfb8aa3b, v3
	v_exp_f32_e32 v3, v3
	v_add_f32_e32 v2, 1.0, v2
	v_mul_f32_e32 v4, 0xbfb8aa3b, v4
	v_exp_f32_e32 v4, v4
	v_add_f32_e32 v3, 1.0, v3
	v_mul_f32_e32 v5, 0xbfb8aa3b, v5
	v_exp_f32_e32 v5, v5
	v_add_f32_e32 v4, 1.0, v4
	s_mov_b64 s[36:37], s[46:47]
	s_mov_b64 s[20:21], s[44:45]
	v_add_f32_e32 v5, 1.0, v5
	s_waitcnt vmcnt(0)
	v_lshlrev_b32_e32 v122, 16, v118
	v_and_b32_e32 v123, 0xffff0000, v118
	v_lshlrev_b32_e32 v126, 16, v121
	v_and_b32_e32 v118, 0xffff0000, v121
	v_div_scale_f32 v121, s[12:13], v110, v110, v122
	v_rcp_f32_e32 v127, v121
	v_lshlrev_b32_e32 v125, 16, v120
	v_and_b32_e32 v120, 0xffff0000, v120
	v_lshlrev_b32_e32 v124, 16, v119
	v_fma_f32 v128, -v121, v127, 1.0
	v_fmac_f32_e32 v127, v128, v127
	v_div_scale_f32 v128, vcc, v122, v110, v122
	v_mul_f32_e32 v129, v128, v127
	v_fma_f32 v145, -v121, v129, v128
	v_fmac_f32_e32 v129, v145, v127
	v_fma_f32 v121, -v121, v129, v128
	v_div_fmas_f32 v121, v121, v127, v129
	v_div_fixup_f32 v110, v121, v110, v122
	v_div_scale_f32 v121, s[12:13], v106, v106, v125
	v_rcp_f32_e32 v122, v121
	v_and_b32_e32 v119, 0xffff0000, v119
	v_fma_f32 v127, -v121, v122, 1.0
	v_fmac_f32_e32 v122, v127, v122
	v_div_scale_f32 v127, vcc, v125, v106, v125
	v_mul_f32_e32 v128, v127, v122
	v_fma_f32 v129, -v121, v128, v127
	v_fmac_f32_e32 v128, v129, v122
	v_fma_f32 v121, -v121, v128, v127
	v_div_fmas_f32 v121, v121, v122, v128
	v_div_fixup_f32 v106, v121, v106, v125
	v_div_scale_f32 v121, s[12:13], v111, v111, v123
	v_rcp_f32_e32 v122, v121
	s_nop 0
	v_fma_f32 v125, -v121, v122, 1.0
	v_fmac_f32_e32 v122, v125, v122
	v_div_scale_f32 v125, vcc, v123, v111, v123
	v_mul_f32_e32 v127, v125, v122
	v_fma_f32 v128, -v121, v127, v125
	v_fmac_f32_e32 v127, v128, v122
	v_fma_f32 v121, -v121, v127, v125
	v_div_fmas_f32 v121, v121, v122, v127
	v_div_fixup_f32 v111, v121, v111, v123
	v_div_scale_f32 v121, s[12:13], v107, v107, v120
	v_rcp_f32_e32 v122, v121
	s_nop 0
	v_fma_f32 v123, -v121, v122, 1.0
	v_fmac_f32_e32 v122, v123, v122
	v_div_scale_f32 v123, vcc, v120, v107, v120
	v_mul_f32_e32 v125, v123, v122
	v_fma_f32 v127, -v121, v125, v123
	v_fmac_f32_e32 v125, v127, v122
	v_fma_f32 v121, -v121, v125, v123
	v_div_fmas_f32 v121, v121, v122, v125
	v_div_fixup_f32 v107, v121, v107, v120
	v_div_scale_f32 v120, s[12:13], v112, v112, v124
	v_rcp_f32_e32 v121, v120
	s_nop 0
	v_fma_f32 v122, -v120, v121, 1.0
	v_fmac_f32_e32 v121, v122, v121
	v_div_scale_f32 v122, vcc, v124, v112, v124
	v_mul_f32_e32 v123, v122, v121
	v_fma_f32 v125, -v120, v123, v122
	v_fmac_f32_e32 v123, v125, v121
	v_fma_f32 v120, -v120, v123, v122
	v_div_fmas_f32 v120, v120, v121, v123
	v_div_fixup_f32 v112, v120, v112, v124
	v_div_scale_f32 v120, s[12:13], v108, v108, v126
	v_rcp_f32_e32 v121, v120
	s_nop 0
	v_fma_f32 v122, -v120, v121, 1.0
	v_fmac_f32_e32 v121, v122, v121
	v_div_scale_f32 v122, vcc, v126, v108, v126
	v_mul_f32_e32 v123, v122, v121
	v_fma_f32 v124, -v120, v123, v122
	v_fmac_f32_e32 v123, v124, v121
	v_fma_f32 v120, -v120, v123, v122
	v_div_fmas_f32 v120, v120, v121, v123
	v_div_fixup_f32 v120, v120, v108, v126
	v_mul_f32_e32 v108, 0xbfb8aa3b, v113
	v_exp_f32_e32 v108, v108
	s_nop 0
	v_add_f32_e32 v108, 1.0, v108
	v_div_scale_f32 v113, s[12:13], v108, v108, v119
	v_rcp_f32_e32 v121, v113
	s_nop 0
	v_fma_f32 v122, -v113, v121, 1.0
	v_fmac_f32_e32 v121, v122, v121
	v_div_scale_f32 v122, vcc, v119, v108, v119
	v_mul_f32_e32 v123, v122, v121
	v_fma_f32 v124, -v113, v123, v122
	v_fmac_f32_e32 v123, v124, v121
	v_fma_f32 v113, -v113, v123, v122
	v_div_fmas_f32 v113, v113, v121, v123
	v_div_fixup_f32 v113, v113, v108, v119
	v_mul_f32_e32 v108, 0xbfb8aa3b, v109
	v_exp_f32_e32 v108, v108
	s_nop 0
	v_add_f32_e32 v108, 1.0, v108
	v_div_scale_f32 v109, s[12:13], v108, v108, v118
	v_rcp_f32_e32 v119, v109
	s_nop 0
	v_fma_f32 v121, -v109, v119, 1.0
	v_fmac_f32_e32 v119, v121, v119
	v_div_scale_f32 v121, vcc, v118, v108, v118
	v_mul_f32_e32 v122, v121, v119
	v_fma_f32 v123, -v109, v122, v121
	v_fmac_f32_e32 v122, v123, v119
	v_fma_f32 v109, -v109, v122, v121
	v_div_fmas_f32 v109, v109, v119, v122
	v_div_fixup_f32 v118, v109, v108, v118
	v_cvt_pk_bf16_f32 v108, v110, v111
	v_cvt_pk_bf16_f32 v109, v112, v113
	v_cvt_pk_bf16_f32 v110, v106, v107
	v_lshl_add_u64 v[106:107], s[88:89], 0, v[116:117]
	v_cvt_pk_bf16_f32 v111, v120, v118
	v_lshl_add_u64 v[106:107], v[106:107], 0, v[142:143]
	global_store_dwordx4 v[106:107], v[108:111], off offset:2048
	global_load_dwordx4 v[108:111], v[114:115], off offset:256
	s_waitcnt vmcnt(0)
; #define LAS __attribute__((address_space(3)))
; __device__ __forceinline__ unsigned cvt_pk_bf16(float lo, float hi) { unsigned r; asm volatile("v_cvt_pk_bf16_f32 %0, %1, %2" : "=v"(r) : "v"(lo), "v"(hi)); return r; }
; __device__ __forceinline__ float bf_lo(unsigned w) { return __uint_as_float(w << 16); }
; __device__ __forceinline__ float bf_hi(unsigned w) { return __uint_as_float(w & 0xffff0000u); }
;     __device__ __forceinline__ void operator()(const f32x4 (&acc)[2][2][4][2], const Unit& u, int ui, const LAS float* rtab, int wr, int wc, int fr, int fq) const {
;         const int row0 = u.pm * BM + wr * 64 + fr, col0 = u.pn * BM + wc * 32 + 8 * fq;
; #pragma unroll
;         for (int ai = 0; ai < 2; ++ai)
; #pragma unroll
;             for (int m = 0; m < 4; ++m) {
;                 const int row = row0 + ai * HALF + m * 16;
; #pragma unroll
;                 for (int bj = 0; bj < 2; ++bj) {
;                     const int col = col0 + bj * HALF; const u32x4 yv = *(const u32x4*)(Y + (size_t)row * 1024 + col);
;                     const f32x4 a0 = acc[ai][bj][m][0], a1 = acc[ai][bj][m][1]; float o[8];
;                     const float yy[8] = {bf_lo(yv.x), bf_hi(yv.x), bf_lo(yv.y), bf_hi(yv.y), bf_lo(yv.z), bf_hi(yv.z), bf_lo(yv.w), bf_hi(yv.w)};
; #pragma unroll
;                     for (int e = 0; e < 4; ++e) { o[e] = yy[e] / (1.0f + __expf(-a0[e])); o[4 + e] = yy[4 + e] / (1.0f + __expf(-a1[e])); }
;                     u32x4 w; w.x = cvt_pk_bf16(o[0], o[1]); w.y = cvt_pk_bf16(o[2], o[3]); w.z = cvt_pk_bf16(o[4], o[5]); w.w = cvt_pk_bf16(o[6], o[7]);
;                     *(u32x4*)(MG + (size_t)row * DM + 1024 + col) = w;
;                 }
	v_lshlrev_b32_e32 v112, 16, v108
	v_and_b32_e32 v113, 0xffff0000, v108
	v_lshlrev_b32_e32 v116, 16, v111
	v_and_b32_e32 v108, 0xffff0000, v111
	v_div_scale_f32 v111, s[12:13], v102, v102, v112
	v_rcp_f32_e32 v117, v111
	v_lshlrev_b32_e32 v115, 16, v110
	v_and_b32_e32 v110, 0xffff0000, v110
	v_lshlrev_b32_e32 v114, 16, v109
	v_fma_f32 v118, -v111, v117, 1.0
	v_fmac_f32_e32 v117, v118, v117
	v_div_scale_f32 v118, vcc, v112, v102, v112
	v_mul_f32_e32 v119, v118, v117
	v_fma_f32 v120, -v111, v119, v118
	v_fmac_f32_e32 v119, v120, v117
	v_fma_f32 v111, -v111, v119, v118
	v_div_fmas_f32 v111, v111, v117, v119
	v_div_fixup_f32 v102, v111, v102, v112
	v_div_scale_f32 v111, s[12:13], v98, v98, v115
	v_rcp_f32_e32 v112, v111
	v_and_b32_e32 v109, 0xffff0000, v109
	v_fma_f32 v117, -v111, v112, 1.0
	v_fmac_f32_e32 v112, v117, v112
	v_div_scale_f32 v117, vcc, v115, v98, v115
	v_mul_f32_e32 v118, v117, v112
	v_fma_f32 v119, -v111, v118, v117
	v_fmac_f32_e32 v118, v119, v112
	v_fma_f32 v111, -v111, v118, v117
	v_div_fmas_f32 v111, v111, v112, v118
	v_div_fixup_f32 v111, v111, v98, v115
	v_mul_f32_e32 v98, 0xbfb8aa3b, v103
	v_exp_f32_e32 v98, v98
	s_nop 0
	v_add_f32_e32 v98, 1.0, v98
	v_div_scale_f32 v103, s[12:13], v98, v98, v113
	v_rcp_f32_e32 v112, v103
	s_nop 0
	v_fma_f32 v115, -v103, v112, 1.0
	v_fmac_f32_e32 v112, v115, v112
	v_div_scale_f32 v115, vcc, v113, v98, v113
	v_mul_f32_e32 v117, v115, v112
	v_fma_f32 v118, -v103, v117, v115
	v_fmac_f32_e32 v117, v118, v112
	v_fma_f32 v103, -v103, v117, v115
	v_div_fmas_f32 v103, v103, v112, v117
	v_div_fixup_f32 v98, v103, v98, v113
	v_div_scale_f32 v103, s[12:13], v99, v99, v110
	v_rcp_f32_e32 v112, v103
	v_cvt_pk_bf16_f32 v98, v102, v98
	s_nop 0
	v_fma_f32 v113, -v103, v112, 1.0
	v_fmac_f32_e32 v112, v113, v112
	v_div_scale_f32 v113, vcc, v110, v99, v110
	v_mul_f32_e32 v115, v113, v112
	v_fma_f32 v117, -v103, v115, v113
	v_fmac_f32_e32 v115, v117, v112
	v_fma_f32 v103, -v103, v115, v113
	v_div_fmas_f32 v103, v103, v112, v115
	v_div_fixup_f32 v103, v103, v99, v110
	v_mul_f32_e32 v99, 0xbfb8aa3b, v104
	v_exp_f32_e32 v99, v99
	s_nop 0
	v_add_f32_e32 v99, 1.0, v99
	v_div_scale_f32 v104, s[12:13], v99, v99, v114
	v_rcp_f32_e32 v110, v104
	s_nop 0
	v_fma_f32 v112, -v104, v110, 1.0
	v_fmac_f32_e32 v110, v112, v110
	v_div_scale_f32 v112, vcc, v114, v99, v114
	v_mul_f32_e32 v113, v112, v110
	v_fma_f32 v115, -v104, v113, v112
	v_fmac_f32_e32 v113, v115, v110
	v_fma_f32 v104, -v104, v113, v112
	v_div_fmas_f32 v104, v104, v110, v113
	v_div_fixup_f32 v99, v104, v99, v114
	v_div_scale_f32 v104, s[12:13], v100, v100, v116
	v_rcp_f32_e32 v110, v104
	s_nop 0
	v_fma_f32 v112, -v104, v110, 1.0
	v_fmac_f32_e32 v110, v112, v110
	v_div_scale_f32 v112, vcc, v116, v100, v116
	v_mul_f32_e32 v113, v112, v110
	v_fma_f32 v114, -v104, v113, v112
	v_fmac_f32_e32 v113, v114, v110
	v_fma_f32 v104, -v104, v113, v112
	v_div_fmas_f32 v104, v104, v110, v113
	v_div_fixup_f32 v104, v104, v100, v116
	v_mul_f32_e32 v100, 0xbfb8aa3b, v105
	v_exp_f32_e32 v100, v100
	s_nop 0
	v_add_f32_e32 v100, 1.0, v100
	v_div_scale_f32 v105, s[12:13], v100, v100, v109
	v_rcp_f32_e32 v110, v105
	s_nop 0
	v_fma_f32 v112, -v105, v110, 1.0
	v_fmac_f32_e32 v110, v112, v110
	v_div_scale_f32 v112, vcc, v109, v100, v109
	v_mul_f32_e32 v113, v112, v110
	v_fma_f32 v114, -v105, v113, v112
	v_fmac_f32_e32 v113, v114, v110
	v_fma_f32 v105, -v105, v113, v112
	v_div_fmas_f32 v105, v105, v110, v113
	v_div_fixup_f32 v100, v105, v100, v109
	v_div_scale_f32 v105, s[12:13], v101, v101, v108
	v_rcp_f32_e32 v109, v105
	v_cvt_pk_bf16_f32 v99, v99, v100
	v_cvt_pk_bf16_f32 v100, v111, v103
	s_nop 0
	v_fma_f32 v110, -v105, v109, 1.0
	v_fmac_f32_e32 v109, v110, v109
	v_div_scale_f32 v110, vcc, v108, v101, v108
	v_mul_f32_e32 v112, v110, v109
	v_fma_f32 v113, -v105, v112, v110
	v_fmac_f32_e32 v112, v113, v109
	v_fma_f32 v105, -v105, v112, v110
	v_div_fmas_f32 v105, v105, v109, v112
	v_div_fixup_f32 v101, v105, v101, v108
	v_cvt_pk_bf16_f32 v101, v104, v101
	global_store_dwordx4 v[106:107], v[98:101], off offset:2304
	s_nop 1
	v_or_b32_e32 v98, 32, v144
	v_ashrrev_i32_e32 v99, 31, v98
	v_lshlrev_b64 v[102:103], 11, v[98:99]
	v_lshlrev_b64 v[100:101], 12, v[98:99]
	v_lshl_add_u64 v[98:99], s[86:87], 0, v[102:103]
	v_lshl_add_u64 v[98:99], v[98:99], 0, v[142:143]
	global_load_dwordx4 v[102:105], v[98:99], off
	s_waitcnt vmcnt(0)
; #define LAS __attribute__((address_space(3)))
; __device__ __forceinline__ unsigned cvt_pk_bf16(float lo, float hi) { unsigned r; asm volatile("v_cvt_pk_bf16_f32 %0, %1, %2" : "=v"(r) : "v"(lo), "v"(hi)); return r; }
; __device__ __forceinline__ float bf_lo(unsigned w) { return __uint_as_float(w << 16); }
; __device__ __forceinline__ float bf_hi(unsigned w) { return __uint_as_float(w & 0xffff0000u); }
;     __device__ __forceinline__ void operator()(const f32x4 (&acc)[2][2][4][2], const Unit& u, int ui, const LAS float* rtab, int wr, int wc, int fr, int fq) const {
;         const int row0 = u.pm * BM + wr * 64 + fr, col0 = u.pn * BM + wc * 32 + 8 * fq;
; #pragma unroll
;         for (int ai = 0; ai < 2; ++ai)
; #pragma unroll
;             for (int m = 0; m < 4; ++m) {
;                 const int row = row0 + ai * HALF + m * 16;
; #pragma unroll
;                 for (int bj = 0; bj < 2; ++bj) {
;                     const int col = col0 + bj * HALF; const u32x4 yv = *(const u32x4*)(Y + (size_t)row * 1024 + col);
;                     const f32x4 a0 = acc[ai][bj][m][0], a1 = acc[ai][bj][m][1]; float o[8];
;                     const float yy[8] = {bf_lo(yv.x), bf_hi(yv.x), bf_lo(yv.y), bf_hi(yv.y), bf_lo(yv.z), bf_hi(yv.z), bf_lo(yv.w), bf_hi(yv.w)};
; #pragma unroll
;                     for (int e = 0; e < 4; ++e) { o[e] = yy[e] / (1.0f + __expf(-a0[e])); o[4 + e] = yy[4 + e] / (1.0f + __expf(-a1[e])); }
;                     u32x4 w; w.x = cvt_pk_bf16(o[0], o[1]); w.y = cvt_pk_bf16(o[2], o[3]); w.z = cvt_pk_bf16(o[4], o[5]); w.w = cvt_pk_bf16(o[6], o[7]);
;                     *(u32x4*)(MG + (size_t)row * DM + 1024 + col) = w;
;                 }
	v_lshlrev_b32_e32 v106, 16, v102
	v_and_b32_e32 v107, 0xffff0000, v102
	v_lshlrev_b32_e32 v110, 16, v105
	v_and_b32_e32 v102, 0xffff0000, v105
	v_div_scale_f32 v105, s[12:13], v94, v94, v106
	v_rcp_f32_e32 v111, v105
	v_lshlrev_b32_e32 v109, 16, v104
	v_and_b32_e32 v104, 0xffff0000, v104
	v_lshlrev_b32_e32 v108, 16, v103
	v_fma_f32 v112, -v105, v111, 1.0
	v_fmac_f32_e32 v111, v112, v111
	v_div_scale_f32 v112, vcc, v106, v94, v106
	v_mul_f32_e32 v113, v112, v111
	v_fma_f32 v114, -v105, v113, v112
	v_fmac_f32_e32 v113, v114, v111
	v_fma_f32 v105, -v105, v113, v112
	v_div_fmas_f32 v105, v105, v111, v113
	v_div_fixup_f32 v94, v105, v94, v106
	v_div_scale_f32 v105, s[12:13], v90, v90, v109
	v_rcp_f32_e32 v106, v105
	v_and_b32_e32 v103, 0xffff0000, v103
	v_fma_f32 v111, -v105, v106, 1.0
	v_fmac_f32_e32 v106, v111, v106
	v_div_scale_f32 v111, vcc, v109, v90, v109
	v_mul_f32_e32 v112, v111, v106
	v_fma_f32 v113, -v105, v112, v111
	v_fmac_f32_e32 v112, v113, v106
	v_fma_f32 v105, -v105, v112, v111
	v_div_fmas_f32 v105, v105, v106, v112
	v_div_fixup_f32 v90, v105, v90, v109
	v_div_scale_f32 v105, s[12:13], v95, v95, v107
	v_rcp_f32_e32 v106, v105
	s_nop 0
	v_fma_f32 v109, -v105, v106, 1.0
	v_fmac_f32_e32 v106, v109, v106
	v_div_scale_f32 v109, vcc, v107, v95, v107
	v_mul_f32_e32 v111, v109, v106
	v_fma_f32 v112, -v105, v111, v109
	v_fmac_f32_e32 v111, v112, v106
	v_fma_f32 v105, -v105, v111, v109
	v_div_fmas_f32 v105, v105, v106, v111
	v_div_fixup_f32 v95, v105, v95, v107
	v_div_scale_f32 v105, s[12:13], v91, v91, v104
	v_rcp_f32_e32 v106, v105
	s_nop 0
	v_fma_f32 v107, -v105, v106, 1.0
	v_fmac_f32_e32 v106, v107, v106
	v_div_scale_f32 v107, vcc, v104, v91, v104
	v_mul_f32_e32 v109, v107, v106
	v_fma_f32 v111, -v105, v109, v107
	v_fmac_f32_e32 v109, v111, v106
	v_fma_f32 v105, -v105, v109, v107
	v_div_fmas_f32 v105, v105, v106, v109
	v_div_fixup_f32 v91, v105, v91, v104
	v_div_scale_f32 v104, s[12:13], v96, v96, v108
	v_rcp_f32_e32 v105, v104
	s_nop 0
	v_fma_f32 v106, -v104, v105, 1.0
	v_fmac_f32_e32 v105, v106, v105
	v_div_scale_f32 v106, vcc, v108, v96, v108
	v_mul_f32_e32 v107, v106, v105
	v_fma_f32 v109, -v104, v107, v106
	v_fmac_f32_e32 v107, v109, v105
	v_fma_f32 v104, -v104, v107, v106
	v_div_fmas_f32 v104, v104, v105, v107
	v_div_fixup_f32 v96, v104, v96, v108
	v_div_scale_f32 v104, s[12:13], v92, v92, v110
	v_rcp_f32_e32 v105, v104
	s_nop 0
	v_fma_f32 v106, -v104, v105, 1.0
	v_fmac_f32_e32 v105, v106, v105
	v_div_scale_f32 v106, vcc, v110, v92, v110
	v_mul_f32_e32 v107, v106, v105
	v_fma_f32 v108, -v104, v107, v106
	v_fmac_f32_e32 v107, v108, v105
	v_fma_f32 v104, -v104, v107, v106
	v_div_fmas_f32 v104, v104, v105, v107
	v_div_fixup_f32 v104, v104, v92, v110
	v_mul_f32_e32 v92, 0xbfb8aa3b, v97
	v_exp_f32_e32 v92, v92
	s_nop 0
	v_add_f32_e32 v92, 1.0, v92
	v_div_scale_f32 v97, s[12:13], v92, v92, v103
	v_rcp_f32_e32 v105, v97
	s_nop 0
	v_fma_f32 v106, -v97, v105, 1.0
	v_fmac_f32_e32 v105, v106, v105
	v_div_scale_f32 v106, vcc, v103, v92, v103
	v_mul_f32_e32 v107, v106, v105
	v_fma_f32 v108, -v97, v107, v106
	v_fmac_f32_e32 v107, v108, v105
	v_fma_f32 v97, -v97, v107, v106
	v_div_fmas_f32 v97, v97, v105, v107
	v_div_fixup_f32 v97, v97, v92, v103
	v_mul_f32_e32 v92, 0xbfb8aa3b, v93
	v_exp_f32_e32 v92, v92
	s_nop 0
	v_add_f32_e32 v92, 1.0, v92
	v_div_scale_f32 v93, s[12:13], v92, v92, v102
	v_rcp_f32_e32 v103, v93
	s_nop 0
	v_fma_f32 v105, -v93, v103, 1.0
	v_fmac_f32_e32 v103, v105, v103
	v_div_scale_f32 v105, vcc, v102, v92, v102
	v_mul_f32_e32 v106, v105, v103
	v_fma_f32 v107, -v93, v106, v105
	v_fmac_f32_e32 v106, v107, v103
	v_fma_f32 v93, -v93, v106, v105
	v_div_fmas_f32 v93, v93, v103, v106
	v_div_fixup_f32 v102, v93, v92, v102
	v_cvt_pk_bf16_f32 v92, v94, v95
	v_cvt_pk_bf16_f32 v93, v96, v97
	v_cvt_pk_bf16_f32 v94, v90, v91
	v_lshl_add_u64 v[90:91], s[88:89], 0, v[100:101]
	v_cvt_pk_bf16_f32 v95, v104, v102
	v_lshl_add_u64 v[90:91], v[90:91], 0, v[142:143]
	global_store_dwordx4 v[90:91], v[92:95], off offset:2048
	global_load_dwordx4 v[92:95], v[98:99], off offset:256
	s_waitcnt vmcnt(0)
	v_lshlrev_b32_e32 v96, 16, v92
	v_and_b32_e32 v97, 0xffff0000, v92
	v_lshlrev_b32_e32 v100, 16, v95
	v_and_b32_e32 v92, 0xffff0000, v95
	v_div_scale_f32 v95, s[12:13], v86, v86, v96
	v_rcp_f32_e32 v101, v95
	v_lshlrev_b32_e32 v99, 16, v94
	v_and_b32_e32 v94, 0xffff0000, v94
	v_lshlrev_b32_e32 v98, 16, v93
	v_fma_f32 v102, -v95, v101, 1.0
	v_fmac_f32_e32 v101, v102, v101
	v_div_scale_f32 v102, vcc, v96, v86, v96
	v_mul_f32_e32 v103, v102, v101
	v_fma_f32 v104, -v95, v103, v102
	v_fmac_f32_e32 v103, v104, v101
	v_fma_f32 v95, -v95, v103, v102
	v_div_fmas_f32 v95, v95, v101, v103
	v_div_fixup_f32 v86, v95, v86, v96
	v_div_scale_f32 v95, s[12:13], v82, v82, v99
	v_rcp_f32_e32 v96, v95
	v_and_b32_e32 v93, 0xffff0000, v93
	v_fma_f32 v101, -v95, v96, 1.0
	v_fmac_f32_e32 v96, v101, v96
	v_div_scale_f32 v101, vcc, v99, v82, v99
	v_mul_f32_e32 v102, v101, v96
	v_fma_f32 v103, -v95, v102, v101
	v_fmac_f32_e32 v102, v103, v96
	v_fma_f32 v95, -v95, v102, v101
	v_div_fmas_f32 v95, v95, v96, v102
	v_div_fixup_f32 v95, v95, v82, v99
	v_mul_f32_e32 v82, 0xbfb8aa3b, v87
	v_exp_f32_e32 v82, v82
	s_nop 0
	v_add_f32_e32 v82, 1.0, v82
	v_div_scale_f32 v87, s[12:13], v82, v82, v97
	v_rcp_f32_e32 v96, v87
	s_nop 0
	v_fma_f32 v99, -v87, v96, 1.0
	v_fmac_f32_e32 v96, v99, v96
	v_div_scale_f32 v99, vcc, v97, v82, v97
	v_mul_f32_e32 v101, v99, v96
	v_fma_f32 v102, -v87, v101, v99
	v_fmac_f32_e32 v101, v102, v96
	v_fma_f32 v87, -v87, v101, v99
	v_div_fmas_f32 v87, v87, v96, v101
	v_div_fixup_f32 v82, v87, v82, v97
	v_div_scale_f32 v87, s[12:13], v83, v83, v94
	v_rcp_f32_e32 v96, v87
; #define LAS __attribute__((address_space(3)))
; __device__ __forceinline__ unsigned cvt_pk_bf16(float lo, float hi) { unsigned r; asm volatile("v_cvt_pk_bf16_f32 %0, %1, %2" : "=v"(r) : "v"(lo), "v"(hi)); return r; }
; __device__ __forceinline__ float bf_lo(unsigned w) { return __uint_as_float(w << 16); }
; __device__ __forceinline__ float bf_hi(unsigned w) { return __uint_as_float(w & 0xffff0000u); }
;     __device__ __forceinline__ void operator()(const f32x4 (&acc)[2][2][4][2], const Unit& u, int ui, const LAS float* rtab, int wr, int wc, int fr, int fq) const {
;         const int row0 = u.pm * BM + wr * 64 + fr, col0 = u.pn * BM + wc * 32 + 8 * fq;
; #pragma unroll
;         for (int ai = 0; ai < 2; ++ai)
; #pragma unroll
;             for (int m = 0; m < 4; ++m) {
;                 const int row = row0 + ai * HALF + m * 16;
; #pragma unroll
;                 for (int bj = 0; bj < 2; ++bj) {
;                     const int col = col0 + bj * HALF; const u32x4 yv = *(const u32x4*)(Y + (size_t)row * 1024 + col);
;                     const f32x4 a0 = acc[ai][bj][m][0], a1 = acc[ai][bj][m][1]; float o[8];
;                     const float yy[8] = {bf_lo(yv.x), bf_hi(yv.x), bf_lo(yv.y), bf_hi(yv.y), bf_lo(yv.z), bf_hi(yv.z), bf_lo(yv.w), bf_hi(yv.w)};
; #pragma unroll
;                     for (int e = 0; e < 4; ++e) { o[e] = yy[e] / (1.0f + __expf(-a0[e])); o[4 + e] = yy[4 + e] / (1.0f + __expf(-a1[e])); }
;                     u32x4 w; w.x = cvt_pk_bf16(o[0], o[1]); w.y = cvt_pk_bf16(o[2], o[3]); w.z = cvt_pk_bf16(o[4], o[5]); w.w = cvt_pk_bf16(o[6], o[7]);
;                     *(u32x4*)(MG + (size_t)row * DM + 1024 + col) = w;
;                 }
	v_cvt_pk_bf16_f32 v82, v86, v82
	s_nop 0
	v_fma_f32 v97, -v87, v96, 1.0
	v_fmac_f32_e32 v96, v97, v96
	v_div_scale_f32 v97, vcc, v94, v83, v94
	v_mul_f32_e32 v99, v97, v96
	v_fma_f32 v101, -v87, v99, v97
	v_fmac_f32_e32 v99, v101, v96
	v_fma_f32 v87, -v87, v99, v97
	v_div_fmas_f32 v87, v87, v96, v99
	v_div_fixup_f32 v87, v87, v83, v94
	v_mul_f32_e32 v83, 0xbfb8aa3b, v88
	v_exp_f32_e32 v83, v83
	s_nop 0
	v_add_f32_e32 v83, 1.0, v83
	v_div_scale_f32 v88, s[12:13], v83, v83, v98
	v_rcp_f32_e32 v94, v88
	s_nop 0
	v_fma_f32 v96, -v88, v94, 1.0
	v_fmac_f32_e32 v94, v96, v94
	v_div_scale_f32 v96, vcc, v98, v83, v98
	v_mul_f32_e32 v97, v96, v94
	v_fma_f32 v99, -v88, v97, v96
	v_fmac_f32_e32 v97, v99, v94
	v_fma_f32 v88, -v88, v97, v96
	v_div_fmas_f32 v88, v88, v94, v97
	v_div_fixup_f32 v83, v88, v83, v98
	v_div_scale_f32 v88, s[12:13], v84, v84, v100
	v_rcp_f32_e32 v94, v88
	s_nop 0
	v_fma_f32 v96, -v88, v94, 1.0
	v_fmac_f32_e32 v94, v96, v94
	v_div_scale_f32 v96, vcc, v100, v84, v100
	v_mul_f32_e32 v97, v96, v94
	v_fma_f32 v98, -v88, v97, v96
	v_fmac_f32_e32 v97, v98, v94
	v_fma_f32 v88, -v88, v97, v96
	v_div_fmas_f32 v88, v88, v94, v97
	v_div_fixup_f32 v88, v88, v84, v100
	v_mul_f32_e32 v84, 0xbfb8aa3b, v89
	v_exp_f32_e32 v84, v84
	s_nop 0
	v_add_f32_e32 v84, 1.0, v84
	v_div_scale_f32 v89, s[12:13], v84, v84, v93
	v_rcp_f32_e32 v94, v89
	s_nop 0
	v_fma_f32 v96, -v89, v94, 1.0
	v_fmac_f32_e32 v94, v96, v94
	v_div_scale_f32 v96, vcc, v93, v84, v93
	v_mul_f32_e32 v97, v96, v94
	v_fma_f32 v98, -v89, v97, v96
	v_fmac_f32_e32 v97, v98, v94
	v_fma_f32 v89, -v89, v97, v96
	v_div_fmas_f32 v89, v89, v94, v97
	v_div_fixup_f32 v84, v89, v84, v93
	v_div_scale_f32 v89, s[12:13], v85, v85, v92
	v_rcp_f32_e32 v93, v89
	v_cvt_pk_bf16_f32 v83, v83, v84
	v_cvt_pk_bf16_f32 v84, v95, v87
	s_nop 0
	v_fma_f32 v94, -v89, v93, 1.0
	v_fmac_f32_e32 v93, v94, v93
	v_div_scale_f32 v94, vcc, v92, v85, v92
	v_mul_f32_e32 v96, v94, v93
	v_fma_f32 v97, -v89, v96, v94
	v_fmac_f32_e32 v96, v97, v93
	v_fma_f32 v89, -v89, v96, v94
	v_div_fmas_f32 v89, v89, v93, v96
	v_div_fixup_f32 v85, v89, v85, v92
	v_cvt_pk_bf16_f32 v85, v88, v85
	global_store_dwordx4 v[90:91], v[82:85], off offset:2304
	s_nop 1
	v_or_b32_e32 v82, 48, v144
	v_ashrrev_i32_e32 v83, 31, v82
	v_lshlrev_b64 v[86:87], 11, v[82:83]
	v_lshlrev_b64 v[84:85], 12, v[82:83]
	v_lshl_add_u64 v[82:83], s[86:87], 0, v[86:87]
	v_lshl_add_u64 v[82:83], v[82:83], 0, v[142:143]
	global_load_dwordx4 v[86:89], v[82:83], off
	s_waitcnt vmcnt(0)
	v_lshlrev_b32_e32 v90, 16, v86
	v_and_b32_e32 v91, 0xffff0000, v86
	v_lshlrev_b32_e32 v94, 16, v89
	v_and_b32_e32 v86, 0xffff0000, v89
	v_div_scale_f32 v89, s[12:13], v78, v78, v90
	v_rcp_f32_e32 v95, v89
	v_lshlrev_b32_e32 v93, 16, v88
	v_and_b32_e32 v88, 0xffff0000, v88
	v_lshlrev_b32_e32 v92, 16, v87
	v_fma_f32 v96, -v89, v95, 1.0
	v_fmac_f32_e32 v95, v96, v95
	v_div_scale_f32 v96, vcc, v90, v78, v90
	v_mul_f32_e32 v97, v96, v95
	v_fma_f32 v98, -v89, v97, v96
	v_fmac_f32_e32 v97, v98, v95
	v_fma_f32 v89, -v89, v97, v96
	v_div_fmas_f32 v89, v89, v95, v97
	v_div_fixup_f32 v78, v89, v78, v90
	v_div_scale_f32 v89, s[12:13], v74, v74, v93
	v_rcp_f32_e32 v90, v89
	v_and_b32_e32 v87, 0xffff0000, v87
	v_fma_f32 v95, -v89, v90, 1.0
	v_fmac_f32_e32 v90, v95, v90
	v_div_scale_f32 v95, vcc, v93, v74, v93
	v_mul_f32_e32 v96, v95, v90
	v_fma_f32 v97, -v89, v96, v95
	v_fmac_f32_e32 v96, v97, v90
	v_fma_f32 v89, -v89, v96, v95
	v_div_fmas_f32 v89, v89, v90, v96
	v_div_fixup_f32 v74, v89, v74, v93
	v_div_scale_f32 v89, s[12:13], v79, v79, v91
	v_rcp_f32_e32 v90, v89
	s_nop 0
	v_fma_f32 v93, -v89, v90, 1.0
	v_fmac_f32_e32 v90, v93, v90
	v_div_scale_f32 v93, vcc, v91, v79, v91
	v_mul_f32_e32 v95, v93, v90
	v_fma_f32 v96, -v89, v95, v93
	v_fmac_f32_e32 v95, v96, v90
	v_fma_f32 v89, -v89, v95, v93
	v_div_fmas_f32 v89, v89, v90, v95
	v_div_fixup_f32 v79, v89, v79, v91
	v_div_scale_f32 v89, s[12:13], v75, v75, v88
	v_rcp_f32_e32 v90, v89
	s_nop 0
	v_fma_f32 v91, -v89, v90, 1.0
	v_fmac_f32_e32 v90, v91, v90
	v_div_scale_f32 v91, vcc, v88, v75, v88
	v_mul_f32_e32 v93, v91, v90
	v_fma_f32 v95, -v89, v93, v91
	v_fmac_f32_e32 v93, v95, v90
	v_fma_f32 v89, -v89, v93, v91
	v_div_fmas_f32 v89, v89, v90, v93
	v_div_fixup_f32 v75, v89, v75, v88
	v_div_scale_f32 v88, s[12:13], v80, v80, v92
	v_rcp_f32_e32 v89, v88
	s_nop 0
	v_fma_f32 v90, -v88, v89, 1.0
	v_fmac_f32_e32 v89, v90, v89
	v_div_scale_f32 v90, vcc, v92, v80, v92
	v_mul_f32_e32 v91, v90, v89
	v_fma_f32 v93, -v88, v91, v90
	v_fmac_f32_e32 v91, v93, v89
	v_fma_f32 v88, -v88, v91, v90
	v_div_fmas_f32 v88, v88, v89, v91
	v_div_fixup_f32 v80, v88, v80, v92
	v_div_scale_f32 v88, s[12:13], v76, v76, v94
	v_rcp_f32_e32 v89, v88
	s_nop 0
	v_fma_f32 v90, -v88, v89, 1.0
	v_fmac_f32_e32 v89, v90, v89
	v_div_scale_f32 v90, vcc, v94, v76, v94
	v_mul_f32_e32 v91, v90, v89
	v_fma_f32 v92, -v88, v91, v90
	v_fmac_f32_e32 v91, v92, v89
	v_fma_f32 v88, -v88, v91, v90
	v_div_fmas_f32 v88, v88, v89, v91
	v_div_fixup_f32 v88, v88, v76, v94
	v_mul_f32_e32 v76, 0xbfb8aa3b, v81
	v_exp_f32_e32 v76, v76
	s_nop 0
	v_add_f32_e32 v76, 1.0, v76
	v_div_scale_f32 v81, s[12:13], v76, v76, v87
	v_rcp_f32_e32 v89, v81
	s_nop 0
	v_fma_f32 v90, -v81, v89, 1.0
	v_fmac_f32_e32 v89, v90, v89
	v_div_scale_f32 v90, vcc, v87, v76, v87
	v_mul_f32_e32 v91, v90, v89
	v_fma_f32 v92, -v81, v91, v90
	v_fmac_f32_e32 v91, v92, v89
	v_fma_f32 v81, -v81, v91, v90
	v_div_fmas_f32 v81, v81, v89, v91
	v_div_fixup_f32 v81, v81, v76, v87
	v_mul_f32_e32 v76, 0xbfb8aa3b, v77
	v_exp_f32_e32 v76, v76
	s_nop 0
	v_add_f32_e32 v76, 1.0, v76
	v_div_scale_f32 v77, s[12:13], v76, v76, v86
	v_rcp_f32_e32 v87, v77
	s_nop 0
	v_fma_f32 v89, -v77, v87, 1.0
	v_fmac_f32_e32 v87, v89, v87
	v_div_scale_f32 v89, vcc, v86, v76, v86
	v_mul_f32_e32 v90, v89, v87
	v_fma_f32 v91, -v77, v90, v89
	v_fmac_f32_e32 v90, v91, v87
	v_fma_f32 v77, -v77, v90, v89
	v_div_fmas_f32 v77, v77, v87, v90
	v_div_fixup_f32 v86, v77, v76, v86
	v_cvt_pk_bf16_f32 v76, v78, v79
	v_cvt_pk_bf16_f32 v77, v80, v81
	v_cvt_pk_bf16_f32 v78, v74, v75
	v_lshl_add_u64 v[74:75], s[88:89], 0, v[84:85]
	v_cvt_pk_bf16_f32 v79, v88, v86
	v_lshl_add_u64 v[74:75], v[74:75], 0, v[142:143]
	global_store_dwordx4 v[74:75], v[76:79], off offset:2048
	global_load_dwordx4 v[76:79], v[82:83], off offset:256
	s_waitcnt vmcnt(0)
; #define LAS __attribute__((address_space(3)))
; __device__ __forceinline__ unsigned cvt_pk_bf16(float lo, float hi) { unsigned r; asm volatile("v_cvt_pk_bf16_f32 %0, %1, %2" : "=v"(r) : "v"(lo), "v"(hi)); return r; }
; __device__ __forceinline__ float bf_lo(unsigned w) { return __uint_as_float(w << 16); }
; __device__ __forceinline__ float bf_hi(unsigned w) { return __uint_as_float(w & 0xffff0000u); }
;     __device__ __forceinline__ void operator()(const f32x4 (&acc)[2][2][4][2], const Unit& u, int ui, const LAS float* rtab, int wr, int wc, int fr, int fq) const {
;         const int row0 = u.pm * BM + wr * 64 + fr, col0 = u.pn * BM + wc * 32 + 8 * fq;
; #pragma unroll
;         for (int ai = 0; ai < 2; ++ai)
; #pragma unroll
;             for (int m = 0; m < 4; ++m) {
;                 const int row = row0 + ai * HALF + m * 16;
; #pragma unroll
;                 for (int bj = 0; bj < 2; ++bj) {
;                     const int col = col0 + bj * HALF; const u32x4 yv = *(const u32x4*)(Y + (size_t)row * 1024 + col);
;                     const f32x4 a0 = acc[ai][bj][m][0], a1 = acc[ai][bj][m][1]; float o[8];
;                     const float yy[8] = {bf_lo(yv.x), bf_hi(yv.x), bf_lo(yv.y), bf_hi(yv.y), bf_lo(yv.z), bf_hi(yv.z), bf_lo(yv.w), bf_hi(yv.w)};
; #pragma unroll
;                     for (int e = 0; e < 4; ++e) { o[e] = yy[e] / (1.0f + __expf(-a0[e])); o[4 + e] = yy[4 + e] / (1.0f + __expf(-a1[e])); }
;                     u32x4 w; w.x = cvt_pk_bf16(o[0], o[1]); w.y = cvt_pk_bf16(o[2], o[3]); w.z = cvt_pk_bf16(o[4], o[5]); w.w = cvt_pk_bf16(o[6], o[7]);
;                     *(u32x4*)(MG + (size_t)row * DM + 1024 + col) = w;
;                 }
	v_lshlrev_b32_e32 v80, 16, v76
	v_and_b32_e32 v81, 0xffff0000, v76
	v_lshlrev_b32_e32 v84, 16, v79
	v_and_b32_e32 v76, 0xffff0000, v79
	v_div_scale_f32 v79, s[12:13], v70, v70, v80
	v_rcp_f32_e32 v85, v79
	v_lshlrev_b32_e32 v83, 16, v78
	v_and_b32_e32 v78, 0xffff0000, v78
	v_lshlrev_b32_e32 v82, 16, v77
	v_fma_f32 v86, -v79, v85, 1.0
	v_fmac_f32_e32 v85, v86, v85
	v_div_scale_f32 v86, vcc, v80, v70, v80
	v_mul_f32_e32 v87, v86, v85
	v_fma_f32 v88, -v79, v87, v86
	v_fmac_f32_e32 v87, v88, v85
	v_fma_f32 v79, -v79, v87, v86
	v_div_fmas_f32 v79, v79, v85, v87
	v_div_fixup_f32 v70, v79, v70, v80
	v_div_scale_f32 v79, s[12:13], v66, v66, v83
	v_rcp_f32_e32 v80, v79
	v_and_b32_e32 v77, 0xffff0000, v77
	v_fma_f32 v85, -v79, v80, 1.0
	v_fmac_f32_e32 v80, v85, v80
	v_div_scale_f32 v85, vcc, v83, v66, v83
	v_mul_f32_e32 v86, v85, v80
	v_fma_f32 v87, -v79, v86, v85
	v_fmac_f32_e32 v86, v87, v80
	v_fma_f32 v79, -v79, v86, v85
	v_div_fmas_f32 v79, v79, v80, v86
	v_div_fixup_f32 v79, v79, v66, v83
	v_mul_f32_e32 v66, 0xbfb8aa3b, v71
	v_exp_f32_e32 v66, v66
	s_nop 0
	v_add_f32_e32 v66, 1.0, v66
	v_div_scale_f32 v71, s[12:13], v66, v66, v81
	v_rcp_f32_e32 v80, v71
	s_nop 0
	v_fma_f32 v83, -v71, v80, 1.0
	v_fmac_f32_e32 v80, v83, v80
	v_div_scale_f32 v83, vcc, v81, v66, v81
	v_mul_f32_e32 v85, v83, v80
	v_fma_f32 v86, -v71, v85, v83
	v_fmac_f32_e32 v85, v86, v80
	v_fma_f32 v71, -v71, v85, v83
	v_div_fmas_f32 v71, v71, v80, v85
	v_div_fixup_f32 v66, v71, v66, v81
	v_div_scale_f32 v71, s[12:13], v67, v67, v78
	v_rcp_f32_e32 v80, v71
	v_cvt_pk_bf16_f32 v66, v70, v66
	s_nop 0
	v_fma_f32 v81, -v71, v80, 1.0
	v_fmac_f32_e32 v80, v81, v80
	v_div_scale_f32 v81, vcc, v78, v67, v78
	v_mul_f32_e32 v83, v81, v80
	v_fma_f32 v85, -v71, v83, v81
	v_fmac_f32_e32 v83, v85, v80
	v_fma_f32 v71, -v71, v83, v81
	v_div_fmas_f32 v71, v71, v80, v83
	v_div_fixup_f32 v71, v71, v67, v78
	v_mul_f32_e32 v67, 0xbfb8aa3b, v72
	v_exp_f32_e32 v67, v67
	s_nop 0
	v_add_f32_e32 v67, 1.0, v67
	v_div_scale_f32 v72, s[12:13], v67, v67, v82
	v_rcp_f32_e32 v78, v72
	s_nop 0
	v_fma_f32 v80, -v72, v78, 1.0
	v_fmac_f32_e32 v78, v80, v78
	v_div_scale_f32 v80, vcc, v82, v67, v82
	v_mul_f32_e32 v81, v80, v78
	v_fma_f32 v83, -v72, v81, v80
	v_fmac_f32_e32 v81, v83, v78
	v_fma_f32 v72, -v72, v81, v80
	v_div_fmas_f32 v72, v72, v78, v81
	v_div_fixup_f32 v67, v72, v67, v82
	v_div_scale_f32 v72, s[12:13], v68, v68, v84
	v_rcp_f32_e32 v78, v72
	s_nop 0
	v_fma_f32 v80, -v72, v78, 1.0
	v_fmac_f32_e32 v78, v80, v78
	v_div_scale_f32 v80, vcc, v84, v68, v84
	v_mul_f32_e32 v81, v80, v78
	v_fma_f32 v82, -v72, v81, v80
	v_fmac_f32_e32 v81, v82, v78
	v_fma_f32 v72, -v72, v81, v80
	v_div_fmas_f32 v72, v72, v78, v81
	v_div_fixup_f32 v72, v72, v68, v84
	v_mul_f32_e32 v68, 0xbfb8aa3b, v73
	v_exp_f32_e32 v68, v68
	s_nop 0
	v_add_f32_e32 v68, 1.0, v68
	v_div_scale_f32 v73, s[12:13], v68, v68, v77
	v_rcp_f32_e32 v78, v73
	s_nop 0
	v_fma_f32 v80, -v73, v78, 1.0
	v_fmac_f32_e32 v78, v80, v78
	v_div_scale_f32 v80, vcc, v77, v68, v77
	v_mul_f32_e32 v81, v80, v78
	v_fma_f32 v82, -v73, v81, v80
	v_fmac_f32_e32 v81, v82, v78
	v_fma_f32 v73, -v73, v81, v80
	v_div_fmas_f32 v73, v73, v78, v81
	v_div_fixup_f32 v68, v73, v68, v77
	v_div_scale_f32 v73, s[12:13], v69, v69, v76
	v_rcp_f32_e32 v77, v73
	v_cvt_pk_bf16_f32 v67, v67, v68
	v_cvt_pk_bf16_f32 v68, v79, v71
	s_nop 0
	v_fma_f32 v78, -v73, v77, 1.0
	v_fmac_f32_e32 v77, v78, v77
	v_div_scale_f32 v78, vcc, v76, v69, v76
	v_mul_f32_e32 v80, v78, v77
	v_fma_f32 v81, -v73, v80, v78
	v_fmac_f32_e32 v80, v81, v77
	v_fma_f32 v73, -v73, v80, v78
	v_div_fmas_f32 v73, v73, v77, v80
	v_div_fixup_f32 v69, v73, v69, v76
	v_cvt_pk_bf16_f32 v69, v72, v69
	global_store_dwordx4 v[74:75], v[66:69], off offset:2304
	s_nop 1
	v_add_u32_e32 v66, 0x80, v144
	v_ashrrev_i32_e32 v67, 31, v66
	v_lshlrev_b64 v[70:71], 11, v[66:67]
	v_lshlrev_b64 v[68:69], 12, v[66:67]
	v_lshl_add_u64 v[66:67], s[86:87], 0, v[70:71]
	v_lshl_add_u64 v[66:67], v[66:67], 0, v[142:143]
	global_load_dwordx4 v[70:73], v[66:67], off
	s_waitcnt vmcnt(0)
	v_lshlrev_b32_e32 v74, 16, v70
	v_and_b32_e32 v75, 0xffff0000, v70
	v_lshlrev_b32_e32 v78, 16, v73
	v_and_b32_e32 v70, 0xffff0000, v73
	v_div_scale_f32 v73, s[12:13], v62, v62, v74
	v_rcp_f32_e32 v79, v73
	v_lshlrev_b32_e32 v77, 16, v72
	v_and_b32_e32 v72, 0xffff0000, v72
	v_lshlrev_b32_e32 v76, 16, v71
	v_fma_f32 v80, -v73, v79, 1.0
	v_fmac_f32_e32 v79, v80, v79
	v_div_scale_f32 v80, vcc, v74, v62, v74
	v_mul_f32_e32 v81, v80, v79
	v_fma_f32 v82, -v73, v81, v80
	v_fmac_f32_e32 v81, v82, v79
	v_fma_f32 v73, -v73, v81, v80
	v_div_fmas_f32 v73, v73, v79, v81
	v_div_fixup_f32 v62, v73, v62, v74
	v_div_scale_f32 v73, s[12:13], v58, v58, v77
	v_rcp_f32_e32 v74, v73
	v_and_b32_e32 v71, 0xffff0000, v71
	v_fma_f32 v79, -v73, v74, 1.0
	v_fmac_f32_e32 v74, v79, v74
	v_div_scale_f32 v79, vcc, v77, v58, v77
	v_mul_f32_e32 v80, v79, v74
	v_fma_f32 v81, -v73, v80, v79
	v_fmac_f32_e32 v80, v81, v74
	v_fma_f32 v73, -v73, v80, v79
	v_div_fmas_f32 v73, v73, v74, v80
	v_div_fixup_f32 v58, v73, v58, v77
	v_div_scale_f32 v73, s[12:13], v63, v63, v75
	v_rcp_f32_e32 v74, v73
	s_nop 0
	v_fma_f32 v77, -v73, v74, 1.0
	v_fmac_f32_e32 v74, v77, v74
	v_div_scale_f32 v77, vcc, v75, v63, v75
	v_mul_f32_e32 v79, v77, v74
	v_fma_f32 v80, -v73, v79, v77
	v_fmac_f32_e32 v79, v80, v74
	v_fma_f32 v73, -v73, v79, v77
	v_div_fmas_f32 v73, v73, v74, v79
	v_div_fixup_f32 v63, v73, v63, v75
	v_div_scale_f32 v73, s[12:13], v59, v59, v72
	v_rcp_f32_e32 v74, v73
	s_nop 0
	v_fma_f32 v75, -v73, v74, 1.0
	v_fmac_f32_e32 v74, v75, v74
	v_div_scale_f32 v75, vcc, v72, v59, v72
	v_mul_f32_e32 v77, v75, v74
	v_fma_f32 v79, -v73, v77, v75
; #define LAS __attribute__((address_space(3)))
; __device__ __forceinline__ unsigned cvt_pk_bf16(float lo, float hi) { unsigned r; asm volatile("v_cvt_pk_bf16_f32 %0, %1, %2" : "=v"(r) : "v"(lo), "v"(hi)); return r; }
; __device__ __forceinline__ float bf_lo(unsigned w) { return __uint_as_float(w << 16); }
; __device__ __forceinline__ float bf_hi(unsigned w) { return __uint_as_float(w & 0xffff0000u); }
;     __device__ __forceinline__ void operator()(const f32x4 (&acc)[2][2][4][2], const Unit& u, int ui, const LAS float* rtab, int wr, int wc, int fr, int fq) const {
;         const int row0 = u.pm * BM + wr * 64 + fr, col0 = u.pn * BM + wc * 32 + 8 * fq;
; #pragma unroll
;         for (int ai = 0; ai < 2; ++ai)
; #pragma unroll
;             for (int m = 0; m < 4; ++m) {
;                 const int row = row0 + ai * HALF + m * 16;
; #pragma unroll
;                 for (int bj = 0; bj < 2; ++bj) {
;                     const int col = col0 + bj * HALF; const u32x4 yv = *(const u32x4*)(Y + (size_t)row * 1024 + col);
;                     const f32x4 a0 = acc[ai][bj][m][0], a1 = acc[ai][bj][m][1]; float o[8];
;                     const float yy[8] = {bf_lo(yv.x), bf_hi(yv.x), bf_lo(yv.y), bf_hi(yv.y), bf_lo(yv.z), bf_hi(yv.z), bf_lo(yv.w), bf_hi(yv.w)};
; #pragma unroll
;                     for (int e = 0; e < 4; ++e) { o[e] = yy[e] / (1.0f + __expf(-a0[e])); o[4 + e] = yy[4 + e] / (1.0f + __expf(-a1[e])); }
;                     u32x4 w; w.x = cvt_pk_bf16(o[0], o[1]); w.y = cvt_pk_bf16(o[2], o[3]); w.z = cvt_pk_bf16(o[4], o[5]); w.w = cvt_pk_bf16(o[6], o[7]);
;                     *(u32x4*)(MG + (size_t)row * DM + 1024 + col) = w;
;                 }
	v_fmac_f32_e32 v77, v79, v74
	v_fma_f32 v73, -v73, v77, v75
	v_div_fmas_f32 v73, v73, v74, v77
	v_div_fixup_f32 v59, v73, v59, v72
	v_div_scale_f32 v72, s[12:13], v64, v64, v76
	v_rcp_f32_e32 v73, v72
	s_nop 0
	v_fma_f32 v74, -v72, v73, 1.0
	v_fmac_f32_e32 v73, v74, v73
	v_div_scale_f32 v74, vcc, v76, v64, v76
	v_mul_f32_e32 v75, v74, v73
	v_fma_f32 v77, -v72, v75, v74
	v_fmac_f32_e32 v75, v77, v73
	v_fma_f32 v72, -v72, v75, v74
	v_div_fmas_f32 v72, v72, v73, v75
	v_div_fixup_f32 v64, v72, v64, v76
	v_div_scale_f32 v72, s[12:13], v60, v60, v78
	v_rcp_f32_e32 v73, v72
	s_nop 0
	v_fma_f32 v74, -v72, v73, 1.0
	v_fmac_f32_e32 v73, v74, v73
	v_div_scale_f32 v74, vcc, v78, v60, v78
	v_mul_f32_e32 v75, v74, v73
	v_fma_f32 v76, -v72, v75, v74
	v_fmac_f32_e32 v75, v76, v73
	v_fma_f32 v72, -v72, v75, v74
	v_div_fmas_f32 v72, v72, v73, v75
	v_div_fixup_f32 v72, v72, v60, v78
	v_mul_f32_e32 v60, 0xbfb8aa3b, v65
	v_exp_f32_e32 v60, v60
	s_nop 0
	v_add_f32_e32 v60, 1.0, v60
	v_div_scale_f32 v65, s[12:13], v60, v60, v71
	v_rcp_f32_e32 v73, v65
	s_nop 0
	v_fma_f32 v74, -v65, v73, 1.0
	v_fmac_f32_e32 v73, v74, v73
	v_div_scale_f32 v74, vcc, v71, v60, v71
	v_mul_f32_e32 v75, v74, v73
	v_fma_f32 v76, -v65, v75, v74
	v_fmac_f32_e32 v75, v76, v73
	v_fma_f32 v65, -v65, v75, v74
	v_div_fmas_f32 v65, v65, v73, v75
	v_div_fixup_f32 v65, v65, v60, v71
	v_mul_f32_e32 v60, 0xbfb8aa3b, v61
	v_exp_f32_e32 v60, v60
	s_nop 0
	v_add_f32_e32 v60, 1.0, v60
	v_div_scale_f32 v61, s[12:13], v60, v60, v70
	v_rcp_f32_e32 v71, v61
	s_nop 0
	v_fma_f32 v73, -v61, v71, 1.0
	v_fmac_f32_e32 v71, v73, v71
	v_div_scale_f32 v73, vcc, v70, v60, v70
	v_mul_f32_e32 v74, v73, v71
	v_fma_f32 v75, -v61, v74, v73
	v_fmac_f32_e32 v74, v75, v71
	v_fma_f32 v61, -v61, v74, v73
	v_div_fmas_f32 v61, v61, v71, v74
	v_div_fixup_f32 v70, v61, v60, v70
	v_cvt_pk_bf16_f32 v60, v62, v63
	v_cvt_pk_bf16_f32 v61, v64, v65
	v_cvt_pk_bf16_f32 v62, v58, v59
	v_lshl_add_u64 v[58:59], s[88:89], 0, v[68:69]
	v_cvt_pk_bf16_f32 v63, v72, v70
	v_lshl_add_u64 v[58:59], v[58:59], 0, v[142:143]
	global_store_dwordx4 v[58:59], v[60:63], off offset:2048
	global_load_dwordx4 v[60:63], v[66:67], off offset:256
	s_waitcnt vmcnt(0)
	v_lshlrev_b32_e32 v64, 16, v60
	v_and_b32_e32 v65, 0xffff0000, v60
	v_lshlrev_b32_e32 v68, 16, v63
	v_and_b32_e32 v60, 0xffff0000, v63
	v_div_scale_f32 v63, s[12:13], v54, v54, v64
	v_rcp_f32_e32 v69, v63
	v_lshlrev_b32_e32 v67, 16, v62
	v_and_b32_e32 v62, 0xffff0000, v62
	v_lshlrev_b32_e32 v66, 16, v61
	v_fma_f32 v70, -v63, v69, 1.0
	v_fmac_f32_e32 v69, v70, v69
	v_div_scale_f32 v70, vcc, v64, v54, v64
	v_mul_f32_e32 v71, v70, v69
	v_fma_f32 v72, -v63, v71, v70
	v_fmac_f32_e32 v71, v72, v69
	v_fma_f32 v63, -v63, v71, v70
	v_div_fmas_f32 v63, v63, v69, v71
	v_div_fixup_f32 v54, v63, v54, v64
	v_div_scale_f32 v63, s[12:13], v50, v50, v67
	v_rcp_f32_e32 v64, v63
	v_and_b32_e32 v61, 0xffff0000, v61
	v_fma_f32 v69, -v63, v64, 1.0
	v_fmac_f32_e32 v64, v69, v64
	v_div_scale_f32 v69, vcc, v67, v50, v67
	v_mul_f32_e32 v70, v69, v64
	v_fma_f32 v71, -v63, v70, v69
	v_fmac_f32_e32 v70, v71, v64
	v_fma_f32 v63, -v63, v70, v69
	v_div_fmas_f32 v63, v63, v64, v70
	v_div_fixup_f32 v63, v63, v50, v67
	v_mul_f32_e32 v50, 0xbfb8aa3b, v55
	v_exp_f32_e32 v50, v50
	s_nop 0
	v_add_f32_e32 v50, 1.0, v50
	v_div_scale_f32 v55, s[12:13], v50, v50, v65
	v_rcp_f32_e32 v64, v55
	s_nop 0
	v_fma_f32 v67, -v55, v64, 1.0
	v_fmac_f32_e32 v64, v67, v64
	v_div_scale_f32 v67, vcc, v65, v50, v65
	v_mul_f32_e32 v69, v67, v64
	v_fma_f32 v70, -v55, v69, v67
	v_fmac_f32_e32 v69, v70, v64
	v_fma_f32 v55, -v55, v69, v67
	v_div_fmas_f32 v55, v55, v64, v69
	v_div_fixup_f32 v50, v55, v50, v65
	v_div_scale_f32 v55, s[12:13], v51, v51, v62
	v_rcp_f32_e32 v64, v55
	v_cvt_pk_bf16_f32 v50, v54, v50
	s_nop 0
	v_fma_f32 v65, -v55, v64, 1.0
	v_fmac_f32_e32 v64, v65, v64
	v_div_scale_f32 v65, vcc, v62, v51, v62
	v_mul_f32_e32 v67, v65, v64
	v_fma_f32 v69, -v55, v67, v65
	v_fmac_f32_e32 v67, v69, v64
	v_fma_f32 v55, -v55, v67, v65
	v_div_fmas_f32 v55, v55, v64, v67
	v_div_fixup_f32 v55, v55, v51, v62
	v_mul_f32_e32 v51, 0xbfb8aa3b, v56
	v_exp_f32_e32 v51, v51
	s_nop 0
	v_add_f32_e32 v51, 1.0, v51
	v_div_scale_f32 v56, s[12:13], v51, v51, v66
	v_rcp_f32_e32 v62, v56
	s_nop 0
	v_fma_f32 v64, -v56, v62, 1.0
	v_fmac_f32_e32 v62, v64, v62
	v_div_scale_f32 v64, vcc, v66, v51, v66
	v_mul_f32_e32 v65, v64, v62
	v_fma_f32 v67, -v56, v65, v64
	v_fmac_f32_e32 v65, v67, v62
	v_fma_f32 v56, -v56, v65, v64
	v_div_fmas_f32 v56, v56, v62, v65
	v_div_fixup_f32 v51, v56, v51, v66
	v_div_scale_f32 v56, s[12:13], v52, v52, v68
	v_rcp_f32_e32 v62, v56
	s_nop 0
	v_fma_f32 v64, -v56, v62, 1.0
	v_fmac_f32_e32 v62, v64, v62
	v_div_scale_f32 v64, vcc, v68, v52, v68
	v_mul_f32_e32 v65, v64, v62
	v_fma_f32 v66, -v56, v65, v64
	v_fmac_f32_e32 v65, v66, v62
	v_fma_f32 v56, -v56, v65, v64
	v_div_fmas_f32 v56, v56, v62, v65
	v_div_fixup_f32 v56, v56, v52, v68
	v_mul_f32_e32 v52, 0xbfb8aa3b, v57
	v_exp_f32_e32 v52, v52
	s_nop 0
	v_add_f32_e32 v52, 1.0, v52
	v_div_scale_f32 v57, s[12:13], v52, v52, v61
	v_rcp_f32_e32 v62, v57
	s_nop 0
	v_fma_f32 v64, -v57, v62, 1.0
	v_fmac_f32_e32 v62, v64, v62
	v_div_scale_f32 v64, vcc, v61, v52, v61
	v_mul_f32_e32 v65, v64, v62
	v_fma_f32 v66, -v57, v65, v64
	v_fmac_f32_e32 v65, v66, v62
	v_fma_f32 v57, -v57, v65, v64
	v_div_fmas_f32 v57, v57, v62, v65
	v_div_fixup_f32 v52, v57, v52, v61
	v_div_scale_f32 v57, s[12:13], v53, v53, v60
	v_rcp_f32_e32 v61, v57
	v_cvt_pk_bf16_f32 v51, v51, v52
	v_cvt_pk_bf16_f32 v52, v63, v55
	s_nop 0
	v_fma_f32 v62, -v57, v61, 1.0
	v_fmac_f32_e32 v61, v62, v61
	v_div_scale_f32 v62, vcc, v60, v53, v60
	v_mul_f32_e32 v64, v62, v61
	v_fma_f32 v65, -v57, v64, v62
	v_fmac_f32_e32 v64, v65, v61
	v_fma_f32 v57, -v57, v64, v62
	v_div_fmas_f32 v57, v57, v61, v64
	v_div_fixup_f32 v53, v57, v53, v60
	v_cvt_pk_bf16_f32 v53, v56, v53
	global_store_dwordx4 v[58:59], v[50:53], off offset:2304
	s_nop 1
	v_add_u32_e32 v50, 0x90, v144
	v_ashrrev_i32_e32 v51, 31, v50
	v_lshlrev_b64 v[54:55], 11, v[50:51]
	v_lshlrev_b64 v[52:53], 12, v[50:51]
	v_lshl_add_u64 v[50:51], s[86:87], 0, v[54:55]
	v_lshl_add_u64 v[50:51], v[50:51], 0, v[142:143]
	global_load_dwordx4 v[54:57], v[50:51], off
	s_waitcnt vmcnt(0)
; #define LAS __attribute__((address_space(3)))
; __device__ __forceinline__ unsigned cvt_pk_bf16(float lo, float hi) { unsigned r; asm volatile("v_cvt_pk_bf16_f32 %0, %1, %2" : "=v"(r) : "v"(lo), "v"(hi)); return r; }
; __device__ __forceinline__ float bf_lo(unsigned w) { return __uint_as_float(w << 16); }
; __device__ __forceinline__ float bf_hi(unsigned w) { return __uint_as_float(w & 0xffff0000u); }
;     __device__ __forceinline__ void operator()(const f32x4 (&acc)[2][2][4][2], const Unit& u, int ui, const LAS float* rtab, int wr, int wc, int fr, int fq) const {
;         const int row0 = u.pm * BM + wr * 64 + fr, col0 = u.pn * BM + wc * 32 + 8 * fq;
; #pragma unroll
;         for (int ai = 0; ai < 2; ++ai)
; #pragma unroll
;             for (int m = 0; m < 4; ++m) {
;                 const int row = row0 + ai * HALF + m * 16;
; #pragma unroll
;                 for (int bj = 0; bj < 2; ++bj) {
;                     const int col = col0 + bj * HALF; const u32x4 yv = *(const u32x4*)(Y + (size_t)row * 1024 + col);
;                     const f32x4 a0 = acc[ai][bj][m][0], a1 = acc[ai][bj][m][1]; float o[8];
;                     const float yy[8] = {bf_lo(yv.x), bf_hi(yv.x), bf_lo(yv.y), bf_hi(yv.y), bf_lo(yv.z), bf_hi(yv.z), bf_lo(yv.w), bf_hi(yv.w)};
; #pragma unroll
;                     for (int e = 0; e < 4; ++e) { o[e] = yy[e] / (1.0f + __expf(-a0[e])); o[4 + e] = yy[4 + e] / (1.0f + __expf(-a1[e])); }
;                     u32x4 w; w.x = cvt_pk_bf16(o[0], o[1]); w.y = cvt_pk_bf16(o[2], o[3]); w.z = cvt_pk_bf16(o[4], o[5]); w.w = cvt_pk_bf16(o[6], o[7]);
;                     *(u32x4*)(MG + (size_t)row * DM + 1024 + col) = w;
;                 }
	v_lshlrev_b32_e32 v58, 16, v54
	v_and_b32_e32 v59, 0xffff0000, v54
	v_lshlrev_b32_e32 v62, 16, v57
	v_and_b32_e32 v54, 0xffff0000, v57
	v_div_scale_f32 v57, s[12:13], v46, v46, v58
	v_rcp_f32_e32 v63, v57
	v_lshlrev_b32_e32 v61, 16, v56
	v_and_b32_e32 v56, 0xffff0000, v56
	v_lshlrev_b32_e32 v60, 16, v55
	v_fma_f32 v64, -v57, v63, 1.0
	v_fmac_f32_e32 v63, v64, v63
	v_div_scale_f32 v64, vcc, v58, v46, v58
	v_mul_f32_e32 v65, v64, v63
	v_fma_f32 v66, -v57, v65, v64
	v_fmac_f32_e32 v65, v66, v63
	v_fma_f32 v57, -v57, v65, v64
	v_div_fmas_f32 v57, v57, v63, v65
	v_div_fixup_f32 v46, v57, v46, v58
	v_div_scale_f32 v57, s[12:13], v42, v42, v61
	v_rcp_f32_e32 v58, v57
	v_and_b32_e32 v55, 0xffff0000, v55
	v_fma_f32 v63, -v57, v58, 1.0
	v_fmac_f32_e32 v58, v63, v58
	v_div_scale_f32 v63, vcc, v61, v42, v61
	v_mul_f32_e32 v64, v63, v58
	v_fma_f32 v65, -v57, v64, v63
	v_fmac_f32_e32 v64, v65, v58
	v_fma_f32 v57, -v57, v64, v63
	v_div_fmas_f32 v57, v57, v58, v64
	v_div_fixup_f32 v42, v57, v42, v61
	v_div_scale_f32 v57, s[12:13], v47, v47, v59
	v_rcp_f32_e32 v58, v57
	s_nop 0
	v_fma_f32 v61, -v57, v58, 1.0
	v_fmac_f32_e32 v58, v61, v58
	v_div_scale_f32 v61, vcc, v59, v47, v59
	v_mul_f32_e32 v63, v61, v58
	v_fma_f32 v64, -v57, v63, v61
	v_fmac_f32_e32 v63, v64, v58
	v_fma_f32 v57, -v57, v63, v61
	v_div_fmas_f32 v57, v57, v58, v63
	v_div_fixup_f32 v47, v57, v47, v59
	v_div_scale_f32 v57, s[12:13], v43, v43, v56
	v_rcp_f32_e32 v58, v57
	s_nop 0
	v_fma_f32 v59, -v57, v58, 1.0
	v_fmac_f32_e32 v58, v59, v58
	v_div_scale_f32 v59, vcc, v56, v43, v56
	v_mul_f32_e32 v61, v59, v58
	v_fma_f32 v63, -v57, v61, v59
	v_fmac_f32_e32 v61, v63, v58
	v_fma_f32 v57, -v57, v61, v59
	v_div_fmas_f32 v57, v57, v58, v61
	v_div_fixup_f32 v43, v57, v43, v56
	v_div_scale_f32 v56, s[12:13], v48, v48, v60
	v_rcp_f32_e32 v57, v56
	s_nop 0
	v_fma_f32 v58, -v56, v57, 1.0
	v_fmac_f32_e32 v57, v58, v57
	v_div_scale_f32 v58, vcc, v60, v48, v60
	v_mul_f32_e32 v59, v58, v57
	v_fma_f32 v61, -v56, v59, v58
	v_fmac_f32_e32 v59, v61, v57
	v_fma_f32 v56, -v56, v59, v58
	v_div_fmas_f32 v56, v56, v57, v59
	v_div_fixup_f32 v48, v56, v48, v60
	v_div_scale_f32 v56, s[12:13], v44, v44, v62
	v_rcp_f32_e32 v57, v56
	s_nop 0
	v_fma_f32 v58, -v56, v57, 1.0
	v_fmac_f32_e32 v57, v58, v57
	v_div_scale_f32 v58, vcc, v62, v44, v62
	v_mul_f32_e32 v59, v58, v57
	v_fma_f32 v60, -v56, v59, v58
	v_fmac_f32_e32 v59, v60, v57
	v_fma_f32 v56, -v56, v59, v58
	v_div_fmas_f32 v56, v56, v57, v59
	v_div_fixup_f32 v56, v56, v44, v62
	v_mul_f32_e32 v44, 0xbfb8aa3b, v49
	v_exp_f32_e32 v44, v44
	s_nop 0
	v_add_f32_e32 v44, 1.0, v44
	v_div_scale_f32 v49, s[12:13], v44, v44, v55
	v_rcp_f32_e32 v57, v49
	s_nop 0
	v_fma_f32 v58, -v49, v57, 1.0
	v_fmac_f32_e32 v57, v58, v57
	v_div_scale_f32 v58, vcc, v55, v44, v55
	v_mul_f32_e32 v59, v58, v57
	v_fma_f32 v60, -v49, v59, v58
	v_fmac_f32_e32 v59, v60, v57
	v_fma_f32 v49, -v49, v59, v58
	v_div_fmas_f32 v49, v49, v57, v59
	v_div_fixup_f32 v49, v49, v44, v55
	v_mul_f32_e32 v44, 0xbfb8aa3b, v45
	v_exp_f32_e32 v44, v44
	s_nop 0
	v_add_f32_e32 v44, 1.0, v44
	v_div_scale_f32 v45, s[12:13], v44, v44, v54
	v_rcp_f32_e32 v55, v45
	s_nop 0
	v_fma_f32 v57, -v45, v55, 1.0
	v_fmac_f32_e32 v55, v57, v55
	v_div_scale_f32 v57, vcc, v54, v44, v54
	v_mul_f32_e32 v58, v57, v55
	v_fma_f32 v59, -v45, v58, v57
	v_fmac_f32_e32 v58, v59, v55
	v_fma_f32 v45, -v45, v58, v57
	v_div_fmas_f32 v45, v45, v55, v58
	v_div_fixup_f32 v54, v45, v44, v54
	v_cvt_pk_bf16_f32 v44, v46, v47
	v_cvt_pk_bf16_f32 v45, v48, v49
	v_cvt_pk_bf16_f32 v46, v42, v43
	v_lshl_add_u64 v[42:43], s[88:89], 0, v[52:53]
	v_cvt_pk_bf16_f32 v47, v56, v54
	v_lshl_add_u64 v[42:43], v[42:43], 0, v[142:143]
	global_store_dwordx4 v[42:43], v[44:47], off offset:2048
	global_load_dwordx4 v[44:47], v[50:51], off offset:256
	s_waitcnt vmcnt(0)
	v_lshlrev_b32_e32 v48, 16, v44
	v_and_b32_e32 v49, 0xffff0000, v44
	v_lshlrev_b32_e32 v52, 16, v47
	v_and_b32_e32 v44, 0xffff0000, v47
	v_div_scale_f32 v47, s[12:13], v38, v38, v48
	v_rcp_f32_e32 v53, v47
	v_lshlrev_b32_e32 v51, 16, v46
	v_and_b32_e32 v46, 0xffff0000, v46
	v_lshlrev_b32_e32 v50, 16, v45
	v_fma_f32 v54, -v47, v53, 1.0
	v_fmac_f32_e32 v53, v54, v53
	v_div_scale_f32 v54, vcc, v48, v38, v48
	v_mul_f32_e32 v55, v54, v53
	v_fma_f32 v56, -v47, v55, v54
	v_fmac_f32_e32 v55, v56, v53
	v_fma_f32 v47, -v47, v55, v54
	v_div_fmas_f32 v47, v47, v53, v55
	v_div_fixup_f32 v38, v47, v38, v48
	v_div_scale_f32 v47, s[12:13], v34, v34, v51
	v_rcp_f32_e32 v48, v47
	v_and_b32_e32 v45, 0xffff0000, v45
	v_fma_f32 v53, -v47, v48, 1.0
	v_fmac_f32_e32 v48, v53, v48
	v_div_scale_f32 v53, vcc, v51, v34, v51
	v_mul_f32_e32 v54, v53, v48
	v_fma_f32 v55, -v47, v54, v53
	v_fmac_f32_e32 v54, v55, v48
	v_fma_f32 v47, -v47, v54, v53
	v_div_fmas_f32 v47, v47, v48, v54
	v_div_fixup_f32 v47, v47, v34, v51
	v_mul_f32_e32 v34, 0xbfb8aa3b, v39
	v_exp_f32_e32 v34, v34
	s_nop 0
	v_add_f32_e32 v34, 1.0, v34
	v_div_scale_f32 v39, s[12:13], v34, v34, v49
	v_rcp_f32_e32 v48, v39
	s_nop 0
	v_fma_f32 v51, -v39, v48, 1.0
	v_fmac_f32_e32 v48, v51, v48
	v_div_scale_f32 v51, vcc, v49, v34, v49
	v_mul_f32_e32 v53, v51, v48
	v_fma_f32 v54, -v39, v53, v51
	v_fmac_f32_e32 v53, v54, v48
	v_fma_f32 v39, -v39, v53, v51
	v_div_fmas_f32 v39, v39, v48, v53
	v_div_fixup_f32 v34, v39, v34, v49
	v_div_scale_f32 v39, s[12:13], v35, v35, v46
	v_rcp_f32_e32 v48, v39
	v_cvt_pk_bf16_f32 v34, v38, v34
	s_nop 0
	v_fma_f32 v49, -v39, v48, 1.0
	v_fmac_f32_e32 v48, v49, v48
	v_div_scale_f32 v49, vcc, v46, v35, v46
	v_mul_f32_e32 v51, v49, v48
	v_fma_f32 v53, -v39, v51, v49
	v_fmac_f32_e32 v51, v53, v48
	v_fma_f32 v39, -v39, v51, v49
	v_div_fmas_f32 v39, v39, v48, v51
; #define LAS __attribute__((address_space(3)))
; __device__ __forceinline__ unsigned cvt_pk_bf16(float lo, float hi) { unsigned r; asm volatile("v_cvt_pk_bf16_f32 %0, %1, %2" : "=v"(r) : "v"(lo), "v"(hi)); return r; }
; __device__ __forceinline__ float bf_lo(unsigned w) { return __uint_as_float(w << 16); }
; __device__ __forceinline__ float bf_hi(unsigned w) { return __uint_as_float(w & 0xffff0000u); }
;     __device__ __forceinline__ void operator()(const f32x4 (&acc)[2][2][4][2], const Unit& u, int ui, const LAS float* rtab, int wr, int wc, int fr, int fq) const {
;         const int row0 = u.pm * BM + wr * 64 + fr, col0 = u.pn * BM + wc * 32 + 8 * fq;
; #pragma unroll
;         for (int ai = 0; ai < 2; ++ai)
; #pragma unroll
;             for (int m = 0; m < 4; ++m) {
;                 const int row = row0 + ai * HALF + m * 16;
; #pragma unroll
;                 for (int bj = 0; bj < 2; ++bj) {
;                     const int col = col0 + bj * HALF; const u32x4 yv = *(const u32x4*)(Y + (size_t)row * 1024 + col);
;                     const f32x4 a0 = acc[ai][bj][m][0], a1 = acc[ai][bj][m][1]; float o[8];
;                     const float yy[8] = {bf_lo(yv.x), bf_hi(yv.x), bf_lo(yv.y), bf_hi(yv.y), bf_lo(yv.z), bf_hi(yv.z), bf_lo(yv.w), bf_hi(yv.w)};
; #pragma unroll
;                     for (int e = 0; e < 4; ++e) { o[e] = yy[e] / (1.0f + __expf(-a0[e])); o[4 + e] = yy[4 + e] / (1.0f + __expf(-a1[e])); }
;                     u32x4 w; w.x = cvt_pk_bf16(o[0], o[1]); w.y = cvt_pk_bf16(o[2], o[3]); w.z = cvt_pk_bf16(o[4], o[5]); w.w = cvt_pk_bf16(o[6], o[7]);
;                     *(u32x4*)(MG + (size_t)row * DM + 1024 + col) = w;
;                 }
	v_div_fixup_f32 v39, v39, v35, v46
	v_mul_f32_e32 v35, 0xbfb8aa3b, v40
	v_exp_f32_e32 v35, v35
	s_nop 0
	v_add_f32_e32 v35, 1.0, v35
	v_div_scale_f32 v40, s[12:13], v35, v35, v50
	v_rcp_f32_e32 v46, v40
	s_nop 0
	v_fma_f32 v48, -v40, v46, 1.0
	v_fmac_f32_e32 v46, v48, v46
	v_div_scale_f32 v48, vcc, v50, v35, v50
	v_mul_f32_e32 v49, v48, v46
	v_fma_f32 v51, -v40, v49, v48
	v_fmac_f32_e32 v49, v51, v46
	v_fma_f32 v40, -v40, v49, v48
	v_div_fmas_f32 v40, v40, v46, v49
	v_div_fixup_f32 v35, v40, v35, v50
	v_div_scale_f32 v40, s[12:13], v36, v36, v52
	v_rcp_f32_e32 v46, v40
	s_nop 0
	v_fma_f32 v48, -v40, v46, 1.0
	v_fmac_f32_e32 v46, v48, v46
	v_div_scale_f32 v48, vcc, v52, v36, v52
	v_mul_f32_e32 v49, v48, v46
	v_fma_f32 v50, -v40, v49, v48
	v_fmac_f32_e32 v49, v50, v46
	v_fma_f32 v40, -v40, v49, v48
	v_div_fmas_f32 v40, v40, v46, v49
	v_div_fixup_f32 v40, v40, v36, v52
	v_mul_f32_e32 v36, 0xbfb8aa3b, v41
	v_exp_f32_e32 v36, v36
	s_nop 0
	v_add_f32_e32 v36, 1.0, v36
	v_div_scale_f32 v41, s[12:13], v36, v36, v45
	v_rcp_f32_e32 v46, v41
	s_nop 0
	v_fma_f32 v48, -v41, v46, 1.0
	v_fmac_f32_e32 v46, v48, v46
	v_div_scale_f32 v48, vcc, v45, v36, v45
	v_mul_f32_e32 v49, v48, v46
	v_fma_f32 v50, -v41, v49, v48
	v_fmac_f32_e32 v49, v50, v46
	v_fma_f32 v41, -v41, v49, v48
	v_div_fmas_f32 v41, v41, v46, v49
	v_div_fixup_f32 v36, v41, v36, v45
	v_div_scale_f32 v41, s[12:13], v37, v37, v44
	v_rcp_f32_e32 v45, v41
	v_cvt_pk_bf16_f32 v35, v35, v36
	v_cvt_pk_bf16_f32 v36, v47, v39
	s_nop 0
	v_fma_f32 v46, -v41, v45, 1.0
	v_fmac_f32_e32 v45, v46, v45
	v_div_scale_f32 v46, vcc, v44, v37, v44
	v_mul_f32_e32 v48, v46, v45
	v_fma_f32 v49, -v41, v48, v46
	v_fmac_f32_e32 v48, v49, v45
	v_fma_f32 v41, -v41, v48, v46
	v_div_fmas_f32 v41, v41, v45, v48
	v_div_fixup_f32 v37, v41, v37, v44
	v_cvt_pk_bf16_f32 v37, v40, v37
	global_store_dwordx4 v[42:43], v[34:37], off offset:2304
	s_nop 1
	v_add_u32_e32 v34, 0xa0, v144
	v_ashrrev_i32_e32 v35, 31, v34
	v_lshlrev_b64 v[38:39], 11, v[34:35]
	v_lshlrev_b64 v[36:37], 12, v[34:35]
	v_lshl_add_u64 v[34:35], s[86:87], 0, v[38:39]
	v_lshl_add_u64 v[34:35], v[34:35], 0, v[142:143]
	global_load_dwordx4 v[38:41], v[34:35], off
	s_waitcnt vmcnt(0)
	v_lshlrev_b32_e32 v42, 16, v38
	v_and_b32_e32 v43, 0xffff0000, v38
	v_lshlrev_b32_e32 v46, 16, v41
	v_and_b32_e32 v38, 0xffff0000, v41
	v_div_scale_f32 v41, s[12:13], v30, v30, v42
	v_rcp_f32_e32 v47, v41
	v_lshlrev_b32_e32 v45, 16, v40
	v_and_b32_e32 v40, 0xffff0000, v40
	v_lshlrev_b32_e32 v44, 16, v39
	v_fma_f32 v48, -v41, v47, 1.0
	v_fmac_f32_e32 v47, v48, v47
	v_div_scale_f32 v48, vcc, v42, v30, v42
	v_mul_f32_e32 v49, v48, v47
	v_fma_f32 v50, -v41, v49, v48
	v_fmac_f32_e32 v49, v50, v47
	v_fma_f32 v41, -v41, v49, v48
	v_div_fmas_f32 v41, v41, v47, v49
	v_div_fixup_f32 v30, v41, v30, v42
	v_div_scale_f32 v41, s[12:13], v26, v26, v45
	v_rcp_f32_e32 v42, v41
	v_and_b32_e32 v39, 0xffff0000, v39
	v_fma_f32 v47, -v41, v42, 1.0
	v_fmac_f32_e32 v42, v47, v42
	v_div_scale_f32 v47, vcc, v45, v26, v45
	v_mul_f32_e32 v48, v47, v42
	v_fma_f32 v49, -v41, v48, v47
	v_fmac_f32_e32 v48, v49, v42
	v_fma_f32 v41, -v41, v48, v47
	v_div_fmas_f32 v41, v41, v42, v48
	v_div_fixup_f32 v26, v41, v26, v45
	v_div_scale_f32 v41, s[12:13], v31, v31, v43
	v_rcp_f32_e32 v42, v41
	s_nop 0
	v_fma_f32 v45, -v41, v42, 1.0
	v_fmac_f32_e32 v42, v45, v42
	v_div_scale_f32 v45, vcc, v43, v31, v43
	v_mul_f32_e32 v47, v45, v42
	v_fma_f32 v48, -v41, v47, v45
	v_fmac_f32_e32 v47, v48, v42
	v_fma_f32 v41, -v41, v47, v45
	v_div_fmas_f32 v41, v41, v42, v47
	v_div_fixup_f32 v31, v41, v31, v43
	v_div_scale_f32 v41, s[12:13], v27, v27, v40
	v_rcp_f32_e32 v42, v41
	s_nop 0
	v_fma_f32 v43, -v41, v42, 1.0
	v_fmac_f32_e32 v42, v43, v42
	v_div_scale_f32 v43, vcc, v40, v27, v40
	v_mul_f32_e32 v45, v43, v42
	v_fma_f32 v47, -v41, v45, v43
	v_fmac_f32_e32 v45, v47, v42
	v_fma_f32 v41, -v41, v45, v43
	v_div_fmas_f32 v41, v41, v42, v45
	v_div_fixup_f32 v27, v41, v27, v40
	v_div_scale_f32 v40, s[12:13], v32, v32, v44
	v_rcp_f32_e32 v41, v40
	s_nop 0
	v_fma_f32 v42, -v40, v41, 1.0
	v_fmac_f32_e32 v41, v42, v41
	v_div_scale_f32 v42, vcc, v44, v32, v44
	v_mul_f32_e32 v43, v42, v41
	v_fma_f32 v45, -v40, v43, v42
	v_fmac_f32_e32 v43, v45, v41
	v_fma_f32 v40, -v40, v43, v42
	v_div_fmas_f32 v40, v40, v41, v43
	v_div_fixup_f32 v32, v40, v32, v44
	v_div_scale_f32 v40, s[12:13], v28, v28, v46
	v_rcp_f32_e32 v41, v40
	s_nop 0
	v_fma_f32 v42, -v40, v41, 1.0
	v_fmac_f32_e32 v41, v42, v41
	v_div_scale_f32 v42, vcc, v46, v28, v46
	v_mul_f32_e32 v43, v42, v41
	v_fma_f32 v44, -v40, v43, v42
	v_fmac_f32_e32 v43, v44, v41
	v_fma_f32 v40, -v40, v43, v42
	v_div_fmas_f32 v40, v40, v41, v43
	v_div_fixup_f32 v40, v40, v28, v46
	v_mul_f32_e32 v28, 0xbfb8aa3b, v33
	v_exp_f32_e32 v28, v28
	s_nop 0
	v_add_f32_e32 v28, 1.0, v28
	v_div_scale_f32 v33, s[12:13], v28, v28, v39
	v_rcp_f32_e32 v41, v33
	s_nop 0
	v_fma_f32 v42, -v33, v41, 1.0
	v_fmac_f32_e32 v41, v42, v41
	v_div_scale_f32 v42, vcc, v39, v28, v39
	v_mul_f32_e32 v43, v42, v41
	v_fma_f32 v44, -v33, v43, v42
	v_fmac_f32_e32 v43, v44, v41
	v_fma_f32 v33, -v33, v43, v42
	v_div_fmas_f32 v33, v33, v41, v43
	v_div_fixup_f32 v33, v33, v28, v39
	v_mul_f32_e32 v28, 0xbfb8aa3b, v29
	v_exp_f32_e32 v28, v28
	s_nop 0
	v_add_f32_e32 v28, 1.0, v28
	v_div_scale_f32 v29, s[12:13], v28, v28, v38
	v_rcp_f32_e32 v39, v29
	s_nop 0
	v_fma_f32 v41, -v29, v39, 1.0
	v_fmac_f32_e32 v39, v41, v39
	v_div_scale_f32 v41, vcc, v38, v28, v38
	v_mul_f32_e32 v42, v41, v39
	v_fma_f32 v43, -v29, v42, v41
	v_fmac_f32_e32 v42, v43, v39
	v_fma_f32 v29, -v29, v42, v41
	v_div_fmas_f32 v29, v29, v39, v42
	v_div_fixup_f32 v38, v29, v28, v38
	v_cvt_pk_bf16_f32 v28, v30, v31
	v_cvt_pk_bf16_f32 v29, v32, v33
	v_cvt_pk_bf16_f32 v30, v26, v27
	v_lshl_add_u64 v[26:27], s[88:89], 0, v[36:37]
	v_cvt_pk_bf16_f32 v31, v40, v38
	v_lshl_add_u64 v[26:27], v[26:27], 0, v[142:143]
	global_store_dwordx4 v[26:27], v[28:31], off offset:2048
	global_load_dwordx4 v[28:31], v[34:35], off offset:256
	s_waitcnt vmcnt(0)
; #define LAS __attribute__((address_space(3)))
; __device__ __forceinline__ unsigned cvt_pk_bf16(float lo, float hi) { unsigned r; asm volatile("v_cvt_pk_bf16_f32 %0, %1, %2" : "=v"(r) : "v"(lo), "v"(hi)); return r; }
; __device__ __forceinline__ float bf_lo(unsigned w) { return __uint_as_float(w << 16); }
; __device__ __forceinline__ float bf_hi(unsigned w) { return __uint_as_float(w & 0xffff0000u); }
;     __device__ __forceinline__ void operator()(const f32x4 (&acc)[2][2][4][2], const Unit& u, int ui, const LAS float* rtab, int wr, int wc, int fr, int fq) const {
;         const int row0 = u.pm * BM + wr * 64 + fr, col0 = u.pn * BM + wc * 32 + 8 * fq;
; #pragma unroll
;         for (int ai = 0; ai < 2; ++ai)
; #pragma unroll
;             for (int m = 0; m < 4; ++m) {
;                 const int row = row0 + ai * HALF + m * 16;
; #pragma unroll
;                 for (int bj = 0; bj < 2; ++bj) {
;                     const int col = col0 + bj * HALF; const u32x4 yv = *(const u32x4*)(Y + (size_t)row * 1024 + col);
;                     const f32x4 a0 = acc[ai][bj][m][0], a1 = acc[ai][bj][m][1]; float o[8];
;                     const float yy[8] = {bf_lo(yv.x), bf_hi(yv.x), bf_lo(yv.y), bf_hi(yv.y), bf_lo(yv.z), bf_hi(yv.z), bf_lo(yv.w), bf_hi(yv.w)};
; #pragma unroll
;                     for (int e = 0; e < 4; ++e) { o[e] = yy[e] / (1.0f + __expf(-a0[e])); o[4 + e] = yy[4 + e] / (1.0f + __expf(-a1[e])); }
;                     u32x4 w; w.x = cvt_pk_bf16(o[0], o[1]); w.y = cvt_pk_bf16(o[2], o[3]); w.z = cvt_pk_bf16(o[4], o[5]); w.w = cvt_pk_bf16(o[6], o[7]);
;                     *(u32x4*)(MG + (size_t)row * DM + 1024 + col) = w;
;                 }
	v_lshlrev_b32_e32 v32, 16, v28
	v_and_b32_e32 v33, 0xffff0000, v28
	v_lshlrev_b32_e32 v36, 16, v31
	v_and_b32_e32 v28, 0xffff0000, v31
	v_div_scale_f32 v31, s[12:13], v22, v22, v32
	v_rcp_f32_e32 v37, v31
	v_lshlrev_b32_e32 v35, 16, v30
	v_and_b32_e32 v30, 0xffff0000, v30
	v_lshlrev_b32_e32 v34, 16, v29
	v_fma_f32 v38, -v31, v37, 1.0
	v_fmac_f32_e32 v37, v38, v37
	v_div_scale_f32 v38, vcc, v32, v22, v32
	v_mul_f32_e32 v39, v38, v37
	v_fma_f32 v40, -v31, v39, v38
	v_fmac_f32_e32 v39, v40, v37
	v_fma_f32 v31, -v31, v39, v38
	v_div_fmas_f32 v31, v31, v37, v39
	v_div_fixup_f32 v22, v31, v22, v32
	v_div_scale_f32 v31, s[12:13], v18, v18, v35
	v_rcp_f32_e32 v32, v31
	v_and_b32_e32 v29, 0xffff0000, v29
	v_fma_f32 v37, -v31, v32, 1.0
	v_fmac_f32_e32 v32, v37, v32
	v_div_scale_f32 v37, vcc, v35, v18, v35
	v_mul_f32_e32 v38, v37, v32
	v_fma_f32 v39, -v31, v38, v37
	v_fmac_f32_e32 v38, v39, v32
	v_fma_f32 v31, -v31, v38, v37
	v_div_fmas_f32 v31, v31, v32, v38
	v_div_fixup_f32 v31, v31, v18, v35
	v_mul_f32_e32 v18, 0xbfb8aa3b, v23
	v_exp_f32_e32 v18, v18
	s_nop 0
	v_add_f32_e32 v18, 1.0, v18
	v_div_scale_f32 v23, s[12:13], v18, v18, v33
	v_rcp_f32_e32 v32, v23
	s_nop 0
	v_fma_f32 v35, -v23, v32, 1.0
	v_fmac_f32_e32 v32, v35, v32
	v_div_scale_f32 v35, vcc, v33, v18, v33
	v_mul_f32_e32 v37, v35, v32
	v_fma_f32 v38, -v23, v37, v35
	v_fmac_f32_e32 v37, v38, v32
	v_fma_f32 v23, -v23, v37, v35
	v_div_fmas_f32 v23, v23, v32, v37
	v_div_fixup_f32 v18, v23, v18, v33
	v_div_scale_f32 v23, s[12:13], v19, v19, v30
	v_rcp_f32_e32 v32, v23
	v_cvt_pk_bf16_f32 v18, v22, v18
	s_nop 0
	v_fma_f32 v33, -v23, v32, 1.0
	v_fmac_f32_e32 v32, v33, v32
	v_div_scale_f32 v33, vcc, v30, v19, v30
	v_mul_f32_e32 v35, v33, v32
	v_fma_f32 v37, -v23, v35, v33
	v_fmac_f32_e32 v35, v37, v32
	v_fma_f32 v23, -v23, v35, v33
	v_div_fmas_f32 v23, v23, v32, v35
	v_div_fixup_f32 v23, v23, v19, v30
	v_mul_f32_e32 v19, 0xbfb8aa3b, v24
	v_exp_f32_e32 v19, v19
	s_nop 0
	v_add_f32_e32 v19, 1.0, v19
	v_div_scale_f32 v24, s[12:13], v19, v19, v34
	v_rcp_f32_e32 v30, v24
	s_nop 0
	v_fma_f32 v32, -v24, v30, 1.0
	v_fmac_f32_e32 v30, v32, v30
	v_div_scale_f32 v32, vcc, v34, v19, v34
	v_mul_f32_e32 v33, v32, v30
	v_fma_f32 v35, -v24, v33, v32
	v_fmac_f32_e32 v33, v35, v30
	v_fma_f32 v24, -v24, v33, v32
	v_div_fmas_f32 v24, v24, v30, v33
	v_div_fixup_f32 v19, v24, v19, v34
	v_div_scale_f32 v24, s[12:13], v20, v20, v36
	v_rcp_f32_e32 v30, v24
	s_nop 0
	v_fma_f32 v32, -v24, v30, 1.0
	v_fmac_f32_e32 v30, v32, v30
	v_div_scale_f32 v32, vcc, v36, v20, v36
	v_mul_f32_e32 v33, v32, v30
	v_fma_f32 v34, -v24, v33, v32
	v_fmac_f32_e32 v33, v34, v30
	v_fma_f32 v24, -v24, v33, v32
	v_div_fmas_f32 v24, v24, v30, v33
	v_div_fixup_f32 v24, v24, v20, v36
	v_mul_f32_e32 v20, 0xbfb8aa3b, v25
	v_exp_f32_e32 v20, v20
	s_nop 0
	v_add_f32_e32 v20, 1.0, v20
	v_div_scale_f32 v25, s[12:13], v20, v20, v29
	v_rcp_f32_e32 v30, v25
	s_nop 0
	v_fma_f32 v32, -v25, v30, 1.0
	v_fmac_f32_e32 v30, v32, v30
	v_div_scale_f32 v32, vcc, v29, v20, v29
	v_mul_f32_e32 v33, v32, v30
	v_fma_f32 v34, -v25, v33, v32
	v_fmac_f32_e32 v33, v34, v30
	v_fma_f32 v25, -v25, v33, v32
	v_div_fmas_f32 v25, v25, v30, v33
	v_div_fixup_f32 v20, v25, v20, v29
	v_div_scale_f32 v25, s[12:13], v21, v21, v28
	v_rcp_f32_e32 v29, v25
	v_cvt_pk_bf16_f32 v19, v19, v20
	v_cvt_pk_bf16_f32 v20, v31, v23
	s_nop 0
	v_fma_f32 v30, -v25, v29, 1.0
	v_fmac_f32_e32 v29, v30, v29
	v_div_scale_f32 v30, vcc, v28, v21, v28
	v_mul_f32_e32 v32, v30, v29
	v_fma_f32 v33, -v25, v32, v30
	v_fmac_f32_e32 v32, v33, v29
	v_fma_f32 v25, -v25, v32, v30
	v_div_fmas_f32 v25, v25, v29, v32
	v_div_fixup_f32 v21, v25, v21, v28
	v_cvt_pk_bf16_f32 v21, v24, v21
	global_store_dwordx4 v[26:27], v[18:21], off offset:2304
	s_nop 1
	v_add_u32_e32 v18, 0xb0, v144
	v_ashrrev_i32_e32 v19, 31, v18
	v_lshlrev_b64 v[22:23], 11, v[18:19]
	v_lshlrev_b64 v[20:21], 12, v[18:19]
	v_lshl_add_u64 v[18:19], s[86:87], 0, v[22:23]
	v_lshl_add_u64 v[18:19], v[18:19], 0, v[142:143]
	global_load_dwordx4 v[22:25], v[18:19], off
	s_waitcnt vmcnt(0)
	v_lshlrev_b32_e32 v26, 16, v22
	v_and_b32_e32 v27, 0xffff0000, v22
	v_lshlrev_b32_e32 v30, 16, v25
	v_and_b32_e32 v22, 0xffff0000, v25
	v_div_scale_f32 v25, s[12:13], v14, v14, v26
	v_rcp_f32_e32 v31, v25
	v_lshlrev_b32_e32 v29, 16, v24
	v_and_b32_e32 v24, 0xffff0000, v24
	v_lshlrev_b32_e32 v28, 16, v23
	v_fma_f32 v32, -v25, v31, 1.0
	v_fmac_f32_e32 v31, v32, v31
	v_div_scale_f32 v32, vcc, v26, v14, v26
	v_mul_f32_e32 v33, v32, v31
	v_fma_f32 v34, -v25, v33, v32
	v_fmac_f32_e32 v33, v34, v31
	v_fma_f32 v25, -v25, v33, v32
	v_div_fmas_f32 v25, v25, v31, v33
	v_div_fixup_f32 v14, v25, v14, v26
	v_div_scale_f32 v25, s[12:13], v10, v10, v29
	v_rcp_f32_e32 v26, v25
	v_and_b32_e32 v23, 0xffff0000, v23
	v_fma_f32 v31, -v25, v26, 1.0
	v_fmac_f32_e32 v26, v31, v26
	v_div_scale_f32 v31, vcc, v29, v10, v29
	v_mul_f32_e32 v32, v31, v26
	v_fma_f32 v33, -v25, v32, v31
	v_fmac_f32_e32 v32, v33, v26
	v_fma_f32 v25, -v25, v32, v31
	v_div_fmas_f32 v25, v25, v26, v32
	v_div_fixup_f32 v10, v25, v10, v29
	v_div_scale_f32 v25, s[12:13], v15, v15, v27
	v_rcp_f32_e32 v26, v25
	s_nop 0
	v_fma_f32 v29, -v25, v26, 1.0
	v_fmac_f32_e32 v26, v29, v26
	v_div_scale_f32 v29, vcc, v27, v15, v27
	v_mul_f32_e32 v31, v29, v26
	v_fma_f32 v32, -v25, v31, v29
	v_fmac_f32_e32 v31, v32, v26
	v_fma_f32 v25, -v25, v31, v29
	v_div_fmas_f32 v25, v25, v26, v31
	v_div_fixup_f32 v15, v25, v15, v27
	v_div_scale_f32 v25, s[12:13], v11, v11, v24
	v_rcp_f32_e32 v26, v25
	s_nop 0
	v_fma_f32 v27, -v25, v26, 1.0
	v_fmac_f32_e32 v26, v27, v26
	v_div_scale_f32 v27, vcc, v24, v11, v24
	v_mul_f32_e32 v29, v27, v26
	v_fma_f32 v31, -v25, v29, v27
; __device__ __forceinline__ unsigned cvt_pk_bf16(float lo, float hi) { unsigned r; asm volatile("v_cvt_pk_bf16_f32 %0, %1, %2" : "=v"(r) : "v"(lo), "v"(hi)); return r; }
; __device__ __forceinline__ float bf_lo(unsigned w) { return __uint_as_float(w << 16); }
; __device__ __forceinline__ float bf_hi(unsigned w) { return __uint_as_float(w & 0xffff0000u); }
; #define PG8_WAIT_V(n) asm volatile("s_waitcnt vmcnt(" #n ")" ::: "memory")
; #define PG8_BAR __builtin_amdgcn_s_barrier()
;     __device__ __forceinline__ void operator()(const f32x4 (&acc)[2][2][4][2], const Unit& u, int ui, const LAS float* rtab, int wr, int wc, int fr, int fq) const {
;     ...
;                     const int col = col0 + bj * HALF; const u32x4 yv = *(const u32x4*)(Y + (size_t)row * 1024 + col);
;                     const f32x4 a0 = acc[ai][bj][m][0], a1 = acc[ai][bj][m][1]; float o[8];
;                     const float yy[8] = {bf_lo(yv.x), bf_hi(yv.x), bf_lo(yv.y), bf_hi(yv.y), bf_lo(yv.z), bf_hi(yv.z), bf_lo(yv.w), bf_hi(yv.w)};
; #pragma unroll
;                     for (int e = 0; e < 4; ++e) { o[e] = yy[e] / (1.0f + __expf(-a0[e])); o[4 + e] = yy[4 + e] / (1.0f + __expf(-a1[e])); }
;                     u32x4 w; w.x = cvt_pk_bf16(o[0], o[1]); w.y = cvt_pk_bf16(o[2], o[3]); w.z = cvt_pk_bf16(o[4], o[5]); w.w = cvt_pk_bf16(o[6], o[7]);
;                     *(u32x4*)(MG + (size_t)row * DM + 1024 + col) = w;
; template <class Epi, class Sched>
; __device__ __forceinline__ void gemm_phase(LAS unsigned char* lds, const Gemm g, const Sched& S, const Epi& E) {
;     ...
;     PG8_WAIT_V(0);
;     if (wr == 0) PG8_BAR;
;     PG8_BAR;
	v_fmac_f32_e32 v29, v31, v26
	v_fma_f32 v25, -v25, v29, v27
	v_div_fmas_f32 v25, v25, v26, v29
	v_div_fixup_f32 v11, v25, v11, v24
	v_div_scale_f32 v24, s[12:13], v16, v16, v28
	v_rcp_f32_e32 v25, v24
	s_nop 0
	v_fma_f32 v26, -v24, v25, 1.0
	v_fmac_f32_e32 v25, v26, v25
	v_div_scale_f32 v26, vcc, v28, v16, v28
	v_mul_f32_e32 v27, v26, v25
	v_fma_f32 v29, -v24, v27, v26
	v_fmac_f32_e32 v27, v29, v25
	v_fma_f32 v24, -v24, v27, v26
	v_div_fmas_f32 v24, v24, v25, v27
	v_div_fixup_f32 v16, v24, v16, v28
	v_div_scale_f32 v24, s[12:13], v12, v12, v30
	v_rcp_f32_e32 v25, v24
	s_nop 0
	v_fma_f32 v26, -v24, v25, 1.0
	v_fmac_f32_e32 v25, v26, v25
	v_div_scale_f32 v26, vcc, v30, v12, v30
	v_mul_f32_e32 v27, v26, v25
	v_fma_f32 v28, -v24, v27, v26
	v_fmac_f32_e32 v27, v28, v25
	v_fma_f32 v24, -v24, v27, v26
	v_div_fmas_f32 v24, v24, v25, v27
	v_div_fixup_f32 v24, v24, v12, v30
	v_mul_f32_e32 v12, 0xbfb8aa3b, v17
	v_exp_f32_e32 v12, v12
	s_nop 0
	v_add_f32_e32 v12, 1.0, v12
	v_div_scale_f32 v17, s[12:13], v12, v12, v23
	v_rcp_f32_e32 v25, v17
	s_nop 0
	v_fma_f32 v26, -v17, v25, 1.0
	v_fmac_f32_e32 v25, v26, v25
	v_div_scale_f32 v26, vcc, v23, v12, v23
	v_mul_f32_e32 v27, v26, v25
	v_fma_f32 v28, -v17, v27, v26
	v_fmac_f32_e32 v27, v28, v25
	v_fma_f32 v17, -v17, v27, v26
	v_div_fmas_f32 v17, v17, v25, v27
	v_div_fixup_f32 v17, v17, v12, v23
	v_mul_f32_e32 v12, 0xbfb8aa3b, v13
	v_exp_f32_e32 v12, v12
	s_nop 0
	v_add_f32_e32 v12, 1.0, v12
	v_div_scale_f32 v13, s[12:13], v12, v12, v22
	v_rcp_f32_e32 v23, v13
	s_nop 0
	v_fma_f32 v25, -v13, v23, 1.0
	v_fmac_f32_e32 v23, v25, v23
	v_div_scale_f32 v25, vcc, v22, v12, v22
	v_mul_f32_e32 v26, v25, v23
	v_fma_f32 v27, -v13, v26, v25
	v_fmac_f32_e32 v26, v27, v23
	v_fma_f32 v13, -v13, v26, v25
	v_div_fmas_f32 v13, v13, v23, v26
	v_div_fixup_f32 v22, v13, v12, v22
	v_cvt_pk_bf16_f32 v12, v14, v15
	v_cvt_pk_bf16_f32 v13, v16, v17
	v_cvt_pk_bf16_f32 v14, v10, v11
	v_lshl_add_u64 v[10:11], s[88:89], 0, v[20:21]
	v_cvt_pk_bf16_f32 v15, v24, v22
	v_lshl_add_u64 v[10:11], v[10:11], 0, v[142:143]
	global_store_dwordx4 v[10:11], v[12:15], off offset:2048
	global_load_dwordx4 v[12:15], v[18:19], off offset:256
	s_waitcnt vmcnt(0)
	v_lshlrev_b32_e32 v16, 16, v12
	v_and_b32_e32 v17, 0xffff0000, v12
	v_lshlrev_b32_e32 v20, 16, v15
	v_and_b32_e32 v12, 0xffff0000, v15
	v_div_scale_f32 v15, s[12:13], v6, v6, v16
	v_rcp_f32_e32 v21, v15
	v_lshlrev_b32_e32 v19, 16, v14
	v_and_b32_e32 v14, 0xffff0000, v14
	v_lshlrev_b32_e32 v18, 16, v13
	v_fma_f32 v22, -v15, v21, 1.0
	v_fmac_f32_e32 v21, v22, v21
	v_div_scale_f32 v22, vcc, v16, v6, v16
	v_mul_f32_e32 v23, v22, v21
	v_fma_f32 v24, -v15, v23, v22
	v_fmac_f32_e32 v23, v24, v21
	v_fma_f32 v15, -v15, v23, v22
	v_div_fmas_f32 v15, v15, v21, v23
	v_div_fixup_f32 v6, v15, v6, v16
	v_div_scale_f32 v15, s[12:13], v2, v2, v19
	v_rcp_f32_e32 v16, v15
	v_and_b32_e32 v13, 0xffff0000, v13
	v_fma_f32 v21, -v15, v16, 1.0
	v_fmac_f32_e32 v16, v21, v16
	v_div_scale_f32 v21, vcc, v19, v2, v19
	v_mul_f32_e32 v22, v21, v16
	v_fma_f32 v23, -v15, v22, v21
	v_fmac_f32_e32 v22, v23, v16
	v_fma_f32 v15, -v15, v22, v21
	v_div_fmas_f32 v15, v15, v16, v22
	v_div_fixup_f32 v15, v15, v2, v19
	v_mul_f32_e32 v2, 0xbfb8aa3b, v7
	v_exp_f32_e32 v2, v2
	s_nop 0
	v_add_f32_e32 v2, 1.0, v2
	v_div_scale_f32 v7, s[12:13], v2, v2, v17
	v_rcp_f32_e32 v16, v7
	s_nop 0
	v_fma_f32 v19, -v7, v16, 1.0
	v_fmac_f32_e32 v16, v19, v16
	v_div_scale_f32 v19, vcc, v17, v2, v17
	v_mul_f32_e32 v21, v19, v16
	v_fma_f32 v22, -v7, v21, v19
	v_fmac_f32_e32 v21, v22, v16
	v_fma_f32 v7, -v7, v21, v19
	v_div_fmas_f32 v7, v7, v16, v21
	v_div_fixup_f32 v2, v7, v2, v17
	v_div_scale_f32 v7, s[12:13], v3, v3, v14
	v_rcp_f32_e32 v16, v7
	v_cvt_pk_bf16_f32 v2, v6, v2
	s_nop 0
	v_fma_f32 v17, -v7, v16, 1.0
	v_fmac_f32_e32 v16, v17, v16
	v_div_scale_f32 v17, vcc, v14, v3, v14
	v_mul_f32_e32 v19, v17, v16
	v_fma_f32 v21, -v7, v19, v17
	v_fmac_f32_e32 v19, v21, v16
	v_fma_f32 v7, -v7, v19, v17
	v_div_fmas_f32 v7, v7, v16, v19
	v_div_fixup_f32 v7, v7, v3, v14
	v_mul_f32_e32 v3, 0xbfb8aa3b, v8
	v_exp_f32_e32 v3, v3
	s_nop 0
	v_add_f32_e32 v3, 1.0, v3
	v_div_scale_f32 v8, s[12:13], v3, v3, v18
	v_rcp_f32_e32 v14, v8
	s_nop 0
	v_fma_f32 v16, -v8, v14, 1.0
	v_fmac_f32_e32 v14, v16, v14
	v_div_scale_f32 v16, vcc, v18, v3, v18
	v_mul_f32_e32 v17, v16, v14
	v_fma_f32 v19, -v8, v17, v16
	v_fmac_f32_e32 v17, v19, v14
	v_fma_f32 v8, -v8, v17, v16
	v_div_fmas_f32 v8, v8, v14, v17
	v_div_fixup_f32 v3, v8, v3, v18
	v_div_scale_f32 v8, s[12:13], v4, v4, v20
	v_rcp_f32_e32 v14, v8
	s_nop 0
	v_fma_f32 v16, -v8, v14, 1.0
	v_fmac_f32_e32 v14, v16, v14
	v_div_scale_f32 v16, vcc, v20, v4, v20
	v_mul_f32_e32 v17, v16, v14
	v_fma_f32 v18, -v8, v17, v16
	v_fmac_f32_e32 v17, v18, v14
	v_fma_f32 v8, -v8, v17, v16
	v_div_fmas_f32 v8, v8, v14, v17
	v_div_fixup_f32 v8, v8, v4, v20
	v_mul_f32_e32 v4, 0xbfb8aa3b, v9
	v_exp_f32_e32 v4, v4
	s_nop 0
	v_add_f32_e32 v4, 1.0, v4
	v_div_scale_f32 v9, s[12:13], v4, v4, v13
	v_rcp_f32_e32 v14, v9
	s_nop 0
	v_fma_f32 v16, -v9, v14, 1.0
	v_fmac_f32_e32 v14, v16, v14
	v_div_scale_f32 v16, vcc, v13, v4, v13
	v_mul_f32_e32 v17, v16, v14
	v_fma_f32 v18, -v9, v17, v16
	v_fmac_f32_e32 v17, v18, v14
	v_fma_f32 v9, -v9, v17, v16
	v_div_fmas_f32 v9, v9, v14, v17
	v_div_fixup_f32 v4, v9, v4, v13
	v_div_scale_f32 v9, s[12:13], v5, v5, v12
	v_rcp_f32_e32 v13, v9
	s_mov_b32 s12, s0
	s_mov_b32 s13, s42
	v_cvt_pk_bf16_f32 v3, v3, v4
	v_fma_f32 v14, -v9, v13, 1.0
	v_fmac_f32_e32 v13, v14, v13
	v_div_scale_f32 v14, vcc, v12, v5, v12
	v_mul_f32_e32 v16, v14, v13
	v_fma_f32 v17, -v9, v16, v14
	v_fmac_f32_e32 v16, v17, v13
	v_fma_f32 v9, -v9, v16, v14
	v_div_fmas_f32 v9, v9, v13, v16
	v_div_fixup_f32 v5, v9, v5, v12
	s_and_b64 vcc, exec, s[40:41]
	v_cvt_pk_bf16_f32 v4, v15, v7
	v_cvt_pk_bf16_f32 v5, v8, v5
	global_store_dwordx4 v[10:11], v[2:5], off offset:2304
	s_cbranch_vccz .LBB0_661
	s_waitcnt vmcnt(0)
	s_cmpk_gt_u32 s27, 0xff
	s_cbranch_scc1 .LBB0_672
	s_barrier

; #define PG8_STAGE(bufoff, gbase, voff) do { _Pragma("unroll") for (int _i = 0; _i < 2; ++_i) \
;         __builtin_amdgcn_global_load_lds((const unsigned*)((const char*)(gbase) + (voff)[_i]), (LAS unsigned*)(lds + (bufoff) + ldsw + _i * 8192), 16, 0, 0); } while (0)
; #define PG8_LDA(dst, b, h) do { _Pragma("unroll") for (int m = 0; m < 4; ++m) _Pragma("unroll") for (int k = 0; k < 2; ++k) dst[m][k] = *(const LAS bf16x8*)(lds + PG8_SA(b, h) + aoff + m * 2048 + k * 1024); } while (0)
; #define PG8_LDB(dst, b, h) do { _Pragma("unroll") for (int n = 0; n < 2; ++n) _Pragma("unroll") for (int k = 0; k < 2; ++k) dst[n][k] = *(const LAS bf16x8*)(lds + PG8_SB(b, h) + boff + n * 2048 + k * 1024); } while (0)
; #define PG8_MMA(ai, bj, At, Bt) do { __builtin_amdgcn_s_setprio(1); _Pragma("unroll") for (int m = 0; m < 4; ++m) _Pragma("unroll") for (int n = 0; n < 2; ++n) _Pragma("unroll") for (int k = 0; k < 2; ++k) \
;         acc[ai][bj][m][n] = __builtin_amdgcn_mfma_f32_16x16x32_bf16(Bt[n][k], At[m][k], acc[ai][bj][m][n], 0, 0, 0); __builtin_amdgcn_s_setprio(0); } while (0)
; #define PG8_WAIT_L(n) asm volatile("s_waitcnt lgkmcnt(" #n ")" ::: "memory")
; #define PG8_BAR __builtin_amdgcn_s_barrier()
; #define PG8_SCHED __builtin_amdgcn_sched_barrier(0)
; template <class Epi, class Sched>
; __device__ __forceinline__ void gemm_phase(LAS unsigned char* lds, const Gemm g, const Sched& S, const Epi& E) {
;     ...
;             const char* a1 = cA + (size_t)(t + 1) * kstep;
;             const char* a2 = last ? nA : cA + (size_t)(t + 2) * kstep; const char* b2 = last ? nB : cB + (size_t)(t + 2) * kstep;
;             const char* a3 = a2 + kstep; const char* b3 = b2 + kstep;
;             PG8_LDB(B0, 0, 0); PG8_SCHED; PG8_LDA(At, 0, 0); PG8_STAGE(PG8_SA(1, 1), a1 + hstepA, voffA);
;             PG8_WAIT_L(8); PG8_BAR; PG8_WAIT_L(0); PG8_MMA(0, 0, At, B0); PG8_BAR; PG8_SCHED;
;             PG8_LDB(B1, 0, 1); PG8_STAGE(PG8_SB(0, 0), b2, voffB);
;             PG8_BAR; PG8_WAIT_L(0); PG8_MMA(0, 1, At, B1); PG8_BAR;
;             PG8_LDA(At, 0, 1); PG8_STAGE(PG8_SA(0, 0), a2, voffA);
;             PG8_BAR; PG8_WAIT_L(0); PG8_MMA(1, 0, At, B0); PG8_BAR; PG8_SCHED;
.LBB0_738:
	s_add_u32 s23, s48, 0xfff80080
	s_addc_u32 s50, s49, -1
	s_add_i32 s67, 0, 0x10000
	v_add_u32_e32 v142, s67, v162
	ds_read_b128 v[130:133], v142
	ds_read_b128 v[134:137], v142 offset:1024
	ds_read_b128 v[138:141], v142 offset:2048
	ds_read_b128 v[142:145], v142 offset:3072
	s_cmp_eq_u32 s66, 28
	s_cselect_b32 s53, s35, s50
	s_cselect_b32 s52, s59, s23
	s_cselect_b32 s51, s21, s71
	s_cselect_b32 s50, s68, s70
	v_lshl_add_u64 v[198:199], s[48:49], 0, v[178:179]
	s_add_i32 m0, s26, 0xc000
	ds_read_b128 v[146:149], v210
	ds_read_b128 v[150:153], v210 offset:1024
	ds_read_b128 v[182:185], v210 offset:2048
	ds_read_b128 v[186:189], v210 offset:3072
	ds_read_b128 v[190:193], v210 offset:4096
	ds_read_b128 v[194:197], v210 offset:5120
	ds_read_b128 v[212:215], v210 offset:6144
	ds_read_b128 v[216:219], v210 offset:7168
	global_load_lds_dwordx4 v[198:199], off
	v_lshl_add_u64 v[198:199], s[48:49], 0, v[180:181]
	s_add_i32 m0, s26, 0xe000
	s_nop 0
	global_load_lds_dwordx4 v[198:199], off
	s_waitcnt lgkmcnt(8)
	s_barrier
	s_waitcnt lgkmcnt(0)
	v_mfma_f32_16x16x32_bf16 v[126:129], v[130:133], v[146:149], v[126:129]
	v_mfma_f32_16x16x32_bf16 v[122:125], v[138:141], v[146:149], v[122:125]
	v_mfma_f32_16x16x32_bf16 v[110:113], v[130:133], v[182:185], v[110:113]
	v_mfma_f32_16x16x32_bf16 v[106:109], v[138:141], v[182:185], v[106:109]
	v_mfma_f32_16x16x32_bf16 v[94:97], v[130:133], v[190:193], v[94:97]
	v_mfma_f32_16x16x32_bf16 v[90:93], v[138:141], v[190:193], v[90:93]
	v_mfma_f32_16x16x32_bf16 v[78:81], v[130:133], v[212:215], v[78:81]
	v_mfma_f32_16x16x32_bf16 v[74:77], v[138:141], v[212:215], v[74:77]
	v_mfma_f32_16x16x32_bf16 v[126:129], v[134:137], v[150:153], v[126:129]
	v_mfma_f32_16x16x32_bf16 v[122:125], v[142:145], v[150:153], v[122:125]
	v_mfma_f32_16x16x32_bf16 v[110:113], v[134:137], v[186:189], v[110:113]
	v_mfma_f32_16x16x32_bf16 v[106:109], v[142:145], v[186:189], v[106:109]
	v_mfma_f32_16x16x32_bf16 v[94:97], v[134:137], v[194:197], v[94:97]
	v_mfma_f32_16x16x32_bf16 v[90:93], v[142:145], v[194:197], v[90:93]
	v_mfma_f32_16x16x32_bf16 v[78:81], v[134:137], v[216:219], v[78:81]
	v_mfma_f32_16x16x32_bf16 v[74:77], v[142:145], v[216:219], v[74:77]
	s_barrier
	s_add_i32 s23, 0, 0x14000
	v_add_u32_e32 v198, s23, v162
	s_add_i32 s67, s67, s25
	ds_read_b128 v[220:223], v198
	ds_read_b128 v[224:227], v198 offset:1024
	ds_read_b128 v[228:231], v198 offset:2048
	ds_read_b128 v[232:235], v198 offset:3072
	v_lshl_add_u64 v[198:199], s[50:51], 0, v[174:175]
	s_mov_b32 m0, s67
	v_lshl_add_u64 v[236:237], s[50:51], 0, v[170:171]
	global_load_lds_dwordx4 v[198:199], off
	s_add_i32 m0, s67, 0x2000
	s_nop 0
	global_load_lds_dwordx4 v[236:237], off
	s_barrier
	s_waitcnt lgkmcnt(0)
	v_mfma_f32_16x16x32_bf16 v[118:121], v[220:223], v[146:149], v[118:121]
	v_mfma_f32_16x16x32_bf16 v[114:117], v[228:231], v[146:149], v[114:117]
	v_mfma_f32_16x16x32_bf16 v[102:105], v[220:223], v[182:185], v[102:105]
	v_mfma_f32_16x16x32_bf16 v[98:101], v[228:231], v[182:185], v[98:101]
	v_mfma_f32_16x16x32_bf16 v[86:89], v[220:223], v[190:193], v[86:89]
	v_mfma_f32_16x16x32_bf16 v[82:85], v[228:231], v[190:193], v[82:85]
	v_mfma_f32_16x16x32_bf16 v[70:73], v[220:223], v[212:215], v[70:73]
	v_mfma_f32_16x16x32_bf16 v[66:69], v[228:231], v[212:215], v[66:69]
	v_mfma_f32_16x16x32_bf16 v[118:121], v[224:227], v[150:153], v[118:121]
	v_mfma_f32_16x16x32_bf16 v[114:117], v[232:235], v[150:153], v[114:117]
	v_mfma_f32_16x16x32_bf16 v[102:105], v[224:227], v[186:189], v[102:105]
	v_mfma_f32_16x16x32_bf16 v[98:101], v[232:235], v[186:189], v[98:101]
	v_mfma_f32_16x16x32_bf16 v[86:89], v[224:227], v[194:197], v[86:89]
	v_mfma_f32_16x16x32_bf16 v[82:85], v[232:235], v[194:197], v[82:85]
	v_mfma_f32_16x16x32_bf16 v[70:73], v[224:227], v[216:219], v[70:73]
	v_mfma_f32_16x16x32_bf16 v[66:69], v[232:235], v[216:219], v[66:69]
	s_mov_b32 m0, s26
	v_lshl_add_u64 v[238:239], s[52:53], 0, v[176:177]
	s_barrier
	ds_read_b128 v[146:149], v210 offset:16384
	ds_read_b128 v[150:153], v210 offset:17408
	ds_read_b128 v[182:185], v210 offset:18432
	ds_read_b128 v[186:189], v210 offset:19456
	ds_read_b128 v[190:193], v210 offset:20480
	ds_read_b128 v[194:197], v210 offset:21504
	ds_read_b128 v[212:215], v210 offset:22528
	ds_read_b128 v[216:219], v210 offset:23552
	global_load_lds_dwordx4 v[238:239], off
	v_lshl_add_u64 v[240:241], s[52:53], 0, v[172:173]
	s_mov_b32 m0, s27
	s_nop 0
	global_load_lds_dwordx4 v[240:241], off
	s_barrier
	s_waitcnt lgkmcnt(0)
	v_mfma_f32_16x16x32_bf16 v[62:65], v[130:133], v[146:149], v[62:65]
	v_mfma_f32_16x16x32_bf16 v[58:61], v[138:141], v[146:149], v[58:61]
	v_mfma_f32_16x16x32_bf16 v[46:49], v[130:133], v[182:185], v[46:49]
	v_mfma_f32_16x16x32_bf16 v[42:45], v[138:141], v[182:185], v[42:45]
	v_mfma_f32_16x16x32_bf16 v[30:33], v[130:133], v[190:193], v[30:33]
	v_mfma_f32_16x16x32_bf16 v[26:29], v[138:141], v[190:193], v[26:29]
	v_mfma_f32_16x16x32_bf16 v[14:17], v[130:133], v[212:215], v[14:17]
	v_mfma_f32_16x16x32_bf16 v[10:13], v[138:141], v[212:215], v[10:13]
	v_mfma_f32_16x16x32_bf16 v[62:65], v[134:137], v[150:153], v[62:65]
	v_mfma_f32_16x16x32_bf16 v[58:61], v[142:145], v[150:153], v[58:61]
	v_mfma_f32_16x16x32_bf16 v[46:49], v[134:137], v[186:189], v[46:49]
	v_mfma_f32_16x16x32_bf16 v[42:45], v[142:145], v[186:189], v[42:45]
	v_mfma_f32_16x16x32_bf16 v[30:33], v[134:137], v[194:197], v[30:33]
	v_mfma_f32_16x16x32_bf16 v[26:29], v[142:145], v[194:197], v[26:29]
	v_mfma_f32_16x16x32_bf16 v[14:17], v[134:137], v[216:219], v[14:17]
	v_mfma_f32_16x16x32_bf16 v[10:13], v[142:145], v[216:219], v[10:13]
	s_barrier
; #define PG8_STAGE(bufoff, gbase, voff) do { _Pragma("unroll") for (int _i = 0; _i < 2; ++_i) \
;         __builtin_amdgcn_global_load_lds((const unsigned*)((const char*)(gbase) + (voff)[_i]), (LAS unsigned*)(lds + (bufoff) + ldsw + _i * 8192), 16, 0, 0); } while (0)
; #define PG8_LDA(dst, b, h) do { _Pragma("unroll") for (int m = 0; m < 4; ++m) _Pragma("unroll") for (int k = 0; k < 2; ++k) dst[m][k] = *(const LAS bf16x8*)(lds + PG8_SA(b, h) + aoff + m * 2048 + k * 1024); } while (0)
; #define PG8_LDB(dst, b, h) do { _Pragma("unroll") for (int n = 0; n < 2; ++n) _Pragma("unroll") for (int k = 0; k < 2; ++k) dst[n][k] = *(const LAS bf16x8*)(lds + PG8_SB(b, h) + boff + n * 2048 + k * 1024); } while (0)
; #define PG8_MMA(ai, bj, At, Bt) do { __builtin_amdgcn_s_setprio(1); _Pragma("unroll") for (int m = 0; m < 4; ++m) _Pragma("unroll") for (int n = 0; n < 2; ++n) _Pragma("unroll") for (int k = 0; k < 2; ++k) \
;         acc[ai][bj][m][n] = __builtin_amdgcn_mfma_f32_16x16x32_bf16(Bt[n][k], At[m][k], acc[ai][bj][m][n], 0, 0, 0); __builtin_amdgcn_s_setprio(0); } while (0)
; #define PG8_WAIT_V(n) asm volatile("s_waitcnt vmcnt(" #n ")" ::: "memory")
; #define PG8_WAIT_L(n) asm volatile("s_waitcnt lgkmcnt(" #n ")" ::: "memory")
; #define PG8_BAR __builtin_amdgcn_s_barrier()
; #define PG8_SCHED __builtin_amdgcn_sched_barrier(0)
; template <class Epi, class Sched>
; __device__ __forceinline__ void gemm_phase(LAS unsigned char* lds, const Gemm g, const Sched& S, const Epi& E) {
;     ...
;             PG8_STAGE(PG8_SB(0, 1), b2 + hstepB, voffB);
;             PG8_WAIT_V(6); PG8_BAR; PG8_MMA(1, 1, At, B1); PG8_BAR;
;             PG8_LDB(B0, 1, 0); PG8_SCHED; PG8_LDA(At, 1, 0); PG8_STAGE(PG8_SA(0, 1), a2 + hstepA, voffA);
;             PG8_WAIT_L(8); PG8_BAR; PG8_WAIT_L(0); PG8_MMA(0, 0, At, B0); PG8_BAR; PG8_SCHED;
;             PG8_LDB(B1, 1, 1); PG8_STAGE(PG8_SB(1, 0), b3, voffB);
;             PG8_BAR; PG8_WAIT_L(0); PG8_MMA(0, 1, At, B1); PG8_BAR;
;             PG8_LDA(At, 1, 1); PG8_STAGE(PG8_SA(1, 0), a3, voffA);
	s_add_u32 s84, s50, 0x80000
	s_addc_u32 s85, s51, 0
	s_add_i32 s23, s23, s25
	v_lshl_add_u64 v[130:131], s[84:85], 0, v[174:175]
	s_mov_b32 m0, s23
	s_nop 0
	global_load_lds_dwordx4 v[130:131], off
	v_lshl_add_u64 v[130:131], s[84:85], 0, v[170:171]
	s_add_i32 m0, s23, 0x2000
	s_nop 0
	global_load_lds_dwordx4 v[130:131], off
	s_waitcnt vmcnt(6)
	s_barrier
	v_mfma_f32_16x16x32_bf16 v[54:57], v[220:223], v[146:149], v[54:57]
	v_mfma_f32_16x16x32_bf16 v[50:53], v[228:231], v[146:149], v[50:53]
	v_mfma_f32_16x16x32_bf16 v[38:41], v[220:223], v[182:185], v[38:41]
	v_mfma_f32_16x16x32_bf16 v[34:37], v[228:231], v[182:185], v[34:37]
	v_mfma_f32_16x16x32_bf16 v[22:25], v[220:223], v[190:193], v[22:25]
	v_mfma_f32_16x16x32_bf16 v[18:21], v[228:231], v[190:193], v[18:21]
	v_mfma_f32_16x16x32_bf16 v[6:9], v[220:223], v[212:215], v[6:9]
	v_mfma_f32_16x16x32_bf16 v[2:5], v[228:231], v[212:215], v[2:5]
	v_mfma_f32_16x16x32_bf16 v[54:57], v[224:227], v[150:153], v[54:57]
	v_mfma_f32_16x16x32_bf16 v[50:53], v[232:235], v[150:153], v[50:53]
	v_mfma_f32_16x16x32_bf16 v[38:41], v[224:227], v[186:189], v[38:41]
	v_mfma_f32_16x16x32_bf16 v[34:37], v[232:235], v[186:189], v[34:37]
	v_mfma_f32_16x16x32_bf16 v[22:25], v[224:227], v[194:197], v[22:25]
	v_mfma_f32_16x16x32_bf16 v[18:21], v[232:235], v[194:197], v[18:21]
	v_mfma_f32_16x16x32_bf16 v[6:9], v[224:227], v[216:219], v[6:9]
	v_mfma_f32_16x16x32_bf16 v[2:5], v[232:235], v[216:219], v[2:5]
	s_add_i32 s23, 0, 0x18000
	v_add_u32_e32 v142, s23, v162
	s_barrier
	ds_read_b128 v[130:133], v142
	ds_read_b128 v[134:137], v142 offset:1024
	ds_read_b128 v[138:141], v142 offset:2048
	ds_read_b128 v[142:145], v142 offset:3072
	s_add_u32 s52, s52, 0x80000
	s_addc_u32 s53, s53, 0
	s_mov_b32 m0, s31
	v_lshl_add_u64 v[220:221], s[52:53], 0, v[176:177]
	ds_read_b128 v[146:149], v210 offset:32768
	ds_read_b128 v[150:153], v210 offset:33792
	ds_read_b128 v[182:185], v210 offset:34816
	ds_read_b128 v[186:189], v210 offset:35840
	ds_read_b128 v[190:193], v210 offset:36864
	ds_read_b128 v[194:197], v210 offset:37888
	ds_read_b128 v[212:215], v210 offset:38912
	ds_read_b128 v[216:219], v210 offset:39936
	global_load_lds_dwordx4 v[220:221], off
	v_lshl_add_u64 v[220:221], s[52:53], 0, v[172:173]
	s_mov_b32 m0, s54
	s_nop 0
	global_load_lds_dwordx4 v[220:221], off
	s_waitcnt lgkmcnt(8)
	s_barrier
	s_waitcnt lgkmcnt(0)
	v_mfma_f32_16x16x32_bf16 v[126:129], v[130:133], v[146:149], v[126:129]
	v_mfma_f32_16x16x32_bf16 v[122:125], v[138:141], v[146:149], v[122:125]
	v_mfma_f32_16x16x32_bf16 v[110:113], v[130:133], v[182:185], v[110:113]
	v_mfma_f32_16x16x32_bf16 v[106:109], v[138:141], v[182:185], v[106:109]
	v_mfma_f32_16x16x32_bf16 v[94:97], v[130:133], v[190:193], v[94:97]
	v_mfma_f32_16x16x32_bf16 v[90:93], v[138:141], v[190:193], v[90:93]
	v_mfma_f32_16x16x32_bf16 v[78:81], v[130:133], v[212:215], v[78:81]
	v_mfma_f32_16x16x32_bf16 v[74:77], v[138:141], v[212:215], v[74:77]
	v_mfma_f32_16x16x32_bf16 v[126:129], v[134:137], v[150:153], v[126:129]
	v_mfma_f32_16x16x32_bf16 v[122:125], v[142:145], v[150:153], v[122:125]
	v_mfma_f32_16x16x32_bf16 v[110:113], v[134:137], v[186:189], v[110:113]
	v_mfma_f32_16x16x32_bf16 v[106:109], v[142:145], v[186:189], v[106:109]
	v_mfma_f32_16x16x32_bf16 v[94:97], v[134:137], v[194:197], v[94:97]
	v_mfma_f32_16x16x32_bf16 v[90:93], v[142:145], v[194:197], v[90:93]
	v_mfma_f32_16x16x32_bf16 v[78:81], v[134:137], v[216:219], v[78:81]
	v_mfma_f32_16x16x32_bf16 v[74:77], v[142:145], v[216:219], v[74:77]
	s_barrier
	s_add_i32 s52, 0, 0x1c000
	s_add_i32 s23, s23, s25
	v_add_u32_e32 v211, s52, v162
	v_lshl_add_u64 v[198:199], v[198:199], 0, s[10:11]
	s_mov_b32 m0, s23
	ds_read_b128 v[220:223], v211
	ds_read_b128 v[224:227], v211 offset:1024
	ds_read_b128 v[228:231], v211 offset:2048
	ds_read_b128 v[232:235], v211 offset:3072
	global_load_lds_dwordx4 v[198:199], off
	v_lshl_add_u64 v[198:199], v[236:237], 0, s[10:11]
	s_add_i32 m0, s23, 0x2000
	s_nop 0
	global_load_lds_dwordx4 v[198:199], off
	s_barrier
	s_waitcnt lgkmcnt(0)
	v_mfma_f32_16x16x32_bf16 v[118:121], v[220:223], v[146:149], v[118:121]
	v_mfma_f32_16x16x32_bf16 v[114:117], v[228:231], v[146:149], v[114:117]
	v_mfma_f32_16x16x32_bf16 v[102:105], v[220:223], v[182:185], v[102:105]
	v_mfma_f32_16x16x32_bf16 v[98:101], v[228:231], v[182:185], v[98:101]
	v_mfma_f32_16x16x32_bf16 v[86:89], v[220:223], v[190:193], v[86:89]
	v_mfma_f32_16x16x32_bf16 v[82:85], v[228:231], v[190:193], v[82:85]
	v_mfma_f32_16x16x32_bf16 v[70:73], v[220:223], v[212:215], v[70:73]
	v_mfma_f32_16x16x32_bf16 v[66:69], v[228:231], v[212:215], v[66:69]
	v_mfma_f32_16x16x32_bf16 v[118:121], v[224:227], v[150:153], v[118:121]
	v_mfma_f32_16x16x32_bf16 v[114:117], v[232:235], v[150:153], v[114:117]
	v_mfma_f32_16x16x32_bf16 v[102:105], v[224:227], v[186:189], v[102:105]
	v_mfma_f32_16x16x32_bf16 v[98:101], v[232:235], v[186:189], v[98:101]
	v_mfma_f32_16x16x32_bf16 v[86:89], v[224:227], v[194:197], v[86:89]
	v_mfma_f32_16x16x32_bf16 v[82:85], v[232:235], v[194:197], v[82:85]
	v_mfma_f32_16x16x32_bf16 v[70:73], v[224:227], v[216:219], v[70:73]
	v_mfma_f32_16x16x32_bf16 v[66:69], v[232:235], v[216:219], v[66:69]
	s_mov_b32 m0, s28
	v_lshl_add_u64 v[198:199], v[238:239], 0, s[10:11]
	s_barrier
	ds_read_b128 v[146:149], v210 offset:49152
	ds_read_b128 v[150:153], v210 offset:50176
	ds_read_b128 v[182:185], v210 offset:51200
	ds_read_b128 v[186:189], v210 offset:52224
	ds_read_b128 v[190:193], v210 offset:53248
	ds_read_b128 v[194:197], v210 offset:54272
	ds_read_b128 v[212:215], v210 offset:55296
	ds_read_b128 v[216:219], v210 offset:56320
	global_load_lds_dwordx4 v[198:199], off
	v_lshl_add_u64 v[198:199], v[240:241], 0, s[10:11]
	s_mov_b32 m0, s29
	s_nop 0
	global_load_lds_dwordx4 v[198:199], off
	s_barrier
; #define PG8_STAGE(bufoff, gbase, voff) do { _Pragma("unroll") for (int _i = 0; _i < 2; ++_i) \
;         __builtin_amdgcn_global_load_lds((const unsigned*)((const char*)(gbase) + (voff)[_i]), (LAS unsigned*)(lds + (bufoff) + ldsw + _i * 8192), 16, 0, 0); } while (0)
; #define PG8_MMA(ai, bj, At, Bt) do { __builtin_amdgcn_s_setprio(1); _Pragma("unroll") for (int m = 0; m < 4; ++m) _Pragma("unroll") for (int n = 0; n < 2; ++n) _Pragma("unroll") for (int k = 0; k < 2; ++k) \
;         acc[ai][bj][m][n] = __builtin_amdgcn_mfma_f32_16x16x32_bf16(Bt[n][k], At[m][k], acc[ai][bj][m][n], 0, 0, 0); __builtin_amdgcn_s_setprio(0); } while (0)
; #define PG8_WAIT_V(n) asm volatile("s_waitcnt vmcnt(" #n ")" ::: "memory")
; #define PG8_WAIT_L(n) asm volatile("s_waitcnt lgkmcnt(" #n ")" ::: "memory")
; #define PG8_BAR __builtin_amdgcn_s_barrier()
; #define PG8_SCHED __builtin_amdgcn_sched_barrier(0)
; template <class Epi, class Sched>
; __device__ __forceinline__ void gemm_phase(LAS unsigned char* lds, const Gemm g, const Sched& S, const Epi& E) {
;     ...
;             PG8_BAR; PG8_WAIT_L(0); PG8_MMA(1, 0, At, B0); PG8_BAR; PG8_SCHED;
;             PG8_STAGE(PG8_SB(1, 1), b3 + hstepB, voffB);
;             PG8_WAIT_V(6); PG8_BAR; PG8_MMA(1, 1, At, B1); PG8_BAR;
;         }
	s_waitcnt lgkmcnt(0)
	v_mfma_f32_16x16x32_bf16 v[62:65], v[130:133], v[146:149], v[62:65]
	v_mfma_f32_16x16x32_bf16 v[58:61], v[138:141], v[146:149], v[58:61]
	v_mfma_f32_16x16x32_bf16 v[46:49], v[130:133], v[182:185], v[46:49]
	v_mfma_f32_16x16x32_bf16 v[42:45], v[138:141], v[182:185], v[42:45]
	v_mfma_f32_16x16x32_bf16 v[30:33], v[130:133], v[190:193], v[30:33]
	v_mfma_f32_16x16x32_bf16 v[26:29], v[138:141], v[190:193], v[26:29]
	v_mfma_f32_16x16x32_bf16 v[14:17], v[130:133], v[212:215], v[14:17]
	v_mfma_f32_16x16x32_bf16 v[10:13], v[138:141], v[212:215], v[10:13]
	v_mfma_f32_16x16x32_bf16 v[62:65], v[134:137], v[150:153], v[62:65]
	v_mfma_f32_16x16x32_bf16 v[58:61], v[142:145], v[150:153], v[58:61]
	v_mfma_f32_16x16x32_bf16 v[46:49], v[134:137], v[186:189], v[46:49]
	v_mfma_f32_16x16x32_bf16 v[42:45], v[142:145], v[186:189], v[42:45]
	v_mfma_f32_16x16x32_bf16 v[30:33], v[134:137], v[194:197], v[30:33]
	v_mfma_f32_16x16x32_bf16 v[26:29], v[142:145], v[194:197], v[26:29]
	v_mfma_f32_16x16x32_bf16 v[14:17], v[134:137], v[216:219], v[14:17]
	v_mfma_f32_16x16x32_bf16 v[10:13], v[142:145], v[216:219], v[10:13]
	s_barrier
	s_add_u32 s50, s50, 0x80080
	s_addc_u32 s51, s51, 0
	s_add_i32 s23, s52, s25
	v_lshl_add_u64 v[130:131], s[50:51], 0, v[174:175]
	s_mov_b32 m0, s23
	s_nop 0
	global_load_lds_dwordx4 v[130:131], off
	v_lshl_add_u64 v[130:131], s[50:51], 0, v[170:171]
	s_add_i32 m0, s23, 0x2000
	s_nop 0
	global_load_lds_dwordx4 v[130:131], off
	s_waitcnt vmcnt(6)
	s_barrier
	v_mfma_f32_16x16x32_bf16 v[54:57], v[220:223], v[146:149], v[54:57]
	v_mfma_f32_16x16x32_bf16 v[50:53], v[228:231], v[146:149], v[50:53]
	v_mfma_f32_16x16x32_bf16 v[38:41], v[220:223], v[182:185], v[38:41]
	v_mfma_f32_16x16x32_bf16 v[34:37], v[228:231], v[182:185], v[34:37]
	v_mfma_f32_16x16x32_bf16 v[22:25], v[220:223], v[190:193], v[22:25]
	v_mfma_f32_16x16x32_bf16 v[18:21], v[228:231], v[190:193], v[18:21]
	v_mfma_f32_16x16x32_bf16 v[6:9], v[220:223], v[212:215], v[6:9]
	v_mfma_f32_16x16x32_bf16 v[2:5], v[228:231], v[212:215], v[2:5]
	v_mfma_f32_16x16x32_bf16 v[54:57], v[224:227], v[150:153], v[54:57]
	v_mfma_f32_16x16x32_bf16 v[50:53], v[232:235], v[150:153], v[50:53]
	v_mfma_f32_16x16x32_bf16 v[38:41], v[224:227], v[186:189], v[38:41]
	v_mfma_f32_16x16x32_bf16 v[34:37], v[232:235], v[186:189], v[34:37]
	v_mfma_f32_16x16x32_bf16 v[22:25], v[224:227], v[194:197], v[22:25]
	v_mfma_f32_16x16x32_bf16 v[18:21], v[232:235], v[194:197], v[18:21]
	v_mfma_f32_16x16x32_bf16 v[6:9], v[224:227], v[216:219], v[6:9]
	v_mfma_f32_16x16x32_bf16 v[2:5], v[232:235], v[216:219], v[2:5]
	s_add_i32 s66, s66, 2
	s_add_u32 s48, s48, 0x100
	s_addc_u32 s49, s49, 0
	s_add_u32 s70, s70, 0x100
	s_addc_u32 s71, s71, 0
	s_cmp_gt_u32 s66, 29
	s_barrier
	s_cbranch_scc0 .LBB0_738
; __device__ __forceinline__ unsigned cvt_pk_bf16(float lo, float hi) { unsigned r; asm volatile("v_cvt_pk_bf16_f32 %0, %1, %2" : "=v"(r) : "v"(lo), "v"(hi)); return r; }
; __device__ __forceinline__ float bf_lo(unsigned w) { return __uint_as_float(w << 16); }
; __device__ __forceinline__ float bf_hi(unsigned w) { return __uint_as_float(w & 0xffff0000u); }
;     __device__ __forceinline__ void operator()(const f32x4 (&acc)[2][2][4][2], const Unit& u, int ui, const LAS float* rtab, int wr, int wc, int fr, int fq) const {
;         const int row0 = u.pm * BM + wr * 64 + fr, col0 = u.pn * BM + wc * 32 + 8 * fq;
; #pragma unroll
;         for (int ai = 0; ai < 2; ++ai) {
;             u32x4 xv[4][2];
; #pragma unroll
;             for (int m = 0; m < 4; ++m)
; #pragma unroll
;                 for (int bj = 0; bj < 2; ++bj) xv[m][bj] = *(const u32x4*)(XB + (size_t)(row0 + ai * HALF + m * 16) * DM + col0 + bj * HALF);
; #pragma unroll
;             for (int m = 0; m < 4; ++m) { const int row = row0 + ai * HALF + m * 16; float ss = 0.f;
; #pragma unroll
;                 for (int bj = 0; bj < 2; ++bj) {
;                     const f32x4 a0 = acc[ai][bj][m][0], a1 = acc[ai][bj][m][1]; const u32x4 xo = xv[m][bj]; u32x4 w;
;                     w.x = cvt_pk_bf16(bf_lo(xo.x) + a0[0], bf_hi(xo.x) + a0[1]); w.y = cvt_pk_bf16(bf_lo(xo.y) + a0[2], bf_hi(xo.y) + a0[3]);
;                     w.z = cvt_pk_bf16(bf_lo(xo.z) + a1[0], bf_hi(xo.z) + a1[1]); w.w = cvt_pk_bf16(bf_lo(xo.w) + a1[2], bf_hi(xo.w) + a1[3]);
;                     *(u32x4*)(XB + (size_t)row * DM + col0 + bj * HALF) = w;
; #pragma unroll
;                     for (int e = 0; e < 4; ++e) { const float lo = bf_lo(w[e]), hi = bf_hi(w[e]); ss += lo * lo + hi * hi; }
;                 }
;                 ss += __shfl_xor(ss, 16); ss += __shfl_xor(ss, 32);
;                 if (fq == 0) ssq_next[(size_t)row * 32 + (u.pn & 7) * 4 + wc] = ss; }
	v_lshl_or_b32 v182, s57, 8, v209
	v_lshl_add_u32 v186, s58, 8, v1
	v_ashrrev_i32_e32 v183, 31, v182
	v_lshlrev_b64 v[130:131], 1, v[182:183]
	v_ashrrev_i32_e32 v187, 31, v186
	v_lshl_add_u64 v[184:185], s[74:75], 0, v[130:131]
	v_lshlrev_b64 v[132:133], 12, v[186:187]
	v_lshl_add_u64 v[134:135], v[184:185], 0, v[132:133]
	global_load_dwordx4 v[212:215], v[134:135], off
	global_load_dwordx4 v[216:219], v[134:135], off offset:256
	v_or_b32_e32 v196, 16, v186
	v_or_b32_e32 v192, 32, v186
	v_or_b32_e32 v188, 48, v186
	v_ashrrev_i32_e32 v197, 31, v196
	v_ashrrev_i32_e32 v193, 31, v192
	v_ashrrev_i32_e32 v189, 31, v188
	v_lshlrev_b64 v[198:199], 12, v[196:197]
	v_lshlrev_b64 v[194:195], 12, v[192:193]
	v_lshlrev_b64 v[190:191], 12, v[188:189]
	v_lshl_add_u64 v[132:133], s[74:75], 0, v[132:133]
	v_lshl_add_u64 v[134:135], v[184:185], 0, v[198:199]
	v_lshl_add_u64 v[136:137], v[184:185], 0, v[194:195]
	v_lshl_add_u64 v[220:221], v[184:185], 0, v[190:191]
	v_lshl_add_u64 v[222:223], v[132:133], 0, v[130:131]
	global_load_dwordx4 v[150:153], v[134:135], off
	global_load_dwordx4 v[146:149], v[134:135], off offset:256
	global_load_dwordx4 v[142:145], v[136:137], off
	global_load_dwordx4 v[138:141], v[136:137], off offset:256
	s_nop 0
	global_load_dwordx4 v[134:137], v[220:221], off
	global_load_dwordx4 v[130:133], v[220:221], off offset:256
	s_lshl_b32 s21, s57, 2
	s_and_b32 s21, s21, 28
	s_waitcnt vmcnt(0)
	v_lshlrev_b32_e32 v211, 16, v212
	v_and_b32_e32 v212, 0xffff0000, v212
	v_lshlrev_b32_e32 v220, 16, v213
	v_and_b32_e32 v213, 0xffff0000, v213
	v_lshlrev_b32_e32 v221, 16, v214
	v_and_b32_e32 v214, 0xffff0000, v214
	v_lshlrev_b32_e32 v227, 16, v218
	v_and_b32_e32 v218, 0xffff0000, v218
	v_lshlrev_b32_e32 v224, 16, v215
	v_and_b32_e32 v215, 0xffff0000, v215
	v_lshlrev_b32_e32 v228, 16, v219
	v_and_b32_e32 v219, 0xffff0000, v219
	v_add_f32_e32 v126, v126, v211
	v_add_f32_e32 v127, v127, v212
	v_add_f32_e32 v128, v128, v220
	v_add_f32_e32 v129, v129, v213
	v_add_f32_e32 v122, v122, v221
	v_add_f32_e32 v123, v123, v214
	v_add_f32_e32 v211, v114, v227
	v_add_f32_e32 v212, v115, v218
	v_cvt_pk_bf16_f32 v114, v126, v127
	v_cvt_pk_bf16_f32 v115, v128, v129
	v_add_f32_e32 v124, v124, v224
	v_add_f32_e32 v125, v125, v215
	v_add_f32_e32 v213, v116, v228
	v_add_f32_e32 v214, v117, v219
	v_cvt_pk_bf16_f32 v116, v122, v123
	v_cvt_pk_bf16_f32 v117, v124, v125
	global_store_dwordx4 v[222:223], v[114:117], off
	v_lshlrev_b32_e32 v122, 16, v114
	v_lshlrev_b32_e32 v123, 16, v115
	v_and_b32_e32 v114, 0xffff0000, v114
	v_and_b32_e32 v115, 0xffff0000, v115
	v_lshlrev_b32_e32 v225, 16, v216
	v_lshlrev_b32_e32 v124, 16, v116
	v_and_b32_e32 v116, 0xffff0000, v116
	v_mul_f32_e32 v114, v114, v114
	v_mul_f32_e32 v115, v115, v115
	v_and_b32_e32 v216, 0xffff0000, v216
	v_add_f32_e32 v118, v118, v225
	v_lshlrev_b32_e32 v125, 16, v117
	v_and_b32_e32 v117, 0xffff0000, v117
	v_mul_f32_e32 v116, v116, v116
	v_fmac_f32_e32 v114, v122, v122
	v_fmac_f32_e32 v115, v123, v123
	v_lshlrev_b32_e32 v226, 16, v217
	v_and_b32_e32 v217, 0xffff0000, v217
	v_add_f32_e32 v119, v119, v216
	v_cvt_pk_bf16_f32 v118, v118, v119
	v_mul_f32_e32 v117, v117, v117
	v_and_b32_e32 v127, 0xffff0000, v118
	v_fmac_f32_e32 v116, v124, v124
	v_add_f32_e32 v114, v114, v115
	v_add_f32_e32 v120, v120, v226
	v_add_f32_e32 v121, v121, v217
	v_cvt_pk_bf16_f32 v119, v120, v121
	v_lshlrev_b32_e32 v126, 16, v118
	v_fmac_f32_e32 v117, v125, v125
	v_mul_f32_e32 v122, v127, v127
	v_add_f32_e32 v114, v114, v116
	v_and_b32_e32 v116, 0xffff0000, v119
	v_fmac_f32_e32 v122, v126, v126
	v_add_f32_e32 v114, v114, v117
	v_lshlrev_b32_e32 v115, 16, v119
	v_mul_f32_e32 v116, v116, v116
	v_add_f32_e32 v114, v114, v122
	v_fmac_f32_e32 v116, v115, v115
	v_cvt_pk_bf16_f32 v120, v211, v212
	v_add_f32_e32 v114, v114, v116
	v_and_b32_e32 v116, 0xffff0000, v120
	v_lshlrev_b32_e32 v115, 16, v120
	v_mul_f32_e32 v116, v116, v116
	v_fmac_f32_e32 v116, v115, v115
	v_cvt_pk_bf16_f32 v121, v213, v214
	v_add_f32_e32 v114, v114, v116
	v_and_b32_e32 v116, 0xffff0000, v121
	v_lshlrev_b32_e32 v115, 16, v121
	v_mul_f32_e32 v116, v116, v116
	v_fmac_f32_e32 v116, v115, v115
	v_add_f32_e32 v115, v114, v116
	v_and_b32_e32 v116, 64, v207
	v_xor_b32_e32 v114, 16, v207
	v_add_u32_e32 v117, 64, v116
	v_cmp_lt_i32_e32 vcc, v114, v117
	global_store_dwordx4 v[222:223], v[118:121], off offset:256
	s_nop 0
	v_cndmask_b32_e32 v114, v207, v114, vcc
	v_lshlrev_b32_e32 v114, 2, v114
	ds_bpermute_b32 v116, v114, v115
	s_waitcnt lgkmcnt(0)
	v_add_f32_e32 v116, v115, v116
	v_xor_b32_e32 v115, 32, v207
	v_cmp_lt_i32_e32 vcc, v115, v117
	s_nop 1
	v_cndmask_b32_e32 v115, v207, v115, vcc
	v_lshlrev_b32_e32 v115, 2, v115
	ds_bpermute_b32 v117, v115, v116
	s_and_saveexec_b64 s[48:49], s[42:43]
	s_cbranch_execz .LBB0_741
	s_waitcnt lgkmcnt(0)
	v_add_f32_e32 v118, v116, v117
	v_lshlrev_b64 v[116:117], 7, v[186:187]
	v_lshl_add_u64 v[116:117], s[0:1], 0, v[116:117]
	s_lshl_b32 s68, s21, 2
	v_lshl_add_u64 v[116:117], v[116:117], 0, s[68:69]
	s_lshl_b32 s68, s55, 2
	v_lshl_add_u64 v[116:117], v[116:117], 0, s[68:69]
	global_store_dword v[116:117], v118, off

; #define PG8_STAGE(bufoff, gbase, voff) do { _Pragma("unroll") for (int _i = 0; _i < 2; ++_i) \
;         __builtin_amdgcn_global_load_lds((const unsigned*)((const char*)(gbase) + (voff)[_i]), (LAS unsigned*)(lds + (bufoff) + ldsw + _i * 8192), 16, 0, 0); } while (0)
; #define PG8_LDA(dst, b, h) do { _Pragma("unroll") for (int m = 0; m < 4; ++m) _Pragma("unroll") for (int k = 0; k < 2; ++k) dst[m][k] = *(const LAS bf16x8*)(lds + PG8_SA(b, h) + aoff + m * 2048 + k * 1024); } while (0)
; #define PG8_LDB(dst, b, h) do { _Pragma("unroll") for (int n = 0; n < 2; ++n) _Pragma("unroll") for (int k = 0; k < 2; ++k) dst[n][k] = *(const LAS bf16x8*)(lds + PG8_SB(b, h) + boff + n * 2048 + k * 1024); } while (0)
; #define PG8_MMA(ai, bj, At, Bt) do { __builtin_amdgcn_s_setprio(1); _Pragma("unroll") for (int m = 0; m < 4; ++m) _Pragma("unroll") for (int n = 0; n < 2; ++n) _Pragma("unroll") for (int k = 0; k < 2; ++k) \
;         acc[ai][bj][m][n] = __builtin_amdgcn_mfma_f32_16x16x32_bf16(Bt[n][k], At[m][k], acc[ai][bj][m][n], 0, 0, 0); __builtin_amdgcn_s_setprio(0); } while (0)
; #define PG8_WAIT_L(n) asm volatile("s_waitcnt lgkmcnt(" #n ")" ::: "memory")
; #define PG8_BAR __builtin_amdgcn_s_barrier()
; #define PG8_SCHED __builtin_amdgcn_sched_barrier(0)
; template <class Epi, class Sched>
; __device__ __forceinline__ void gemm_phase(LAS unsigned char* lds, const Gemm g, const Sched& S, const Epi& E) {
;     ...
;             const char* a1 = cA + (size_t)(t + 1) * kstep;
;             const char* a2 = last ? nA : cA + (size_t)(t + 2) * kstep; const char* b2 = last ? nB : cB + (size_t)(t + 2) * kstep;
;             const char* a3 = a2 + kstep; const char* b3 = b2 + kstep;
;             PG8_LDB(B0, 0, 0); PG8_SCHED; PG8_LDA(At, 0, 0); PG8_STAGE(PG8_SA(1, 1), a1 + hstepA, voffA);
;             PG8_WAIT_L(8); PG8_BAR; PG8_WAIT_L(0); PG8_MMA(0, 0, At, B0); PG8_BAR; PG8_SCHED;
;             PG8_LDB(B1, 0, 1); PG8_STAGE(PG8_SB(0, 0), b2, voffB);
;             PG8_BAR; PG8_WAIT_L(0); PG8_MMA(0, 1, At, B1); PG8_BAR;
;             PG8_LDA(At, 0, 1); PG8_STAGE(PG8_SA(0, 0), a2, voffA);
;             PG8_BAR; PG8_WAIT_L(0); PG8_MMA(1, 0, At, B0); PG8_BAR; PG8_SCHED;
.LBB0_830:
	s_add_u32 s23, s44, 0xfff80080
	s_addc_u32 s46, s45, -1
	s_add_i32 s67, 0, 0x10000
	v_add_u32_e32 v162, s67, v142
	ds_read_b128 v[146:149], v162
	ds_read_b128 v[150:153], v162 offset:1024
	ds_read_b128 v[170:173], v162 offset:2048
	ds_read_b128 v[174:177], v162 offset:3072
	s_cmp_eq_u32 s66, 28
	s_cselect_b32 s49, s21, s46
	s_cselect_b32 s48, s56, s23
	s_cselect_b32 s47, s1, s59
	s_cselect_b32 s46, s57, s58
	v_lshl_add_u64 v[198:199], s[44:45], 0, v[138:139]
	s_add_i32 m0, s27, 0xc000
	ds_read_b128 v[178:181], v145
	ds_read_b128 v[182:185], v145 offset:1024
	ds_read_b128 v[186:189], v145 offset:2048
	ds_read_b128 v[190:193], v145 offset:3072
	ds_read_b128 v[194:197], v145 offset:4096
	ds_read_b128 v[210:213], v145 offset:5120
	ds_read_b128 v[214:217], v145 offset:6144
	ds_read_b128 v[218:221], v145 offset:7168
	global_load_lds_dwordx4 v[198:199], off
	v_lshl_add_u64 v[198:199], s[44:45], 0, v[140:141]
	s_add_i32 m0, s27, 0xe000
	s_nop 0
	global_load_lds_dwordx4 v[198:199], off
	s_waitcnt lgkmcnt(8)
	s_barrier
	s_waitcnt lgkmcnt(0)
	v_mfma_f32_16x16x32_bf16 v[126:129], v[146:149], v[178:181], v[126:129]
	v_mfma_f32_16x16x32_bf16 v[122:125], v[170:173], v[178:181], v[122:125]
	v_mfma_f32_16x16x32_bf16 v[110:113], v[146:149], v[186:189], v[110:113]
	v_mfma_f32_16x16x32_bf16 v[106:109], v[170:173], v[186:189], v[106:109]
	v_mfma_f32_16x16x32_bf16 v[94:97], v[146:149], v[194:197], v[94:97]
	v_mfma_f32_16x16x32_bf16 v[90:93], v[170:173], v[194:197], v[90:93]
	v_mfma_f32_16x16x32_bf16 v[78:81], v[146:149], v[214:217], v[78:81]
	v_mfma_f32_16x16x32_bf16 v[74:77], v[170:173], v[214:217], v[74:77]
	v_mfma_f32_16x16x32_bf16 v[126:129], v[150:153], v[182:185], v[126:129]
	v_mfma_f32_16x16x32_bf16 v[122:125], v[174:177], v[182:185], v[122:125]
	v_mfma_f32_16x16x32_bf16 v[110:113], v[150:153], v[190:193], v[110:113]
	v_mfma_f32_16x16x32_bf16 v[106:109], v[174:177], v[190:193], v[106:109]
	v_mfma_f32_16x16x32_bf16 v[94:97], v[150:153], v[210:213], v[94:97]
	v_mfma_f32_16x16x32_bf16 v[90:93], v[174:177], v[210:213], v[90:93]
	v_mfma_f32_16x16x32_bf16 v[78:81], v[150:153], v[218:221], v[78:81]
	v_mfma_f32_16x16x32_bf16 v[74:77], v[174:177], v[218:221], v[74:77]
	s_barrier
	s_add_i32 s23, 0, 0x14000
	s_add_i32 s67, s67, s26
	v_add_u32_e32 v162, s23, v142
	v_lshl_add_u64 v[198:199], s[46:47], 0, v[134:135]
	s_mov_b32 m0, s67
	ds_read_b128 v[222:225], v162
	ds_read_b128 v[226:229], v162 offset:1024
	ds_read_b128 v[230:233], v162 offset:2048
	ds_read_b128 v[234:237], v162 offset:3072
	global_load_lds_dwordx4 v[198:199], off
	v_lshl_add_u64 v[238:239], s[46:47], 0, v[130:131]
	s_add_i32 m0, s67, 0x2000
	s_nop 0
	global_load_lds_dwordx4 v[238:239], off
	s_barrier
	s_waitcnt lgkmcnt(0)
	v_mfma_f32_16x16x32_bf16 v[118:121], v[222:225], v[178:181], v[118:121]
	v_mfma_f32_16x16x32_bf16 v[114:117], v[230:233], v[178:181], v[114:117]
	v_mfma_f32_16x16x32_bf16 v[102:105], v[222:225], v[186:189], v[102:105]
	v_mfma_f32_16x16x32_bf16 v[98:101], v[230:233], v[186:189], v[98:101]
	v_mfma_f32_16x16x32_bf16 v[86:89], v[222:225], v[194:197], v[86:89]
	v_mfma_f32_16x16x32_bf16 v[82:85], v[230:233], v[194:197], v[82:85]
	v_mfma_f32_16x16x32_bf16 v[70:73], v[222:225], v[214:217], v[70:73]
	v_mfma_f32_16x16x32_bf16 v[66:69], v[230:233], v[214:217], v[66:69]
	v_mfma_f32_16x16x32_bf16 v[118:121], v[226:229], v[182:185], v[118:121]
	v_mfma_f32_16x16x32_bf16 v[114:117], v[234:237], v[182:185], v[114:117]
	v_mfma_f32_16x16x32_bf16 v[102:105], v[226:229], v[190:193], v[102:105]
	v_mfma_f32_16x16x32_bf16 v[98:101], v[234:237], v[190:193], v[98:101]
	v_mfma_f32_16x16x32_bf16 v[86:89], v[226:229], v[210:213], v[86:89]
	v_mfma_f32_16x16x32_bf16 v[82:85], v[234:237], v[210:213], v[82:85]
	v_mfma_f32_16x16x32_bf16 v[70:73], v[226:229], v[218:221], v[70:73]
	v_mfma_f32_16x16x32_bf16 v[66:69], v[234:237], v[218:221], v[66:69]
	s_mov_b32 m0, s27
	v_lshl_add_u64 v[240:241], s[48:49], 0, v[136:137]
	s_barrier
	ds_read_b128 v[178:181], v145 offset:16384
	ds_read_b128 v[182:185], v145 offset:17408
	ds_read_b128 v[186:189], v145 offset:18432
	ds_read_b128 v[190:193], v145 offset:19456
	ds_read_b128 v[194:197], v145 offset:20480
	ds_read_b128 v[210:213], v145 offset:21504
	ds_read_b128 v[214:217], v145 offset:22528
	ds_read_b128 v[218:221], v145 offset:23552
	global_load_lds_dwordx4 v[240:241], off
	v_lshl_add_u64 v[242:243], s[48:49], 0, v[132:133]
	s_mov_b32 m0, s28
	s_nop 0
	global_load_lds_dwordx4 v[242:243], off
	s_barrier
	s_waitcnt lgkmcnt(0)
	v_mfma_f32_16x16x32_bf16 v[62:65], v[146:149], v[178:181], v[62:65]
	v_mfma_f32_16x16x32_bf16 v[58:61], v[170:173], v[178:181], v[58:61]
	v_mfma_f32_16x16x32_bf16 v[46:49], v[146:149], v[186:189], v[46:49]
	v_mfma_f32_16x16x32_bf16 v[42:45], v[170:173], v[186:189], v[42:45]
	v_mfma_f32_16x16x32_bf16 v[30:33], v[146:149], v[194:197], v[30:33]
	v_mfma_f32_16x16x32_bf16 v[26:29], v[170:173], v[194:197], v[26:29]
	v_mfma_f32_16x16x32_bf16 v[14:17], v[146:149], v[214:217], v[14:17]
	v_mfma_f32_16x16x32_bf16 v[10:13], v[170:173], v[214:217], v[10:13]
	v_mfma_f32_16x16x32_bf16 v[62:65], v[150:153], v[182:185], v[62:65]
	v_mfma_f32_16x16x32_bf16 v[58:61], v[174:177], v[182:185], v[58:61]
	v_mfma_f32_16x16x32_bf16 v[46:49], v[150:153], v[190:193], v[46:49]
	v_mfma_f32_16x16x32_bf16 v[42:45], v[174:177], v[190:193], v[42:45]
	v_mfma_f32_16x16x32_bf16 v[30:33], v[150:153], v[210:213], v[30:33]
	v_mfma_f32_16x16x32_bf16 v[26:29], v[174:177], v[210:213], v[26:29]
	v_mfma_f32_16x16x32_bf16 v[14:17], v[150:153], v[218:221], v[14:17]
	v_mfma_f32_16x16x32_bf16 v[10:13], v[174:177], v[218:221], v[10:13]
	s_barrier
; #define PG8_STAGE(bufoff, gbase, voff) do { _Pragma("unroll") for (int _i = 0; _i < 2; ++_i) \
;         __builtin_amdgcn_global_load_lds((const unsigned*)((const char*)(gbase) + (voff)[_i]), (LAS unsigned*)(lds + (bufoff) + ldsw + _i * 8192), 16, 0, 0); } while (0)
; #define PG8_LDA(dst, b, h) do { _Pragma("unroll") for (int m = 0; m < 4; ++m) _Pragma("unroll") for (int k = 0; k < 2; ++k) dst[m][k] = *(const LAS bf16x8*)(lds + PG8_SA(b, h) + aoff + m * 2048 + k * 1024); } while (0)
; #define PG8_LDB(dst, b, h) do { _Pragma("unroll") for (int n = 0; n < 2; ++n) _Pragma("unroll") for (int k = 0; k < 2; ++k) dst[n][k] = *(const LAS bf16x8*)(lds + PG8_SB(b, h) + boff + n * 2048 + k * 1024); } while (0)
; #define PG8_MMA(ai, bj, At, Bt) do { __builtin_amdgcn_s_setprio(1); _Pragma("unroll") for (int m = 0; m < 4; ++m) _Pragma("unroll") for (int n = 0; n < 2; ++n) _Pragma("unroll") for (int k = 0; k < 2; ++k) \
;         acc[ai][bj][m][n] = __builtin_amdgcn_mfma_f32_16x16x32_bf16(Bt[n][k], At[m][k], acc[ai][bj][m][n], 0, 0, 0); __builtin_amdgcn_s_setprio(0); } while (0)
; #define PG8_WAIT_V(n) asm volatile("s_waitcnt vmcnt(" #n ")" ::: "memory")
; #define PG8_WAIT_L(n) asm volatile("s_waitcnt lgkmcnt(" #n ")" ::: "memory")
; #define PG8_BAR __builtin_amdgcn_s_barrier()
; #define PG8_SCHED __builtin_amdgcn_sched_barrier(0)
; template <class Epi, class Sched>
; __device__ __forceinline__ void gemm_phase(LAS unsigned char* lds, const Gemm g, const Sched& S, const Epi& E) {
;     ...
;             PG8_STAGE(PG8_SB(0, 1), b2 + hstepB, voffB);
;             PG8_WAIT_V(6); PG8_BAR; PG8_MMA(1, 1, At, B1); PG8_BAR;
;             PG8_LDB(B0, 1, 0); PG8_SCHED; PG8_LDA(At, 1, 0); PG8_STAGE(PG8_SA(0, 1), a2 + hstepA, voffA);
;             PG8_WAIT_L(8); PG8_BAR; PG8_WAIT_L(0); PG8_MMA(0, 0, At, B0); PG8_BAR; PG8_SCHED;
;             PG8_LDB(B1, 1, 1); PG8_STAGE(PG8_SB(1, 0), b3, voffB);
;             PG8_BAR; PG8_WAIT_L(0); PG8_MMA(0, 1, At, B1); PG8_BAR;
;             PG8_LDA(At, 1, 1); PG8_STAGE(PG8_SA(1, 0), a3, voffA);
	s_add_u32 s70, s46, 0x80000
	s_addc_u32 s71, s47, 0
	s_add_i32 s23, s23, s26
	v_lshl_add_u64 v[146:147], s[70:71], 0, v[134:135]
	s_mov_b32 m0, s23
	s_nop 0
	global_load_lds_dwordx4 v[146:147], off
	v_lshl_add_u64 v[146:147], s[70:71], 0, v[130:131]
	s_add_i32 m0, s23, 0x2000
	s_nop 0
	global_load_lds_dwordx4 v[146:147], off
	s_waitcnt vmcnt(6)
	s_barrier
	v_mfma_f32_16x16x32_bf16 v[54:57], v[222:225], v[178:181], v[54:57]
	v_mfma_f32_16x16x32_bf16 v[50:53], v[230:233], v[178:181], v[50:53]
	v_mfma_f32_16x16x32_bf16 v[38:41], v[222:225], v[186:189], v[38:41]
	v_mfma_f32_16x16x32_bf16 v[34:37], v[230:233], v[186:189], v[34:37]
	v_mfma_f32_16x16x32_bf16 v[22:25], v[222:225], v[194:197], v[22:25]
	v_mfma_f32_16x16x32_bf16 v[18:21], v[230:233], v[194:197], v[18:21]
	v_mfma_f32_16x16x32_bf16 v[6:9], v[222:225], v[214:217], v[6:9]
	v_mfma_f32_16x16x32_bf16 v[2:5], v[230:233], v[214:217], v[2:5]
	v_mfma_f32_16x16x32_bf16 v[54:57], v[226:229], v[182:185], v[54:57]
	v_mfma_f32_16x16x32_bf16 v[50:53], v[234:237], v[182:185], v[50:53]
	v_mfma_f32_16x16x32_bf16 v[38:41], v[226:229], v[190:193], v[38:41]
	v_mfma_f32_16x16x32_bf16 v[34:37], v[234:237], v[190:193], v[34:37]
	v_mfma_f32_16x16x32_bf16 v[22:25], v[226:229], v[210:213], v[22:25]
	v_mfma_f32_16x16x32_bf16 v[18:21], v[234:237], v[210:213], v[18:21]
	v_mfma_f32_16x16x32_bf16 v[6:9], v[226:229], v[218:221], v[6:9]
	v_mfma_f32_16x16x32_bf16 v[2:5], v[234:237], v[218:221], v[2:5]
	s_add_i32 s23, 0, 0x18000
	v_add_u32_e32 v162, s23, v142
	s_barrier
	ds_read_b128 v[146:149], v162
	ds_read_b128 v[150:153], v162 offset:1024
	ds_read_b128 v[170:173], v162 offset:2048
	ds_read_b128 v[174:177], v162 offset:3072
	s_add_u32 s48, s48, 0x80000
	s_addc_u32 s49, s49, 0
	s_mov_b32 m0, s29
	v_lshl_add_u64 v[222:223], s[48:49], 0, v[136:137]
	ds_read_b128 v[178:181], v145 offset:32768
	ds_read_b128 v[182:185], v145 offset:33792
	ds_read_b128 v[186:189], v145 offset:34816
	ds_read_b128 v[190:193], v145 offset:35840
	ds_read_b128 v[194:197], v145 offset:36864
	ds_read_b128 v[210:213], v145 offset:37888
	ds_read_b128 v[214:217], v145 offset:38912
	ds_read_b128 v[218:221], v145 offset:39936
	global_load_lds_dwordx4 v[222:223], off
	v_lshl_add_u64 v[222:223], s[48:49], 0, v[132:133]
	s_mov_b32 m0, s31
	s_nop 0
	global_load_lds_dwordx4 v[222:223], off
	s_waitcnt lgkmcnt(8)
	s_barrier
	s_waitcnt lgkmcnt(0)
	v_mfma_f32_16x16x32_bf16 v[126:129], v[146:149], v[178:181], v[126:129]
	v_mfma_f32_16x16x32_bf16 v[122:125], v[170:173], v[178:181], v[122:125]
	v_mfma_f32_16x16x32_bf16 v[110:113], v[146:149], v[186:189], v[110:113]
	v_mfma_f32_16x16x32_bf16 v[106:109], v[170:173], v[186:189], v[106:109]
	v_mfma_f32_16x16x32_bf16 v[94:97], v[146:149], v[194:197], v[94:97]
	v_mfma_f32_16x16x32_bf16 v[90:93], v[170:173], v[194:197], v[90:93]
	v_mfma_f32_16x16x32_bf16 v[78:81], v[146:149], v[214:217], v[78:81]
	v_mfma_f32_16x16x32_bf16 v[74:77], v[170:173], v[214:217], v[74:77]
	v_mfma_f32_16x16x32_bf16 v[126:129], v[150:153], v[182:185], v[126:129]
	v_mfma_f32_16x16x32_bf16 v[122:125], v[174:177], v[182:185], v[122:125]
	v_mfma_f32_16x16x32_bf16 v[110:113], v[150:153], v[190:193], v[110:113]
	v_mfma_f32_16x16x32_bf16 v[106:109], v[174:177], v[190:193], v[106:109]
	v_mfma_f32_16x16x32_bf16 v[94:97], v[150:153], v[210:213], v[94:97]
	v_mfma_f32_16x16x32_bf16 v[90:93], v[174:177], v[210:213], v[90:93]
	v_mfma_f32_16x16x32_bf16 v[78:81], v[150:153], v[218:221], v[78:81]
	v_mfma_f32_16x16x32_bf16 v[74:77], v[174:177], v[218:221], v[74:77]
	s_barrier
	s_add_i32 s48, 0, 0x1c000
	s_add_i32 s23, s23, s26
	v_add_u32_e32 v162, s48, v142
	v_lshl_add_u64 v[198:199], v[198:199], 0, s[10:11]
	s_mov_b32 m0, s23
	ds_read_b128 v[222:225], v162
	ds_read_b128 v[226:229], v162 offset:1024
	ds_read_b128 v[230:233], v162 offset:2048
	ds_read_b128 v[234:237], v162 offset:3072
	global_load_lds_dwordx4 v[198:199], off
	v_lshl_add_u64 v[198:199], v[238:239], 0, s[10:11]
	s_add_i32 m0, s23, 0x2000
	s_nop 0
	global_load_lds_dwordx4 v[198:199], off
	s_barrier
	s_waitcnt lgkmcnt(0)
	v_mfma_f32_16x16x32_bf16 v[118:121], v[222:225], v[178:181], v[118:121]
	v_mfma_f32_16x16x32_bf16 v[114:117], v[230:233], v[178:181], v[114:117]
	v_mfma_f32_16x16x32_bf16 v[102:105], v[222:225], v[186:189], v[102:105]
	v_mfma_f32_16x16x32_bf16 v[98:101], v[230:233], v[186:189], v[98:101]
	v_mfma_f32_16x16x32_bf16 v[86:89], v[222:225], v[194:197], v[86:89]
	v_mfma_f32_16x16x32_bf16 v[82:85], v[230:233], v[194:197], v[82:85]
	v_mfma_f32_16x16x32_bf16 v[70:73], v[222:225], v[214:217], v[70:73]
	v_mfma_f32_16x16x32_bf16 v[66:69], v[230:233], v[214:217], v[66:69]
	v_mfma_f32_16x16x32_bf16 v[118:121], v[226:229], v[182:185], v[118:121]
	v_mfma_f32_16x16x32_bf16 v[114:117], v[234:237], v[182:185], v[114:117]
	v_mfma_f32_16x16x32_bf16 v[102:105], v[226:229], v[190:193], v[102:105]
	v_mfma_f32_16x16x32_bf16 v[98:101], v[234:237], v[190:193], v[98:101]
	v_mfma_f32_16x16x32_bf16 v[86:89], v[226:229], v[210:213], v[86:89]
	v_mfma_f32_16x16x32_bf16 v[82:85], v[234:237], v[210:213], v[82:85]
	v_mfma_f32_16x16x32_bf16 v[70:73], v[226:229], v[218:221], v[70:73]
	v_mfma_f32_16x16x32_bf16 v[66:69], v[234:237], v[218:221], v[66:69]
	s_mov_b32 m0, s50
	v_lshl_add_u64 v[198:199], v[240:241], 0, s[10:11]
	s_barrier
	ds_read_b128 v[178:181], v145 offset:49152
	ds_read_b128 v[182:185], v145 offset:50176
	ds_read_b128 v[186:189], v145 offset:51200
	ds_read_b128 v[190:193], v145 offset:52224
	ds_read_b128 v[194:197], v145 offset:53248
	ds_read_b128 v[210:213], v145 offset:54272
	ds_read_b128 v[214:217], v145 offset:55296
	ds_read_b128 v[218:221], v145 offset:56320
	global_load_lds_dwordx4 v[198:199], off
	v_lshl_add_u64 v[198:199], v[242:243], 0, s[10:11]
	s_mov_b32 m0, s51
	s_nop 0
	global_load_lds_dwordx4 v[198:199], off
	s_barrier
; __device__ __forceinline__ unsigned cvt_pk_bf16(float lo, float hi) { unsigned r; asm volatile("v_cvt_pk_bf16_f32 %0, %1, %2" : "=v"(r) : "v"(lo), "v"(hi)); return r; }
; #define PG8_STAGE(bufoff, gbase, voff) do { _Pragma("unroll") for (int _i = 0; _i < 2; ++_i) \
;         __builtin_amdgcn_global_load_lds((const unsigned*)((const char*)(gbase) + (voff)[_i]), (LAS unsigned*)(lds + (bufoff) + ldsw + _i * 8192), 16, 0, 0); } while (0)
; #define PG8_MMA(ai, bj, At, Bt) do { __builtin_amdgcn_s_setprio(1); _Pragma("unroll") for (int m = 0; m < 4; ++m) _Pragma("unroll") for (int n = 0; n < 2; ++n) _Pragma("unroll") for (int k = 0; k < 2; ++k) \
;         acc[ai][bj][m][n] = __builtin_amdgcn_mfma_f32_16x16x32_bf16(Bt[n][k], At[m][k], acc[ai][bj][m][n], 0, 0, 0); __builtin_amdgcn_s_setprio(0); } while (0)
; #define PG8_WAIT_V(n) asm volatile("s_waitcnt vmcnt(" #n ")" ::: "memory")
; #define PG8_BAR __builtin_amdgcn_s_barrier()
;     __device__ __forceinline__ void operator()(const f32x4 (&acc)[2][2][4][2], const Unit& u, int ui, const LAS float* rtab, int wr, int wc, int fr, int fq) const {
;         const int row0 = u.pm * BM + wr * 64 + fr, col0 = u.pn * BM + wc * 32 + 8 * fq;
; #pragma unroll
;         for (int ai = 0; ai < 2; ++ai)
; #pragma unroll
;             for (int m = 0; m < 4; ++m) {
;                 const int row = row0 + ai * HALF + m * 16; const float rs = rtab[ui * 256 + wr * 64 + fr + ai * HALF + m * 16];
; #pragma unroll
;                 for (int bj = 0; bj < 2; ++bj) {
;                     f32x4 v0 = acc[ai][bj][m][0] * rs, v1 = acc[ai][bj][m][1] * rs;
; #pragma unroll
;                     for (int e = 0; e < 4; ++e) { const float a = fmaxf(v0[e], 0.f), b = fmaxf(v1[e], 0.f); v0[e] = a * a; v1[e] = b * b; }
;                     u32x4 w; w.x = cvt_pk_bf16(v0[0], v0[1]); w.y = cvt_pk_bf16(v0[2], v0[3]); w.z = cvt_pk_bf16(v1[0], v1[1]); w.w = cvt_pk_bf16(v1[2], v1[3]);
;                     *(u32x4*)(H + (size_t)row * DFF + col0 + bj * HALF) = w;
; template <class Epi, class Sched>
; __device__ __forceinline__ void gemm_phase(LAS unsigned char* lds, const Gemm g, const Sched& S, const Epi& E) {
;     ...
;             PG8_BAR; PG8_WAIT_L(0); PG8_MMA(1, 0, At, B0); PG8_BAR; PG8_SCHED;
;             PG8_STAGE(PG8_SB(1, 1), b3 + hstepB, voffB);
;             PG8_WAIT_V(6); PG8_BAR; PG8_MMA(1, 1, At, B1); PG8_BAR;
;         }
	s_waitcnt lgkmcnt(0)
	v_mfma_f32_16x16x32_bf16 v[62:65], v[146:149], v[178:181], v[62:65]
	v_mfma_f32_16x16x32_bf16 v[58:61], v[170:173], v[178:181], v[58:61]
	v_mfma_f32_16x16x32_bf16 v[46:49], v[146:149], v[186:189], v[46:49]
	v_mfma_f32_16x16x32_bf16 v[42:45], v[170:173], v[186:189], v[42:45]
	v_mfma_f32_16x16x32_bf16 v[30:33], v[146:149], v[194:197], v[30:33]
	v_mfma_f32_16x16x32_bf16 v[26:29], v[170:173], v[194:197], v[26:29]
	v_mfma_f32_16x16x32_bf16 v[14:17], v[146:149], v[214:217], v[14:17]
	v_mfma_f32_16x16x32_bf16 v[10:13], v[170:173], v[214:217], v[10:13]
	v_mfma_f32_16x16x32_bf16 v[62:65], v[150:153], v[182:185], v[62:65]
	v_mfma_f32_16x16x32_bf16 v[58:61], v[174:177], v[182:185], v[58:61]
	v_mfma_f32_16x16x32_bf16 v[46:49], v[150:153], v[190:193], v[46:49]
	v_mfma_f32_16x16x32_bf16 v[42:45], v[174:177], v[190:193], v[42:45]
	v_mfma_f32_16x16x32_bf16 v[30:33], v[150:153], v[210:213], v[30:33]
	v_mfma_f32_16x16x32_bf16 v[26:29], v[174:177], v[210:213], v[26:29]
	v_mfma_f32_16x16x32_bf16 v[14:17], v[150:153], v[218:221], v[14:17]
	v_mfma_f32_16x16x32_bf16 v[10:13], v[174:177], v[218:221], v[10:13]
	s_barrier
	s_add_u32 s46, s46, 0x80080
	s_addc_u32 s47, s47, 0
	s_add_i32 s23, s48, s26
	v_lshl_add_u64 v[146:147], s[46:47], 0, v[134:135]
	s_mov_b32 m0, s23
	s_nop 0
	global_load_lds_dwordx4 v[146:147], off
	v_lshl_add_u64 v[146:147], s[46:47], 0, v[130:131]
	s_add_i32 m0, s23, 0x2000
	s_nop 0
	global_load_lds_dwordx4 v[146:147], off
	s_waitcnt vmcnt(6)
	s_barrier
	v_mfma_f32_16x16x32_bf16 v[54:57], v[222:225], v[178:181], v[54:57]
	v_mfma_f32_16x16x32_bf16 v[50:53], v[230:233], v[178:181], v[50:53]
	v_mfma_f32_16x16x32_bf16 v[38:41], v[222:225], v[186:189], v[38:41]
	v_mfma_f32_16x16x32_bf16 v[34:37], v[230:233], v[186:189], v[34:37]
	v_mfma_f32_16x16x32_bf16 v[22:25], v[222:225], v[194:197], v[22:25]
	v_mfma_f32_16x16x32_bf16 v[18:21], v[230:233], v[194:197], v[18:21]
	v_mfma_f32_16x16x32_bf16 v[6:9], v[222:225], v[214:217], v[6:9]
	v_mfma_f32_16x16x32_bf16 v[2:5], v[230:233], v[214:217], v[2:5]
	v_mfma_f32_16x16x32_bf16 v[54:57], v[226:229], v[182:185], v[54:57]
	v_mfma_f32_16x16x32_bf16 v[50:53], v[234:237], v[182:185], v[50:53]
	v_mfma_f32_16x16x32_bf16 v[38:41], v[226:229], v[190:193], v[38:41]
	v_mfma_f32_16x16x32_bf16 v[34:37], v[234:237], v[190:193], v[34:37]
	v_mfma_f32_16x16x32_bf16 v[22:25], v[226:229], v[210:213], v[22:25]
	v_mfma_f32_16x16x32_bf16 v[18:21], v[234:237], v[210:213], v[18:21]
	v_mfma_f32_16x16x32_bf16 v[6:9], v[226:229], v[218:221], v[6:9]
	v_mfma_f32_16x16x32_bf16 v[2:5], v[234:237], v[218:221], v[2:5]
	s_add_i32 s66, s66, 2
	s_add_u32 s44, s44, 0x100
	s_addc_u32 s45, s45, 0
	s_add_u32 s58, s58, 0x100
	s_addc_u32 s59, s59, 0
	s_cmp_gt_u32 s66, 29
	s_barrier
	s_cbranch_scc0 .LBB0_830
	v_lshl_add_u32 v146, s55, 10, v143
	ds_read_b32 v150, v146
	v_lshl_add_u32 v148, s54, 8, v1
	v_lshl_or_b32 v152, s53, 8, v144
	v_ashrrev_i32_e32 v149, 31, v148
	v_ashrrev_i32_e32 v153, 31, v152
	s_waitcnt lgkmcnt(0)
	v_pk_mul_f32 v[124:125], v[124:125], v[150:151] op_sel_hi:[1,0]
	v_pk_mul_f32 v[128:129], v[128:129], v[150:151] op_sel_hi:[1,0]
	v_pk_mul_f32 v[126:127], v[126:127], v[150:151] op_sel_hi:[1,0]
	v_pk_mul_f32 v[122:123], v[122:123], v[150:151] op_sel_hi:[1,0]
	v_max_f32_e32 v124, 0, v124
	v_max_f32_e32 v126, 0, v126
	v_max_f32_e32 v122, 0, v122
	v_max_f32_e32 v123, 0, v123
	v_max_f32_e32 v128, 0, v128
	v_mul_f32_e32 v147, v124, v124
	v_max_f32_e32 v124, 0, v129
	v_lshlrev_b64 v[170:171], 14, v[148:149]
	v_mul_f32_e32 v126, v126, v126
	v_mul_f32_e32 v122, v122, v122
	v_max_f32_e32 v127, 0, v127
	v_mul_f32_e32 v123, v123, v123
	v_mul_f32_e32 v128, v128, v128
	v_max_f32_e32 v125, 0, v125
	v_mul_f32_e32 v129, v124, v124
	v_mul_f32_e32 v127, v127, v127
	v_mul_f32_e32 v149, v125, v125
	v_cvt_pk_bf16_f32 v124, v126, v127
	v_cvt_pk_bf16_f32 v125, v128, v129
	v_cvt_pk_bf16_f32 v126, v122, v123
	v_lshl_add_u64 v[122:123], s[72:73], 0, v[170:171]
	v_lshlrev_b64 v[128:129], 1, v[152:153]
	v_pk_mul_f32 v[116:117], v[116:117], v[150:151] op_sel_hi:[1,0]
	v_pk_mul_f32 v[114:115], v[114:115], v[150:151] op_sel_hi:[1,0]
	v_lshl_add_u64 v[122:123], v[122:123], 0, v[128:129]
	v_pk_mul_f32 v[120:121], v[120:121], v[150:151] op_sel_hi:[1,0]
	v_pk_mul_f32 v[118:119], v[118:119], v[150:151] op_sel_hi:[1,0]
	v_max_f32_e32 v114, 0, v114
	v_max_f32_e32 v115, 0, v115
	v_max_f32_e32 v116, 0, v116
	v_cvt_pk_bf16_f32 v127, v147, v149
	global_store_dwordx4 v[122:123], v[124:127], off
	v_max_f32_e32 v118, 0, v118
	v_max_f32_e32 v117, 0, v117
	v_mul_f32_e32 v124, v114, v114
	v_max_f32_e32 v114, 0, v119
	v_mul_f32_e32 v119, v115, v115
	v_max_f32_e32 v115, 0, v120
	v_mul_f32_e32 v120, v116, v116
	v_max_f32_e32 v116, 0, v121
	v_mul_f32_e32 v118, v118, v118
	v_mul_f32_e32 v114, v114, v114
	v_mul_f32_e32 v115, v115, v115
	v_mul_f32_e32 v116, v116, v116
	v_mul_f32_e32 v117, v117, v117
	v_cvt_pk_bf16_f32 v114, v118, v114
	v_cvt_pk_bf16_f32 v115, v115, v116
	v_cvt_pk_bf16_f32 v116, v124, v119
	v_cvt_pk_bf16_f32 v117, v120, v117
	ds_read_b32 v118, v146 offset:64
	global_store_dwordx4 v[122:123], v[114:117], off offset:256
	s_mov_b32 s1, 0x200000
	s_mov_b64 s[44:45], 0x240000
	v_or_b32_e32 v114, 16, v148
	s_waitcnt lgkmcnt(0)
; __device__ __forceinline__ unsigned cvt_pk_bf16(float lo, float hi) { unsigned r; asm volatile("v_cvt_pk_bf16_f32 %0, %1, %2" : "=v"(r) : "v"(lo), "v"(hi)); return r; }
;     __device__ __forceinline__ void operator()(const f32x4 (&acc)[2][2][4][2], const Unit& u, int ui, const LAS float* rtab, int wr, int wc, int fr, int fq) const {
;     ...
;         for (int ai = 0; ai < 2; ++ai)
; #pragma unroll
;             for (int m = 0; m < 4; ++m) {
;                 const int row = row0 + ai * HALF + m * 16; const float rs = rtab[ui * 256 + wr * 64 + fr + ai * HALF + m * 16];
; #pragma unroll
;                 for (int bj = 0; bj < 2; ++bj) {
;                     f32x4 v0 = acc[ai][bj][m][0] * rs, v1 = acc[ai][bj][m][1] * rs;
; #pragma unroll
;                     for (int e = 0; e < 4; ++e) { const float a = fmaxf(v0[e], 0.f), b = fmaxf(v1[e], 0.f); v0[e] = a * a; v1[e] = b * b; }
;                     u32x4 w; w.x = cvt_pk_bf16(v0[0], v0[1]); w.y = cvt_pk_bf16(v0[2], v0[3]); w.z = cvt_pk_bf16(v1[0], v1[1]); w.w = cvt_pk_bf16(v1[2], v1[3]);
;                     *(u32x4*)(H + (size_t)row * DFF + col0 + bj * HALF) = w;
;                 }
;             }
	v_pk_mul_f32 v[108:109], v[108:109], v[118:119] op_sel_hi:[1,0]
	v_pk_mul_f32 v[106:107], v[106:107], v[118:119] op_sel_hi:[1,0]
	v_pk_mul_f32 v[112:113], v[112:113], v[118:119] op_sel_hi:[1,0]
	v_pk_mul_f32 v[110:111], v[110:111], v[118:119] op_sel_hi:[1,0]
	v_max_f32_e32 v106, 0, v106
	v_max_f32_e32 v107, 0, v107
	v_max_f32_e32 v108, 0, v108
	v_ashrrev_i32_e32 v115, 31, v114
	v_max_f32_e32 v110, 0, v110
	v_mul_f32_e32 v116, v106, v106
	v_max_f32_e32 v106, 0, v111
	v_mul_f32_e32 v111, v107, v107
	v_max_f32_e32 v107, 0, v112
	v_mul_f32_e32 v112, v108, v108
	v_max_f32_e32 v108, 0, v113
	v_lshlrev_b64 v[114:115], 14, v[114:115]
	v_mul_f32_e32 v110, v110, v110
	v_mul_f32_e32 v106, v106, v106
	v_mul_f32_e32 v107, v107, v107
	v_mul_f32_e32 v108, v108, v108
	v_max_f32_e32 v109, 0, v109
	v_cvt_pk_bf16_f32 v106, v110, v106
	v_cvt_pk_bf16_f32 v107, v107, v108
	v_cvt_pk_bf16_f32 v108, v116, v111
	v_lshl_add_u64 v[110:111], s[72:73], 0, v[114:115]
	v_pk_mul_f32 v[100:101], v[100:101], v[118:119] op_sel_hi:[1,0]
	v_pk_mul_f32 v[98:99], v[98:99], v[118:119] op_sel_hi:[1,0]
	v_mul_f32_e32 v109, v109, v109
	v_lshl_add_u64 v[110:111], v[110:111], 0, v[128:129]
	v_pk_mul_f32 v[104:105], v[104:105], v[118:119] op_sel_hi:[1,0]
	v_pk_mul_f32 v[102:103], v[102:103], v[118:119] op_sel_hi:[1,0]
	v_max_f32_e32 v98, 0, v98
	v_max_f32_e32 v99, 0, v99
	v_max_f32_e32 v100, 0, v100
	v_cvt_pk_bf16_f32 v109, v112, v109
	global_store_dwordx4 v[110:111], v[106:109], off
	v_max_f32_e32 v102, 0, v102
	v_max_f32_e32 v101, 0, v101
	v_mul_f32_e32 v106, v98, v98
	v_max_f32_e32 v98, 0, v103
	v_mul_f32_e32 v103, v99, v99
	v_max_f32_e32 v99, 0, v104
	v_mul_f32_e32 v104, v100, v100
	v_max_f32_e32 v100, 0, v105
	v_mul_f32_e32 v102, v102, v102
	v_mul_f32_e32 v98, v98, v98
	v_mul_f32_e32 v99, v99, v99
	v_mul_f32_e32 v100, v100, v100
	v_mul_f32_e32 v101, v101, v101
	v_cvt_pk_bf16_f32 v98, v102, v98
	v_cvt_pk_bf16_f32 v99, v99, v100
	v_cvt_pk_bf16_f32 v100, v106, v103
	v_cvt_pk_bf16_f32 v101, v104, v101
	ds_read_b32 v102, v146 offset:128
	global_store_dwordx4 v[110:111], v[98:101], off offset:256
	s_mov_b32 s54, s20
	s_mov_b32 s53, s0
	v_or_b32_e32 v98, 32, v148
	s_waitcnt lgkmcnt(0)
	v_pk_mul_f32 v[92:93], v[92:93], v[102:103] op_sel_hi:[1,0]
	v_pk_mul_f32 v[90:91], v[90:91], v[102:103] op_sel_hi:[1,0]
	v_pk_mul_f32 v[96:97], v[96:97], v[102:103] op_sel_hi:[1,0]
	v_pk_mul_f32 v[94:95], v[94:95], v[102:103] op_sel_hi:[1,0]
	v_max_f32_e32 v90, 0, v90
	v_max_f32_e32 v91, 0, v91
	v_max_f32_e32 v92, 0, v92
	v_ashrrev_i32_e32 v99, 31, v98
	v_max_f32_e32 v94, 0, v94
	v_mul_f32_e32 v100, v90, v90
	v_max_f32_e32 v90, 0, v95
	v_mul_f32_e32 v95, v91, v91
	v_max_f32_e32 v91, 0, v96
	v_mul_f32_e32 v96, v92, v92
	v_max_f32_e32 v92, 0, v97
	v_lshlrev_b64 v[98:99], 14, v[98:99]
	v_mul_f32_e32 v94, v94, v94
	v_mul_f32_e32 v90, v90, v90
	v_mul_f32_e32 v91, v91, v91
	v_mul_f32_e32 v92, v92, v92
	v_max_f32_e32 v93, 0, v93
	v_cvt_pk_bf16_f32 v90, v94, v90
	v_cvt_pk_bf16_f32 v91, v91, v92
	v_cvt_pk_bf16_f32 v92, v100, v95
	v_lshl_add_u64 v[94:95], s[72:73], 0, v[98:99]
	v_pk_mul_f32 v[84:85], v[84:85], v[102:103] op_sel_hi:[1,0]
	v_pk_mul_f32 v[82:83], v[82:83], v[102:103] op_sel_hi:[1,0]
	v_mul_f32_e32 v93, v93, v93
	v_lshl_add_u64 v[94:95], v[94:95], 0, v[128:129]
	v_pk_mul_f32 v[88:89], v[88:89], v[102:103] op_sel_hi:[1,0]
	v_pk_mul_f32 v[86:87], v[86:87], v[102:103] op_sel_hi:[1,0]
	v_max_f32_e32 v82, 0, v82
	v_max_f32_e32 v83, 0, v83
	v_max_f32_e32 v84, 0, v84
	v_cvt_pk_bf16_f32 v93, v96, v93
	global_store_dwordx4 v[94:95], v[90:93], off
	v_max_f32_e32 v86, 0, v86
	v_max_f32_e32 v85, 0, v85
	v_mul_f32_e32 v90, v82, v82
	v_max_f32_e32 v82, 0, v87
	v_mul_f32_e32 v87, v83, v83
	v_max_f32_e32 v83, 0, v88
	v_mul_f32_e32 v88, v84, v84
	v_max_f32_e32 v84, 0, v89
	v_mul_f32_e32 v86, v86, v86
	v_mul_f32_e32 v82, v82, v82
	v_mul_f32_e32 v83, v83, v83
	v_mul_f32_e32 v84, v84, v84
	v_mul_f32_e32 v85, v85, v85
	v_cvt_pk_bf16_f32 v82, v86, v82
	v_cvt_pk_bf16_f32 v83, v83, v84
	v_cvt_pk_bf16_f32 v84, v90, v87
	v_cvt_pk_bf16_f32 v85, v88, v85
	ds_read_b32 v86, v146 offset:192
	global_store_dwordx4 v[94:95], v[82:85], off offset:256
	s_mov_b64 s[46:47], s[36:37]
	s_mov_b32 s55, s52
	v_or_b32_e32 v82, 48, v148
	s_waitcnt lgkmcnt(0)
	v_pk_mul_f32 v[76:77], v[76:77], v[86:87] op_sel_hi:[1,0]
	v_pk_mul_f32 v[74:75], v[74:75], v[86:87] op_sel_hi:[1,0]
	v_pk_mul_f32 v[80:81], v[80:81], v[86:87] op_sel_hi:[1,0]
	v_pk_mul_f32 v[78:79], v[78:79], v[86:87] op_sel_hi:[1,0]
	v_max_f32_e32 v74, 0, v74
	v_max_f32_e32 v75, 0, v75
	v_max_f32_e32 v76, 0, v76
	v_ashrrev_i32_e32 v83, 31, v82
	v_max_f32_e32 v78, 0, v78
	v_mul_f32_e32 v84, v74, v74
	v_max_f32_e32 v74, 0, v79
	v_mul_f32_e32 v79, v75, v75
	v_max_f32_e32 v75, 0, v80
	v_mul_f32_e32 v80, v76, v76
	v_max_f32_e32 v76, 0, v81
	v_lshlrev_b64 v[82:83], 14, v[82:83]
	v_mul_f32_e32 v78, v78, v78
	v_mul_f32_e32 v74, v74, v74
	v_mul_f32_e32 v75, v75, v75
	v_mul_f32_e32 v76, v76, v76
	v_max_f32_e32 v77, 0, v77
	v_cvt_pk_bf16_f32 v74, v78, v74
	v_cvt_pk_bf16_f32 v75, v75, v76
	v_cvt_pk_bf16_f32 v76, v84, v79
	v_lshl_add_u64 v[78:79], s[72:73], 0, v[82:83]
	v_pk_mul_f32 v[68:69], v[68:69], v[86:87] op_sel_hi:[1,0]
	v_pk_mul_f32 v[66:67], v[66:67], v[86:87] op_sel_hi:[1,0]
	v_mul_f32_e32 v77, v77, v77
	v_lshl_add_u64 v[78:79], v[78:79], 0, v[128:129]
	v_pk_mul_f32 v[72:73], v[72:73], v[86:87] op_sel_hi:[1,0]
	v_pk_mul_f32 v[70:71], v[70:71], v[86:87] op_sel_hi:[1,0]
	v_max_f32_e32 v66, 0, v66
	v_max_f32_e32 v67, 0, v67
	v_max_f32_e32 v68, 0, v68
	v_cvt_pk_bf16_f32 v77, v80, v77
	global_store_dwordx4 v[78:79], v[74:77], off
	v_max_f32_e32 v70, 0, v70
	v_max_f32_e32 v69, 0, v69
	v_mul_f32_e32 v74, v66, v66
	v_max_f32_e32 v66, 0, v71
	v_mul_f32_e32 v71, v67, v67
	v_max_f32_e32 v67, 0, v72
	v_mul_f32_e32 v72, v68, v68
	v_max_f32_e32 v68, 0, v73
	v_mul_f32_e32 v70, v70, v70
	v_mul_f32_e32 v66, v66, v66
	v_mul_f32_e32 v67, v67, v67
	v_mul_f32_e32 v68, v68, v68
	v_mul_f32_e32 v69, v69, v69
	v_cvt_pk_bf16_f32 v66, v70, v66
	v_cvt_pk_bf16_f32 v67, v67, v68
	v_cvt_pk_bf16_f32 v68, v74, v71
	v_cvt_pk_bf16_f32 v69, v72, v69
	ds_read_b32 v70, v146 offset:512
	global_store_dwordx4 v[78:79], v[66:69], off offset:256
	s_waitcnt lgkmcnt(0)
; __device__ __forceinline__ unsigned cvt_pk_bf16(float lo, float hi) { unsigned r; asm volatile("v_cvt_pk_bf16_f32 %0, %1, %2" : "=v"(r) : "v"(lo), "v"(hi)); return r; }
;     __device__ __forceinline__ void operator()(const f32x4 (&acc)[2][2][4][2], const Unit& u, int ui, const LAS float* rtab, int wr, int wc, int fr, int fq) const {
;     ...
;         for (int ai = 0; ai < 2; ++ai)
; #pragma unroll
;             for (int m = 0; m < 4; ++m) {
;                 const int row = row0 + ai * HALF + m * 16; const float rs = rtab[ui * 256 + wr * 64 + fr + ai * HALF + m * 16];
; #pragma unroll
;                 for (int bj = 0; bj < 2; ++bj) {
;                     f32x4 v0 = acc[ai][bj][m][0] * rs, v1 = acc[ai][bj][m][1] * rs;
; #pragma unroll
;                     for (int e = 0; e < 4; ++e) { const float a = fmaxf(v0[e], 0.f), b = fmaxf(v1[e], 0.f); v0[e] = a * a; v1[e] = b * b; }
;                     u32x4 w; w.x = cvt_pk_bf16(v0[0], v0[1]); w.y = cvt_pk_bf16(v0[2], v0[3]); w.z = cvt_pk_bf16(v1[0], v1[1]); w.w = cvt_pk_bf16(v1[2], v1[3]);
;                     *(u32x4*)(H + (size_t)row * DFF + col0 + bj * HALF) = w;
;                 }
;             }
	v_pk_mul_f32 v[58:59], v[58:59], v[70:71] op_sel_hi:[1,0]
	v_pk_mul_f32 v[62:63], v[62:63], v[70:71] op_sel_hi:[1,0]
	v_pk_mul_f32 v[60:61], v[60:61], v[70:71] op_sel_hi:[1,0]
	v_max_f32_e32 v58, 0, v58
	v_pk_mul_f32 v[64:65], v[64:65], v[70:71] op_sel_hi:[1,0]
	v_max_f32_e32 v62, 0, v62
	v_mul_f32_e32 v66, v58, v58
	v_max_f32_e32 v58, 0, v63
	v_max_f32_e32 v59, 0, v59
	v_max_f32_e32 v60, 0, v60
	v_mul_f32_e32 v62, v62, v62
	v_mul_f32_e32 v58, v58, v58
	v_mul_f32_e32 v63, v59, v59
	v_max_f32_e32 v59, 0, v64
	v_mul_f32_e32 v64, v60, v60
	v_max_f32_e32 v60, 0, v65
	v_mul_f32_e32 v59, v59, v59
	v_max_f32_e32 v61, 0, v61
	v_mul_f32_e32 v60, v60, v60
	v_cvt_pk_bf16_f32 v58, v62, v58
	v_add_co_u32_e32 v62, vcc, s1, v122
	v_pk_mul_f32 v[52:53], v[52:53], v[70:71] op_sel_hi:[1,0]
	v_pk_mul_f32 v[50:51], v[50:51], v[70:71] op_sel_hi:[1,0]
	v_mul_f32_e32 v61, v61, v61
	v_cvt_pk_bf16_f32 v59, v59, v60
	v_cvt_pk_bf16_f32 v60, v66, v63
	v_addc_co_u32_e32 v63, vcc, 0, v123, vcc
	v_pk_mul_f32 v[56:57], v[56:57], v[70:71] op_sel_hi:[1,0]
	v_pk_mul_f32 v[54:55], v[54:55], v[70:71] op_sel_hi:[1,0]
	v_max_f32_e32 v50, 0, v50
	v_max_f32_e32 v51, 0, v51
	v_max_f32_e32 v52, 0, v52
	v_cvt_pk_bf16_f32 v61, v64, v61
	global_store_dwordx4 v[62:63], v[58:61], off
	v_max_f32_e32 v54, 0, v54
	v_max_f32_e32 v53, 0, v53
	v_mul_f32_e32 v58, v50, v50
	v_max_f32_e32 v50, 0, v55
	v_mul_f32_e32 v55, v51, v51
	v_max_f32_e32 v51, 0, v56
	v_mul_f32_e32 v56, v52, v52
	v_max_f32_e32 v52, 0, v57
	v_mul_f32_e32 v54, v54, v54
	v_mul_f32_e32 v50, v50, v50
	v_mul_f32_e32 v51, v51, v51
	v_mul_f32_e32 v52, v52, v52
	v_mul_f32_e32 v53, v53, v53
	v_cvt_pk_bf16_f32 v50, v54, v50
	v_cvt_pk_bf16_f32 v51, v51, v52
	v_cvt_pk_bf16_f32 v52, v58, v55
	v_cvt_pk_bf16_f32 v53, v56, v53
	ds_read_b32 v54, v146 offset:576
	v_lshl_add_u64 v[56:57], v[122:123], 0, s[84:85]
	global_store_dwordx4 v[56:57], v[50:53], off offset:256
	s_mov_b32 s1, 0x240000
	s_waitcnt lgkmcnt(0)
	v_pk_mul_f32 v[42:43], v[42:43], v[54:55] op_sel_hi:[1,0]
	v_pk_mul_f32 v[46:47], v[46:47], v[54:55] op_sel_hi:[1,0]
	v_pk_mul_f32 v[44:45], v[44:45], v[54:55] op_sel_hi:[1,0]
	v_max_f32_e32 v42, 0, v42
	v_pk_mul_f32 v[48:49], v[48:49], v[54:55] op_sel_hi:[1,0]
	v_max_f32_e32 v46, 0, v46
	v_mul_f32_e32 v50, v42, v42
	v_max_f32_e32 v42, 0, v47
	v_max_f32_e32 v43, 0, v43
	v_max_f32_e32 v44, 0, v44
	v_mul_f32_e32 v46, v46, v46
	v_mul_f32_e32 v42, v42, v42
	v_mul_f32_e32 v47, v43, v43
	v_max_f32_e32 v43, 0, v48
	v_mul_f32_e32 v48, v44, v44
	v_max_f32_e32 v44, 0, v49
	v_mul_f32_e32 v43, v43, v43
	v_max_f32_e32 v45, 0, v45
	v_mul_f32_e32 v44, v44, v44
	v_cvt_pk_bf16_f32 v42, v46, v42
	v_add_co_u32_e32 v46, vcc, s1, v122
	v_pk_mul_f32 v[36:37], v[36:37], v[54:55] op_sel_hi:[1,0]
	v_pk_mul_f32 v[34:35], v[34:35], v[54:55] op_sel_hi:[1,0]
	v_mul_f32_e32 v45, v45, v45
	v_cvt_pk_bf16_f32 v43, v43, v44
	v_cvt_pk_bf16_f32 v44, v50, v47
	v_addc_co_u32_e32 v47, vcc, 0, v123, vcc
	v_pk_mul_f32 v[40:41], v[40:41], v[54:55] op_sel_hi:[1,0]
	v_pk_mul_f32 v[38:39], v[38:39], v[54:55] op_sel_hi:[1,0]
	v_max_f32_e32 v34, 0, v34
	v_max_f32_e32 v35, 0, v35
	v_max_f32_e32 v36, 0, v36
	v_cvt_pk_bf16_f32 v45, v48, v45
	global_store_dwordx4 v[46:47], v[42:45], off
	v_max_f32_e32 v38, 0, v38
	v_max_f32_e32 v37, 0, v37
	v_mul_f32_e32 v42, v34, v34
	v_max_f32_e32 v34, 0, v39
	v_mul_f32_e32 v39, v35, v35
	v_max_f32_e32 v35, 0, v40
	v_mul_f32_e32 v40, v36, v36
	v_max_f32_e32 v36, 0, v41
	v_mul_f32_e32 v38, v38, v38
	v_mul_f32_e32 v34, v34, v34
	v_mul_f32_e32 v35, v35, v35
	v_mul_f32_e32 v36, v36, v36
	v_mul_f32_e32 v37, v37, v37
	v_cvt_pk_bf16_f32 v34, v38, v34
	v_cvt_pk_bf16_f32 v35, v35, v36
	v_cvt_pk_bf16_f32 v36, v42, v39
	v_cvt_pk_bf16_f32 v37, v40, v37
	ds_read_b32 v38, v146 offset:640
	v_lshl_add_u64 v[40:41], v[122:123], 0, s[44:45]
	global_store_dwordx4 v[40:41], v[34:37], off offset:256
	s_mov_b32 s1, 0x280000
	s_mov_b64 s[44:45], 0x280000
	s_waitcnt lgkmcnt(0)
; __device__ __forceinline__ unsigned cvt_pk_bf16(float lo, float hi) { unsigned r; asm volatile("v_cvt_pk_bf16_f32 %0, %1, %2" : "=v"(r) : "v"(lo), "v"(hi)); return r; }
; #define PG8_WAIT_V(n) asm volatile("s_waitcnt vmcnt(" #n ")" ::: "memory")
; #define PG8_BAR __builtin_amdgcn_s_barrier()
;     __device__ __forceinline__ void operator()(const f32x4 (&acc)[2][2][4][2], const Unit& u, int ui, const LAS float* rtab, int wr, int wc, int fr, int fq) const {
;     ...
;         for (int ai = 0; ai < 2; ++ai)
; #pragma unroll
;             for (int m = 0; m < 4; ++m) {
;                 const int row = row0 + ai * HALF + m * 16; const float rs = rtab[ui * 256 + wr * 64 + fr + ai * HALF + m * 16];
; #pragma unroll
;                 for (int bj = 0; bj < 2; ++bj) {
;                     f32x4 v0 = acc[ai][bj][m][0] * rs, v1 = acc[ai][bj][m][1] * rs;
; #pragma unroll
;                     for (int e = 0; e < 4; ++e) { const float a = fmaxf(v0[e], 0.f), b = fmaxf(v1[e], 0.f); v0[e] = a * a; v1[e] = b * b; }
;                     u32x4 w; w.x = cvt_pk_bf16(v0[0], v0[1]); w.y = cvt_pk_bf16(v0[2], v0[3]); w.z = cvt_pk_bf16(v1[0], v1[1]); w.w = cvt_pk_bf16(v1[2], v1[3]);
;                     *(u32x4*)(H + (size_t)row * DFF + col0 + bj * HALF) = w;
;                 }
;             }
; template <class Epi, class Sched>
; __device__ __forceinline__ void gemm_phase(LAS unsigned char* lds, const Gemm g, const Sched& S, const Epi& E) {
;     ...
;         if (!has_next) break;
; #pragma unroll
;         for (int a = 0; a < 2; ++a)
; #pragma unroll
;             for (int b = 0; b < 2; ++b)
; #pragma unroll
;                 for (int m = 0; m < 4; ++m)
; #pragma unroll
;                     for (int n = 0; n < 2; ++n) acc[a][b][m][n] = (f32x4){0.f, 0.f, 0.f, 0.f};
;         cur = nxt; cA = nA; cB = nB; ++ui;
;     }
;     PG8_WAIT_V(0);
;     if (wr == 0) PG8_BAR;
;     PG8_BAR;
	v_pk_mul_f32 v[26:27], v[26:27], v[38:39] op_sel_hi:[1,0]
	v_pk_mul_f32 v[30:31], v[30:31], v[38:39] op_sel_hi:[1,0]
	v_pk_mul_f32 v[28:29], v[28:29], v[38:39] op_sel_hi:[1,0]
	v_max_f32_e32 v26, 0, v26
	v_pk_mul_f32 v[32:33], v[32:33], v[38:39] op_sel_hi:[1,0]
	v_max_f32_e32 v30, 0, v30
	v_mul_f32_e32 v34, v26, v26
	v_max_f32_e32 v26, 0, v31
	v_max_f32_e32 v27, 0, v27
	v_max_f32_e32 v28, 0, v28
	v_mul_f32_e32 v30, v30, v30
	v_mul_f32_e32 v26, v26, v26
	v_mul_f32_e32 v31, v27, v27
	v_max_f32_e32 v27, 0, v32
	v_mul_f32_e32 v32, v28, v28
	v_max_f32_e32 v28, 0, v33
	v_mul_f32_e32 v27, v27, v27
	v_max_f32_e32 v29, 0, v29
	v_mul_f32_e32 v28, v28, v28
	v_cvt_pk_bf16_f32 v26, v30, v26
	v_add_co_u32_e32 v30, vcc, s1, v122
	v_pk_mul_f32 v[20:21], v[20:21], v[38:39] op_sel_hi:[1,0]
	v_pk_mul_f32 v[18:19], v[18:19], v[38:39] op_sel_hi:[1,0]
	v_mul_f32_e32 v29, v29, v29
	v_cvt_pk_bf16_f32 v27, v27, v28
	v_cvt_pk_bf16_f32 v28, v34, v31
	v_addc_co_u32_e32 v31, vcc, 0, v123, vcc
	v_pk_mul_f32 v[24:25], v[24:25], v[38:39] op_sel_hi:[1,0]
	v_pk_mul_f32 v[22:23], v[22:23], v[38:39] op_sel_hi:[1,0]
	v_max_f32_e32 v18, 0, v18
	v_max_f32_e32 v19, 0, v19
	v_max_f32_e32 v20, 0, v20
	v_cvt_pk_bf16_f32 v29, v32, v29
	global_store_dwordx4 v[30:31], v[26:29], off
	v_max_f32_e32 v22, 0, v22
	v_max_f32_e32 v21, 0, v21
	v_mul_f32_e32 v26, v18, v18
	v_max_f32_e32 v18, 0, v23
	v_mul_f32_e32 v23, v19, v19
	v_max_f32_e32 v19, 0, v24
	v_mul_f32_e32 v24, v20, v20
	v_max_f32_e32 v20, 0, v25
	v_mul_f32_e32 v22, v22, v22
	v_mul_f32_e32 v18, v18, v18
	v_mul_f32_e32 v19, v19, v19
	v_mul_f32_e32 v20, v20, v20
	v_mul_f32_e32 v21, v21, v21
	v_cvt_pk_bf16_f32 v18, v22, v18
	v_cvt_pk_bf16_f32 v19, v19, v20
	v_cvt_pk_bf16_f32 v20, v26, v23
	v_cvt_pk_bf16_f32 v21, v24, v21
	ds_read_b32 v22, v146 offset:704
	v_lshl_add_u64 v[24:25], v[122:123], 0, s[44:45]
	global_store_dwordx4 v[24:25], v[18:21], off offset:256
	s_mov_b32 s1, 0x2c0000
	s_mov_b64 s[44:45], 0x2c0000
	s_waitcnt lgkmcnt(0)
	v_pk_mul_f32 v[12:13], v[12:13], v[22:23] op_sel_hi:[1,0]
	v_pk_mul_f32 v[10:11], v[10:11], v[22:23] op_sel_hi:[1,0]
	v_pk_mul_f32 v[16:17], v[16:17], v[22:23] op_sel_hi:[1,0]
	v_pk_mul_f32 v[14:15], v[14:15], v[22:23] op_sel_hi:[1,0]
	v_max_f32_e32 v10, 0, v10
	v_max_f32_e32 v11, 0, v11
	v_max_f32_e32 v12, 0, v12
	v_mul_f32_e32 v18, v10, v10
	v_max_f32_e32 v10, 0, v15
	v_mul_f32_e32 v15, v11, v11
	v_max_f32_e32 v11, 0, v16
	v_mul_f32_e32 v16, v12, v12
	v_max_f32_e32 v12, 0, v17
	v_max_f32_e32 v13, 0, v13
	v_max_f32_e32 v14, 0, v14
	v_mul_f32_e32 v10, v10, v10
	v_mul_f32_e32 v11, v11, v11
	v_mul_f32_e32 v12, v12, v12
	v_mul_f32_e32 v13, v13, v13
	v_mul_f32_e32 v14, v14, v14
	v_cvt_pk_bf16_f32 v10, v14, v10
	v_cvt_pk_bf16_f32 v11, v11, v12
	v_cvt_pk_bf16_f32 v12, v18, v15
	v_cvt_pk_bf16_f32 v13, v16, v13
	v_add_co_u32_e32 v16, vcc, s1, v122
	v_pk_mul_f32 v[4:5], v[4:5], v[22:23] op_sel_hi:[1,0]
	v_pk_mul_f32 v[2:3], v[2:3], v[22:23] op_sel_hi:[1,0]
	v_addc_co_u32_e32 v17, vcc, 0, v123, vcc
	v_pk_mul_f32 v[8:9], v[8:9], v[22:23] op_sel_hi:[1,0]
	v_pk_mul_f32 v[6:7], v[6:7], v[22:23] op_sel_hi:[1,0]
	v_max_f32_e32 v2, 0, v2
	v_max_f32_e32 v3, 0, v3
	v_max_f32_e32 v4, 0, v4
	global_store_dwordx4 v[16:17], v[10:13], off
	v_max_f32_e32 v5, 0, v5
	v_lshl_add_u64 v[14:15], v[122:123], 0, s[44:45]
	v_mul_f32_e32 v10, v2, v2
	v_max_f32_e32 v2, 0, v7
	v_mul_f32_e32 v7, v3, v3
	v_max_f32_e32 v3, 0, v8
	v_mul_f32_e32 v8, v4, v4
	v_max_f32_e32 v4, 0, v9
	v_max_f32_e32 v6, 0, v6
	v_mul_f32_e32 v2, v2, v2
	v_mul_f32_e32 v3, v3, v3
	v_mul_f32_e32 v4, v4, v4
	v_mul_f32_e32 v5, v5, v5
	s_and_b64 vcc, exec, s[42:43]
	s_mov_b64 s[44:45], s[34:35]
	v_mul_f32_e32 v6, v6, v6
	v_cvt_pk_bf16_f32 v2, v6, v2
	v_cvt_pk_bf16_f32 v3, v3, v4
	v_cvt_pk_bf16_f32 v4, v10, v7
	v_cvt_pk_bf16_f32 v5, v8, v5
	global_store_dwordx4 v[14:15], v[2:5], off offset:256
	s_cbranch_vccz .LBB0_823
	s_waitcnt vmcnt(0)
	s_cmpk_gt_u32 s13, 0xff
	s_cbranch_scc1 .LBB0_834
	s_barrier

; #define PG8_WAIT_V(n) asm volatile("s_waitcnt vmcnt(" #n ")" ::: "memory")
; #define PG8_BAR __builtin_amdgcn_s_barrier()
; template <class Epi, class Sched>
; __device__ __forceinline__ void gemm_phase(LAS unsigned char* lds, const Gemm g, const Sched& S, const Epi& E) {
;     ...
;     PG8_WAIT_V(0);
;     if (wr == 0) PG8_BAR;
;     PG8_BAR;
; __device__ __forceinline__ void xcd_barrier(const XcdBarrier& b) {
;     asm volatile("s_waitcnt vmcnt(0)" ::: "memory");
;     __syncthreads();
;     if (threadIdx.x == 0) {
;         unsigned* bar = b.bar;
;         __builtin_amdgcn_s_waitcnt(0);
;         unsigned nloc = b.st[0], nx = b.st[1];
;         if (nloc == 0u) { xcd_barrier_complete(bar, b.x, nloc, nx); b.st[0] = nloc; b.st[1] = nx; }
.LBB0_835:
	s_waitcnt vmcnt(0)
	s_barrier
	s_mov_b64 s[0:1], exec
	v_readlane_b32 s20, v253, 8
	v_readlane_b32 s21, v253, 9
	s_and_b64 s[20:21], s[0:1], s[20:21]
	s_mov_b64 exec, s[20:21]
	s_cbranch_execz .LBB0_887
	v_readlane_b32 s13, v252, 20
	s_waitcnt vmcnt(0) expcnt(0) lgkmcnt(0)
	s_nop 0
	v_mov_b32_e32 v1, s13
	ds_read_b32 v3, v1
	v_readlane_b32 s13, v252, 21
	s_waitcnt lgkmcnt(0)
	v_cmp_ne_u32_e32 vcc, 0, v3
	v_mov_b32_e32 v1, s13
	ds_read_b32 v2, v1
	s_cbranch_vccnz .LBB0_851
	s_mov_b32 s13, 1
	s_branch .LBB0_839

; #define PG8_STAGE(bufoff, gbase, voff) do { _Pragma("unroll") for (int _i = 0; _i < 2; ++_i) \
;         __builtin_amdgcn_global_load_lds((const unsigned*)((const char*)(gbase) + (voff)[_i]), (LAS unsigned*)(lds + (bufoff) + ldsw + _i * 8192), 16, 0, 0); } while (0)
; #define PG8_LDA(dst, b, h) do { _Pragma("unroll") for (int m = 0; m < 4; ++m) _Pragma("unroll") for (int k = 0; k < 2; ++k) dst[m][k] = *(const LAS bf16x8*)(lds + PG8_SA(b, h) + aoff + m * 2048 + k * 1024); } while (0)
; #define PG8_LDB(dst, b, h) do { _Pragma("unroll") for (int n = 0; n < 2; ++n) _Pragma("unroll") for (int k = 0; k < 2; ++k) dst[n][k] = *(const LAS bf16x8*)(lds + PG8_SB(b, h) + boff + n * 2048 + k * 1024); } while (0)
; #define PG8_MMA(ai, bj, At, Bt) do { __builtin_amdgcn_s_setprio(1); _Pragma("unroll") for (int m = 0; m < 4; ++m) _Pragma("unroll") for (int n = 0; n < 2; ++n) _Pragma("unroll") for (int k = 0; k < 2; ++k) \
;         acc[ai][bj][m][n] = __builtin_amdgcn_mfma_f32_16x16x32_bf16(Bt[n][k], At[m][k], acc[ai][bj][m][n], 0, 0, 0); __builtin_amdgcn_s_setprio(0); } while (0)
; #define PG8_WAIT_L(n) asm volatile("s_waitcnt lgkmcnt(" #n ")" ::: "memory")
; #define PG8_BAR __builtin_amdgcn_s_barrier()
; #define PG8_SCHED __builtin_amdgcn_sched_barrier(0)
; template <class Epi, class Sched>
; __device__ __forceinline__ void gemm_phase(LAS unsigned char* lds, const Gemm g, const Sched& S, const Epi& E) {
;     ...
;             const char* a1 = cA + (size_t)(t + 1) * kstep;
;             const char* a2 = last ? nA : cA + (size_t)(t + 2) * kstep; const char* b2 = last ? nB : cB + (size_t)(t + 2) * kstep;
;             const char* a3 = a2 + kstep; const char* b3 = b2 + kstep;
;             PG8_LDB(B0, 0, 0); PG8_SCHED; PG8_LDA(At, 0, 0); PG8_STAGE(PG8_SA(1, 1), a1 + hstepA, voffA);
;             PG8_WAIT_L(8); PG8_BAR; PG8_WAIT_L(0); PG8_MMA(0, 0, At, B0); PG8_BAR; PG8_SCHED;
;             PG8_LDB(B1, 0, 1); PG8_STAGE(PG8_SB(0, 0), b2, voffB);
;             PG8_BAR; PG8_WAIT_L(0); PG8_MMA(0, 1, At, B1); PG8_BAR;
;             PG8_LDA(At, 0, 1); PG8_STAGE(PG8_SA(0, 0), a2, voffA);
;             PG8_BAR; PG8_WAIT_L(0); PG8_MMA(1, 0, At, B0); PG8_BAR; PG8_SCHED;
.LBB0_899:
	s_add_u32 s23, s44, 0xffe00080
	s_addc_u32 s46, s45, -1
	s_add_i32 s67, 0, 0x10000
	v_add_u32_e32 v142, s67, v162
	ds_read_b128 v[130:133], v142
	ds_read_b128 v[134:137], v142 offset:1024
	ds_read_b128 v[138:141], v142 offset:2048
	ds_read_b128 v[142:145], v142 offset:3072
	s_cmpk_eq_i32 s66, 0x7c
	s_cselect_b32 s49, s25, s46
	s_cselect_b32 s48, s57, s23
	s_cselect_b32 s47, s21, s68
	s_cselect_b32 s46, s58, s59
	v_lshl_add_u64 v[198:199], s[44:45], 0, v[178:179]
	s_add_i32 m0, s31, 0xc000
	ds_read_b128 v[146:149], v210
	ds_read_b128 v[150:153], v210 offset:1024
	ds_read_b128 v[182:185], v210 offset:2048
	ds_read_b128 v[186:189], v210 offset:3072
	ds_read_b128 v[190:193], v210 offset:4096
	ds_read_b128 v[194:197], v210 offset:5120
	ds_read_b128 v[212:215], v210 offset:6144
	ds_read_b128 v[216:219], v210 offset:7168
	global_load_lds_dwordx4 v[198:199], off
	v_lshl_add_u64 v[198:199], s[44:45], 0, v[180:181]
	s_add_i32 m0, s31, 0xe000
	s_nop 0
	global_load_lds_dwordx4 v[198:199], off
	s_waitcnt lgkmcnt(8)
	s_barrier
	s_waitcnt lgkmcnt(0)
	v_mfma_f32_16x16x32_bf16 v[126:129], v[130:133], v[146:149], v[126:129]
	v_mfma_f32_16x16x32_bf16 v[122:125], v[138:141], v[146:149], v[122:125]
	v_mfma_f32_16x16x32_bf16 v[110:113], v[130:133], v[182:185], v[110:113]
	v_mfma_f32_16x16x32_bf16 v[106:109], v[138:141], v[182:185], v[106:109]
	v_mfma_f32_16x16x32_bf16 v[94:97], v[130:133], v[190:193], v[94:97]
	v_mfma_f32_16x16x32_bf16 v[90:93], v[138:141], v[190:193], v[90:93]
	v_mfma_f32_16x16x32_bf16 v[78:81], v[130:133], v[212:215], v[78:81]
	v_mfma_f32_16x16x32_bf16 v[74:77], v[138:141], v[212:215], v[74:77]
	v_mfma_f32_16x16x32_bf16 v[126:129], v[134:137], v[150:153], v[126:129]
	v_mfma_f32_16x16x32_bf16 v[122:125], v[142:145], v[150:153], v[122:125]
	v_mfma_f32_16x16x32_bf16 v[110:113], v[134:137], v[186:189], v[110:113]
	v_mfma_f32_16x16x32_bf16 v[106:109], v[142:145], v[186:189], v[106:109]
	v_mfma_f32_16x16x32_bf16 v[94:97], v[134:137], v[194:197], v[94:97]
	v_mfma_f32_16x16x32_bf16 v[90:93], v[142:145], v[194:197], v[90:93]
	v_mfma_f32_16x16x32_bf16 v[78:81], v[134:137], v[216:219], v[78:81]
	v_mfma_f32_16x16x32_bf16 v[74:77], v[142:145], v[216:219], v[74:77]
	s_barrier
	s_add_i32 s23, 0, 0x14000
	v_add_u32_e32 v198, s23, v162
	s_add_i32 s67, s67, s27
	ds_read_b128 v[220:223], v198
	ds_read_b128 v[224:227], v198 offset:1024
	ds_read_b128 v[228:231], v198 offset:2048
	ds_read_b128 v[232:235], v198 offset:3072
	v_lshl_add_u64 v[198:199], s[46:47], 0, v[174:175]
	s_mov_b32 m0, s67
	v_lshl_add_u64 v[236:237], s[46:47], 0, v[170:171]
	global_load_lds_dwordx4 v[198:199], off
	s_add_i32 m0, s67, 0x2000
	s_nop 0
	global_load_lds_dwordx4 v[236:237], off
	s_barrier
	s_waitcnt lgkmcnt(0)
	v_mfma_f32_16x16x32_bf16 v[118:121], v[220:223], v[146:149], v[118:121]
	v_mfma_f32_16x16x32_bf16 v[114:117], v[228:231], v[146:149], v[114:117]
	v_mfma_f32_16x16x32_bf16 v[102:105], v[220:223], v[182:185], v[102:105]
	v_mfma_f32_16x16x32_bf16 v[98:101], v[228:231], v[182:185], v[98:101]
	v_mfma_f32_16x16x32_bf16 v[86:89], v[220:223], v[190:193], v[86:89]
	v_mfma_f32_16x16x32_bf16 v[82:85], v[228:231], v[190:193], v[82:85]
	v_mfma_f32_16x16x32_bf16 v[70:73], v[220:223], v[212:215], v[70:73]
	v_mfma_f32_16x16x32_bf16 v[66:69], v[228:231], v[212:215], v[66:69]
	v_mfma_f32_16x16x32_bf16 v[118:121], v[224:227], v[150:153], v[118:121]
	v_mfma_f32_16x16x32_bf16 v[114:117], v[232:235], v[150:153], v[114:117]
	v_mfma_f32_16x16x32_bf16 v[102:105], v[224:227], v[186:189], v[102:105]
	v_mfma_f32_16x16x32_bf16 v[98:101], v[232:235], v[186:189], v[98:101]
	v_mfma_f32_16x16x32_bf16 v[86:89], v[224:227], v[194:197], v[86:89]
	v_mfma_f32_16x16x32_bf16 v[82:85], v[232:235], v[194:197], v[82:85]
	v_mfma_f32_16x16x32_bf16 v[70:73], v[224:227], v[216:219], v[70:73]
	v_mfma_f32_16x16x32_bf16 v[66:69], v[232:235], v[216:219], v[66:69]
	s_mov_b32 m0, s31
	v_lshl_add_u64 v[238:239], s[48:49], 0, v[176:177]
	s_barrier
	ds_read_b128 v[146:149], v210 offset:16384
	ds_read_b128 v[150:153], v210 offset:17408
	ds_read_b128 v[182:185], v210 offset:18432
	ds_read_b128 v[186:189], v210 offset:19456
	ds_read_b128 v[190:193], v210 offset:20480
	ds_read_b128 v[194:197], v210 offset:21504
	ds_read_b128 v[212:215], v210 offset:22528
	ds_read_b128 v[216:219], v210 offset:23552
	global_load_lds_dwordx4 v[238:239], off
	v_lshl_add_u64 v[240:241], s[48:49], 0, v[172:173]
	s_mov_b32 m0, s50
	s_nop 0
	global_load_lds_dwordx4 v[240:241], off
	s_barrier
	s_waitcnt lgkmcnt(0)
	v_mfma_f32_16x16x32_bf16 v[62:65], v[130:133], v[146:149], v[62:65]
	v_mfma_f32_16x16x32_bf16 v[58:61], v[138:141], v[146:149], v[58:61]
	v_mfma_f32_16x16x32_bf16 v[46:49], v[130:133], v[182:185], v[46:49]
	v_mfma_f32_16x16x32_bf16 v[42:45], v[138:141], v[182:185], v[42:45]
	v_mfma_f32_16x16x32_bf16 v[30:33], v[130:133], v[190:193], v[30:33]
	v_mfma_f32_16x16x32_bf16 v[26:29], v[138:141], v[190:193], v[26:29]
	v_mfma_f32_16x16x32_bf16 v[14:17], v[130:133], v[212:215], v[14:17]
	v_mfma_f32_16x16x32_bf16 v[10:13], v[138:141], v[212:215], v[10:13]
	v_mfma_f32_16x16x32_bf16 v[62:65], v[134:137], v[150:153], v[62:65]
	v_mfma_f32_16x16x32_bf16 v[58:61], v[142:145], v[150:153], v[58:61]
	v_mfma_f32_16x16x32_bf16 v[46:49], v[134:137], v[186:189], v[46:49]
	v_mfma_f32_16x16x32_bf16 v[42:45], v[142:145], v[186:189], v[42:45]
	v_mfma_f32_16x16x32_bf16 v[30:33], v[134:137], v[194:197], v[30:33]
	v_mfma_f32_16x16x32_bf16 v[26:29], v[142:145], v[194:197], v[26:29]
	v_mfma_f32_16x16x32_bf16 v[14:17], v[134:137], v[216:219], v[14:17]
	v_mfma_f32_16x16x32_bf16 v[10:13], v[142:145], v[216:219], v[10:13]
	s_barrier
; #define PG8_STAGE(bufoff, gbase, voff) do { _Pragma("unroll") for (int _i = 0; _i < 2; ++_i) \
;         __builtin_amdgcn_global_load_lds((const unsigned*)((const char*)(gbase) + (voff)[_i]), (LAS unsigned*)(lds + (bufoff) + ldsw + _i * 8192), 16, 0, 0); } while (0)
; #define PG8_LDA(dst, b, h) do { _Pragma("unroll") for (int m = 0; m < 4; ++m) _Pragma("unroll") for (int k = 0; k < 2; ++k) dst[m][k] = *(const LAS bf16x8*)(lds + PG8_SA(b, h) + aoff + m * 2048 + k * 1024); } while (0)
; #define PG8_LDB(dst, b, h) do { _Pragma("unroll") for (int n = 0; n < 2; ++n) _Pragma("unroll") for (int k = 0; k < 2; ++k) dst[n][k] = *(const LAS bf16x8*)(lds + PG8_SB(b, h) + boff + n * 2048 + k * 1024); } while (0)
; #define PG8_MMA(ai, bj, At, Bt) do { __builtin_amdgcn_s_setprio(1); _Pragma("unroll") for (int m = 0; m < 4; ++m) _Pragma("unroll") for (int n = 0; n < 2; ++n) _Pragma("unroll") for (int k = 0; k < 2; ++k) \
;         acc[ai][bj][m][n] = __builtin_amdgcn_mfma_f32_16x16x32_bf16(Bt[n][k], At[m][k], acc[ai][bj][m][n], 0, 0, 0); __builtin_amdgcn_s_setprio(0); } while (0)
; #define PG8_WAIT_V(n) asm volatile("s_waitcnt vmcnt(" #n ")" ::: "memory")
; #define PG8_WAIT_L(n) asm volatile("s_waitcnt lgkmcnt(" #n ")" ::: "memory")
; #define PG8_BAR __builtin_amdgcn_s_barrier()
; #define PG8_SCHED __builtin_amdgcn_sched_barrier(0)
; template <class Epi, class Sched>
; __device__ __forceinline__ void gemm_phase(LAS unsigned char* lds, const Gemm g, const Sched& S, const Epi& E) {
;     ...
;             PG8_STAGE(PG8_SB(0, 1), b2 + hstepB, voffB);
;             PG8_WAIT_V(6); PG8_BAR; PG8_MMA(1, 1, At, B1); PG8_BAR;
;             PG8_LDB(B0, 1, 0); PG8_SCHED; PG8_LDA(At, 1, 0); PG8_STAGE(PG8_SA(0, 1), a2 + hstepA, voffA);
;             PG8_WAIT_L(8); PG8_BAR; PG8_WAIT_L(0); PG8_MMA(0, 0, At, B0); PG8_BAR; PG8_SCHED;
;             PG8_LDB(B1, 1, 1); PG8_STAGE(PG8_SB(1, 0), b3, voffB);
;             PG8_BAR; PG8_WAIT_L(0); PG8_MMA(0, 1, At, B1); PG8_BAR;
;             PG8_LDA(At, 1, 1); PG8_STAGE(PG8_SA(1, 0), a3, voffA);
	s_add_u32 s70, s46, 0x200000
	s_addc_u32 s71, s47, 0
	s_add_i32 s23, s23, s27
	v_lshl_add_u64 v[130:131], s[70:71], 0, v[174:175]
	s_mov_b32 m0, s23
	s_nop 0
	global_load_lds_dwordx4 v[130:131], off
	v_lshl_add_u64 v[130:131], s[70:71], 0, v[170:171]
	s_add_i32 m0, s23, 0x2000
	s_nop 0
	global_load_lds_dwordx4 v[130:131], off
	s_waitcnt vmcnt(6)
	s_barrier
	v_mfma_f32_16x16x32_bf16 v[54:57], v[220:223], v[146:149], v[54:57]
	v_mfma_f32_16x16x32_bf16 v[50:53], v[228:231], v[146:149], v[50:53]
	v_mfma_f32_16x16x32_bf16 v[38:41], v[220:223], v[182:185], v[38:41]
	v_mfma_f32_16x16x32_bf16 v[34:37], v[228:231], v[182:185], v[34:37]
	v_mfma_f32_16x16x32_bf16 v[22:25], v[220:223], v[190:193], v[22:25]
	v_mfma_f32_16x16x32_bf16 v[18:21], v[228:231], v[190:193], v[18:21]
	v_mfma_f32_16x16x32_bf16 v[6:9], v[220:223], v[212:215], v[6:9]
	v_mfma_f32_16x16x32_bf16 v[2:5], v[228:231], v[212:215], v[2:5]
	v_mfma_f32_16x16x32_bf16 v[54:57], v[224:227], v[150:153], v[54:57]
	v_mfma_f32_16x16x32_bf16 v[50:53], v[232:235], v[150:153], v[50:53]
	v_mfma_f32_16x16x32_bf16 v[38:41], v[224:227], v[186:189], v[38:41]
	v_mfma_f32_16x16x32_bf16 v[34:37], v[232:235], v[186:189], v[34:37]
	v_mfma_f32_16x16x32_bf16 v[22:25], v[224:227], v[194:197], v[22:25]
	v_mfma_f32_16x16x32_bf16 v[18:21], v[232:235], v[194:197], v[18:21]
	v_mfma_f32_16x16x32_bf16 v[6:9], v[224:227], v[216:219], v[6:9]
	v_mfma_f32_16x16x32_bf16 v[2:5], v[232:235], v[216:219], v[2:5]
	s_add_i32 s23, 0, 0x18000
	v_add_u32_e32 v142, s23, v162
	s_barrier
	ds_read_b128 v[130:133], v142
	ds_read_b128 v[134:137], v142 offset:1024
	ds_read_b128 v[138:141], v142 offset:2048
	ds_read_b128 v[142:145], v142 offset:3072
	s_add_u32 s48, s48, 0x200000
	s_addc_u32 s49, s49, 0
	s_mov_b32 m0, s51
	v_lshl_add_u64 v[220:221], s[48:49], 0, v[176:177]
	ds_read_b128 v[146:149], v210 offset:32768
	ds_read_b128 v[150:153], v210 offset:33792
	ds_read_b128 v[182:185], v210 offset:34816
	ds_read_b128 v[186:189], v210 offset:35840
	ds_read_b128 v[190:193], v210 offset:36864
	ds_read_b128 v[194:197], v210 offset:37888
	ds_read_b128 v[212:215], v210 offset:38912
	ds_read_b128 v[216:219], v210 offset:39936
	global_load_lds_dwordx4 v[220:221], off
	v_lshl_add_u64 v[220:221], s[48:49], 0, v[172:173]
	s_mov_b32 m0, s52
	s_nop 0
	global_load_lds_dwordx4 v[220:221], off
	s_waitcnt lgkmcnt(8)
	s_barrier
	s_waitcnt lgkmcnt(0)
	v_mfma_f32_16x16x32_bf16 v[126:129], v[130:133], v[146:149], v[126:129]
	v_mfma_f32_16x16x32_bf16 v[122:125], v[138:141], v[146:149], v[122:125]
	v_mfma_f32_16x16x32_bf16 v[110:113], v[130:133], v[182:185], v[110:113]
	v_mfma_f32_16x16x32_bf16 v[106:109], v[138:141], v[182:185], v[106:109]
	v_mfma_f32_16x16x32_bf16 v[94:97], v[130:133], v[190:193], v[94:97]
	v_mfma_f32_16x16x32_bf16 v[90:93], v[138:141], v[190:193], v[90:93]
	v_mfma_f32_16x16x32_bf16 v[78:81], v[130:133], v[212:215], v[78:81]
	v_mfma_f32_16x16x32_bf16 v[74:77], v[138:141], v[212:215], v[74:77]
	v_mfma_f32_16x16x32_bf16 v[126:129], v[134:137], v[150:153], v[126:129]
	v_mfma_f32_16x16x32_bf16 v[122:125], v[142:145], v[150:153], v[122:125]
	v_mfma_f32_16x16x32_bf16 v[110:113], v[134:137], v[186:189], v[110:113]
	v_mfma_f32_16x16x32_bf16 v[106:109], v[142:145], v[186:189], v[106:109]
	v_mfma_f32_16x16x32_bf16 v[94:97], v[134:137], v[194:197], v[94:97]
	v_mfma_f32_16x16x32_bf16 v[90:93], v[142:145], v[194:197], v[90:93]
	v_mfma_f32_16x16x32_bf16 v[78:81], v[134:137], v[216:219], v[78:81]
	v_mfma_f32_16x16x32_bf16 v[74:77], v[142:145], v[216:219], v[74:77]
	s_barrier
	s_add_i32 s48, 0, 0x1c000
	s_add_i32 s23, s23, s27
	v_add_u32_e32 v211, s48, v162
	v_lshl_add_u64 v[198:199], v[198:199], 0, s[10:11]
	s_mov_b32 m0, s23
	ds_read_b128 v[220:223], v211
	ds_read_b128 v[224:227], v211 offset:1024
	ds_read_b128 v[228:231], v211 offset:2048
	ds_read_b128 v[232:235], v211 offset:3072
	global_load_lds_dwordx4 v[198:199], off
	v_lshl_add_u64 v[198:199], v[236:237], 0, s[10:11]
	s_add_i32 m0, s23, 0x2000
	s_nop 0
	global_load_lds_dwordx4 v[198:199], off
	s_barrier
	s_waitcnt lgkmcnt(0)
	v_mfma_f32_16x16x32_bf16 v[118:121], v[220:223], v[146:149], v[118:121]
	v_mfma_f32_16x16x32_bf16 v[114:117], v[228:231], v[146:149], v[114:117]
	v_mfma_f32_16x16x32_bf16 v[102:105], v[220:223], v[182:185], v[102:105]
	v_mfma_f32_16x16x32_bf16 v[98:101], v[228:231], v[182:185], v[98:101]
	v_mfma_f32_16x16x32_bf16 v[86:89], v[220:223], v[190:193], v[86:89]
	v_mfma_f32_16x16x32_bf16 v[82:85], v[228:231], v[190:193], v[82:85]
	v_mfma_f32_16x16x32_bf16 v[70:73], v[220:223], v[212:215], v[70:73]
	v_mfma_f32_16x16x32_bf16 v[66:69], v[228:231], v[212:215], v[66:69]
	v_mfma_f32_16x16x32_bf16 v[118:121], v[224:227], v[150:153], v[118:121]
	v_mfma_f32_16x16x32_bf16 v[114:117], v[232:235], v[150:153], v[114:117]
	v_mfma_f32_16x16x32_bf16 v[102:105], v[224:227], v[186:189], v[102:105]
	v_mfma_f32_16x16x32_bf16 v[98:101], v[232:235], v[186:189], v[98:101]
	v_mfma_f32_16x16x32_bf16 v[86:89], v[224:227], v[194:197], v[86:89]
	v_mfma_f32_16x16x32_bf16 v[82:85], v[232:235], v[194:197], v[82:85]
	v_mfma_f32_16x16x32_bf16 v[70:73], v[224:227], v[216:219], v[70:73]
	v_mfma_f32_16x16x32_bf16 v[66:69], v[232:235], v[216:219], v[66:69]
	s_mov_b32 m0, s28
	v_lshl_add_u64 v[198:199], v[238:239], 0, s[10:11]
	s_barrier
	ds_read_b128 v[146:149], v210 offset:49152
	ds_read_b128 v[150:153], v210 offset:50176
	ds_read_b128 v[182:185], v210 offset:51200
	ds_read_b128 v[186:189], v210 offset:52224
	ds_read_b128 v[190:193], v210 offset:53248
	ds_read_b128 v[194:197], v210 offset:54272
	ds_read_b128 v[212:215], v210 offset:55296
	ds_read_b128 v[216:219], v210 offset:56320
	global_load_lds_dwordx4 v[198:199], off
	v_lshl_add_u64 v[198:199], v[240:241], 0, s[10:11]
	s_mov_b32 m0, s29
	s_nop 0
	global_load_lds_dwordx4 v[198:199], off
	s_barrier
; #define PG8_STAGE(bufoff, gbase, voff) do { _Pragma("unroll") for (int _i = 0; _i < 2; ++_i) \
;         __builtin_amdgcn_global_load_lds((const unsigned*)((const char*)(gbase) + (voff)[_i]), (LAS unsigned*)(lds + (bufoff) + ldsw + _i * 8192), 16, 0, 0); } while (0)
; #define PG8_MMA(ai, bj, At, Bt) do { __builtin_amdgcn_s_setprio(1); _Pragma("unroll") for (int m = 0; m < 4; ++m) _Pragma("unroll") for (int n = 0; n < 2; ++n) _Pragma("unroll") for (int k = 0; k < 2; ++k) \
;         acc[ai][bj][m][n] = __builtin_amdgcn_mfma_f32_16x16x32_bf16(Bt[n][k], At[m][k], acc[ai][bj][m][n], 0, 0, 0); __builtin_amdgcn_s_setprio(0); } while (0)
; #define PG8_WAIT_V(n) asm volatile("s_waitcnt vmcnt(" #n ")" ::: "memory")
; #define PG8_WAIT_L(n) asm volatile("s_waitcnt lgkmcnt(" #n ")" ::: "memory")
; #define PG8_BAR __builtin_amdgcn_s_barrier()
; #define PG8_SCHED __builtin_amdgcn_sched_barrier(0)
; template <class Epi, class Sched>
; __device__ __forceinline__ void gemm_phase(LAS unsigned char* lds, const Gemm g, const Sched& S, const Epi& E) {
;     ...
;             PG8_BAR; PG8_WAIT_L(0); PG8_MMA(1, 0, At, B0); PG8_BAR; PG8_SCHED;
;             PG8_STAGE(PG8_SB(1, 1), b3 + hstepB, voffB);
;             PG8_WAIT_V(6); PG8_BAR; PG8_MMA(1, 1, At, B1); PG8_BAR;
;         }
	s_waitcnt lgkmcnt(0)
	v_mfma_f32_16x16x32_bf16 v[62:65], v[130:133], v[146:149], v[62:65]
	v_mfma_f32_16x16x32_bf16 v[58:61], v[138:141], v[146:149], v[58:61]
	v_mfma_f32_16x16x32_bf16 v[46:49], v[130:133], v[182:185], v[46:49]
	v_mfma_f32_16x16x32_bf16 v[42:45], v[138:141], v[182:185], v[42:45]
	v_mfma_f32_16x16x32_bf16 v[30:33], v[130:133], v[190:193], v[30:33]
	v_mfma_f32_16x16x32_bf16 v[26:29], v[138:141], v[190:193], v[26:29]
	v_mfma_f32_16x16x32_bf16 v[14:17], v[130:133], v[212:215], v[14:17]
	v_mfma_f32_16x16x32_bf16 v[10:13], v[138:141], v[212:215], v[10:13]
	v_mfma_f32_16x16x32_bf16 v[62:65], v[134:137], v[150:153], v[62:65]
	v_mfma_f32_16x16x32_bf16 v[58:61], v[142:145], v[150:153], v[58:61]
	v_mfma_f32_16x16x32_bf16 v[46:49], v[134:137], v[186:189], v[46:49]
	v_mfma_f32_16x16x32_bf16 v[42:45], v[142:145], v[186:189], v[42:45]
	v_mfma_f32_16x16x32_bf16 v[30:33], v[134:137], v[194:197], v[30:33]
	v_mfma_f32_16x16x32_bf16 v[26:29], v[142:145], v[194:197], v[26:29]
	v_mfma_f32_16x16x32_bf16 v[14:17], v[134:137], v[216:219], v[14:17]
	v_mfma_f32_16x16x32_bf16 v[10:13], v[142:145], v[216:219], v[10:13]
	s_barrier
	s_add_u32 s46, s46, 0x200080
	s_addc_u32 s47, s47, 0
	s_add_i32 s23, s48, s27
	v_lshl_add_u64 v[130:131], s[46:47], 0, v[174:175]
	s_mov_b32 m0, s23
	s_nop 0
	global_load_lds_dwordx4 v[130:131], off
	v_lshl_add_u64 v[130:131], s[46:47], 0, v[170:171]
	s_add_i32 m0, s23, 0x2000
	s_nop 0
	global_load_lds_dwordx4 v[130:131], off
	s_waitcnt vmcnt(6)
	s_barrier
	v_mfma_f32_16x16x32_bf16 v[54:57], v[220:223], v[146:149], v[54:57]
	v_mfma_f32_16x16x32_bf16 v[50:53], v[228:231], v[146:149], v[50:53]
	v_mfma_f32_16x16x32_bf16 v[38:41], v[220:223], v[182:185], v[38:41]
	v_mfma_f32_16x16x32_bf16 v[34:37], v[228:231], v[182:185], v[34:37]
	v_mfma_f32_16x16x32_bf16 v[22:25], v[220:223], v[190:193], v[22:25]
	v_mfma_f32_16x16x32_bf16 v[18:21], v[228:231], v[190:193], v[18:21]
	v_mfma_f32_16x16x32_bf16 v[6:9], v[220:223], v[212:215], v[6:9]
	v_mfma_f32_16x16x32_bf16 v[2:5], v[228:231], v[212:215], v[2:5]
	v_mfma_f32_16x16x32_bf16 v[54:57], v[224:227], v[150:153], v[54:57]
	v_mfma_f32_16x16x32_bf16 v[50:53], v[232:235], v[150:153], v[50:53]
	v_mfma_f32_16x16x32_bf16 v[38:41], v[224:227], v[186:189], v[38:41]
	v_mfma_f32_16x16x32_bf16 v[34:37], v[232:235], v[186:189], v[34:37]
	v_mfma_f32_16x16x32_bf16 v[22:25], v[224:227], v[194:197], v[22:25]
	v_mfma_f32_16x16x32_bf16 v[18:21], v[232:235], v[194:197], v[18:21]
	v_mfma_f32_16x16x32_bf16 v[6:9], v[224:227], v[216:219], v[6:9]
	v_mfma_f32_16x16x32_bf16 v[2:5], v[232:235], v[216:219], v[2:5]
	s_add_i32 s66, s66, 2
	s_add_u32 s44, s44, 0x100
	s_addc_u32 s45, s45, 0
	s_add_u32 s59, s59, 0x100
	s_addc_u32 s68, s68, 0
	s_cmpk_gt_u32 s66, 0x7d
	s_barrier
	s_cbranch_scc0 .LBB0_899
; __device__ __forceinline__ unsigned cvt_pk_bf16(float lo, float hi) { unsigned r; asm volatile("v_cvt_pk_bf16_f32 %0, %1, %2" : "=v"(r) : "v"(lo), "v"(hi)); return r; }
; __device__ __forceinline__ float bf_lo(unsigned w) { return __uint_as_float(w << 16); }
; __device__ __forceinline__ float bf_hi(unsigned w) { return __uint_as_float(w & 0xffff0000u); }
;     __device__ __forceinline__ void operator()(const f32x4 (&acc)[2][2][4][2], const Unit& u, int ui, const LAS float* rtab, int wr, int wc, int fr, int fq) const {
;         const int row0 = u.pm * BM + wr * 64 + fr, col0 = u.pn * BM + wc * 32 + 8 * fq;
; #pragma unroll
;         for (int ai = 0; ai < 2; ++ai) {
;             u32x4 xv[4][2];
; #pragma unroll
;             for (int m = 0; m < 4; ++m)
; #pragma unroll
;                 for (int bj = 0; bj < 2; ++bj) xv[m][bj] = *(const u32x4*)(XB + (size_t)(row0 + ai * HALF + m * 16) * DM + col0 + bj * HALF);
; #pragma unroll
;             for (int m = 0; m < 4; ++m) { const int row = row0 + ai * HALF + m * 16; float ss = 0.f;
; #pragma unroll
;                 for (int bj = 0; bj < 2; ++bj) {
;                     const f32x4 a0 = acc[ai][bj][m][0], a1 = acc[ai][bj][m][1]; const u32x4 xo = xv[m][bj]; u32x4 w;
;                     w.x = cvt_pk_bf16(bf_lo(xo.x) + a0[0], bf_hi(xo.x) + a0[1]); w.y = cvt_pk_bf16(bf_lo(xo.y) + a0[2], bf_hi(xo.y) + a0[3]);
;                     w.z = cvt_pk_bf16(bf_lo(xo.z) + a1[0], bf_hi(xo.z) + a1[1]); w.w = cvt_pk_bf16(bf_lo(xo.w) + a1[2], bf_hi(xo.w) + a1[3]);
;                     *(u32x4*)(XB + (size_t)row * DM + col0 + bj * HALF) = w;
; #pragma unroll
;                     for (int e = 0; e < 4; ++e) { const float lo = bf_lo(w[e]), hi = bf_hi(w[e]); ss += lo * lo + hi * hi; }
;                 }
;                 ss += __shfl_xor(ss, 16); ss += __shfl_xor(ss, 32);
;                 if (fq == 0) ssq_next[(size_t)row * 32 + (u.pn & 7) * 4 + wc] = ss; }
	v_lshl_or_b32 v182, s55, 8, v209
	v_lshl_add_u32 v186, s56, 8, v1
	v_ashrrev_i32_e32 v183, 31, v182
	v_lshlrev_b64 v[130:131], 1, v[182:183]
	v_ashrrev_i32_e32 v187, 31, v186
	v_lshl_add_u64 v[184:185], s[74:75], 0, v[130:131]
	v_lshlrev_b64 v[132:133], 12, v[186:187]
	v_lshl_add_u64 v[134:135], v[184:185], 0, v[132:133]
	global_load_dwordx4 v[212:215], v[134:135], off
	global_load_dwordx4 v[216:219], v[134:135], off offset:256
	v_or_b32_e32 v196, 16, v186
	v_or_b32_e32 v192, 32, v186
	v_or_b32_e32 v188, 48, v186
	v_ashrrev_i32_e32 v197, 31, v196
	v_ashrrev_i32_e32 v193, 31, v192
	v_ashrrev_i32_e32 v189, 31, v188
	v_lshlrev_b64 v[198:199], 12, v[196:197]
	v_lshlrev_b64 v[194:195], 12, v[192:193]
	v_lshlrev_b64 v[190:191], 12, v[188:189]
	v_lshl_add_u64 v[132:133], s[74:75], 0, v[132:133]
	v_lshl_add_u64 v[134:135], v[184:185], 0, v[198:199]
	v_lshl_add_u64 v[136:137], v[184:185], 0, v[194:195]
	v_lshl_add_u64 v[220:221], v[184:185], 0, v[190:191]
	v_lshl_add_u64 v[222:223], v[132:133], 0, v[130:131]
	global_load_dwordx4 v[150:153], v[134:135], off
	global_load_dwordx4 v[146:149], v[134:135], off offset:256
	global_load_dwordx4 v[142:145], v[136:137], off
	global_load_dwordx4 v[138:141], v[136:137], off offset:256
	s_nop 0
	global_load_dwordx4 v[134:137], v[220:221], off
	global_load_dwordx4 v[130:133], v[220:221], off offset:256
	s_lshl_b32 s21, s55, 2
	s_and_b32 s21, s21, 28
	s_waitcnt vmcnt(0)
	v_lshlrev_b32_e32 v211, 16, v212
	v_and_b32_e32 v212, 0xffff0000, v212
	v_lshlrev_b32_e32 v220, 16, v213
	v_and_b32_e32 v213, 0xffff0000, v213
	v_lshlrev_b32_e32 v221, 16, v214
	v_and_b32_e32 v214, 0xffff0000, v214
	v_lshlrev_b32_e32 v227, 16, v218
	v_and_b32_e32 v218, 0xffff0000, v218
	v_lshlrev_b32_e32 v224, 16, v215
	v_and_b32_e32 v215, 0xffff0000, v215
	v_lshlrev_b32_e32 v228, 16, v219
	v_and_b32_e32 v219, 0xffff0000, v219
	v_add_f32_e32 v126, v126, v211
	v_add_f32_e32 v127, v127, v212
	v_add_f32_e32 v128, v128, v220
	v_add_f32_e32 v129, v129, v213
	v_add_f32_e32 v122, v122, v221
	v_add_f32_e32 v123, v123, v214
	v_add_f32_e32 v211, v114, v227
	v_add_f32_e32 v212, v115, v218
	v_cvt_pk_bf16_f32 v114, v126, v127
	v_cvt_pk_bf16_f32 v115, v128, v129
	v_add_f32_e32 v124, v124, v224
	v_add_f32_e32 v125, v125, v215
	v_add_f32_e32 v213, v116, v228
	v_add_f32_e32 v214, v117, v219
	v_cvt_pk_bf16_f32 v116, v122, v123
	v_cvt_pk_bf16_f32 v117, v124, v125
	global_store_dwordx4 v[222:223], v[114:117], off
	v_lshlrev_b32_e32 v122, 16, v114
	v_lshlrev_b32_e32 v123, 16, v115
	v_and_b32_e32 v114, 0xffff0000, v114
	v_and_b32_e32 v115, 0xffff0000, v115
	v_lshlrev_b32_e32 v225, 16, v216
	v_lshlrev_b32_e32 v124, 16, v116
	v_and_b32_e32 v116, 0xffff0000, v116
	v_mul_f32_e32 v114, v114, v114
	v_mul_f32_e32 v115, v115, v115
	v_and_b32_e32 v216, 0xffff0000, v216
	v_add_f32_e32 v118, v118, v225
	v_lshlrev_b32_e32 v125, 16, v117
	v_and_b32_e32 v117, 0xffff0000, v117
	v_mul_f32_e32 v116, v116, v116
	v_fmac_f32_e32 v114, v122, v122
	v_fmac_f32_e32 v115, v123, v123
	v_lshlrev_b32_e32 v226, 16, v217
	v_and_b32_e32 v217, 0xffff0000, v217
	v_add_f32_e32 v119, v119, v216
	v_cvt_pk_bf16_f32 v118, v118, v119
	v_mul_f32_e32 v117, v117, v117
	v_and_b32_e32 v127, 0xffff0000, v118
	v_fmac_f32_e32 v116, v124, v124
	v_add_f32_e32 v114, v114, v115
	v_add_f32_e32 v120, v120, v226
	v_add_f32_e32 v121, v121, v217
	v_cvt_pk_bf16_f32 v119, v120, v121
	v_lshlrev_b32_e32 v126, 16, v118
	v_fmac_f32_e32 v117, v125, v125
	v_mul_f32_e32 v122, v127, v127
	v_add_f32_e32 v114, v114, v116
	v_and_b32_e32 v116, 0xffff0000, v119
	v_fmac_f32_e32 v122, v126, v126
	v_add_f32_e32 v114, v114, v117
	v_lshlrev_b32_e32 v115, 16, v119
	v_mul_f32_e32 v116, v116, v116
	v_add_f32_e32 v114, v114, v122
	v_fmac_f32_e32 v116, v115, v115
	v_cvt_pk_bf16_f32 v120, v211, v212
	v_add_f32_e32 v114, v114, v116
	v_and_b32_e32 v116, 0xffff0000, v120
	v_lshlrev_b32_e32 v115, 16, v120
	v_mul_f32_e32 v116, v116, v116
	v_fmac_f32_e32 v116, v115, v115
	v_cvt_pk_bf16_f32 v121, v213, v214
	v_add_f32_e32 v114, v114, v116
	v_and_b32_e32 v116, 0xffff0000, v121
	v_lshlrev_b32_e32 v115, 16, v121
	v_mul_f32_e32 v116, v116, v116
	v_fmac_f32_e32 v116, v115, v115
	v_add_f32_e32 v115, v114, v116
	v_and_b32_e32 v116, 64, v207
	v_xor_b32_e32 v114, 16, v207
	v_add_u32_e32 v117, 64, v116
	v_cmp_lt_i32_e32 vcc, v114, v117
	global_store_dwordx4 v[222:223], v[118:121], off offset:256
	s_nop 0
	v_cndmask_b32_e32 v114, v207, v114, vcc
	v_lshlrev_b32_e32 v114, 2, v114
	ds_bpermute_b32 v116, v114, v115
	s_waitcnt lgkmcnt(0)
	v_add_f32_e32 v116, v115, v116
	v_xor_b32_e32 v115, 32, v207
	v_cmp_lt_i32_e32 vcc, v115, v117
	s_nop 1
	v_cndmask_b32_e32 v115, v207, v115, vcc
	v_lshlrev_b32_e32 v115, 2, v115
	ds_bpermute_b32 v117, v115, v116
	s_and_saveexec_b64 s[44:45], s[40:41]
	s_cbranch_execz .LBB0_902
	s_waitcnt lgkmcnt(0)
	v_add_f32_e32 v118, v116, v117
	v_lshlrev_b64 v[116:117], 7, v[186:187]
	v_lshl_add_u64 v[116:117], s[0:1], 0, v[116:117]
	s_lshl_b32 s68, s21, 2
	v_lshl_add_u64 v[116:117], v[116:117], 0, s[68:69]
	s_lshl_b32 s68, s53, 2
	v_lshl_add_u64 v[116:117], v[116:117], 0, s[68:69]
	global_store_dword v[116:117], v118, off
